# v52 plus nt (streaming) hint on every store of the four GEMM epilogues
# baseline (speedup 1.0000x reference)
.LBB0_262:
	ds_read_b128 v[128:131], v181
	ds_read_b128 v[132:135], v181 offset:1024
	ds_read_b128 v[136:139], v181 offset:2048
	ds_read_b128 v[140:143], v181 offset:3072
	s_add_u32 s6, s4, 0xfff80080
	s_addc_u32 s7, s5, -1
	s_cmp_eq_u32 s37, 28
	s_cselect_b32 s9, s10, s7
	s_cselect_b32 s8, s11, s6
	s_cselect_b32 s7, s20, s36
	s_cselect_b32 s6, s34, s35
	v_lshl_add_u64 v[176:177], s[4:5], 0, v[158:159]
	s_add_i32 m0, s44, 0xc000
	ds_read_b128 v[144:147], v182
	ds_read_b128 v[168:171], v182 offset:1024
	ds_read_b128 v[172:175], v182 offset:2048
	ds_read_b128 v[184:187], v182 offset:3072
	ds_read_b128 v[188:191], v182 offset:4096
	ds_read_b128 v[192:195], v182 offset:5120
	ds_read_b128 v[196:199], v182 offset:6144
	ds_read_b128 v[200:203], v182 offset:7168
	global_load_lds_dwordx4 v[176:177], off
	v_lshl_add_u64 v[176:177], s[4:5], 0, v[160:161]
	s_add_i32 m0, s44, 0xe000
	s_nop 0
	global_load_lds_dwordx4 v[176:177], off
	s_waitcnt lgkmcnt(8)
	s_barrier
	s_waitcnt lgkmcnt(0)
	s_setprio 1
	s_waitcnt lgkmcnt(0)
	v_mfma_f32_16x16x32_bf16 v[124:127], v[128:131], v[144:147], v[124:127]
	v_mfma_f32_16x16x32_bf16 v[120:123], v[136:139], v[144:147], v[120:123]
	v_mfma_f32_16x16x32_bf16 v[108:111], v[128:131], v[172:175], v[108:111]
	v_mfma_f32_16x16x32_bf16 v[104:107], v[136:139], v[172:175], v[104:107]
	v_mfma_f32_16x16x32_bf16 v[92:95], v[128:131], v[188:191], v[92:95]
	v_mfma_f32_16x16x32_bf16 v[88:91], v[136:139], v[188:191], v[88:91]
	v_mfma_f32_16x16x32_bf16 v[76:79], v[128:131], v[196:199], v[76:79]
	v_mfma_f32_16x16x32_bf16 v[72:75], v[136:139], v[196:199], v[72:75]
	v_mfma_f32_16x16x32_bf16 v[124:127], v[132:135], v[168:171], v[124:127]
	v_mfma_f32_16x16x32_bf16 v[120:123], v[140:143], v[168:171], v[120:123]
	v_mfma_f32_16x16x32_bf16 v[108:111], v[132:135], v[184:187], v[108:111]
	v_mfma_f32_16x16x32_bf16 v[104:107], v[140:143], v[184:187], v[104:107]
	v_mfma_f32_16x16x32_bf16 v[92:95], v[132:135], v[192:195], v[92:95]
	v_mfma_f32_16x16x32_bf16 v[88:91], v[140:143], v[192:195], v[88:91]
	v_mfma_f32_16x16x32_bf16 v[76:79], v[132:135], v[200:203], v[76:79]
	v_mfma_f32_16x16x32_bf16 v[72:75], v[140:143], v[200:203], v[72:75]
	s_setprio 0
	s_barrier
	s_add_i32 s39, s80, s33
	v_lshl_add_u64 v[176:177], s[6:7], 0, v[150:151]
	s_mov_b32 m0, s39
	ds_read_b128 v[204:207], v183
	ds_read_b128 v[210:213], v183 offset:1024
	ds_read_b128 v[214:217], v183 offset:2048
	ds_read_b128 v[218:221], v183 offset:3072
	global_load_lds_dwordx4 v[176:177], off
	v_lshl_add_u64 v[222:223], s[6:7], 0, v[154:155]
	s_add_i32 m0, s39, 0x2000
	s_nop 0
	global_load_lds_dwordx4 v[222:223], off
	s_barrier
	s_waitcnt lgkmcnt(0)
	s_setprio 1
	s_waitcnt lgkmcnt(0)
	v_mfma_f32_16x16x32_bf16 v[116:119], v[204:207], v[144:147], v[116:119]
	v_mfma_f32_16x16x32_bf16 v[112:115], v[214:217], v[144:147], v[112:115]
	v_mfma_f32_16x16x32_bf16 v[100:103], v[204:207], v[172:175], v[100:103]
	v_mfma_f32_16x16x32_bf16 v[96:99], v[214:217], v[172:175], v[96:99]
	v_mfma_f32_16x16x32_bf16 v[84:87], v[204:207], v[188:191], v[84:87]
	v_mfma_f32_16x16x32_bf16 v[80:83], v[214:217], v[188:191], v[80:83]
	v_mfma_f32_16x16x32_bf16 v[68:71], v[204:207], v[196:199], v[68:71]
	v_mfma_f32_16x16x32_bf16 v[64:67], v[214:217], v[196:199], v[64:67]
	v_mfma_f32_16x16x32_bf16 v[116:119], v[210:213], v[168:171], v[116:119]
	v_mfma_f32_16x16x32_bf16 v[112:115], v[218:221], v[168:171], v[112:115]
	v_mfma_f32_16x16x32_bf16 v[100:103], v[210:213], v[184:187], v[100:103]
	v_mfma_f32_16x16x32_bf16 v[96:99], v[218:221], v[184:187], v[96:99]
	v_mfma_f32_16x16x32_bf16 v[84:87], v[210:213], v[192:195], v[84:87]
	v_mfma_f32_16x16x32_bf16 v[80:83], v[218:221], v[192:195], v[80:83]
	v_mfma_f32_16x16x32_bf16 v[68:71], v[210:213], v[200:203], v[68:71]
	v_mfma_f32_16x16x32_bf16 v[64:67], v[218:221], v[200:203], v[64:67]
	s_setprio 0
	s_mov_b32 m0, s44
	v_lshl_add_u64 v[224:225], s[8:9], 0, v[148:149]
	s_barrier
	ds_read_b128 v[144:147], v182 offset:16384
	ds_read_b128 v[168:171], v182 offset:17408
	ds_read_b128 v[172:175], v182 offset:18432
	ds_read_b128 v[184:187], v182 offset:19456
	ds_read_b128 v[188:191], v182 offset:20480
	ds_read_b128 v[192:195], v182 offset:21504
	ds_read_b128 v[196:199], v182 offset:22528
	ds_read_b128 v[200:203], v182 offset:23552
	global_load_lds_dwordx4 v[224:225], off
	v_lshl_add_u64 v[226:227], s[8:9], 0, v[152:153]
	s_mov_b32 m0, s45
	s_nop 0
	global_load_lds_dwordx4 v[226:227], off
	s_barrier
	s_waitcnt lgkmcnt(0)
	s_setprio 1
	s_waitcnt lgkmcnt(0)
	v_mfma_f32_16x16x32_bf16 v[60:63], v[128:131], v[144:147], v[60:63]
	v_mfma_f32_16x16x32_bf16 v[56:59], v[136:139], v[144:147], v[56:59]
	v_mfma_f32_16x16x32_bf16 v[44:47], v[128:131], v[172:175], v[44:47]
	v_mfma_f32_16x16x32_bf16 v[40:43], v[136:139], v[172:175], v[40:43]
	v_mfma_f32_16x16x32_bf16 v[28:31], v[128:131], v[188:191], v[28:31]
	v_mfma_f32_16x16x32_bf16 v[24:27], v[136:139], v[188:191], v[24:27]
	v_mfma_f32_16x16x32_bf16 v[12:15], v[128:131], v[196:199], v[12:15]
	v_mfma_f32_16x16x32_bf16 v[8:11], v[136:139], v[196:199], v[8:11]
	v_mfma_f32_16x16x32_bf16 v[60:63], v[132:135], v[168:171], v[60:63]
	v_mfma_f32_16x16x32_bf16 v[56:59], v[140:143], v[168:171], v[56:59]
	v_mfma_f32_16x16x32_bf16 v[44:47], v[132:135], v[184:187], v[44:47]
	v_mfma_f32_16x16x32_bf16 v[40:43], v[140:143], v[184:187], v[40:43]
	v_mfma_f32_16x16x32_bf16 v[28:31], v[132:135], v[192:195], v[28:31]
	v_mfma_f32_16x16x32_bf16 v[24:27], v[140:143], v[192:195], v[24:27]
	v_mfma_f32_16x16x32_bf16 v[12:15], v[132:135], v[200:203], v[12:15]
	v_mfma_f32_16x16x32_bf16 v[8:11], v[140:143], v[200:203], v[8:11]
	s_setprio 0
	s_barrier
	s_add_u32 s78, s6, 0x80000
	s_addc_u32 s79, s7, 0
	s_add_i32 s39, s81, s33
	v_lshl_add_u64 v[128:129], s[78:79], 0, v[150:151]
	s_mov_b32 m0, s39
	s_nop 0
	global_load_lds_dwordx4 v[128:129], off
	v_lshl_add_u64 v[128:129], s[78:79], 0, v[154:155]
	s_add_i32 m0, s39, 0x2000
	s_nop 0
	global_load_lds_dwordx4 v[128:129], off
	s_waitcnt vmcnt(6)
	s_barrier
	s_setprio 1
	v_mfma_f32_16x16x32_bf16 v[52:55], v[204:207], v[144:147], v[52:55]
	v_mfma_f32_16x16x32_bf16 v[48:51], v[214:217], v[144:147], v[48:51]
	v_mfma_f32_16x16x32_bf16 v[36:39], v[204:207], v[172:175], v[36:39]
	v_mfma_f32_16x16x32_bf16 v[32:35], v[214:217], v[172:175], v[32:35]
	v_mfma_f32_16x16x32_bf16 v[20:23], v[204:207], v[188:191], v[20:23]
	v_mfma_f32_16x16x32_bf16 v[16:19], v[214:217], v[188:191], v[16:19]
	v_mfma_f32_16x16x32_bf16 v[4:7], v[204:207], v[196:199], v[4:7]
	v_mfma_f32_16x16x32_bf16 v[0:3], v[214:217], v[196:199], v[0:3]
	v_mfma_f32_16x16x32_bf16 v[52:55], v[210:213], v[168:171], v[52:55]
	v_mfma_f32_16x16x32_bf16 v[48:51], v[218:221], v[168:171], v[48:51]
	v_mfma_f32_16x16x32_bf16 v[36:39], v[210:213], v[184:187], v[36:39]
	v_mfma_f32_16x16x32_bf16 v[32:35], v[218:221], v[184:187], v[32:35]
	v_mfma_f32_16x16x32_bf16 v[20:23], v[210:213], v[192:195], v[20:23]
	v_mfma_f32_16x16x32_bf16 v[16:19], v[218:221], v[192:195], v[16:19]
	v_mfma_f32_16x16x32_bf16 v[4:7], v[210:213], v[200:203], v[4:7]
	v_mfma_f32_16x16x32_bf16 v[0:3], v[218:221], v[200:203], v[0:3]
	s_setprio 0
	s_add_i32 s39, 0, 0x18000
	v_add_u32_e32 v140, s39, v180
	s_barrier
	ds_read_b128 v[128:131], v140
	ds_read_b128 v[132:135], v140 offset:1024
	ds_read_b128 v[136:139], v140 offset:2048
	ds_read_b128 v[140:143], v140 offset:3072
	s_add_u32 s8, s8, 0x80000
	s_addc_u32 s9, s9, 0
	s_mov_b32 m0, s51
	v_lshl_add_u64 v[204:205], s[8:9], 0, v[148:149]
	ds_read_b128 v[144:147], v182 offset:32768
	ds_read_b128 v[168:171], v182 offset:33792
	ds_read_b128 v[172:175], v182 offset:34816
	ds_read_b128 v[184:187], v182 offset:35840
	ds_read_b128 v[188:191], v182 offset:36864
	ds_read_b128 v[192:195], v182 offset:37888
	ds_read_b128 v[196:199], v182 offset:38912
	ds_read_b128 v[200:203], v182 offset:39936
	global_load_lds_dwordx4 v[204:205], off
	v_lshl_add_u64 v[204:205], s[8:9], 0, v[152:153]
	s_mov_b32 m0, s55
	s_nop 0
	global_load_lds_dwordx4 v[204:205], off
	s_waitcnt lgkmcnt(8)
	s_barrier
	s_waitcnt lgkmcnt(0)
	s_setprio 1
	s_waitcnt lgkmcnt(0)
	v_mfma_f32_16x16x32_bf16 v[124:127], v[128:131], v[144:147], v[124:127]
	v_mfma_f32_16x16x32_bf16 v[120:123], v[136:139], v[144:147], v[120:123]
	v_mfma_f32_16x16x32_bf16 v[108:111], v[128:131], v[172:175], v[108:111]
	v_mfma_f32_16x16x32_bf16 v[104:107], v[136:139], v[172:175], v[104:107]
	v_mfma_f32_16x16x32_bf16 v[92:95], v[128:131], v[188:191], v[92:95]
	v_mfma_f32_16x16x32_bf16 v[88:91], v[136:139], v[188:191], v[88:91]
	v_mfma_f32_16x16x32_bf16 v[76:79], v[128:131], v[196:199], v[76:79]
	v_mfma_f32_16x16x32_bf16 v[72:75], v[136:139], v[196:199], v[72:75]
	v_mfma_f32_16x16x32_bf16 v[124:127], v[132:135], v[168:171], v[124:127]
	v_mfma_f32_16x16x32_bf16 v[120:123], v[140:143], v[168:171], v[120:123]
	v_mfma_f32_16x16x32_bf16 v[108:111], v[132:135], v[184:187], v[108:111]
	v_mfma_f32_16x16x32_bf16 v[104:107], v[140:143], v[184:187], v[104:107]
	v_mfma_f32_16x16x32_bf16 v[92:95], v[132:135], v[192:195], v[92:95]
	v_mfma_f32_16x16x32_bf16 v[88:91], v[140:143], v[192:195], v[88:91]
	v_mfma_f32_16x16x32_bf16 v[76:79], v[132:135], v[200:203], v[76:79]
	v_mfma_f32_16x16x32_bf16 v[72:75], v[140:143], v[200:203], v[72:75]
	s_setprio 0
	s_barrier
	s_add_i32 s8, 0, 0x1c000
	s_add_i32 s9, s39, s33
	v_add_u32_e32 v156, s8, v180
	v_lshl_add_u64 v[176:177], v[176:177], 0, s[24:25]
	s_mov_b32 m0, s9
	ds_read_b128 v[204:207], v156
	ds_read_b128 v[210:213], v156 offset:1024
	ds_read_b128 v[214:217], v156 offset:2048
	ds_read_b128 v[218:221], v156 offset:3072
	global_load_lds_dwordx4 v[176:177], off
	v_lshl_add_u64 v[176:177], v[222:223], 0, s[24:25]
	s_add_i32 m0, s9, 0x2000
	s_nop 0
	global_load_lds_dwordx4 v[176:177], off
	s_barrier
	s_waitcnt lgkmcnt(0)
	s_setprio 1
	s_waitcnt lgkmcnt(0)
	v_mfma_f32_16x16x32_bf16 v[116:119], v[204:207], v[144:147], v[116:119]
	v_mfma_f32_16x16x32_bf16 v[112:115], v[214:217], v[144:147], v[112:115]
	v_mfma_f32_16x16x32_bf16 v[100:103], v[204:207], v[172:175], v[100:103]
	v_mfma_f32_16x16x32_bf16 v[96:99], v[214:217], v[172:175], v[96:99]
	v_mfma_f32_16x16x32_bf16 v[84:87], v[204:207], v[188:191], v[84:87]
	v_mfma_f32_16x16x32_bf16 v[80:83], v[214:217], v[188:191], v[80:83]
	v_mfma_f32_16x16x32_bf16 v[68:71], v[204:207], v[196:199], v[68:71]
	v_mfma_f32_16x16x32_bf16 v[64:67], v[214:217], v[196:199], v[64:67]
	v_mfma_f32_16x16x32_bf16 v[116:119], v[210:213], v[168:171], v[116:119]
	v_mfma_f32_16x16x32_bf16 v[112:115], v[218:221], v[168:171], v[112:115]
	v_mfma_f32_16x16x32_bf16 v[100:103], v[210:213], v[184:187], v[100:103]
	v_mfma_f32_16x16x32_bf16 v[96:99], v[218:221], v[184:187], v[96:99]
	v_mfma_f32_16x16x32_bf16 v[84:87], v[210:213], v[192:195], v[84:87]
	v_mfma_f32_16x16x32_bf16 v[80:83], v[218:221], v[192:195], v[80:83]
	v_mfma_f32_16x16x32_bf16 v[68:71], v[210:213], v[200:203], v[68:71]
	v_mfma_f32_16x16x32_bf16 v[64:67], v[218:221], v[200:203], v[64:67]
	s_setprio 0
	s_mov_b32 m0, s83
	v_lshl_add_u64 v[176:177], v[224:225], 0, s[24:25]
	s_barrier
	ds_read_b128 v[144:147], v182 offset:49152
	ds_read_b128 v[168:171], v182 offset:50176
	ds_read_b128 v[172:175], v182 offset:51200
	ds_read_b128 v[184:187], v182 offset:52224
	ds_read_b128 v[188:191], v182 offset:53248
	ds_read_b128 v[192:195], v182 offset:54272
	ds_read_b128 v[196:199], v182 offset:55296
	ds_read_b128 v[200:203], v182 offset:56320
	global_load_lds_dwordx4 v[176:177], off
	v_lshl_add_u64 v[176:177], v[226:227], 0, s[24:25]
	s_mov_b32 m0, s91
	s_nop 0
	global_load_lds_dwordx4 v[176:177], off
	s_barrier
	s_waitcnt lgkmcnt(0)
	s_setprio 1
	s_waitcnt lgkmcnt(0)
	v_mfma_f32_16x16x32_bf16 v[60:63], v[128:131], v[144:147], v[60:63]
	v_mfma_f32_16x16x32_bf16 v[56:59], v[136:139], v[144:147], v[56:59]
	v_mfma_f32_16x16x32_bf16 v[44:47], v[128:131], v[172:175], v[44:47]
	v_mfma_f32_16x16x32_bf16 v[40:43], v[136:139], v[172:175], v[40:43]
	v_mfma_f32_16x16x32_bf16 v[28:31], v[128:131], v[188:191], v[28:31]
	v_mfma_f32_16x16x32_bf16 v[24:27], v[136:139], v[188:191], v[24:27]
	v_mfma_f32_16x16x32_bf16 v[12:15], v[128:131], v[196:199], v[12:15]
	v_mfma_f32_16x16x32_bf16 v[8:11], v[136:139], v[196:199], v[8:11]
	v_mfma_f32_16x16x32_bf16 v[60:63], v[132:135], v[168:171], v[60:63]
	v_mfma_f32_16x16x32_bf16 v[56:59], v[140:143], v[168:171], v[56:59]
	v_mfma_f32_16x16x32_bf16 v[44:47], v[132:135], v[184:187], v[44:47]
	v_mfma_f32_16x16x32_bf16 v[40:43], v[140:143], v[184:187], v[40:43]
	v_mfma_f32_16x16x32_bf16 v[28:31], v[132:135], v[192:195], v[28:31]
	v_mfma_f32_16x16x32_bf16 v[24:27], v[140:143], v[192:195], v[24:27]
	v_mfma_f32_16x16x32_bf16 v[12:15], v[132:135], v[200:203], v[12:15]
	v_mfma_f32_16x16x32_bf16 v[8:11], v[140:143], v[200:203], v[8:11]
	s_setprio 0
	s_barrier
	s_add_u32 s6, s6, 0x80080
	s_addc_u32 s7, s7, 0
	s_add_i32 s8, s8, s33
	v_lshl_add_u64 v[128:129], s[6:7], 0, v[150:151]
	s_mov_b32 m0, s8
	s_nop 0
	global_load_lds_dwordx4 v[128:129], off
	v_lshl_add_u64 v[128:129], s[6:7], 0, v[154:155]
	s_add_i32 m0, s8, 0x2000
	s_nop 0
	global_load_lds_dwordx4 v[128:129], off
	s_waitcnt vmcnt(6)
	s_barrier
	s_setprio 1
	v_mfma_f32_16x16x32_bf16 v[52:55], v[204:207], v[144:147], v[52:55]
	v_mfma_f32_16x16x32_bf16 v[48:51], v[214:217], v[144:147], v[48:51]
	v_mfma_f32_16x16x32_bf16 v[36:39], v[204:207], v[172:175], v[36:39]
	v_mfma_f32_16x16x32_bf16 v[32:35], v[214:217], v[172:175], v[32:35]
	v_mfma_f32_16x16x32_bf16 v[20:23], v[204:207], v[188:191], v[20:23]
	v_mfma_f32_16x16x32_bf16 v[16:19], v[214:217], v[188:191], v[16:19]
	v_mfma_f32_16x16x32_bf16 v[4:7], v[204:207], v[196:199], v[4:7]
	v_mfma_f32_16x16x32_bf16 v[0:3], v[214:217], v[196:199], v[0:3]
	v_mfma_f32_16x16x32_bf16 v[52:55], v[210:213], v[168:171], v[52:55]
	v_mfma_f32_16x16x32_bf16 v[48:51], v[218:221], v[168:171], v[48:51]
	v_mfma_f32_16x16x32_bf16 v[36:39], v[210:213], v[184:187], v[36:39]
	v_mfma_f32_16x16x32_bf16 v[32:35], v[218:221], v[184:187], v[32:35]
	v_mfma_f32_16x16x32_bf16 v[20:23], v[210:213], v[192:195], v[20:23]
	v_mfma_f32_16x16x32_bf16 v[16:19], v[218:221], v[192:195], v[16:19]
	v_mfma_f32_16x16x32_bf16 v[4:7], v[210:213], v[200:203], v[4:7]
	v_mfma_f32_16x16x32_bf16 v[0:3], v[218:221], v[200:203], v[0:3]
	s_setprio 0
	s_add_i32 s37, s37, 2
	s_add_u32 s4, s4, 0x100
	s_addc_u32 s5, s5, 0
	s_add_u32 s35, s35, 0x100
	s_addc_u32 s36, s36, 0
	s_cmp_gt_u32 s37, 29
	s_barrier
	s_cbranch_scc0 .LBB0_262
	v_mov_b32_e32 v185, v179
	v_mov_b32_e32 v184, v178
	s_cmp_lt_i32 s90, 33
	s_mov_b64 s[4:5], -1
	s_cbranch_scc0 .LBB0_589
	s_cmp_gt_i32 s82, 3
	s_cbranch_scc0 .LBB0_586
	s_cmp_gt_u32 s82, 7
	s_cbranch_scc0 .LBB0_551
	s_cmp_gt_u32 s82, 15
	s_cbranch_scc0 .LBB0_548
	s_cmp_gt_u32 s82, 23
	s_cbranch_scc0 .LBB0_545
	s_cmp_gt_u32 s82, 27
	s_cbranch_scc0 .LBB0_486
	s_cmp_gt_u32 s82, 31
	s_cbranch_scc0 .LBB0_315
	s_cmp_gt_u32 s82, 35
	s_cbranch_scc0 .LBB0_280
	s_cmp_gt_u32 s82, 39
	s_cbranch_scc0 .LBB0_277
	s_lshl_b32 s4, s90, 8
	s_add_i32 s4, s4, s57
	v_lshl_add_u32 v128, v185, 3, s59
	v_add_u32_e32 v132, s4, v184
	v_ashrrev_i32_e32 v129, 31, v128
	v_mad_i64_i32 v[130:131], s[4:5], v132, s28, 0
	s_cmp_gt_u32 s82, 41
	s_mov_b64 s[4:5], -1
	v_lshl_add_u64 v[130:131], s[0:1], 0, v[130:131]
	v_lshlrev_b64 v[128:129], 1, v[128:129]
	v_add_u32_e32 v138, 16, v132
	v_add_u32_e32 v137, 32, v132
	v_add_u32_e32 v136, 48, v132
	v_add_u32_e32 v135, 0x80, v132
	v_add_u32_e32 v134, 0x90, v132
	v_add_u32_e32 v133, 0xa0, v132
	v_add_u32_e32 v132, 0xb0, v132
	s_cbranch_scc0 .LBB0_274
	s_lshl_b32 s20, s82, 8
	s_lshl_b64 s[4:5], s[20:21], 1
	v_lshl_add_u64 v[144:145], v[130:131], 0, s[4:5]
	v_cvt_pk_bf16_f32 v140, v124, v125
	v_cvt_pk_bf16_f32 v141, v126, v127
	v_cvt_pk_bf16_f32 v142, v120, v121
	v_cvt_pk_bf16_f32 v143, v122, v123
	v_lshl_add_u64 v[144:145], v[144:145], 0, v[128:129]
	global_store_dwordx4 v[144:145], v[140:143], off nt
	s_nop 1
	v_cvt_pk_bf16_f32 v140, v116, v117
	v_cvt_pk_bf16_f32 v141, v118, v119
	v_cvt_pk_bf16_f32 v142, v112, v113
	v_cvt_pk_bf16_f32 v143, v114, v115
	global_store_dwordx4 v[144:145], v[140:143], off offset:256 nt
	v_mov_b64_e32 v[144:145], s[0:1]
	v_mad_i64_i32 v[146:147], s[6:7], v138, s28, v[144:145]
	v_lshl_add_u64 v[146:147], v[146:147], 0, s[4:5]
	v_cvt_pk_bf16_f32 v140, v108, v109
	v_cvt_pk_bf16_f32 v141, v110, v111
	v_cvt_pk_bf16_f32 v142, v104, v105
	v_cvt_pk_bf16_f32 v143, v106, v107
	v_lshl_add_u64 v[146:147], v[146:147], 0, v[128:129]
	global_store_dwordx4 v[146:147], v[140:143], off nt
	s_nop 1
	v_cvt_pk_bf16_f32 v140, v100, v101
	v_cvt_pk_bf16_f32 v141, v102, v103
	v_cvt_pk_bf16_f32 v142, v96, v97
	v_cvt_pk_bf16_f32 v143, v98, v99
	global_store_dwordx4 v[146:147], v[140:143], off offset:256 nt
	v_mad_i64_i32 v[146:147], s[6:7], v137, s28, v[144:145]
	v_lshl_add_u64 v[146:147], v[146:147], 0, s[4:5]
	v_cvt_pk_bf16_f32 v140, v92, v93
	v_cvt_pk_bf16_f32 v141, v94, v95
	v_cvt_pk_bf16_f32 v142, v88, v89
	v_cvt_pk_bf16_f32 v143, v90, v91
	v_lshl_add_u64 v[146:147], v[146:147], 0, v[128:129]
	global_store_dwordx4 v[146:147], v[140:143], off nt
	s_nop 1
	v_cvt_pk_bf16_f32 v140, v84, v85
	v_cvt_pk_bf16_f32 v141, v86, v87
	v_cvt_pk_bf16_f32 v142, v80, v81
	v_cvt_pk_bf16_f32 v143, v82, v83
	global_store_dwordx4 v[146:147], v[140:143], off offset:256 nt
	v_mad_i64_i32 v[146:147], s[6:7], v136, s28, v[144:145]
	v_lshl_add_u64 v[146:147], v[146:147], 0, s[4:5]
	v_cvt_pk_bf16_f32 v140, v76, v77
	v_cvt_pk_bf16_f32 v141, v78, v79
	v_cvt_pk_bf16_f32 v142, v72, v73
	v_cvt_pk_bf16_f32 v143, v74, v75
	v_lshl_add_u64 v[146:147], v[146:147], 0, v[128:129]
	global_store_dwordx4 v[146:147], v[140:143], off nt
	s_nop 1
	v_cvt_pk_bf16_f32 v140, v68, v69
	v_cvt_pk_bf16_f32 v141, v70, v71
	v_cvt_pk_bf16_f32 v142, v64, v65
	v_cvt_pk_bf16_f32 v143, v66, v67
	global_store_dwordx4 v[146:147], v[140:143], off offset:256 nt
	v_mad_i64_i32 v[146:147], s[6:7], v135, s28, v[144:145]
	v_lshl_add_u64 v[146:147], v[146:147], 0, s[4:5]
	v_cvt_pk_bf16_f32 v140, v60, v61
	v_cvt_pk_bf16_f32 v141, v62, v63
	v_cvt_pk_bf16_f32 v142, v56, v57
	v_cvt_pk_bf16_f32 v143, v58, v59
	v_lshl_add_u64 v[146:147], v[146:147], 0, v[128:129]
	global_store_dwordx4 v[146:147], v[140:143], off nt
	s_nop 1
	v_cvt_pk_bf16_f32 v140, v52, v53
	v_cvt_pk_bf16_f32 v141, v54, v55
	v_cvt_pk_bf16_f32 v142, v48, v49
	v_cvt_pk_bf16_f32 v143, v50, v51
	global_store_dwordx4 v[146:147], v[140:143], off offset:256 nt
	v_mad_i64_i32 v[146:147], s[6:7], v134, s28, v[144:145]
	v_lshl_add_u64 v[146:147], v[146:147], 0, s[4:5]
	v_cvt_pk_bf16_f32 v140, v44, v45
	v_cvt_pk_bf16_f32 v141, v46, v47
	v_cvt_pk_bf16_f32 v142, v40, v41
	v_cvt_pk_bf16_f32 v143, v42, v43
	v_lshl_add_u64 v[146:147], v[146:147], 0, v[128:129]
	global_store_dwordx4 v[146:147], v[140:143], off nt
	s_nop 1
	v_cvt_pk_bf16_f32 v140, v36, v37
	v_cvt_pk_bf16_f32 v141, v38, v39
	v_cvt_pk_bf16_f32 v142, v32, v33
	v_cvt_pk_bf16_f32 v143, v34, v35
	global_store_dwordx4 v[146:147], v[140:143], off offset:256 nt
	v_mad_i64_i32 v[146:147], s[6:7], v133, s28, v[144:145]
	v_lshl_add_u64 v[146:147], v[146:147], 0, s[4:5]
	v_cvt_pk_bf16_f32 v140, v28, v29
	v_cvt_pk_bf16_f32 v141, v30, v31
	v_cvt_pk_bf16_f32 v142, v24, v25
	v_cvt_pk_bf16_f32 v143, v26, v27
	v_lshl_add_u64 v[146:147], v[146:147], 0, v[128:129]
	v_mad_i64_i32 v[144:145], s[6:7], v132, s28, v[144:145]
	global_store_dwordx4 v[146:147], v[140:143], off nt
	v_lshl_add_u64 v[144:145], v[144:145], 0, s[4:5]
	v_lshl_add_u64 v[144:145], v[144:145], 0, v[128:129]
	v_cvt_pk_bf16_f32 v140, v20, v21
	v_cvt_pk_bf16_f32 v141, v22, v23
	v_cvt_pk_bf16_f32 v142, v16, v17
	v_cvt_pk_bf16_f32 v143, v18, v19
	global_store_dwordx4 v[146:147], v[140:143], off offset:256 nt
	s_mov_b64 s[4:5], 0
	s_nop 0
	v_cvt_pk_bf16_f32 v140, v12, v13
	v_cvt_pk_bf16_f32 v141, v14, v15
	v_cvt_pk_bf16_f32 v142, v8, v9
	v_cvt_pk_bf16_f32 v143, v10, v11
	global_store_dwordx4 v[144:145], v[140:143], off nt
	s_nop 1
	v_cvt_pk_bf16_f32 v140, v4, v5
	v_cvt_pk_bf16_f32 v141, v6, v7
	v_cvt_pk_bf16_f32 v142, v0, v1
	v_cvt_pk_bf16_f32 v143, v2, v3
	global_store_dwordx4 v[144:145], v[140:143], off offset:256 nt
.LBB0_274:
	s_andn2_b64 vcc, exec, s[4:5]
	s_cbranch_vccnz .LBB0_276
	s_lshl_b32 s20, s82, 9
	v_pk_mul_f32 v[142:143], v[126:127], s[30:31] op_sel_hi:[1,0]
	v_pk_mul_f32 v[140:141], v[124:125], s[30:31] op_sel_hi:[1,0]
	v_pk_mul_f32 v[144:145], v[122:123], s[30:31] op_sel_hi:[1,0]
	v_pk_mul_f32 v[146:147], v[120:121], s[30:31] op_sel_hi:[1,0]
	v_lshl_add_u64 v[130:131], v[130:131], 0, s[20:21]
	v_cvt_pk_bf16_f32 v140, v140, v141
	v_cvt_pk_bf16_f32 v141, v142, v143
	v_cvt_pk_bf16_f32 v142, v146, v147
	v_cvt_pk_bf16_f32 v143, v144, v145
	v_lshl_add_u64 v[130:131], v[130:131], 0, v[128:129]
	global_store_dwordx4 v[130:131], v[140:143], off nt
	v_pk_mul_f32 v[144:145], v[114:115], s[30:31] op_sel_hi:[1,0]
	v_pk_mul_f32 v[146:147], v[112:113], s[30:31] op_sel_hi:[1,0]
	v_pk_mul_f32 v[142:143], v[118:119], s[30:31] op_sel_hi:[1,0]
	v_pk_mul_f32 v[140:141], v[116:117], s[30:31] op_sel_hi:[1,0]
	s_nop 0
	v_cvt_pk_bf16_f32 v140, v140, v141
	v_cvt_pk_bf16_f32 v141, v142, v143
	v_cvt_pk_bf16_f32 v142, v146, v147
	v_cvt_pk_bf16_f32 v143, v144, v145
	global_store_dwordx4 v[130:131], v[140:143], off offset:256 nt
	v_pk_mul_f32 v[130:131], v[110:111], s[30:31] op_sel_hi:[1,0]
	v_pk_mul_f32 v[144:145], v[106:107], s[30:31] op_sel_hi:[1,0]
	v_pk_mul_f32 v[140:141], v[108:109], s[30:31] op_sel_hi:[1,0]
	v_pk_mul_f32 v[142:143], v[104:105], s[30:31] op_sel_hi:[1,0]
	v_cvt_pk_bf16_f32 v140, v140, v141
	v_cvt_pk_bf16_f32 v141, v130, v131
	v_mov_b64_e32 v[130:131], s[0:1]
	v_mad_i64_i32 v[138:139], s[4:5], v138, s28, v[130:131]
	v_lshl_add_u64 v[138:139], v[138:139], 0, s[20:21]
	v_cvt_pk_bf16_f32 v142, v142, v143
	v_cvt_pk_bf16_f32 v143, v144, v145
	v_lshl_add_u64 v[144:145], v[138:139], 0, v[128:129]
	global_store_dwordx4 v[144:145], v[140:143], off nt
	v_pk_mul_f32 v[138:139], v[100:101], s[30:31] op_sel_hi:[1,0]
	v_pk_mul_f32 v[146:147], v[96:97], s[30:31] op_sel_hi:[1,0]
	v_pk_mul_f32 v[140:141], v[102:103], s[30:31] op_sel_hi:[1,0]
	v_pk_mul_f32 v[142:143], v[98:99], s[30:31] op_sel_hi:[1,0]
	v_cvt_pk_bf16_f32 v138, v138, v139
	v_cvt_pk_bf16_f32 v139, v140, v141
	v_cvt_pk_bf16_f32 v140, v146, v147
	v_cvt_pk_bf16_f32 v141, v142, v143
	global_store_dwordx4 v[144:145], v[138:141], off offset:256 nt
	v_pk_mul_f32 v[142:143], v[90:91], s[30:31] op_sel_hi:[1,0]
	v_pk_mul_f32 v[144:145], v[88:89], s[30:31] op_sel_hi:[1,0]
	v_pk_mul_f32 v[140:141], v[94:95], s[30:31] op_sel_hi:[1,0]
	v_pk_mul_f32 v[138:139], v[92:93], s[30:31] op_sel_hi:[1,0]
	v_pk_mul_f32 v[146:147], v[80:81], s[30:31] op_sel_hi:[1,0]
	v_cvt_pk_bf16_f32 v138, v138, v139
	v_cvt_pk_bf16_f32 v139, v140, v141
	v_cvt_pk_bf16_f32 v141, v142, v143
	v_mad_i64_i32 v[142:143], s[4:5], v137, s28, v[130:131]
	v_lshl_add_u64 v[142:143], v[142:143], 0, s[20:21]
	v_cvt_pk_bf16_f32 v140, v144, v145
	v_lshl_add_u64 v[142:143], v[142:143], 0, v[128:129]
	global_store_dwordx4 v[142:143], v[138:141], off nt
	v_pk_mul_f32 v[144:145], v[82:83], s[30:31] op_sel_hi:[1,0]
	v_mad_i64_i32 v[136:137], s[4:5], v136, s28, v[130:131]
	v_pk_mul_f32 v[140:141], v[86:87], s[30:31] op_sel_hi:[1,0]
	v_pk_mul_f32 v[138:139], v[84:85], s[30:31] op_sel_hi:[1,0]
	v_lshl_add_u64 v[136:137], v[136:137], 0, s[20:21]
	v_cvt_pk_bf16_f32 v138, v138, v139
	v_cvt_pk_bf16_f32 v139, v140, v141
	v_cvt_pk_bf16_f32 v140, v146, v147
	v_cvt_pk_bf16_f32 v141, v144, v145
	global_store_dwordx4 v[142:143], v[138:141], off offset:256 nt
	v_pk_mul_f32 v[142:143], v[74:75], s[30:31] op_sel_hi:[1,0]
	v_pk_mul_f32 v[144:145], v[72:73], s[30:31] op_sel_hi:[1,0]
	v_pk_mul_f32 v[140:141], v[78:79], s[30:31] op_sel_hi:[1,0]
	v_pk_mul_f32 v[138:139], v[76:77], s[30:31] op_sel_hi:[1,0]
	s_nop 0
	v_cvt_pk_bf16_f32 v138, v138, v139
	v_cvt_pk_bf16_f32 v139, v140, v141
	v_cvt_pk_bf16_f32 v140, v144, v145
	v_cvt_pk_bf16_f32 v141, v142, v143
	v_lshl_add_u64 v[142:143], v[136:137], 0, v[128:129]
	global_store_dwordx4 v[142:143], v[138:141], off nt
	v_pk_mul_f32 v[136:137], v[68:69], s[30:31] op_sel_hi:[1,0]
	v_pk_mul_f32 v[144:145], v[64:65], s[30:31] op_sel_hi:[1,0]
	v_pk_mul_f32 v[138:139], v[70:71], s[30:31] op_sel_hi:[1,0]
	v_pk_mul_f32 v[140:141], v[66:67], s[30:31] op_sel_hi:[1,0]
	v_cvt_pk_bf16_f32 v136, v136, v137
	v_cvt_pk_bf16_f32 v137, v138, v139
	v_cvt_pk_bf16_f32 v138, v144, v145
	v_cvt_pk_bf16_f32 v139, v140, v141
	global_store_dwordx4 v[142:143], v[136:139], off offset:256 nt
	v_pk_mul_f32 v[140:141], v[58:59], s[30:31] op_sel_hi:[1,0]
	v_pk_mul_f32 v[142:143], v[56:57], s[30:31] op_sel_hi:[1,0]
	v_pk_mul_f32 v[138:139], v[62:63], s[30:31] op_sel_hi:[1,0]
	v_pk_mul_f32 v[136:137], v[60:61], s[30:31] op_sel_hi:[1,0]
	v_pk_mul_f32 v[144:145], v[48:49], s[30:31] op_sel_hi:[1,0]
	v_cvt_pk_bf16_f32 v136, v136, v137
	v_cvt_pk_bf16_f32 v137, v138, v139
	v_cvt_pk_bf16_f32 v139, v140, v141
	v_mad_i64_i32 v[140:141], s[4:5], v135, s28, v[130:131]
	v_lshl_add_u64 v[140:141], v[140:141], 0, s[20:21]
	v_cvt_pk_bf16_f32 v138, v142, v143
	v_lshl_add_u64 v[140:141], v[140:141], 0, v[128:129]
	global_store_dwordx4 v[140:141], v[136:139], off nt
	v_pk_mul_f32 v[142:143], v[50:51], s[30:31] op_sel_hi:[1,0]
	v_mad_i64_i32 v[134:135], s[4:5], v134, s28, v[130:131]
	v_pk_mul_f32 v[138:139], v[54:55], s[30:31] op_sel_hi:[1,0]
	v_pk_mul_f32 v[136:137], v[52:53], s[30:31] op_sel_hi:[1,0]
	v_lshl_add_u64 v[134:135], v[134:135], 0, s[20:21]
	v_cvt_pk_bf16_f32 v136, v136, v137
	v_cvt_pk_bf16_f32 v137, v138, v139
	v_cvt_pk_bf16_f32 v138, v144, v145
	v_cvt_pk_bf16_f32 v139, v142, v143
	global_store_dwordx4 v[140:141], v[136:139], off offset:256 nt
	v_pk_mul_f32 v[140:141], v[42:43], s[30:31] op_sel_hi:[1,0]
	v_pk_mul_f32 v[142:143], v[40:41], s[30:31] op_sel_hi:[1,0]
	v_pk_mul_f32 v[138:139], v[46:47], s[30:31] op_sel_hi:[1,0]
	v_pk_mul_f32 v[136:137], v[44:45], s[30:31] op_sel_hi:[1,0]
	s_nop 0
	v_cvt_pk_bf16_f32 v136, v136, v137
	v_cvt_pk_bf16_f32 v137, v138, v139
	v_cvt_pk_bf16_f32 v138, v142, v143
	v_cvt_pk_bf16_f32 v139, v140, v141
	v_lshl_add_u64 v[140:141], v[134:135], 0, v[128:129]
	global_store_dwordx4 v[140:141], v[136:139], off nt
	v_pk_mul_f32 v[134:135], v[36:37], s[30:31] op_sel_hi:[1,0]
	v_pk_mul_f32 v[142:143], v[32:33], s[30:31] op_sel_hi:[1,0]
	v_pk_mul_f32 v[136:137], v[38:39], s[30:31] op_sel_hi:[1,0]
	v_pk_mul_f32 v[138:139], v[34:35], s[30:31] op_sel_hi:[1,0]
	v_cvt_pk_bf16_f32 v134, v134, v135
	v_cvt_pk_bf16_f32 v135, v136, v137
	v_cvt_pk_bf16_f32 v136, v142, v143
	v_cvt_pk_bf16_f32 v137, v138, v139
	global_store_dwordx4 v[140:141], v[134:137], off offset:256 nt
	v_pk_mul_f32 v[138:139], v[26:27], s[30:31] op_sel_hi:[1,0]
	v_pk_mul_f32 v[140:141], v[24:25], s[30:31] op_sel_hi:[1,0]
	v_pk_mul_f32 v[136:137], v[30:31], s[30:31] op_sel_hi:[1,0]
	v_pk_mul_f32 v[134:135], v[28:29], s[30:31] op_sel_hi:[1,0]
	v_pk_mul_f32 v[142:143], v[16:17], s[30:31] op_sel_hi:[1,0]
	v_cvt_pk_bf16_f32 v134, v134, v135
	v_cvt_pk_bf16_f32 v135, v136, v137
	v_cvt_pk_bf16_f32 v137, v138, v139
	v_mad_i64_i32 v[138:139], s[4:5], v133, s28, v[130:131]
	v_lshl_add_u64 v[138:139], v[138:139], 0, s[20:21]
	v_cvt_pk_bf16_f32 v136, v140, v141
	v_lshl_add_u64 v[138:139], v[138:139], 0, v[128:129]
	global_store_dwordx4 v[138:139], v[134:137], off nt
	v_pk_mul_f32 v[140:141], v[18:19], s[30:31] op_sel_hi:[1,0]
	v_mad_i64_i32 v[130:131], s[4:5], v132, s28, v[130:131]
	v_pk_mul_f32 v[136:137], v[22:23], s[30:31] op_sel_hi:[1,0]
	v_pk_mul_f32 v[134:135], v[20:21], s[30:31] op_sel_hi:[1,0]
	v_lshl_add_u64 v[130:131], v[130:131], 0, s[20:21]
	v_cvt_pk_bf16_f32 v134, v134, v135
	v_cvt_pk_bf16_f32 v135, v136, v137
	v_cvt_pk_bf16_f32 v136, v142, v143
	v_cvt_pk_bf16_f32 v137, v140, v141
	global_store_dwordx4 v[138:139], v[134:137], off offset:256 nt
	v_pk_mul_f32 v[138:139], v[10:11], s[30:31] op_sel_hi:[1,0]
	v_pk_mul_f32 v[140:141], v[8:9], s[30:31] op_sel_hi:[1,0]
	v_pk_mul_f32 v[136:137], v[14:15], s[30:31] op_sel_hi:[1,0]
	v_pk_mul_f32 v[134:135], v[12:13], s[30:31] op_sel_hi:[1,0]
	v_lshl_add_u64 v[132:133], v[130:131], 0, v[128:129]
	v_cvt_pk_bf16_f32 v134, v134, v135
	v_cvt_pk_bf16_f32 v135, v136, v137
	v_cvt_pk_bf16_f32 v136, v140, v141
	v_cvt_pk_bf16_f32 v137, v138, v139
	global_store_dwordx4 v[132:133], v[134:137], off nt
	v_pk_mul_f32 v[130:131], v[6:7], s[30:31] op_sel_hi:[1,0]
	v_pk_mul_f32 v[128:129], v[4:5], s[30:31] op_sel_hi:[1,0]
	v_pk_mul_f32 v[134:135], v[2:3], s[30:31] op_sel_hi:[1,0]
	v_pk_mul_f32 v[136:137], v[0:1], s[30:31] op_sel_hi:[1,0]
	v_cvt_pk_bf16_f32 v128, v128, v129
	v_cvt_pk_bf16_f32 v129, v130, v131
	v_cvt_pk_bf16_f32 v130, v136, v137
	v_cvt_pk_bf16_f32 v131, v134, v135
	global_store_dwordx4 v[132:133], v[128:131], off offset:256 nt

.LBB0_277:
	s_andn2_b64 vcc, exec, s[4:5]
	s_cbranch_vccnz .LBB0_279
	s_lshl_b32 s4, s90, 8
	s_add_i32 s4, s4, s57
	v_lshl_add_u32 v132, v185, 3, s59
	v_add_u32_e32 v138, s4, v184
	v_mov_b64_e32 v[134:135], s[0:1]
	v_ashrrev_i32_e32 v133, 31, v132
	v_mad_i64_i32 v[136:137], s[4:5], v138, s28, v[134:135]
	s_lshl_b32 s20, s82, 9
	v_lshl_add_u64 v[136:137], v[136:137], 0, s[20:21]
	v_lshlrev_b64 v[132:133], 1, v[132:133]
	v_cvt_pk_bf16_f32 v128, v124, v125
	v_cvt_pk_bf16_f32 v129, v126, v127
	v_cvt_pk_bf16_f32 v130, v120, v121
	v_cvt_pk_bf16_f32 v131, v122, v123
	v_lshl_add_u64 v[136:137], v[136:137], 0, v[132:133]
	global_store_dwordx4 v[136:137], v[128:131], off nt
	s_nop 1
	v_cvt_pk_bf16_f32 v128, v116, v117
	v_cvt_pk_bf16_f32 v129, v118, v119
	v_cvt_pk_bf16_f32 v130, v112, v113
	v_cvt_pk_bf16_f32 v131, v114, v115
	global_store_dwordx4 v[136:137], v[128:131], off offset:256 nt
	v_add_u32_e32 v136, 16, v138
	v_mad_i64_i32 v[136:137], s[4:5], v136, s28, v[134:135]
	v_lshl_add_u64 v[136:137], v[136:137], 0, s[20:21]
	v_cvt_pk_bf16_f32 v128, v108, v109
	v_cvt_pk_bf16_f32 v129, v110, v111
	v_cvt_pk_bf16_f32 v130, v104, v105
	v_cvt_pk_bf16_f32 v131, v106, v107
	v_lshl_add_u64 v[136:137], v[136:137], 0, v[132:133]
	global_store_dwordx4 v[136:137], v[128:131], off nt
	s_nop 1
	v_cvt_pk_bf16_f32 v128, v100, v101
	v_cvt_pk_bf16_f32 v129, v102, v103
	v_cvt_pk_bf16_f32 v130, v96, v97
	v_cvt_pk_bf16_f32 v131, v98, v99
	global_store_dwordx4 v[136:137], v[128:131], off offset:256 nt
	v_add_u32_e32 v136, 32, v138
	v_mad_i64_i32 v[136:137], s[4:5], v136, s28, v[134:135]
	v_lshl_add_u64 v[136:137], v[136:137], 0, s[20:21]
	v_cvt_pk_bf16_f32 v128, v92, v93
	v_cvt_pk_bf16_f32 v129, v94, v95
	v_cvt_pk_bf16_f32 v130, v88, v89
	v_cvt_pk_bf16_f32 v131, v90, v91
	v_lshl_add_u64 v[136:137], v[136:137], 0, v[132:133]
	global_store_dwordx4 v[136:137], v[128:131], off nt
	s_nop 1
	v_cvt_pk_bf16_f32 v128, v84, v85
	v_cvt_pk_bf16_f32 v129, v86, v87
	v_cvt_pk_bf16_f32 v130, v80, v81
	v_cvt_pk_bf16_f32 v131, v82, v83
	global_store_dwordx4 v[136:137], v[128:131], off offset:256 nt
	v_add_u32_e32 v136, 48, v138
	v_mad_i64_i32 v[136:137], s[4:5], v136, s28, v[134:135]
	v_lshl_add_u64 v[136:137], v[136:137], 0, s[20:21]
	v_cvt_pk_bf16_f32 v128, v76, v77
	v_cvt_pk_bf16_f32 v129, v78, v79
	v_cvt_pk_bf16_f32 v130, v72, v73
	v_cvt_pk_bf16_f32 v131, v74, v75
	v_lshl_add_u64 v[136:137], v[136:137], 0, v[132:133]
	global_store_dwordx4 v[136:137], v[128:131], off nt
	s_nop 1
	v_cvt_pk_bf16_f32 v128, v68, v69
	v_cvt_pk_bf16_f32 v129, v70, v71
	v_cvt_pk_bf16_f32 v130, v64, v65
	v_cvt_pk_bf16_f32 v131, v66, v67
	global_store_dwordx4 v[136:137], v[128:131], off offset:256 nt
	v_add_u32_e32 v136, 0x80, v138
	v_mad_i64_i32 v[136:137], s[4:5], v136, s28, v[134:135]
	v_lshl_add_u64 v[136:137], v[136:137], 0, s[20:21]
	v_cvt_pk_bf16_f32 v128, v60, v61
	v_cvt_pk_bf16_f32 v129, v62, v63
	v_cvt_pk_bf16_f32 v130, v56, v57
	v_cvt_pk_bf16_f32 v131, v58, v59
	v_lshl_add_u64 v[136:137], v[136:137], 0, v[132:133]
	global_store_dwordx4 v[136:137], v[128:131], off nt
	s_nop 1
	v_cvt_pk_bf16_f32 v128, v52, v53
	v_cvt_pk_bf16_f32 v129, v54, v55
	v_cvt_pk_bf16_f32 v130, v48, v49
	v_cvt_pk_bf16_f32 v131, v50, v51
	global_store_dwordx4 v[136:137], v[128:131], off offset:256 nt
	v_add_u32_e32 v136, 0x90, v138
	v_mad_i64_i32 v[136:137], s[4:5], v136, s28, v[134:135]
	v_lshl_add_u64 v[136:137], v[136:137], 0, s[20:21]
	v_cvt_pk_bf16_f32 v128, v44, v45
	v_cvt_pk_bf16_f32 v129, v46, v47
	v_cvt_pk_bf16_f32 v130, v40, v41
	v_cvt_pk_bf16_f32 v131, v42, v43
	v_lshl_add_u64 v[136:137], v[136:137], 0, v[132:133]
	global_store_dwordx4 v[136:137], v[128:131], off nt
	s_nop 1
	v_cvt_pk_bf16_f32 v128, v36, v37
	v_cvt_pk_bf16_f32 v129, v38, v39
	v_cvt_pk_bf16_f32 v130, v32, v33
	v_cvt_pk_bf16_f32 v131, v34, v35
	global_store_dwordx4 v[136:137], v[128:131], off offset:256 nt
	v_add_u32_e32 v136, 0xa0, v138
	v_mad_i64_i32 v[136:137], s[4:5], v136, s28, v[134:135]
	v_lshl_add_u64 v[136:137], v[136:137], 0, s[20:21]
	v_cvt_pk_bf16_f32 v128, v28, v29
	v_cvt_pk_bf16_f32 v129, v30, v31
	v_cvt_pk_bf16_f32 v130, v24, v25
	v_cvt_pk_bf16_f32 v131, v26, v27
	v_lshl_add_u64 v[136:137], v[136:137], 0, v[132:133]
	global_store_dwordx4 v[136:137], v[128:131], off nt
	s_nop 1
	v_cvt_pk_bf16_f32 v128, v20, v21
	v_cvt_pk_bf16_f32 v129, v22, v23
	v_cvt_pk_bf16_f32 v130, v16, v17
	v_cvt_pk_bf16_f32 v131, v18, v19
	global_store_dwordx4 v[136:137], v[128:131], off offset:256 nt
	v_add_u32_e32 v136, 0xb0, v138
	v_mad_i64_i32 v[134:135], s[4:5], v136, s28, v[134:135]
	v_lshl_add_u64 v[134:135], v[134:135], 0, s[20:21]
	v_cvt_pk_bf16_f32 v128, v12, v13
	v_cvt_pk_bf16_f32 v129, v14, v15
	v_cvt_pk_bf16_f32 v130, v8, v9
	v_cvt_pk_bf16_f32 v131, v10, v11
	v_lshl_add_u64 v[132:133], v[134:135], 0, v[132:133]
	global_store_dwordx4 v[132:133], v[128:131], off nt
	s_nop 1
	v_cvt_pk_bf16_f32 v128, v4, v5
	v_cvt_pk_bf16_f32 v129, v6, v7
	v_cvt_pk_bf16_f32 v130, v0, v1
	v_cvt_pk_bf16_f32 v131, v2, v3
	global_store_dwordx4 v[132:133], v[128:131], off offset:256 nt

.LBB0_280:
	s_andn2_b64 vcc, exec, s[4:5]
	s_cbranch_vccnz .LBB0_314
	s_lshl_b32 s4, s90, 8
	s_add_i32 s4, s4, s57
	v_add_u32_e32 v134, s4, v184
	v_mov_b64_e32 v[130:131], s[0:1]
	v_mad_i64_i32 v[130:131], s[4:5], v134, s28, v[130:131]
	s_lshl_b32 s4, s82, 9
	s_mov_b32 s5, s21
	v_lshl_add_u32 v128, v185, 3, s59
	v_lshl_add_u64 v[130:131], v[130:131], 0, s[4:5]
	v_readlane_b32 s4, v252, 0
	v_ashrrev_i32_e32 v129, 31, v128
	v_lshlrev_b32_e32 v156, 10, v134
	v_readlane_b32 s5, v252, 1
	v_readlane_b32 s6, v252, 2
	v_readlane_b32 s7, v252, 3
	v_cvt_pk_bf16_f32 v136, v124, v125
	v_cvt_pk_bf16_f32 v137, v126, v127
	v_cvt_pk_bf16_f32 v138, v120, v121
	v_cvt_pk_bf16_f32 v139, v122, v123
	v_lshl_add_u64 v[130:131], v[128:129], 1, v[130:131]
	v_lshl_add_u64 v[132:133], v[156:157], 2, s[6:7]
	s_mov_b64 s[4:5], 0x3200000
	v_and_b32_e32 v140, 0xffffff80, v134
	global_store_dwordx4 v[130:131], v[136:139], off nt
	v_and_b32_e32 v135, 0xfffff800, v134
	v_cmp_eq_u32_e32 vcc, s56, v140
	v_lshl_add_u64 v[136:137], v[132:133], 0, s[4:5]
	s_mov_b64 s[4:5], 0x5580000
	v_lshl_add_u64 v[132:133], v[132:133], 0, s[4:5]
	v_cndmask_b32_e32 v132, 0, v132, vcc
	v_cndmask_b32_e32 v133, 0, v133, vcc
	v_cmp_eq_u32_e32 vcc, s53, v135
	s_lshl_b32 s20, s82, 8
	s_nop 0
	v_cndmask_b32_e32 v133, v133, v137, vcc
	v_cndmask_b32_e32 v132, v132, v136, vcc
	v_cmp_ne_u64_e64 s[4:5], 0, v[132:133]
	v_lshl_add_u64 v[132:133], s[20:21], 2, v[132:133]
	s_and_saveexec_b64 s[6:7], s[4:5]
	s_cbranch_execz .LBB0_283
	s_movk_i32 s8, 0x8000
	v_lshl_add_u64 v[136:137], v[128:129], 2, v[132:133]
	s_mov_b32 s9, -1
	v_lshl_add_u64 v[138:139], v[136:137], 0, s[8:9]
	v_add_co_u32_e32 v136, vcc, 0xffff8000, v136
	s_nop 1
	v_addc_co_u32_e32 v137, vcc, -1, v137, vcc
	global_store_dwordx4 v[136:137], v[124:127], off nt
	global_store_dwordx4 v[138:139], v[120:123], off offset:16 nt
.LBB0_283:
	s_or_b64 exec, exec, s[6:7]
	v_cvt_pk_bf16_f32 v136, v116, v117
	v_cvt_pk_bf16_f32 v137, v118, v119
	v_cvt_pk_bf16_f32 v138, v112, v113
	v_cvt_pk_bf16_f32 v139, v114, v115
	global_store_dwordx4 v[130:131], v[136:139], off offset:256 nt
	s_and_saveexec_b64 s[6:7], s[4:5]
	s_cbranch_execz .LBB0_285
	s_movk_i32 s4, 0x8200
	v_lshl_add_u64 v[130:131], v[128:129], 2, v[132:133]
	s_mov_b32 s5, -1
	v_lshl_add_u64 v[132:133], v[130:131], 0, s[4:5]
	v_add_co_u32_e32 v130, vcc, 0xffff9000, v130
	s_nop 1
	v_addc_co_u32_e32 v131, vcc, -1, v131, vcc
	global_store_dwordx4 v[130:131], v[116:119], off offset:-3584 nt
	global_store_dwordx4 v[132:133], v[112:115], off offset:16 nt
.LBB0_285:
	s_or_b64 exec, exec, s[6:7]
	v_add_u32_e32 v132, 16, v134
	v_mov_b64_e32 v[130:131], s[0:1]
	v_mad_i64_i32 v[130:131], s[4:5], v132, s28, v[130:131]
	s_lshl_b32 s6, s20, 1
	s_mov_b32 s7, s21
	v_readlane_b32 s8, v252, 0
	v_lshlrev_b32_e32 v156, 10, v132
	v_lshl_add_u64 v[130:131], v[130:131], 0, s[6:7]
	v_readlane_b32 s10, v252, 2
	v_readlane_b32 s11, v252, 3
	v_and_b32_e32 v135, 0xfffff800, v132
	v_and_b32_e32 v140, 0xffffff80, v132
	v_cvt_pk_bf16_f32 v136, v108, v109
	v_cvt_pk_bf16_f32 v137, v110, v111
	v_cvt_pk_bf16_f32 v138, v104, v105
	v_cvt_pk_bf16_f32 v139, v106, v107
	v_lshl_add_u64 v[130:131], v[128:129], 1, v[130:131]
	v_lshl_add_u64 v[132:133], v[156:157], 2, s[10:11]
	s_mov_b64 s[4:5], 0x3200000
	global_store_dwordx4 v[130:131], v[136:139], off nt
	v_cmp_eq_u32_e32 vcc, s56, v140
	v_readlane_b32 s9, v252, 1
	v_lshl_add_u64 v[136:137], v[132:133], 0, s[4:5]
	s_mov_b64 s[4:5], 0x5580000
	v_lshl_add_u64 v[132:133], v[132:133], 0, s[4:5]
	v_cndmask_b32_e32 v132, 0, v132, vcc
	v_cndmask_b32_e32 v133, 0, v133, vcc
	v_cmp_eq_u32_e32 vcc, s53, v135
	s_nop 1
	v_cndmask_b32_e32 v133, v133, v137, vcc
	v_cndmask_b32_e32 v132, v132, v136, vcc
	v_cmp_ne_u64_e64 s[4:5], 0, v[132:133]
	v_lshl_add_u64 v[132:133], s[20:21], 2, v[132:133]
	s_and_saveexec_b64 s[8:9], s[4:5]
	s_cbranch_execz .LBB0_287
	s_movk_i32 s10, 0x8000
	v_lshl_add_u64 v[136:137], v[128:129], 2, v[132:133]
	s_mov_b32 s11, -1
	v_lshl_add_u64 v[138:139], v[136:137], 0, s[10:11]
	v_add_co_u32_e32 v136, vcc, 0xffff8000, v136
	s_nop 1
	v_addc_co_u32_e32 v137, vcc, -1, v137, vcc
	global_store_dwordx4 v[136:137], v[108:111], off nt
	global_store_dwordx4 v[138:139], v[104:107], off offset:16 nt
.LBB0_287:
	s_or_b64 exec, exec, s[8:9]
	v_cvt_pk_bf16_f32 v136, v100, v101
	v_cvt_pk_bf16_f32 v137, v102, v103
	v_cvt_pk_bf16_f32 v138, v96, v97
	v_cvt_pk_bf16_f32 v139, v98, v99
	global_store_dwordx4 v[130:131], v[136:139], off offset:256 nt
	s_and_saveexec_b64 s[8:9], s[4:5]
	s_cbranch_execz .LBB0_289
	s_movk_i32 s4, 0x8200
	v_lshl_add_u64 v[130:131], v[128:129], 2, v[132:133]
	s_mov_b32 s5, -1
	v_lshl_add_u64 v[132:133], v[130:131], 0, s[4:5]
	v_add_co_u32_e32 v130, vcc, 0xffff9000, v130
	s_nop 1
	v_addc_co_u32_e32 v131, vcc, -1, v131, vcc
	global_store_dwordx4 v[130:131], v[100:103], off offset:-3584 nt
	global_store_dwordx4 v[132:133], v[96:99], off offset:16 nt
.LBB0_289:
	s_or_b64 exec, exec, s[8:9]
	v_add_u32_e32 v132, 32, v134
	v_mov_b64_e32 v[130:131], s[0:1]
	v_mad_i64_i32 v[130:131], s[4:5], v132, s28, v[130:131]
	s_mov_b32 s7, s21
	v_readlane_b32 s8, v252, 0
	v_lshlrev_b32_e32 v156, 10, v132
	v_lshl_add_u64 v[130:131], v[130:131], 0, s[6:7]
	v_readlane_b32 s10, v252, 2
	v_readlane_b32 s11, v252, 3
	v_and_b32_e32 v135, 0xfffff800, v132
	v_and_b32_e32 v140, 0xffffff80, v132
	v_cvt_pk_bf16_f32 v136, v92, v93
	v_cvt_pk_bf16_f32 v137, v94, v95
	v_cvt_pk_bf16_f32 v138, v88, v89
	v_cvt_pk_bf16_f32 v139, v90, v91
	v_lshl_add_u64 v[130:131], v[128:129], 1, v[130:131]
	v_lshl_add_u64 v[132:133], v[156:157], 2, s[10:11]
	s_mov_b64 s[4:5], 0x3200000
	global_store_dwordx4 v[130:131], v[136:139], off nt
	v_cmp_eq_u32_e32 vcc, s56, v140
	v_readlane_b32 s9, v252, 1
	v_lshl_add_u64 v[136:137], v[132:133], 0, s[4:5]
	s_mov_b64 s[4:5], 0x5580000
	v_lshl_add_u64 v[132:133], v[132:133], 0, s[4:5]
	v_cndmask_b32_e32 v132, 0, v132, vcc
	v_cndmask_b32_e32 v133, 0, v133, vcc
	v_cmp_eq_u32_e32 vcc, s53, v135
	s_nop 1
	v_cndmask_b32_e32 v133, v133, v137, vcc
	v_cndmask_b32_e32 v132, v132, v136, vcc
	v_cmp_ne_u64_e64 s[4:5], 0, v[132:133]
	v_lshl_add_u64 v[132:133], s[20:21], 2, v[132:133]
	s_and_saveexec_b64 s[8:9], s[4:5]
	s_cbranch_execz .LBB0_291
	s_movk_i32 s10, 0x8000
	v_lshl_add_u64 v[136:137], v[128:129], 2, v[132:133]
	s_mov_b32 s11, -1
	v_lshl_add_u64 v[138:139], v[136:137], 0, s[10:11]
	v_add_co_u32_e32 v136, vcc, 0xffff8000, v136
	s_nop 1
	v_addc_co_u32_e32 v137, vcc, -1, v137, vcc
	global_store_dwordx4 v[136:137], v[92:95], off nt
	global_store_dwordx4 v[138:139], v[88:91], off offset:16 nt
.LBB0_291:
	s_or_b64 exec, exec, s[8:9]
	v_cvt_pk_bf16_f32 v136, v84, v85
	v_cvt_pk_bf16_f32 v137, v86, v87
	v_cvt_pk_bf16_f32 v138, v80, v81
	v_cvt_pk_bf16_f32 v139, v82, v83
	global_store_dwordx4 v[130:131], v[136:139], off offset:256 nt
	s_and_saveexec_b64 s[8:9], s[4:5]
	s_cbranch_execz .LBB0_293
	s_movk_i32 s4, 0x8200
	v_lshl_add_u64 v[130:131], v[128:129], 2, v[132:133]
	s_mov_b32 s5, -1
	v_lshl_add_u64 v[132:133], v[130:131], 0, s[4:5]
	v_add_co_u32_e32 v130, vcc, 0xffff9000, v130
	s_nop 1
	v_addc_co_u32_e32 v131, vcc, -1, v131, vcc
	global_store_dwordx4 v[130:131], v[84:87], off offset:-3584 nt
	global_store_dwordx4 v[132:133], v[80:83], off offset:16 nt
.LBB0_293:
	s_or_b64 exec, exec, s[8:9]
	v_add_u32_e32 v132, 48, v134
	v_mov_b64_e32 v[130:131], s[0:1]
	v_mad_i64_i32 v[130:131], s[4:5], v132, s28, v[130:131]
	s_mov_b32 s7, s21
	v_readlane_b32 s8, v252, 0
	v_lshlrev_b32_e32 v156, 10, v132
	v_lshl_add_u64 v[130:131], v[130:131], 0, s[6:7]
	v_readlane_b32 s10, v252, 2
	v_readlane_b32 s11, v252, 3
	v_and_b32_e32 v135, 0xfffff800, v132
	v_and_b32_e32 v140, 0xffffff80, v132
	v_cvt_pk_bf16_f32 v136, v76, v77
	v_cvt_pk_bf16_f32 v137, v78, v79
	v_cvt_pk_bf16_f32 v138, v72, v73
	v_cvt_pk_bf16_f32 v139, v74, v75
	v_lshl_add_u64 v[130:131], v[128:129], 1, v[130:131]
	v_lshl_add_u64 v[132:133], v[156:157], 2, s[10:11]
	s_mov_b64 s[4:5], 0x3200000
	global_store_dwordx4 v[130:131], v[136:139], off nt
	v_cmp_eq_u32_e32 vcc, s56, v140
	v_readlane_b32 s9, v252, 1
	v_lshl_add_u64 v[136:137], v[132:133], 0, s[4:5]
	s_mov_b64 s[4:5], 0x5580000
	v_lshl_add_u64 v[132:133], v[132:133], 0, s[4:5]
	v_cndmask_b32_e32 v132, 0, v132, vcc
	v_cndmask_b32_e32 v133, 0, v133, vcc
	v_cmp_eq_u32_e32 vcc, s53, v135
	s_nop 1
	v_cndmask_b32_e32 v133, v133, v137, vcc
	v_cndmask_b32_e32 v132, v132, v136, vcc
	v_cmp_ne_u64_e64 s[4:5], 0, v[132:133]
	v_lshl_add_u64 v[132:133], s[20:21], 2, v[132:133]
	s_and_saveexec_b64 s[8:9], s[4:5]
	s_cbranch_execz .LBB0_295
	s_movk_i32 s10, 0x8000
	v_lshl_add_u64 v[136:137], v[128:129], 2, v[132:133]
	s_mov_b32 s11, -1
	v_lshl_add_u64 v[138:139], v[136:137], 0, s[10:11]
	v_add_co_u32_e32 v136, vcc, 0xffff8000, v136
	s_nop 1
	v_addc_co_u32_e32 v137, vcc, -1, v137, vcc
	global_store_dwordx4 v[136:137], v[76:79], off nt
	global_store_dwordx4 v[138:139], v[72:75], off offset:16 nt
.LBB0_295:
	s_or_b64 exec, exec, s[8:9]
	v_cvt_pk_bf16_f32 v136, v68, v69
	v_cvt_pk_bf16_f32 v137, v70, v71
	v_cvt_pk_bf16_f32 v138, v64, v65
	v_cvt_pk_bf16_f32 v139, v66, v67
	global_store_dwordx4 v[130:131], v[136:139], off offset:256 nt
	s_and_saveexec_b64 s[8:9], s[4:5]
	s_cbranch_execz .LBB0_297
	s_movk_i32 s4, 0x8200
	v_lshl_add_u64 v[130:131], v[128:129], 2, v[132:133]
	s_mov_b32 s5, -1
	v_lshl_add_u64 v[132:133], v[130:131], 0, s[4:5]
	v_add_co_u32_e32 v130, vcc, 0xffff9000, v130
	s_nop 1
	v_addc_co_u32_e32 v131, vcc, -1, v131, vcc
	global_store_dwordx4 v[130:131], v[68:71], off offset:-3584 nt
	global_store_dwordx4 v[132:133], v[64:67], off offset:16 nt
.LBB0_297:
	s_or_b64 exec, exec, s[8:9]
	v_add_u32_e32 v132, 0x80, v134
	v_mov_b64_e32 v[130:131], s[0:1]
	v_mad_i64_i32 v[130:131], s[4:5], v132, s28, v[130:131]
	s_mov_b32 s7, s21
	v_readlane_b32 s8, v252, 0
	v_lshlrev_b32_e32 v156, 10, v132
	v_lshl_add_u64 v[130:131], v[130:131], 0, s[6:7]
	v_readlane_b32 s10, v252, 2
	v_readlane_b32 s11, v252, 3
	v_and_b32_e32 v135, 0xfffff800, v132
	v_and_b32_e32 v140, 0xffffff80, v132
	v_cvt_pk_bf16_f32 v136, v60, v61
	v_cvt_pk_bf16_f32 v137, v62, v63
	v_cvt_pk_bf16_f32 v138, v56, v57
	v_cvt_pk_bf16_f32 v139, v58, v59
	v_lshl_add_u64 v[130:131], v[128:129], 1, v[130:131]
	v_lshl_add_u64 v[132:133], v[156:157], 2, s[10:11]
	s_mov_b64 s[4:5], 0x3200000
	global_store_dwordx4 v[130:131], v[136:139], off nt
	v_cmp_eq_u32_e32 vcc, s56, v140
	v_readlane_b32 s9, v252, 1
	v_lshl_add_u64 v[136:137], v[132:133], 0, s[4:5]
	s_mov_b64 s[4:5], 0x5580000
	v_lshl_add_u64 v[132:133], v[132:133], 0, s[4:5]
	v_cndmask_b32_e32 v132, 0, v132, vcc
	v_cndmask_b32_e32 v133, 0, v133, vcc
	v_cmp_eq_u32_e32 vcc, s53, v135
	s_nop 1
	v_cndmask_b32_e32 v133, v133, v137, vcc
	v_cndmask_b32_e32 v132, v132, v136, vcc
	v_cmp_ne_u64_e64 s[4:5], 0, v[132:133]
	v_lshl_add_u64 v[132:133], s[20:21], 2, v[132:133]
	s_and_saveexec_b64 s[8:9], s[4:5]
	s_cbranch_execz .LBB0_299
	s_movk_i32 s10, 0x8000
	v_lshl_add_u64 v[136:137], v[128:129], 2, v[132:133]
	s_mov_b32 s11, -1
	v_lshl_add_u64 v[138:139], v[136:137], 0, s[10:11]
	v_add_co_u32_e32 v136, vcc, 0xffff8000, v136
	s_nop 1
	v_addc_co_u32_e32 v137, vcc, -1, v137, vcc
	global_store_dwordx4 v[136:137], v[60:63], off nt
	global_store_dwordx4 v[138:139], v[56:59], off offset:16 nt
.LBB0_299:
	s_or_b64 exec, exec, s[8:9]
	v_cvt_pk_bf16_f32 v136, v52, v53
	v_cvt_pk_bf16_f32 v137, v54, v55
	v_cvt_pk_bf16_f32 v138, v48, v49
	v_cvt_pk_bf16_f32 v139, v50, v51
	global_store_dwordx4 v[130:131], v[136:139], off offset:256 nt
	s_and_saveexec_b64 s[8:9], s[4:5]
	s_cbranch_execz .LBB0_301
	s_movk_i32 s4, 0x8200
	v_lshl_add_u64 v[130:131], v[128:129], 2, v[132:133]
	s_mov_b32 s5, -1
	v_lshl_add_u64 v[132:133], v[130:131], 0, s[4:5]
	v_add_co_u32_e32 v130, vcc, 0xffff9000, v130
	s_nop 1
	v_addc_co_u32_e32 v131, vcc, -1, v131, vcc
	global_store_dwordx4 v[130:131], v[52:55], off offset:-3584 nt
	global_store_dwordx4 v[132:133], v[48:51], off offset:16 nt
.LBB0_301:
	s_or_b64 exec, exec, s[8:9]
	v_add_u32_e32 v132, 0x90, v134
	v_mov_b64_e32 v[130:131], s[0:1]
	v_mad_i64_i32 v[130:131], s[4:5], v132, s28, v[130:131]
	s_mov_b32 s7, s21
	v_readlane_b32 s8, v252, 0
	v_lshlrev_b32_e32 v156, 10, v132
	v_lshl_add_u64 v[130:131], v[130:131], 0, s[6:7]
	v_readlane_b32 s10, v252, 2
	v_readlane_b32 s11, v252, 3
	v_and_b32_e32 v135, 0xfffff800, v132
	v_and_b32_e32 v140, 0xffffff80, v132
	v_cvt_pk_bf16_f32 v136, v44, v45
	v_cvt_pk_bf16_f32 v137, v46, v47
	v_cvt_pk_bf16_f32 v138, v40, v41
	v_cvt_pk_bf16_f32 v139, v42, v43
	v_lshl_add_u64 v[130:131], v[128:129], 1, v[130:131]
	v_lshl_add_u64 v[132:133], v[156:157], 2, s[10:11]
	s_mov_b64 s[4:5], 0x3200000
	global_store_dwordx4 v[130:131], v[136:139], off nt
	v_cmp_eq_u32_e32 vcc, s56, v140
	v_readlane_b32 s9, v252, 1
	v_lshl_add_u64 v[136:137], v[132:133], 0, s[4:5]
	s_mov_b64 s[4:5], 0x5580000
	v_lshl_add_u64 v[132:133], v[132:133], 0, s[4:5]
	v_cndmask_b32_e32 v132, 0, v132, vcc
	v_cndmask_b32_e32 v133, 0, v133, vcc
	v_cmp_eq_u32_e32 vcc, s53, v135
	s_nop 1
	v_cndmask_b32_e32 v133, v133, v137, vcc
	v_cndmask_b32_e32 v132, v132, v136, vcc
	v_cmp_ne_u64_e64 s[4:5], 0, v[132:133]
	v_lshl_add_u64 v[132:133], s[20:21], 2, v[132:133]
	s_and_saveexec_b64 s[8:9], s[4:5]
	s_cbranch_execz .LBB0_303
	s_movk_i32 s10, 0x8000
	v_lshl_add_u64 v[136:137], v[128:129], 2, v[132:133]
	s_mov_b32 s11, -1
	v_lshl_add_u64 v[138:139], v[136:137], 0, s[10:11]
	v_add_co_u32_e32 v136, vcc, 0xffff8000, v136
	s_nop 1
	v_addc_co_u32_e32 v137, vcc, -1, v137, vcc
	global_store_dwordx4 v[136:137], v[44:47], off nt
	global_store_dwordx4 v[138:139], v[40:43], off offset:16 nt
.LBB0_303:
	s_or_b64 exec, exec, s[8:9]
	v_cvt_pk_bf16_f32 v136, v36, v37
	v_cvt_pk_bf16_f32 v137, v38, v39
	v_cvt_pk_bf16_f32 v138, v32, v33
	v_cvt_pk_bf16_f32 v139, v34, v35
	global_store_dwordx4 v[130:131], v[136:139], off offset:256 nt
	s_and_saveexec_b64 s[8:9], s[4:5]
	s_cbranch_execz .LBB0_305
	s_movk_i32 s4, 0x8200
	v_lshl_add_u64 v[130:131], v[128:129], 2, v[132:133]
	s_mov_b32 s5, -1
	v_lshl_add_u64 v[132:133], v[130:131], 0, s[4:5]
	v_add_co_u32_e32 v130, vcc, 0xffff9000, v130
	s_nop 1
	v_addc_co_u32_e32 v131, vcc, -1, v131, vcc
	global_store_dwordx4 v[130:131], v[36:39], off offset:-3584 nt
	global_store_dwordx4 v[132:133], v[32:35], off offset:16 nt
.LBB0_305:
	s_or_b64 exec, exec, s[8:9]
	v_add_u32_e32 v132, 0xa0, v134
	v_mov_b64_e32 v[130:131], s[0:1]
	v_mad_i64_i32 v[130:131], s[4:5], v132, s28, v[130:131]
	s_mov_b32 s7, s21
	v_readlane_b32 s8, v252, 0
	v_lshlrev_b32_e32 v156, 10, v132
	v_lshl_add_u64 v[130:131], v[130:131], 0, s[6:7]
	v_readlane_b32 s10, v252, 2
	v_readlane_b32 s11, v252, 3
	v_and_b32_e32 v135, 0xfffff800, v132
	v_and_b32_e32 v140, 0xffffff80, v132
	v_cvt_pk_bf16_f32 v136, v28, v29
	v_cvt_pk_bf16_f32 v137, v30, v31
	v_cvt_pk_bf16_f32 v138, v24, v25
	v_cvt_pk_bf16_f32 v139, v26, v27
	v_lshl_add_u64 v[130:131], v[128:129], 1, v[130:131]
	v_lshl_add_u64 v[132:133], v[156:157], 2, s[10:11]
	s_mov_b64 s[4:5], 0x3200000
	global_store_dwordx4 v[130:131], v[136:139], off nt
	v_cmp_eq_u32_e32 vcc, s56, v140
	v_readlane_b32 s9, v252, 1
	v_lshl_add_u64 v[136:137], v[132:133], 0, s[4:5]
	s_mov_b64 s[4:5], 0x5580000
	v_lshl_add_u64 v[132:133], v[132:133], 0, s[4:5]
	v_cndmask_b32_e32 v132, 0, v132, vcc
	v_cndmask_b32_e32 v133, 0, v133, vcc
	v_cmp_eq_u32_e32 vcc, s53, v135
	s_nop 1
	v_cndmask_b32_e32 v133, v133, v137, vcc
	v_cndmask_b32_e32 v132, v132, v136, vcc
	v_cmp_ne_u64_e64 s[4:5], 0, v[132:133]
	v_lshl_add_u64 v[132:133], s[20:21], 2, v[132:133]
	s_and_saveexec_b64 s[8:9], s[4:5]
	s_cbranch_execz .LBB0_307
	s_movk_i32 s10, 0x8000
	v_lshl_add_u64 v[136:137], v[128:129], 2, v[132:133]
	s_mov_b32 s11, -1
	v_lshl_add_u64 v[138:139], v[136:137], 0, s[10:11]
	v_add_co_u32_e32 v136, vcc, 0xffff8000, v136
	s_nop 1
	v_addc_co_u32_e32 v137, vcc, -1, v137, vcc
	global_store_dwordx4 v[136:137], v[28:31], off nt
	global_store_dwordx4 v[138:139], v[24:27], off offset:16 nt
.LBB0_307:
	s_or_b64 exec, exec, s[8:9]
	v_cvt_pk_bf16_f32 v136, v20, v21
	v_cvt_pk_bf16_f32 v137, v22, v23
	v_cvt_pk_bf16_f32 v138, v16, v17
	v_cvt_pk_bf16_f32 v139, v18, v19
	global_store_dwordx4 v[130:131], v[136:139], off offset:256 nt
	s_and_saveexec_b64 s[8:9], s[4:5]
	s_cbranch_execz .LBB0_309
	s_movk_i32 s4, 0x8200
	v_lshl_add_u64 v[130:131], v[128:129], 2, v[132:133]
	s_mov_b32 s5, -1
	v_lshl_add_u64 v[132:133], v[130:131], 0, s[4:5]
	v_add_co_u32_e32 v130, vcc, 0xffff9000, v130
	s_nop 1
	v_addc_co_u32_e32 v131, vcc, -1, v131, vcc
	global_store_dwordx4 v[130:131], v[20:23], off offset:-3584 nt
	global_store_dwordx4 v[132:133], v[16:19], off offset:16 nt
.LBB0_309:
	s_or_b64 exec, exec, s[8:9]
	v_add_u32_e32 v136, 0xb0, v134
	v_mov_b64_e32 v[130:131], s[0:1]
	v_mad_i64_i32 v[130:131], s[4:5], v136, s28, v[130:131]
	s_mov_b32 s7, s21
	v_lshl_add_u64 v[130:131], v[130:131], 0, s[6:7]
	v_readlane_b32 s4, v252, 0
	v_lshlrev_b32_e32 v156, 10, v136
	v_cvt_pk_bf16_f32 v132, v12, v13
	v_cvt_pk_bf16_f32 v133, v14, v15
	v_cvt_pk_bf16_f32 v134, v8, v9
	v_cvt_pk_bf16_f32 v135, v10, v11
	v_lshl_add_u64 v[130:131], v[128:129], 1, v[130:131]
	v_readlane_b32 s5, v252, 1
	v_readlane_b32 s6, v252, 2
	v_readlane_b32 s7, v252, 3
	global_store_dwordx4 v[130:131], v[132:135], off nt
	s_mov_b64 s[4:5], 0x3200000
	v_and_b32_e32 v138, 0xffffff80, v136
	v_lshl_add_u64 v[132:133], v[156:157], 2, s[6:7]
	v_lshl_add_u64 v[134:135], v[132:133], 0, s[4:5]
	s_mov_b64 s[4:5], 0x5580000
	v_and_b32_e32 v137, 0xfffff800, v136
	v_lshl_add_u64 v[132:133], v[132:133], 0, s[4:5]
	v_cmp_eq_u32_e32 vcc, s56, v138
	s_nop 1
	v_cndmask_b32_e32 v132, 0, v132, vcc
	v_cndmask_b32_e32 v133, 0, v133, vcc
	v_cmp_eq_u32_e32 vcc, s53, v137
	s_nop 1
	v_cndmask_b32_e32 v133, v133, v135, vcc
	v_cndmask_b32_e32 v132, v132, v134, vcc
	v_cmp_ne_u64_e64 s[4:5], 0, v[132:133]
	v_lshl_add_u64 v[132:133], s[20:21], 2, v[132:133]
	s_and_saveexec_b64 s[6:7], s[4:5]
	s_cbranch_execz .LBB0_311
	s_movk_i32 s8, 0x8000
	v_lshl_add_u64 v[134:135], v[128:129], 2, v[132:133]
	s_mov_b32 s9, -1
	v_lshl_add_u64 v[136:137], v[134:135], 0, s[8:9]
	v_add_co_u32_e32 v134, vcc, 0xffff8000, v134
	s_nop 1
	v_addc_co_u32_e32 v135, vcc, -1, v135, vcc
	global_store_dwordx4 v[134:135], v[12:15], off nt
	global_store_dwordx4 v[136:137], v[8:11], off offset:16 nt
.LBB0_311:
	s_or_b64 exec, exec, s[6:7]
	v_cvt_pk_bf16_f32 v134, v4, v5
	v_cvt_pk_bf16_f32 v135, v6, v7
	v_cvt_pk_bf16_f32 v136, v0, v1
	v_cvt_pk_bf16_f32 v137, v2, v3
	global_store_dwordx4 v[130:131], v[134:137], off offset:256 nt
	s_and_saveexec_b64 s[6:7], s[4:5]
	s_cbranch_execz .LBB0_313
	s_movk_i32 s4, 0x8200
	v_lshl_add_u64 v[128:129], v[128:129], 2, v[132:133]
	s_mov_b32 s5, -1
	v_lshl_add_u64 v[130:131], v[128:129], 0, s[4:5]
	v_add_co_u32_e32 v128, vcc, 0xffff9000, v128
	s_nop 1
	v_addc_co_u32_e32 v129, vcc, -1, v129, vcc
	global_store_dwordx4 v[128:129], v[4:7], off offset:-3584 nt
	global_store_dwordx4 v[130:131], v[0:3], off offset:16 nt

.LBB0_321:
	v_mov_b64_e32 v[174:175], s[0:1]
	v_lshl_add_u32 v170, v185, 3, s59
	v_lshlrev_b32_e32 v145, 8, v185
	v_mad_i64_i32 v[174:175], s[8:9], v172, s28, v[174:175]
	s_lshl_b32 s20, s82, 9
	v_ashrrev_i32_e32 v171, 31, v170
	v_lshlrev_b32_e32 v144, 5, v170
	v_and_b32_e32 v145, 0x100, v145
	v_lshl_add_u64 v[174:175], v[174:175], 0, s[20:21]
	v_lshlrev_b32_e32 v156, 6, v184
	v_lshlrev_b32_e32 v173, 1, v189
	v_lshlrev_b32_e32 v176, 4, v184
	v_cmp_gt_i32_e64 s[6:7], s56, v172
	v_and_or_b32 v186, v144, s42, v145
	v_cvt_pk_bf16_f32 v144, v136, v137
	v_cvt_pk_bf16_f32 v145, v138, v139
	v_cvt_pk_bf16_f32 v146, v140, v141
	v_cvt_pk_bf16_f32 v147, v142, v143
	v_lshl_add_u64 v[174:175], v[170:171], 1, v[174:175]
	v_lshlrev_b32_e32 v191, 7, v172
	v_and_b32_e32 v188, 0xc0, v156
	v_lshrrev_b32_e32 v177, 7, v172
	v_and_b32_e32 v190, 0xf8, v173
	v_and_b32_e32 v187, 0xf0, v176
	v_lshrrev_b32_e32 v173, 9, v172
	v_lshrrev_b32_e32 v176, 1, v172
	global_store_dwordx4 v[174:175], v[144:147], off nt
	s_and_saveexec_b64 s[8:9], s[6:7]
	s_cbranch_execz .LBB0_323
	s_lshl_b32 s10, s82, 21
	s_add_i32 s10, s10, 0xfc800000
	v_lshlrev_b32_e32 v156, 3, v184
	v_add_u32_e32 v194, s10, v186
	v_and_b32_e32 v156, 0xf8, v156
	s_movk_i32 s10, 0xf000
	v_and_or_b32 v156, v191, s10, v156
	v_add_u32_e32 v156, v156, v194
	v_lshl_add_u64 v[192:193], v[156:157], 1, s[88:89]
	v_add_u32_e32 v156, v177, v188
	v_lshl_or_b32 v156, v156, 12, v190
	s_mov_b32 s10, 0x800000
	v_add3_u32 v156, v156, v194, s10
	global_store_dwordx4 v[192:193], v[144:147], off nt
	v_lshl_add_u64 v[192:193], v[156:157], 1, s[88:89]
	global_store_dwordx4 v[192:193], v[144:147], off nt
	v_add_u32_e32 v156, v173, v187
	v_and_b32_e32 v192, 0xf8, v176
	v_lshl_or_b32 v156, v156, 12, v192
	s_mov_b32 s10, 0x1000000
	v_add3_u32 v156, v156, v194, s10
	v_lshl_add_u64 v[192:193], v[156:157], 1, s[88:89]
	global_store_dwordx4 v[192:193], v[144:147], off nt
.LBB0_323:
	s_or_b64 exec, exec, s[8:9]
	v_readlane_b32 s8, v252, 0
	v_lshlrev_b32_e32 v156, 10, v172
	v_readlane_b32 s9, v252, 1
	v_readlane_b32 s10, v252, 2
	v_readlane_b32 s11, v252, 3
	s_mov_b64 s[8:9], 0x2a00000
	v_and_b32_e32 v193, 0xffffff80, v172
	v_lshl_add_u64 v[144:145], v[156:157], 2, s[10:11]
	v_lshl_add_u64 v[146:147], v[144:145], 0, s[8:9]
	s_mov_b64 s[8:9], 0x5500000
	v_and_b32_e32 v192, 0xfffff800, v172
	v_lshl_add_u64 v[144:145], v[144:145], 0, s[8:9]
	v_cmp_eq_u32_e32 vcc, s56, v193
	s_lshl_b32 s20, s82, 8
	s_nop 0
	v_cndmask_b32_e32 v144, 0, v144, vcc
	v_cndmask_b32_e32 v145, 0, v145, vcc
	v_cmp_eq_u32_e32 vcc, s53, v192
	s_nop 1
	v_cndmask_b32_e32 v145, v145, v147, vcc
	v_cndmask_b32_e32 v144, v144, v146, vcc
	v_cmp_ne_u64_e64 s[8:9], 0, v[144:145]
	v_lshl_add_u64 v[144:145], s[20:21], 2, v[144:145]
	s_and_saveexec_b64 s[10:11], s[8:9]
	s_cbranch_execz .LBB0_328
	s_movk_i32 s34, 0x9000
	v_readlane_b32 s36, v252, 44
	s_mov_b32 s35, -1
	v_readlane_b32 s37, v252, 45
	v_lshl_add_u64 v[146:147], v[144:145], 0, s[34:35]
	s_mov_b64 s[34:35], -1
	s_and_b64 vcc, exec, s[36:37]
	s_cbranch_vccz .LBB0_326
	v_lshl_add_u64 v[192:193], v[170:171], 2, v[146:147]
	global_store_dwordx4 v[192:193], v[136:139], off nt
	global_store_dwordx4 v[192:193], v[140:143], off offset:16 nt
	s_mov_b64 s[34:35], 0
.LBB0_326:
	s_andn2_b64 vcc, exec, s[34:35]
	s_cbranch_vccnz .LBB0_328
	v_lshlrev_b64 v[196:197], 2, v[168:169]
	v_lshl_add_u64 v[146:147], v[146:147], 0, v[196:197]
	v_mov_b32_e32 v192, v136
	v_mov_b32_e32 v193, v138
	v_mov_b32_e32 v194, v140
	v_mov_b32_e32 v195, v142
	global_store_dwordx4 v[146:147], v[192:195], off nt
	v_lshl_add_u64 v[146:147], v[144:145], 0, v[196:197]
	v_add_co_u32_e32 v140, vcc, 0xffffa000, v146
	v_mov_b32_e32 v136, v137
	v_mov_b32_e32 v137, v139
	v_mov_b32_e32 v138, v141
	v_mov_b32_e32 v139, v143
	v_addc_co_u32_e32 v141, vcc, -1, v147, vcc
	global_store_dwordx4 v[140:141], v[136:139], off offset:-4032 nt

.LBB0_330:
	s_waitcnt vmcnt(0)
	v_cvt_pk_bf16_f32 v128, v136, v137
	v_cvt_pk_bf16_f32 v129, v138, v139
	v_cvt_pk_bf16_f32 v130, v140, v141
	v_cvt_pk_bf16_f32 v131, v142, v143
	global_store_dwordx4 v[174:175], v[128:131], off offset:256 nt
	s_and_saveexec_b64 s[10:11], s[6:7]
	s_cbranch_execz .LBB0_332
	s_lshl_b32 s6, s82, 21
	s_add_i32 s6, s6, 0xfc900000
	v_lshlrev_b32_e32 v132, 3, v184
	v_add_u32_e32 v134, s6, v186
	v_and_b32_e32 v132, 0xf8, v132
	s_movk_i32 s6, 0xf000
	v_and_or_b32 v132, v191, s6, v132
	v_add_u32_e32 v156, v132, v134
	v_lshl_add_u64 v[132:133], v[156:157], 1, s[88:89]
	global_store_dwordx4 v[132:133], v[128:131], off nt
	v_add_u32_e32 v132, v177, v188
	v_lshl_or_b32 v132, v132, 12, v190
	s_mov_b32 s6, 0x800000
	v_add3_u32 v156, v132, v134, s6
	v_lshl_add_u64 v[132:133], v[156:157], 1, s[88:89]
	global_store_dwordx4 v[132:133], v[128:131], off nt
	v_add_u32_e32 v132, v173, v187
	v_and_b32_e32 v133, 0xf8, v176
	v_lshl_or_b32 v132, v132, 12, v133
	s_mov_b32 s6, 0x1000000
	v_add3_u32 v156, v132, v134, s6
	v_lshl_add_u64 v[132:133], v[156:157], 1, s[88:89]
	global_store_dwordx4 v[132:133], v[128:131], off nt
.LBB0_332:
	s_or_b64 exec, exec, s[10:11]
	v_readlane_b32 s6, v252, 44
	v_readlane_b32 s7, v252, 45
	s_nop 1
	v_cndmask_b32_e64 v128, 0, 1, s[6:7]
	v_cmp_ne_u32_e64 s[6:7], 1, v128
	s_and_saveexec_b64 s[10:11], s[8:9]
	s_cbranch_execz .LBB0_337
	s_movk_i32 s8, 0x9200
	s_mov_b32 s9, -1
	v_lshl_add_u64 v[128:129], v[144:145], 0, s[8:9]
	s_and_b64 vcc, exec, s[6:7]
	s_mov_b64 s[8:9], -1
	s_cbranch_vccnz .LBB0_335
	v_lshl_add_u64 v[130:131], v[170:171], 2, v[128:129]
	s_mov_b64 s[8:9], 0
	global_store_dwordx4 v[130:131], v[136:139], off nt
	global_store_dwordx4 v[130:131], v[140:143], off offset:16 nt
.LBB0_335:
	s_andn2_b64 vcc, exec, s[8:9]
	s_cbranch_vccnz .LBB0_337
	v_lshlrev_b64 v[132:133], 2, v[168:169]
	v_lshl_add_u64 v[134:135], v[128:129], 0, v[132:133]
	v_lshl_add_u64 v[132:133], v[144:145], 0, v[132:133]
	v_mov_b32_e32 v128, v136
	v_mov_b32_e32 v129, v138
	v_mov_b32_e32 v130, v140
	v_mov_b32_e32 v131, v142
	v_add_co_u32_e32 v132, vcc, 0xffffa000, v132
	global_store_dwordx4 v[134:135], v[128:131], off nt
	s_nop 0
	v_addc_co_u32_e32 v133, vcc, -1, v133, vcc
	v_mov_b32_e32 v128, v137
	v_mov_b32_e32 v129, v139
	v_mov_b32_e32 v130, v141
	v_mov_b32_e32 v131, v143
	global_store_dwordx4 v[132:133], v[128:131], off offset:-3520 nt

.LBB0_342:
	v_mov_b64_e32 v[174:175], s[0:1]
	v_mad_i64_i32 v[174:175], s[10:11], v176, s28, v[174:175]
	s_lshl_b32 s34, s20, 1
	s_mov_b32 s35, s21
	v_lshl_add_u64 v[174:175], v[174:175], 0, s[34:35]
	v_lshlrev_b32_e32 v173, 3, v156
	v_lshlrev_b32_e32 v156, 1, v156
	v_cmp_gt_i32_e64 s[8:9], s56, v176
	v_cvt_pk_bf16_f32 v144, v136, v137
	v_cvt_pk_bf16_f32 v145, v138, v139
	v_cvt_pk_bf16_f32 v146, v140, v141
	v_cvt_pk_bf16_f32 v147, v142, v143
	v_lshl_add_u64 v[174:175], v[170:171], 1, v[174:175]
	v_lshlrev_b32_e32 v193, 7, v176
	v_and_b32_e32 v194, 0xf8, v173
	v_lshrrev_b32_e32 v191, 7, v176
	v_and_b32_e32 v192, 0xf8, v156
	v_lshrrev_b32_e32 v173, 9, v176
	v_lshrrev_b32_e32 v177, 1, v176
	global_store_dwordx4 v[174:175], v[144:147], off nt
	s_and_saveexec_b64 s[10:11], s[8:9]
	s_cbranch_execz .LBB0_344
	s_lshl_b32 s35, s82, 21
	s_add_i32 s35, s35, 0xfc800000
	v_add_u32_e32 v195, s35, v186
	s_movk_i32 s35, 0xf000
	v_and_or_b32 v156, v193, s35, v194
	v_add_u32_e32 v156, v156, v195
	v_lshl_add_u64 v[196:197], v[156:157], 1, s[88:89]
	v_add_u32_e32 v156, v191, v188
	v_lshl_or_b32 v156, v156, 12, v192
	s_mov_b32 s35, 0x800000
	v_add3_u32 v156, v156, v195, s35
	global_store_dwordx4 v[196:197], v[144:147], off nt
	v_lshl_add_u64 v[196:197], v[156:157], 1, s[88:89]
	global_store_dwordx4 v[196:197], v[144:147], off nt
	v_add_u32_e32 v156, v173, v187
	v_and_b32_e32 v196, 0xf8, v177
	v_lshl_or_b32 v156, v156, 12, v196
	s_mov_b32 s35, 0x1000000
	v_add3_u32 v156, v156, v195, s35
	v_lshl_add_u64 v[196:197], v[156:157], 1, s[88:89]
	global_store_dwordx4 v[196:197], v[144:147], off nt
.LBB0_344:
	s_or_b64 exec, exec, s[10:11]
	v_readlane_b32 s84, v252, 0
	v_lshlrev_b32_e32 v156, 10, v176
	v_readlane_b32 s86, v252, 2
	v_readlane_b32 s87, v252, 3
	s_mov_b64 s[10:11], 0x2a00000
	v_and_b32_e32 v196, 0xffffff80, v176
	v_lshl_add_u64 v[144:145], v[156:157], 2, s[86:87]
	v_lshl_add_u64 v[146:147], v[144:145], 0, s[10:11]
	s_mov_b64 s[10:11], 0x5500000
	v_and_b32_e32 v195, 0xfffff800, v176
	v_lshl_add_u64 v[144:145], v[144:145], 0, s[10:11]
	v_cmp_eq_u32_e32 vcc, s56, v196
	v_readlane_b32 s85, v252, 1
	s_nop 0
	v_cndmask_b32_e32 v144, 0, v144, vcc
	v_cndmask_b32_e32 v145, 0, v145, vcc
	v_cmp_eq_u32_e32 vcc, s53, v195
	s_nop 1
	v_cndmask_b32_e32 v145, v145, v147, vcc
	v_cndmask_b32_e32 v144, v144, v146, vcc
	v_cmp_ne_u64_e64 s[10:11], 0, v[144:145]
	v_lshl_add_u64 v[144:145], s[20:21], 2, v[144:145]
	s_and_saveexec_b64 s[36:37], s[10:11]
	s_cbranch_execz .LBB0_349
	s_movk_i32 s78, 0x9000
	s_mov_b32 s79, -1
	v_lshl_add_u64 v[146:147], v[144:145], 0, s[78:79]
	s_and_b64 vcc, exec, s[6:7]
	s_mov_b64 s[78:79], -1
	s_cbranch_vccnz .LBB0_347
	v_lshl_add_u64 v[196:197], v[170:171], 2, v[146:147]
	s_mov_b64 s[78:79], 0
	global_store_dwordx4 v[196:197], v[136:139], off nt
	global_store_dwordx4 v[196:197], v[140:143], off offset:16 nt
.LBB0_347:
	s_andn2_b64 vcc, exec, s[78:79]
	s_cbranch_vccnz .LBB0_349
	v_lshlrev_b64 v[200:201], 2, v[168:169]
	v_lshl_add_u64 v[146:147], v[146:147], 0, v[200:201]
	v_mov_b32_e32 v196, v136
	v_mov_b32_e32 v197, v138
	v_mov_b32_e32 v198, v140
	v_mov_b32_e32 v199, v142
	global_store_dwordx4 v[146:147], v[196:199], off nt
	v_lshl_add_u64 v[146:147], v[144:145], 0, v[200:201]
	v_add_co_u32_e32 v140, vcc, 0xffffa000, v146
	v_mov_b32_e32 v136, v137
	v_mov_b32_e32 v137, v139
	v_mov_b32_e32 v138, v141
	v_mov_b32_e32 v139, v143
	v_addc_co_u32_e32 v141, vcc, -1, v147, vcc
	global_store_dwordx4 v[140:141], v[136:139], off offset:-4032 nt

.LBB0_351:
	s_waitcnt vmcnt(0)
	v_cvt_pk_bf16_f32 v128, v136, v137
	v_cvt_pk_bf16_f32 v129, v138, v139
	v_cvt_pk_bf16_f32 v130, v140, v141
	v_cvt_pk_bf16_f32 v131, v142, v143
	global_store_dwordx4 v[174:175], v[128:131], off offset:256 nt
	s_and_saveexec_b64 s[36:37], s[8:9]
	s_cbranch_execz .LBB0_353
	s_lshl_b32 s8, s82, 21
	s_add_i32 s8, s8, 0xfc900000
	v_add_u32_e32 v134, s8, v186
	s_movk_i32 s8, 0xf000
	v_and_or_b32 v132, v193, s8, v194
	v_add_u32_e32 v156, v132, v134
	v_lshl_add_u64 v[132:133], v[156:157], 1, s[88:89]
	global_store_dwordx4 v[132:133], v[128:131], off nt
	v_add_u32_e32 v132, v191, v188
	v_lshl_or_b32 v132, v132, 12, v192
	s_mov_b32 s8, 0x800000
	v_add3_u32 v156, v132, v134, s8
	v_lshl_add_u64 v[132:133], v[156:157], 1, s[88:89]
	global_store_dwordx4 v[132:133], v[128:131], off nt
	v_add_u32_e32 v132, v173, v187
	v_and_b32_e32 v133, 0xf8, v177
	v_lshl_or_b32 v132, v132, 12, v133
	s_mov_b32 s8, 0x1000000
	v_add3_u32 v156, v132, v134, s8
	v_lshl_add_u64 v[132:133], v[156:157], 1, s[88:89]
	global_store_dwordx4 v[132:133], v[128:131], off nt
.LBB0_353:
	s_or_b64 exec, exec, s[36:37]
	s_and_saveexec_b64 s[8:9], s[10:11]
	s_cbranch_execz .LBB0_358
	s_movk_i32 s10, 0x9200
	s_mov_b32 s11, -1
	v_lshl_add_u64 v[128:129], v[144:145], 0, s[10:11]
	s_and_b64 vcc, exec, s[6:7]
	s_mov_b64 s[10:11], -1
	s_cbranch_vccnz .LBB0_356
	v_lshl_add_u64 v[130:131], v[170:171], 2, v[128:129]
	s_mov_b64 s[10:11], 0
	global_store_dwordx4 v[130:131], v[136:139], off nt
	global_store_dwordx4 v[130:131], v[140:143], off offset:16 nt
.LBB0_356:
	s_andn2_b64 vcc, exec, s[10:11]
	s_cbranch_vccnz .LBB0_358
	v_lshlrev_b64 v[132:133], 2, v[168:169]
	v_lshl_add_u64 v[134:135], v[128:129], 0, v[132:133]
	v_lshl_add_u64 v[132:133], v[144:145], 0, v[132:133]
	v_mov_b32_e32 v128, v136
	v_mov_b32_e32 v129, v138
	v_mov_b32_e32 v130, v140
	v_mov_b32_e32 v131, v142
	v_add_co_u32_e32 v132, vcc, 0xffffa000, v132
	global_store_dwordx4 v[134:135], v[128:131], off nt
	s_nop 0
	v_addc_co_u32_e32 v133, vcc, -1, v133, vcc
	v_mov_b32_e32 v128, v137
	v_mov_b32_e32 v129, v139
	v_mov_b32_e32 v130, v141
	v_mov_b32_e32 v131, v143
	global_store_dwordx4 v[132:133], v[128:131], off offset:-3520 nt

.LBB0_363:
	v_mov_b64_e32 v[174:175], s[0:1]
	v_mad_i64_i32 v[174:175], s[10:11], v176, s28, v[174:175]
	s_mov_b32 s35, s21
	v_lshl_add_u64 v[174:175], v[174:175], 0, s[34:35]
	v_lshlrev_b32_e32 v156, 1, v156
	v_cmp_gt_i32_e64 s[8:9], s56, v176
	v_cvt_pk_bf16_f32 v144, v136, v137
	v_cvt_pk_bf16_f32 v145, v138, v139
	v_cvt_pk_bf16_f32 v146, v140, v141
	v_cvt_pk_bf16_f32 v147, v142, v143
	v_lshl_add_u64 v[174:175], v[170:171], 1, v[174:175]
	v_lshlrev_b32_e32 v193, 7, v176
	v_lshrrev_b32_e32 v191, 7, v176
	v_and_b32_e32 v192, 0xf8, v156
	v_lshrrev_b32_e32 v173, 9, v176
	v_lshrrev_b32_e32 v177, 1, v176
	global_store_dwordx4 v[174:175], v[144:147], off nt
	s_and_saveexec_b64 s[10:11], s[8:9]
	s_cbranch_execz .LBB0_365
	s_lshl_b32 s35, s82, 21
	s_add_i32 s35, s35, 0xfc800000
	v_lshlrev_b32_e32 v156, 3, v184
	v_add_u32_e32 v196, s35, v186
	v_and_b32_e32 v156, 0xf8, v156
	s_movk_i32 s35, 0xf000
	v_and_or_b32 v156, v193, s35, v156
	v_add_u32_e32 v156, v156, v196
	v_lshl_add_u64 v[194:195], v[156:157], 1, s[88:89]
	v_add_u32_e32 v156, v191, v188
	v_lshl_or_b32 v156, v156, 12, v192
	s_mov_b32 s35, 0x800000
	v_add3_u32 v156, v156, v196, s35
	global_store_dwordx4 v[194:195], v[144:147], off nt
	v_lshl_add_u64 v[194:195], v[156:157], 1, s[88:89]
	global_store_dwordx4 v[194:195], v[144:147], off nt
	v_add_u32_e32 v156, v173, v187
	v_and_b32_e32 v194, 0xf8, v177
	v_lshl_or_b32 v156, v156, 12, v194
	s_mov_b32 s35, 0x1000000
	v_add3_u32 v156, v156, v196, s35
	v_lshl_add_u64 v[194:195], v[156:157], 1, s[88:89]
	global_store_dwordx4 v[194:195], v[144:147], off nt
.LBB0_365:
	s_or_b64 exec, exec, s[10:11]
	v_readlane_b32 s84, v252, 0
	v_lshlrev_b32_e32 v156, 10, v176
	v_readlane_b32 s86, v252, 2
	v_readlane_b32 s87, v252, 3
	s_mov_b64 s[10:11], 0x2a00000
	v_and_b32_e32 v195, 0xffffff80, v176
	v_lshl_add_u64 v[144:145], v[156:157], 2, s[86:87]
	v_lshl_add_u64 v[146:147], v[144:145], 0, s[10:11]
	s_mov_b64 s[10:11], 0x5500000
	v_and_b32_e32 v194, 0xfffff800, v176
	v_lshl_add_u64 v[144:145], v[144:145], 0, s[10:11]
	v_cmp_eq_u32_e32 vcc, s56, v195
	v_readlane_b32 s85, v252, 1
	s_nop 0
	v_cndmask_b32_e32 v144, 0, v144, vcc
	v_cndmask_b32_e32 v145, 0, v145, vcc
	v_cmp_eq_u32_e32 vcc, s53, v194
	s_nop 1
	v_cndmask_b32_e32 v145, v145, v147, vcc
	v_cndmask_b32_e32 v144, v144, v146, vcc
	v_cmp_ne_u64_e64 s[10:11], 0, v[144:145]
	v_lshl_add_u64 v[144:145], s[20:21], 2, v[144:145]
	s_and_saveexec_b64 s[36:37], s[10:11]
	s_cbranch_execz .LBB0_370
	s_movk_i32 s78, 0x9000
	s_mov_b32 s79, -1
	v_lshl_add_u64 v[146:147], v[144:145], 0, s[78:79]
	s_and_b64 vcc, exec, s[6:7]
	s_mov_b64 s[78:79], -1
	s_cbranch_vccnz .LBB0_368
	v_lshl_add_u64 v[194:195], v[170:171], 2, v[146:147]
	s_mov_b64 s[78:79], 0
	global_store_dwordx4 v[194:195], v[136:139], off nt
	global_store_dwordx4 v[194:195], v[140:143], off offset:16 nt
.LBB0_368:
	s_andn2_b64 vcc, exec, s[78:79]
	s_cbranch_vccnz .LBB0_370
	v_lshlrev_b64 v[198:199], 2, v[168:169]
	v_lshl_add_u64 v[146:147], v[146:147], 0, v[198:199]
	v_mov_b32_e32 v194, v136
	v_mov_b32_e32 v195, v138
	v_mov_b32_e32 v196, v140
	v_mov_b32_e32 v197, v142
	global_store_dwordx4 v[146:147], v[194:197], off nt
	v_lshl_add_u64 v[146:147], v[144:145], 0, v[198:199]
	v_add_co_u32_e32 v140, vcc, 0xffffa000, v146
	v_mov_b32_e32 v136, v137
	v_mov_b32_e32 v137, v139
	v_mov_b32_e32 v138, v141
	v_mov_b32_e32 v139, v143
	v_addc_co_u32_e32 v141, vcc, -1, v147, vcc
	global_store_dwordx4 v[140:141], v[136:139], off offset:-4032 nt

.LBB0_372:
	s_waitcnt vmcnt(0)
	v_cvt_pk_bf16_f32 v128, v136, v137
	v_cvt_pk_bf16_f32 v129, v138, v139
	v_cvt_pk_bf16_f32 v130, v140, v141
	v_cvt_pk_bf16_f32 v131, v142, v143
	global_store_dwordx4 v[174:175], v[128:131], off offset:256 nt
	s_and_saveexec_b64 s[36:37], s[8:9]
	s_cbranch_execz .LBB0_374
	s_lshl_b32 s8, s82, 21
	s_add_i32 s8, s8, 0xfc900000
	v_lshlrev_b32_e32 v132, 3, v184
	v_add_u32_e32 v134, s8, v186
	v_and_b32_e32 v132, 0xf8, v132
	s_movk_i32 s8, 0xf000
	v_and_or_b32 v132, v193, s8, v132
	v_add_u32_e32 v156, v132, v134
	v_lshl_add_u64 v[132:133], v[156:157], 1, s[88:89]
	global_store_dwordx4 v[132:133], v[128:131], off nt
	v_add_u32_e32 v132, v191, v188
	v_lshl_or_b32 v132, v132, 12, v192
	s_mov_b32 s8, 0x800000
	v_add3_u32 v156, v132, v134, s8
	v_lshl_add_u64 v[132:133], v[156:157], 1, s[88:89]
	global_store_dwordx4 v[132:133], v[128:131], off nt
	v_add_u32_e32 v132, v173, v187
	v_and_b32_e32 v133, 0xf8, v177
	v_lshl_or_b32 v132, v132, 12, v133
	s_mov_b32 s8, 0x1000000
	v_add3_u32 v156, v132, v134, s8
	v_lshl_add_u64 v[132:133], v[156:157], 1, s[88:89]
	global_store_dwordx4 v[132:133], v[128:131], off nt

.LBB0_384:
	v_mov_b64_e32 v[174:175], s[0:1]
	v_mad_i64_i32 v[174:175], s[10:11], v176, s28, v[174:175]
	s_mov_b32 s35, s21
	v_lshl_add_u64 v[174:175], v[174:175], 0, s[34:35]
	v_lshlrev_b32_e32 v173, 3, v156
	v_lshlrev_b32_e32 v156, 1, v156
	v_cmp_gt_i32_e64 s[8:9], s56, v176
	v_cvt_pk_bf16_f32 v144, v136, v137
	v_cvt_pk_bf16_f32 v145, v138, v139
	v_cvt_pk_bf16_f32 v146, v140, v141
	v_cvt_pk_bf16_f32 v147, v142, v143
	v_lshl_add_u64 v[174:175], v[170:171], 1, v[174:175]
	v_lshlrev_b32_e32 v193, 7, v176
	v_and_b32_e32 v194, 0xf8, v173
	v_lshrrev_b32_e32 v191, 7, v176
	v_and_b32_e32 v192, 0xf8, v156
	v_lshrrev_b32_e32 v173, 9, v176
	v_lshrrev_b32_e32 v177, 1, v176
	global_store_dwordx4 v[174:175], v[144:147], off nt
	s_and_saveexec_b64 s[10:11], s[8:9]
	s_cbranch_execz .LBB0_386
	s_lshl_b32 s35, s82, 21
	s_add_i32 s35, s35, 0xfc800000
	v_add_u32_e32 v195, s35, v186
	s_movk_i32 s35, 0xf000
	v_and_or_b32 v156, v193, s35, v194
	v_add_u32_e32 v156, v156, v195
	v_lshl_add_u64 v[196:197], v[156:157], 1, s[88:89]
	v_add_u32_e32 v156, v191, v188
	v_lshl_or_b32 v156, v156, 12, v192
	s_mov_b32 s35, 0x800000
	v_add3_u32 v156, v156, v195, s35
	global_store_dwordx4 v[196:197], v[144:147], off nt
	v_lshl_add_u64 v[196:197], v[156:157], 1, s[88:89]
	global_store_dwordx4 v[196:197], v[144:147], off nt
	v_add_u32_e32 v156, v173, v187
	v_and_b32_e32 v196, 0xf8, v177
	v_lshl_or_b32 v156, v156, 12, v196
	s_mov_b32 s35, 0x1000000
	v_add3_u32 v156, v156, v195, s35
	v_lshl_add_u64 v[196:197], v[156:157], 1, s[88:89]
	global_store_dwordx4 v[196:197], v[144:147], off nt

.LBB0_405:
	v_mov_b64_e32 v[172:173], s[0:1]
	v_mad_i64_i32 v[172:173], s[10:11], v174, s28, v[172:173]
	s_mov_b32 s35, s21
	v_lshl_add_u64 v[172:173], v[172:173], 0, s[34:35]
	v_cmp_gt_i32_e64 s[8:9], s56, v174
	v_cvt_pk_bf16_f32 v144, v136, v137
	v_cvt_pk_bf16_f32 v145, v138, v139
	v_cvt_pk_bf16_f32 v146, v140, v141
	v_cvt_pk_bf16_f32 v147, v142, v143
	v_lshl_add_u64 v[172:173], v[170:171], 1, v[172:173]
	v_lshlrev_b32_e32 v191, 7, v174
	v_lshrrev_b32_e32 v177, 7, v174
	v_lshrrev_b32_e32 v175, 9, v174
	v_lshrrev_b32_e32 v176, 1, v174
	global_store_dwordx4 v[172:173], v[144:147], off nt
	s_and_saveexec_b64 s[10:11], s[8:9]
	s_cbranch_execz .LBB0_407
	s_lshl_b32 s35, s82, 21
	s_add_i32 s35, s35, 0xfc800000
	v_lshlrev_b32_e32 v156, 3, v184
	v_add_u32_e32 v194, s35, v186
	v_and_b32_e32 v156, 0xf8, v156
	s_movk_i32 s35, 0xf000
	v_and_or_b32 v156, v191, s35, v156
	v_add_u32_e32 v156, v156, v194
	v_lshl_add_u64 v[192:193], v[156:157], 1, s[88:89]
	v_add_u32_e32 v156, v177, v188
	v_lshl_or_b32 v156, v156, 12, v190
	s_mov_b32 s35, 0x800000
	v_add3_u32 v156, v156, v194, s35
	global_store_dwordx4 v[192:193], v[144:147], off nt
	v_lshl_add_u64 v[192:193], v[156:157], 1, s[88:89]
	global_store_dwordx4 v[192:193], v[144:147], off nt
	v_add_u32_e32 v156, v175, v187
	v_and_b32_e32 v192, 0xf8, v176
	v_lshl_or_b32 v156, v156, 12, v192
	s_mov_b32 s35, 0x1000000
	v_add3_u32 v156, v156, v194, s35
	v_lshl_add_u64 v[192:193], v[156:157], 1, s[88:89]
	global_store_dwordx4 v[192:193], v[144:147], off nt
.LBB0_407:
	s_or_b64 exec, exec, s[10:11]
	v_readlane_b32 s84, v252, 0
	v_lshlrev_b32_e32 v156, 10, v174
	v_readlane_b32 s86, v252, 2
	v_readlane_b32 s87, v252, 3
	s_mov_b64 s[10:11], 0x2a00000
	v_and_b32_e32 v193, 0xffffff80, v174
	v_lshl_add_u64 v[144:145], v[156:157], 2, s[86:87]
	v_lshl_add_u64 v[146:147], v[144:145], 0, s[10:11]
	s_mov_b64 s[10:11], 0x5500000
	v_and_b32_e32 v192, 0xfffff800, v174
	v_lshl_add_u64 v[144:145], v[144:145], 0, s[10:11]
	v_cmp_eq_u32_e32 vcc, s56, v193
	v_readlane_b32 s85, v252, 1
	s_nop 0
	v_cndmask_b32_e32 v144, 0, v144, vcc
	v_cndmask_b32_e32 v145, 0, v145, vcc
	v_cmp_eq_u32_e32 vcc, s53, v192
	s_nop 1
	v_cndmask_b32_e32 v145, v145, v147, vcc
	v_cndmask_b32_e32 v144, v144, v146, vcc
	v_cmp_ne_u64_e64 s[10:11], 0, v[144:145]
	v_lshl_add_u64 v[144:145], s[20:21], 2, v[144:145]
	s_and_saveexec_b64 s[36:37], s[10:11]
	s_cbranch_execz .LBB0_412
	s_movk_i32 s78, 0x9000
	s_mov_b32 s79, -1
	v_lshl_add_u64 v[146:147], v[144:145], 0, s[78:79]
	s_and_b64 vcc, exec, s[6:7]
	s_mov_b64 s[78:79], -1
	s_cbranch_vccnz .LBB0_410
	v_lshl_add_u64 v[192:193], v[170:171], 2, v[146:147]
	s_mov_b64 s[78:79], 0
	global_store_dwordx4 v[192:193], v[136:139], off nt
	global_store_dwordx4 v[192:193], v[140:143], off offset:16 nt
.LBB0_410:
	s_andn2_b64 vcc, exec, s[78:79]
	s_cbranch_vccnz .LBB0_412
	v_lshlrev_b64 v[196:197], 2, v[168:169]
	v_lshl_add_u64 v[146:147], v[146:147], 0, v[196:197]
	v_mov_b32_e32 v192, v136
	v_mov_b32_e32 v193, v138
	v_mov_b32_e32 v194, v140
	v_mov_b32_e32 v195, v142
	global_store_dwordx4 v[146:147], v[192:195], off nt
	v_lshl_add_u64 v[146:147], v[144:145], 0, v[196:197]
	v_add_co_u32_e32 v140, vcc, 0xffffa000, v146
	v_mov_b32_e32 v136, v137
	v_mov_b32_e32 v137, v139
	v_mov_b32_e32 v138, v141
	v_mov_b32_e32 v139, v143
	v_addc_co_u32_e32 v141, vcc, -1, v147, vcc
	global_store_dwordx4 v[140:141], v[136:139], off offset:-4032 nt

.LBB0_414:
	s_waitcnt vmcnt(0)
	v_cvt_pk_bf16_f32 v128, v136, v137
	v_cvt_pk_bf16_f32 v129, v138, v139
	v_cvt_pk_bf16_f32 v130, v140, v141
	v_cvt_pk_bf16_f32 v131, v142, v143
	global_store_dwordx4 v[172:173], v[128:131], off offset:256 nt
	s_and_saveexec_b64 s[36:37], s[8:9]
	s_cbranch_execz .LBB0_416
	s_lshl_b32 s8, s82, 21
	s_add_i32 s8, s8, 0xfc900000
	v_lshlrev_b32_e32 v132, 3, v184
	v_add_u32_e32 v134, s8, v186
	v_and_b32_e32 v132, 0xf8, v132
	s_movk_i32 s8, 0xf000
	v_and_or_b32 v132, v191, s8, v132
	v_add_u32_e32 v156, v132, v134
	v_lshl_add_u64 v[132:133], v[156:157], 1, s[88:89]
	global_store_dwordx4 v[132:133], v[128:131], off nt
	v_add_u32_e32 v132, v177, v188
	v_lshl_or_b32 v132, v132, 12, v190
	s_mov_b32 s8, 0x800000
	v_add3_u32 v156, v132, v134, s8
	v_lshl_add_u64 v[132:133], v[156:157], 1, s[88:89]
	global_store_dwordx4 v[132:133], v[128:131], off nt
	v_add_u32_e32 v132, v175, v187
	v_and_b32_e32 v133, 0xf8, v176
	v_lshl_or_b32 v132, v132, 12, v133
	s_mov_b32 s8, 0x1000000
	v_add3_u32 v156, v132, v134, s8
	v_lshl_add_u64 v[132:133], v[156:157], 1, s[88:89]
	global_store_dwordx4 v[132:133], v[128:131], off nt

.LBB0_426:
	v_mov_b64_e32 v[172:173], s[0:1]
	v_mad_i64_i32 v[172:173], s[10:11], v174, s28, v[172:173]
	s_mov_b32 s35, s21
	v_lshl_add_u64 v[172:173], v[172:173], 0, s[34:35]
	v_lshlrev_b32_e32 v175, 3, v156
	v_lshlrev_b32_e32 v156, 1, v156
	v_cmp_gt_i32_e64 s[8:9], s56, v174
	v_cvt_pk_bf16_f32 v144, v136, v137
	v_cvt_pk_bf16_f32 v145, v138, v139
	v_cvt_pk_bf16_f32 v146, v140, v141
	v_cvt_pk_bf16_f32 v147, v142, v143
	v_lshl_add_u64 v[172:173], v[170:171], 1, v[172:173]
	v_lshlrev_b32_e32 v191, 7, v174
	v_and_b32_e32 v192, 0xf8, v175
	v_lshrrev_b32_e32 v177, 7, v174
	v_and_b32_e32 v190, 0xf8, v156
	v_lshrrev_b32_e32 v175, 9, v174
	v_lshrrev_b32_e32 v176, 1, v174
	global_store_dwordx4 v[172:173], v[144:147], off nt
	s_and_saveexec_b64 s[10:11], s[8:9]
	s_cbranch_execz .LBB0_428
	s_lshl_b32 s35, s82, 21
	s_add_i32 s35, s35, 0xfc800000
	v_add_u32_e32 v193, s35, v186
	s_movk_i32 s35, 0xf000
	v_and_or_b32 v156, v191, s35, v192
	v_add_u32_e32 v156, v156, v193
	v_lshl_add_u64 v[194:195], v[156:157], 1, s[88:89]
	v_add_u32_e32 v156, v177, v188
	v_lshl_or_b32 v156, v156, 12, v190
	s_mov_b32 s35, 0x800000
	v_add3_u32 v156, v156, v193, s35
	global_store_dwordx4 v[194:195], v[144:147], off nt
	v_lshl_add_u64 v[194:195], v[156:157], 1, s[88:89]
	global_store_dwordx4 v[194:195], v[144:147], off nt
	v_add_u32_e32 v156, v175, v187
	v_and_b32_e32 v194, 0xf8, v176
	v_lshl_or_b32 v156, v156, 12, v194
	s_mov_b32 s35, 0x1000000
	v_add3_u32 v156, v156, v193, s35
	v_lshl_add_u64 v[194:195], v[156:157], 1, s[88:89]
	global_store_dwordx4 v[194:195], v[144:147], off nt
.LBB0_428:
	s_or_b64 exec, exec, s[10:11]
	v_readlane_b32 s84, v252, 0
	v_lshlrev_b32_e32 v156, 10, v174
	v_readlane_b32 s86, v252, 2
	v_readlane_b32 s87, v252, 3
	s_mov_b64 s[10:11], 0x2a00000
	v_and_b32_e32 v194, 0xffffff80, v174
	v_lshl_add_u64 v[144:145], v[156:157], 2, s[86:87]
	v_lshl_add_u64 v[146:147], v[144:145], 0, s[10:11]
	s_mov_b64 s[10:11], 0x5500000
	v_and_b32_e32 v193, 0xfffff800, v174
	v_lshl_add_u64 v[144:145], v[144:145], 0, s[10:11]
	v_cmp_eq_u32_e32 vcc, s56, v194
	v_readlane_b32 s85, v252, 1
	s_nop 0
	v_cndmask_b32_e32 v144, 0, v144, vcc
	v_cndmask_b32_e32 v145, 0, v145, vcc
	v_cmp_eq_u32_e32 vcc, s53, v193
	s_nop 1
	v_cndmask_b32_e32 v145, v145, v147, vcc
	v_cndmask_b32_e32 v144, v144, v146, vcc
	v_cmp_ne_u64_e64 s[10:11], 0, v[144:145]
	v_lshl_add_u64 v[144:145], s[20:21], 2, v[144:145]
	s_and_saveexec_b64 s[36:37], s[10:11]
	s_cbranch_execz .LBB0_433
	s_movk_i32 s78, 0x9000
	s_mov_b32 s79, -1
	v_lshl_add_u64 v[146:147], v[144:145], 0, s[78:79]
	s_and_b64 vcc, exec, s[6:7]
	s_mov_b64 s[78:79], -1
	s_cbranch_vccnz .LBB0_431
	v_lshl_add_u64 v[194:195], v[170:171], 2, v[146:147]
	s_mov_b64 s[78:79], 0
	global_store_dwordx4 v[194:195], v[136:139], off nt
	global_store_dwordx4 v[194:195], v[140:143], off offset:16 nt

.LBB0_435:
	s_waitcnt vmcnt(0)
	v_cvt_pk_bf16_f32 v128, v136, v137
	v_cvt_pk_bf16_f32 v129, v138, v139
	v_cvt_pk_bf16_f32 v130, v140, v141
	v_cvt_pk_bf16_f32 v131, v142, v143
	global_store_dwordx4 v[172:173], v[128:131], off offset:256 nt
	s_and_saveexec_b64 s[36:37], s[8:9]
	s_cbranch_execz .LBB0_437
	s_lshl_b32 s8, s82, 21
	s_add_i32 s8, s8, 0xfc900000
	v_add_u32_e32 v134, s8, v186
	s_movk_i32 s8, 0xf000
	v_and_or_b32 v132, v191, s8, v192
	v_add_u32_e32 v156, v132, v134
	v_lshl_add_u64 v[132:133], v[156:157], 1, s[88:89]
	global_store_dwordx4 v[132:133], v[128:131], off nt
	v_add_u32_e32 v132, v177, v188
	v_lshl_or_b32 v132, v132, 12, v190
	s_mov_b32 s8, 0x800000
	v_add3_u32 v156, v132, v134, s8
	v_lshl_add_u64 v[132:133], v[156:157], 1, s[88:89]
	global_store_dwordx4 v[132:133], v[128:131], off nt
	v_add_u32_e32 v132, v175, v187
	v_and_b32_e32 v133, 0xf8, v176
	v_lshl_or_b32 v132, v132, 12, v133
	s_mov_b32 s8, 0x1000000
	v_add3_u32 v156, v132, v134, s8
	v_lshl_add_u64 v[132:133], v[156:157], 1, s[88:89]
	global_store_dwordx4 v[132:133], v[128:131], off nt

.LBB0_447:
	v_mov_b64_e32 v[172:173], s[0:1]
	v_mad_i64_i32 v[172:173], s[10:11], v174, s28, v[172:173]
	s_mov_b32 s35, s21
	v_lshl_add_u64 v[172:173], v[172:173], 0, s[34:35]
	v_lshlrev_b32_e32 v156, 1, v156
	v_cmp_gt_i32_e64 s[8:9], s56, v174
	v_cvt_pk_bf16_f32 v144, v136, v137
	v_cvt_pk_bf16_f32 v145, v138, v139
	v_cvt_pk_bf16_f32 v146, v140, v141
	v_cvt_pk_bf16_f32 v147, v142, v143
	v_lshl_add_u64 v[172:173], v[170:171], 1, v[172:173]
	v_lshlrev_b32_e32 v191, 7, v174
	v_lshrrev_b32_e32 v177, 7, v174
	v_and_b32_e32 v190, 0xf8, v156
	v_lshrrev_b32_e32 v175, 9, v174
	v_lshrrev_b32_e32 v176, 1, v174
	global_store_dwordx4 v[172:173], v[144:147], off nt
	s_and_saveexec_b64 s[10:11], s[8:9]
	s_cbranch_execz .LBB0_449
	s_lshl_b32 s35, s82, 21
	s_add_i32 s35, s35, 0xfc800000
	v_lshlrev_b32_e32 v156, 3, v184
	v_add_u32_e32 v194, s35, v186
	v_and_b32_e32 v156, 0xf8, v156
	s_movk_i32 s35, 0xf000
	v_and_or_b32 v156, v191, s35, v156
	v_add_u32_e32 v156, v156, v194
	v_lshl_add_u64 v[192:193], v[156:157], 1, s[88:89]
	v_add_u32_e32 v156, v177, v188
	v_lshl_or_b32 v156, v156, 12, v190
	s_mov_b32 s35, 0x800000
	v_add3_u32 v156, v156, v194, s35
	global_store_dwordx4 v[192:193], v[144:147], off nt
	v_lshl_add_u64 v[192:193], v[156:157], 1, s[88:89]
	global_store_dwordx4 v[192:193], v[144:147], off nt
	v_add_u32_e32 v156, v175, v187
	v_and_b32_e32 v192, 0xf8, v176
	v_lshl_or_b32 v156, v156, 12, v192
	s_mov_b32 s35, 0x1000000
	v_add3_u32 v156, v156, v194, s35
	v_lshl_add_u64 v[192:193], v[156:157], 1, s[88:89]
	global_store_dwordx4 v[192:193], v[144:147], off nt

.LBB0_468:
	v_mov_b64_e32 v[172:173], s[0:1]
	v_mad_i64_i32 v[172:173], s[10:11], v174, s28, v[172:173]
	s_mov_b32 s35, s21
	v_lshl_add_u64 v[172:173], v[172:173], 0, s[34:35]
	v_lshlrev_b32_e32 v175, 3, v156
	v_lshlrev_b32_e32 v156, 1, v156
	v_cmp_gt_i32_e64 s[8:9], s56, v174
	v_cvt_pk_bf16_f32 v144, v136, v137
	v_cvt_pk_bf16_f32 v145, v138, v139
	v_cvt_pk_bf16_f32 v146, v140, v141
	v_cvt_pk_bf16_f32 v147, v142, v143
	v_lshl_add_u64 v[172:173], v[170:171], 1, v[172:173]
	v_lshlrev_b32_e32 v190, 7, v174
	v_and_b32_e32 v191, 0xf8, v175
	v_lshrrev_b32_e32 v177, 7, v174
	v_and_b32_e32 v189, 0xf8, v156
	v_lshrrev_b32_e32 v175, 9, v174
	v_lshrrev_b32_e32 v176, 1, v174
	global_store_dwordx4 v[172:173], v[144:147], off nt
	s_and_saveexec_b64 s[10:11], s[8:9]
	s_cbranch_execz .LBB0_470
	s_lshl_b32 s34, s82, 21
	s_add_i32 s34, s34, 0xfc800000
	v_add_u32_e32 v194, s34, v186
	s_movk_i32 s34, 0xf000
	v_and_or_b32 v156, v190, s34, v191
	v_add_u32_e32 v156, v156, v194
	v_lshl_add_u64 v[192:193], v[156:157], 1, s[88:89]
	v_add_u32_e32 v156, v177, v188
	v_lshl_or_b32 v156, v156, 12, v189
	s_mov_b32 s34, 0x800000
	v_add3_u32 v156, v156, v194, s34
	global_store_dwordx4 v[192:193], v[144:147], off nt
	v_lshl_add_u64 v[192:193], v[156:157], 1, s[88:89]
	global_store_dwordx4 v[192:193], v[144:147], off nt
	v_add_u32_e32 v156, v175, v187
	v_and_b32_e32 v192, 0xf8, v176
	v_lshl_or_b32 v156, v156, 12, v192
	s_mov_b32 s34, 0x1000000
	v_add3_u32 v156, v156, v194, s34
	v_lshl_add_u64 v[192:193], v[156:157], 1, s[88:89]
	global_store_dwordx4 v[192:193], v[144:147], off nt
.LBB0_470:
	s_or_b64 exec, exec, s[10:11]
	v_readlane_b32 s84, v252, 0
	v_lshlrev_b32_e32 v156, 10, v174
	v_readlane_b32 s86, v252, 2
	v_readlane_b32 s87, v252, 3
	s_mov_b64 s[10:11], 0x2a00000
	v_and_b32_e32 v193, 0xffffff80, v174
	v_lshl_add_u64 v[144:145], v[156:157], 2, s[86:87]
	v_lshl_add_u64 v[146:147], v[144:145], 0, s[10:11]
	s_mov_b64 s[10:11], 0x5500000
	v_and_b32_e32 v192, 0xfffff800, v174
	v_lshl_add_u64 v[144:145], v[144:145], 0, s[10:11]
	v_cmp_eq_u32_e32 vcc, s56, v193
	v_readlane_b32 s85, v252, 1
	s_nop 0
	v_cndmask_b32_e32 v144, 0, v144, vcc
	v_cndmask_b32_e32 v145, 0, v145, vcc
	v_cmp_eq_u32_e32 vcc, s53, v192
	s_nop 1
	v_cndmask_b32_e32 v145, v145, v147, vcc
	v_cndmask_b32_e32 v144, v144, v146, vcc
	v_cmp_ne_u64_e64 s[10:11], 0, v[144:145]
	v_lshl_add_u64 v[144:145], s[20:21], 2, v[144:145]
	s_and_saveexec_b64 s[34:35], s[10:11]
	s_cbranch_execz .LBB0_475
	s_movk_i32 s36, 0x9000
	s_mov_b32 s37, -1
	v_lshl_add_u64 v[146:147], v[144:145], 0, s[36:37]
	s_and_b64 vcc, exec, s[6:7]
	s_mov_b64 s[36:37], -1
	s_cbranch_vccnz .LBB0_473
	v_lshl_add_u64 v[192:193], v[170:171], 2, v[146:147]
	s_mov_b64 s[36:37], 0
	global_store_dwordx4 v[192:193], v[136:139], off nt
	global_store_dwordx4 v[192:193], v[140:143], off offset:16 nt
.LBB0_473:
	s_andn2_b64 vcc, exec, s[36:37]
	s_cbranch_vccnz .LBB0_475
	v_lshlrev_b64 v[196:197], 2, v[168:169]
	v_lshl_add_u64 v[146:147], v[146:147], 0, v[196:197]
	v_mov_b32_e32 v192, v136
	v_mov_b32_e32 v193, v138
	v_mov_b32_e32 v194, v140
	v_mov_b32_e32 v195, v142
	global_store_dwordx4 v[146:147], v[192:195], off nt
	v_lshl_add_u64 v[146:147], v[144:145], 0, v[196:197]
	v_add_co_u32_e32 v140, vcc, 0xffffa000, v146
	v_mov_b32_e32 v136, v137
	v_mov_b32_e32 v137, v139
	v_mov_b32_e32 v138, v141
	v_mov_b32_e32 v139, v143
	v_addc_co_u32_e32 v141, vcc, -1, v147, vcc
	global_store_dwordx4 v[140:141], v[136:139], off offset:-4032 nt

.LBB0_477:
	s_waitcnt vmcnt(0)
	v_cvt_pk_bf16_f32 v128, v136, v137
	v_cvt_pk_bf16_f32 v129, v138, v139
	v_cvt_pk_bf16_f32 v130, v140, v141
	v_cvt_pk_bf16_f32 v131, v142, v143
	global_store_dwordx4 v[172:173], v[128:131], off offset:256 nt
	s_and_saveexec_b64 s[4:5], s[8:9]
	s_cbranch_execz .LBB0_479
	s_lshl_b32 s8, s82, 21
	s_add_i32 s8, s8, 0xfc900000
	v_add_u32_e32 v134, s8, v186
	s_movk_i32 s8, 0xf000
	v_and_or_b32 v132, v190, s8, v191
	v_add_u32_e32 v156, v132, v134
	v_lshl_add_u64 v[132:133], v[156:157], 1, s[88:89]
	global_store_dwordx4 v[132:133], v[128:131], off nt
	v_add_u32_e32 v132, v177, v188
	v_lshl_or_b32 v132, v132, 12, v189
	s_mov_b32 s8, 0x800000
	v_add3_u32 v156, v132, v134, s8
	v_lshl_add_u64 v[132:133], v[156:157], 1, s[88:89]
	global_store_dwordx4 v[132:133], v[128:131], off nt
	v_add_u32_e32 v132, v175, v187
	v_and_b32_e32 v133, 0xf8, v176
	v_lshl_or_b32 v132, v132, 12, v133
	s_mov_b32 s8, 0x1000000
	v_add3_u32 v156, v132, v134, s8
	v_lshl_add_u64 v[132:133], v[156:157], 1, s[88:89]
	global_store_dwordx4 v[132:133], v[128:131], off nt
.LBB0_479:
	s_or_b64 exec, exec, s[4:5]
	s_and_saveexec_b64 s[4:5], s[10:11]
	s_cbranch_execz .LBB0_484
	s_movk_i32 s8, 0x9200
	s_mov_b32 s9, -1
	v_lshl_add_u64 v[128:129], v[144:145], 0, s[8:9]
	s_and_b64 vcc, exec, s[6:7]
	s_mov_b64 s[6:7], -1
	s_cbranch_vccnz .LBB0_482
	v_lshl_add_u64 v[130:131], v[170:171], 2, v[128:129]
	s_mov_b64 s[6:7], 0
	global_store_dwordx4 v[130:131], v[136:139], off nt
	global_store_dwordx4 v[130:131], v[140:143], off offset:16 nt
.LBB0_482:
	s_andn2_b64 vcc, exec, s[6:7]
	s_cbranch_vccnz .LBB0_484
	v_lshlrev_b64 v[132:133], 2, v[168:169]
	v_lshl_add_u64 v[134:135], v[128:129], 0, v[132:133]
	v_lshl_add_u64 v[132:133], v[144:145], 0, v[132:133]
	v_mov_b32_e32 v128, v136
	v_mov_b32_e32 v129, v138
	v_mov_b32_e32 v130, v140
	v_mov_b32_e32 v131, v142
	v_add_co_u32_e32 v132, vcc, 0xffffa000, v132
	global_store_dwordx4 v[134:135], v[128:131], off nt
	s_nop 0
	v_addc_co_u32_e32 v133, vcc, -1, v133, vcc
	v_mov_b32_e32 v128, v137
	v_mov_b32_e32 v129, v139
	v_mov_b32_e32 v130, v141
	v_mov_b32_e32 v131, v143
	global_store_dwordx4 v[132:133], v[128:131], off offset:-3520 nt

.LBB0_486:
	s_andn2_b64 vcc, exec, s[4:5]
	s_cbranch_vccnz .LBB0_544
	s_cmp_lg_u32 s59, 0
	s_cbranch_scc1 .Lepi4_plain
	s_lshl_b32 s8, s90, 8
	s_add_i32 s8, s8, s57
	v_mul_u32_u24_e32 v168, 0x5800, v184
	v_lshl_add_u32 v168, v185, 4, v168
	s_mul_i32 s20, s8, 0x5800
	s_lshl_b32 s6, s82, 9
	s_add_u32 s20, s20, s6
	s_lshl_b32 s6, s59, 1
	s_add_u32 s20, s20, s6
	s_add_u32 s4, s0, s20
	s_addc_u32 s5, s1, 0
	v_add_u32_e32 v169, s8, v184
	v_lshlrev_b32_e32 v169, 6, v169
	v_lshl_add_u32 v169, v185, 4, v169
	v_add_u32_e32 v170, 0x2000, v169
	global_load_dwordx4 v[190:193], v169, s[16:17]
	global_load_dwordx4 v[226:229], v169, s[18:19]
	global_load_dwordx4 v[194:197], v169, s[16:17] offset:1024
	global_load_dwordx4 v[230:233], v169, s[18:19] offset:1024
	global_load_dwordx4 v[198:201], v169, s[16:17] offset:2048
	global_load_dwordx4 v[234:237], v169, s[18:19] offset:2048
	global_load_dwordx4 v[202:205], v169, s[16:17] offset:3072
	global_load_dwordx4 v[238:241], v169, s[18:19] offset:3072
	global_load_dwordx4 v[210:213], v170, s[16:17]
	global_load_dwordx4 v[242:245], v170, s[18:19]
	global_load_dwordx4 v[214:217], v170, s[16:17] offset:1024
	global_load_dwordx4 v[246:249], v170, s[18:19] offset:1024
	global_load_dwordx4 v[218:221], v170, s[16:17] offset:2048
	global_load_dwordx4 v[140:143], v170, s[18:19] offset:2048
	global_load_dwordx4 v[222:225], v170, s[16:17] offset:3072
	global_load_dwordx4 v[144:147], v170, s[18:19] offset:3072
	s_waitcnt vmcnt(0)
	s_nop 1
	v_mul_f32_e32 v171, v125, v226
	v_fma_f32 v132, v124, v190, -v171
	v_mul_f32_e32 v171, v124, v226
	v_fma_f32 v136, v125, v190, v171
	v_mul_f32_e32 v171, v127, v227
	v_fma_f32 v133, v126, v191, -v171
	v_mul_f32_e32 v171, v126, v227
	v_fma_f32 v137, v127, v191, v171
	v_mul_f32_e32 v171, v121, v228
	v_fma_f32 v134, v120, v192, -v171
	v_mul_f32_e32 v171, v120, v228
	v_fma_f32 v138, v121, v192, v171
	v_mul_f32_e32 v171, v123, v229
	v_fma_f32 v135, v122, v193, -v171
	v_mul_f32_e32 v171, v122, v229
	v_fma_f32 v139, v123, v193, v171
	v_mul_f32_e32 v132, s30, v132
	v_mul_f32_e32 v136, s30, v136
	v_mul_f32_e32 v133, s30, v133
	v_mul_f32_e32 v137, s30, v137
	v_mul_f32_e32 v134, s30, v134
	v_mul_f32_e32 v138, s30, v138
	v_mul_f32_e32 v135, s30, v135
	v_mul_f32_e32 v139, s30, v139
	v_cvt_pk_bf16_f32 v128, v132, v136
	v_cvt_pk_bf16_f32 v129, v133, v137
	v_cvt_pk_bf16_f32 v130, v134, v138
	v_cvt_pk_bf16_f32 v131, v135, v139
	global_store_dwordx4 v168, v[128:131], s[4:5] nt
	s_nop 1
	v_mul_f32_e32 v171, v117, v226
	v_fma_f32 v132, v116, v190, -v171
	v_mul_f32_e32 v171, v116, v226
	v_fma_f32 v136, v117, v190, v171
	v_mul_f32_e32 v171, v119, v227
	v_fma_f32 v133, v118, v191, -v171
	v_mul_f32_e32 v171, v118, v227
	v_fma_f32 v137, v119, v191, v171
	v_mul_f32_e32 v171, v113, v228
	v_fma_f32 v134, v112, v192, -v171
	v_mul_f32_e32 v171, v112, v228
	v_fma_f32 v138, v113, v192, v171
	v_mul_f32_e32 v171, v115, v229
	v_fma_f32 v135, v114, v193, -v171
	v_mul_f32_e32 v171, v114, v229
	v_fma_f32 v139, v115, v193, v171
	v_mul_f32_e32 v132, s30, v132
	v_mul_f32_e32 v136, s30, v136
	v_mul_f32_e32 v133, s30, v133
	v_mul_f32_e32 v137, s30, v137
	v_mul_f32_e32 v134, s30, v134
	v_mul_f32_e32 v138, s30, v138
	v_mul_f32_e32 v135, s30, v135
	v_mul_f32_e32 v139, s30, v139
	v_cvt_pk_bf16_f32 v128, v132, v136
	v_cvt_pk_bf16_f32 v129, v133, v137
	v_cvt_pk_bf16_f32 v130, v134, v138
	v_cvt_pk_bf16_f32 v131, v135, v139
	global_store_dwordx4 v168, v[128:131], s[4:5] offset:256 nt
	s_add_u32 s4, s4, 0x58000
	s_addc_u32 s5, s5, 0
	s_nop 1
	v_mul_f32_e32 v171, v109, v230
	v_fma_f32 v132, v108, v194, -v171
	v_mul_f32_e32 v171, v108, v230
	v_fma_f32 v136, v109, v194, v171
	v_mul_f32_e32 v171, v111, v231
	v_fma_f32 v133, v110, v195, -v171
	v_mul_f32_e32 v171, v110, v231
	v_fma_f32 v137, v111, v195, v171
	v_mul_f32_e32 v171, v105, v232
	v_fma_f32 v134, v104, v196, -v171
	v_mul_f32_e32 v171, v104, v232
	v_fma_f32 v138, v105, v196, v171
	v_mul_f32_e32 v171, v107, v233
	v_fma_f32 v135, v106, v197, -v171
	v_mul_f32_e32 v171, v106, v233
	v_fma_f32 v139, v107, v197, v171
	v_mul_f32_e32 v132, s30, v132
	v_mul_f32_e32 v136, s30, v136
	v_mul_f32_e32 v133, s30, v133
	v_mul_f32_e32 v137, s30, v137
	v_mul_f32_e32 v134, s30, v134
	v_mul_f32_e32 v138, s30, v138
	v_mul_f32_e32 v135, s30, v135
	v_mul_f32_e32 v139, s30, v139
	v_cvt_pk_bf16_f32 v128, v132, v136
	v_cvt_pk_bf16_f32 v129, v133, v137
	v_cvt_pk_bf16_f32 v130, v134, v138
	v_cvt_pk_bf16_f32 v131, v135, v139
	global_store_dwordx4 v168, v[128:131], s[4:5] nt
	s_nop 1
	v_mul_f32_e32 v171, v101, v230
	v_fma_f32 v132, v100, v194, -v171
	v_mul_f32_e32 v171, v100, v230
	v_fma_f32 v136, v101, v194, v171
	v_mul_f32_e32 v171, v103, v231
	v_fma_f32 v133, v102, v195, -v171
	v_mul_f32_e32 v171, v102, v231
	v_fma_f32 v137, v103, v195, v171
	v_mul_f32_e32 v171, v97, v232
	v_fma_f32 v134, v96, v196, -v171
	v_mul_f32_e32 v171, v96, v232
	v_fma_f32 v138, v97, v196, v171
	v_mul_f32_e32 v171, v99, v233
	v_fma_f32 v135, v98, v197, -v171
	v_mul_f32_e32 v171, v98, v233
	v_fma_f32 v139, v99, v197, v171
	v_mul_f32_e32 v132, s30, v132
	v_mul_f32_e32 v136, s30, v136
	v_mul_f32_e32 v133, s30, v133
	v_mul_f32_e32 v137, s30, v137
	v_mul_f32_e32 v134, s30, v134
	v_mul_f32_e32 v138, s30, v138
	v_mul_f32_e32 v135, s30, v135
	v_mul_f32_e32 v139, s30, v139
	v_cvt_pk_bf16_f32 v128, v132, v136
	v_cvt_pk_bf16_f32 v129, v133, v137
	v_cvt_pk_bf16_f32 v130, v134, v138
	v_cvt_pk_bf16_f32 v131, v135, v139
	global_store_dwordx4 v168, v[128:131], s[4:5] offset:256 nt
	s_add_u32 s4, s4, 0x58000
	s_addc_u32 s5, s5, 0
	s_nop 1
	v_mul_f32_e32 v171, v93, v234
	v_fma_f32 v132, v92, v198, -v171
	v_mul_f32_e32 v171, v92, v234
	v_fma_f32 v136, v93, v198, v171
	v_mul_f32_e32 v171, v95, v235
	v_fma_f32 v133, v94, v199, -v171
	v_mul_f32_e32 v171, v94, v235
	v_fma_f32 v137, v95, v199, v171
	v_mul_f32_e32 v171, v89, v236
	v_fma_f32 v134, v88, v200, -v171
	v_mul_f32_e32 v171, v88, v236
	v_fma_f32 v138, v89, v200, v171
	v_mul_f32_e32 v171, v91, v237
	v_fma_f32 v135, v90, v201, -v171
	v_mul_f32_e32 v171, v90, v237
	v_fma_f32 v139, v91, v201, v171
	v_mul_f32_e32 v132, s30, v132
	v_mul_f32_e32 v136, s30, v136
	v_mul_f32_e32 v133, s30, v133
	v_mul_f32_e32 v137, s30, v137
	v_mul_f32_e32 v134, s30, v134
	v_mul_f32_e32 v138, s30, v138
	v_mul_f32_e32 v135, s30, v135
	v_mul_f32_e32 v139, s30, v139
	v_cvt_pk_bf16_f32 v128, v132, v136
	v_cvt_pk_bf16_f32 v129, v133, v137
	v_cvt_pk_bf16_f32 v130, v134, v138
	v_cvt_pk_bf16_f32 v131, v135, v139
	global_store_dwordx4 v168, v[128:131], s[4:5] nt
	s_nop 1
	v_mul_f32_e32 v171, v85, v234
	v_fma_f32 v132, v84, v198, -v171
	v_mul_f32_e32 v171, v84, v234
	v_fma_f32 v136, v85, v198, v171
	v_mul_f32_e32 v171, v87, v235
	v_fma_f32 v133, v86, v199, -v171
	v_mul_f32_e32 v171, v86, v235
	v_fma_f32 v137, v87, v199, v171
	v_mul_f32_e32 v171, v81, v236
	v_fma_f32 v134, v80, v200, -v171
	v_mul_f32_e32 v171, v80, v236
	v_fma_f32 v138, v81, v200, v171
	v_mul_f32_e32 v171, v83, v237
	v_fma_f32 v135, v82, v201, -v171
	v_mul_f32_e32 v171, v82, v237
	v_fma_f32 v139, v83, v201, v171
	v_mul_f32_e32 v132, s30, v132
	v_mul_f32_e32 v136, s30, v136
	v_mul_f32_e32 v133, s30, v133
	v_mul_f32_e32 v137, s30, v137
	v_mul_f32_e32 v134, s30, v134
	v_mul_f32_e32 v138, s30, v138
	v_mul_f32_e32 v135, s30, v135
	v_mul_f32_e32 v139, s30, v139
	v_cvt_pk_bf16_f32 v128, v132, v136
	v_cvt_pk_bf16_f32 v129, v133, v137
	v_cvt_pk_bf16_f32 v130, v134, v138
	v_cvt_pk_bf16_f32 v131, v135, v139
	global_store_dwordx4 v168, v[128:131], s[4:5] offset:256 nt
	s_add_u32 s4, s4, 0x58000
	s_addc_u32 s5, s5, 0
	s_nop 1
	v_mul_f32_e32 v171, v77, v238
	v_fma_f32 v132, v76, v202, -v171
	v_mul_f32_e32 v171, v76, v238
	v_fma_f32 v136, v77, v202, v171
	v_mul_f32_e32 v171, v79, v239
	v_fma_f32 v133, v78, v203, -v171
	v_mul_f32_e32 v171, v78, v239
	v_fma_f32 v137, v79, v203, v171
	v_mul_f32_e32 v171, v73, v240
	v_fma_f32 v134, v72, v204, -v171
	v_mul_f32_e32 v171, v72, v240
	v_fma_f32 v138, v73, v204, v171
	v_mul_f32_e32 v171, v75, v241
	v_fma_f32 v135, v74, v205, -v171
	v_mul_f32_e32 v171, v74, v241
	v_fma_f32 v139, v75, v205, v171
	v_mul_f32_e32 v132, s30, v132
	v_mul_f32_e32 v136, s30, v136
	v_mul_f32_e32 v133, s30, v133
	v_mul_f32_e32 v137, s30, v137
	v_mul_f32_e32 v134, s30, v134
	v_mul_f32_e32 v138, s30, v138
	v_mul_f32_e32 v135, s30, v135
	v_mul_f32_e32 v139, s30, v139
	v_cvt_pk_bf16_f32 v128, v132, v136
	v_cvt_pk_bf16_f32 v129, v133, v137
	v_cvt_pk_bf16_f32 v130, v134, v138
	v_cvt_pk_bf16_f32 v131, v135, v139
	global_store_dwordx4 v168, v[128:131], s[4:5] nt
	s_nop 1
	v_mul_f32_e32 v171, v69, v238
	v_fma_f32 v132, v68, v202, -v171
	v_mul_f32_e32 v171, v68, v238
	v_fma_f32 v136, v69, v202, v171
	v_mul_f32_e32 v171, v71, v239
	v_fma_f32 v133, v70, v203, -v171
	v_mul_f32_e32 v171, v70, v239
	v_fma_f32 v137, v71, v203, v171
	v_mul_f32_e32 v171, v65, v240
	v_fma_f32 v134, v64, v204, -v171
	v_mul_f32_e32 v171, v64, v240
	v_fma_f32 v138, v65, v204, v171
	v_mul_f32_e32 v171, v67, v241
	v_fma_f32 v135, v66, v205, -v171
	v_mul_f32_e32 v171, v66, v241
	v_fma_f32 v139, v67, v205, v171
	v_mul_f32_e32 v132, s30, v132
	v_mul_f32_e32 v136, s30, v136
	v_mul_f32_e32 v133, s30, v133
	v_mul_f32_e32 v137, s30, v137
	v_mul_f32_e32 v134, s30, v134
	v_mul_f32_e32 v138, s30, v138
	v_mul_f32_e32 v135, s30, v135
	v_mul_f32_e32 v139, s30, v139
	v_cvt_pk_bf16_f32 v128, v132, v136
	v_cvt_pk_bf16_f32 v129, v133, v137
	v_cvt_pk_bf16_f32 v130, v134, v138
	v_cvt_pk_bf16_f32 v131, v135, v139
	global_store_dwordx4 v168, v[128:131], s[4:5] offset:256 nt
	s_add_u32 s4, s4, 0x1b8000
	s_addc_u32 s5, s5, 0
	s_nop 1
	v_mul_f32_e32 v171, v61, v242
	v_fma_f32 v132, v60, v210, -v171
	v_mul_f32_e32 v171, v60, v242
	v_fma_f32 v136, v61, v210, v171
	v_mul_f32_e32 v171, v63, v243
	v_fma_f32 v133, v62, v211, -v171
	v_mul_f32_e32 v171, v62, v243
	v_fma_f32 v137, v63, v211, v171
	v_mul_f32_e32 v171, v57, v244
	v_fma_f32 v134, v56, v212, -v171
	v_mul_f32_e32 v171, v56, v244
	v_fma_f32 v138, v57, v212, v171
	v_mul_f32_e32 v171, v59, v245
	v_fma_f32 v135, v58, v213, -v171
	v_mul_f32_e32 v171, v58, v245
	v_fma_f32 v139, v59, v213, v171
	v_mul_f32_e32 v132, s30, v132
	v_mul_f32_e32 v136, s30, v136
	v_mul_f32_e32 v133, s30, v133
	v_mul_f32_e32 v137, s30, v137
	v_mul_f32_e32 v134, s30, v134
	v_mul_f32_e32 v138, s30, v138
	v_mul_f32_e32 v135, s30, v135
	v_mul_f32_e32 v139, s30, v139
	v_cvt_pk_bf16_f32 v128, v132, v136
	v_cvt_pk_bf16_f32 v129, v133, v137
	v_cvt_pk_bf16_f32 v130, v134, v138
	v_cvt_pk_bf16_f32 v131, v135, v139
	global_store_dwordx4 v168, v[128:131], s[4:5] nt
	s_nop 1
	v_mul_f32_e32 v171, v53, v242
	v_fma_f32 v132, v52, v210, -v171
	v_mul_f32_e32 v171, v52, v242
	v_fma_f32 v136, v53, v210, v171
	v_mul_f32_e32 v171, v55, v243
	v_fma_f32 v133, v54, v211, -v171
	v_mul_f32_e32 v171, v54, v243
	v_fma_f32 v137, v55, v211, v171
	v_mul_f32_e32 v171, v49, v244
	v_fma_f32 v134, v48, v212, -v171
	v_mul_f32_e32 v171, v48, v244
	v_fma_f32 v138, v49, v212, v171
	v_mul_f32_e32 v171, v51, v245
	v_fma_f32 v135, v50, v213, -v171
	v_mul_f32_e32 v171, v50, v245
	v_fma_f32 v139, v51, v213, v171
	v_mul_f32_e32 v132, s30, v132
	v_mul_f32_e32 v136, s30, v136
	v_mul_f32_e32 v133, s30, v133
	v_mul_f32_e32 v137, s30, v137
	v_mul_f32_e32 v134, s30, v134
	v_mul_f32_e32 v138, s30, v138
	v_mul_f32_e32 v135, s30, v135
	v_mul_f32_e32 v139, s30, v139
	v_cvt_pk_bf16_f32 v128, v132, v136
	v_cvt_pk_bf16_f32 v129, v133, v137
	v_cvt_pk_bf16_f32 v130, v134, v138
	v_cvt_pk_bf16_f32 v131, v135, v139
	global_store_dwordx4 v168, v[128:131], s[4:5] offset:256 nt
	s_add_u32 s4, s4, 0x58000
	s_addc_u32 s5, s5, 0
	s_nop 1
	v_mul_f32_e32 v171, v45, v246
	v_fma_f32 v132, v44, v214, -v171
	v_mul_f32_e32 v171, v44, v246
	v_fma_f32 v136, v45, v214, v171
	v_mul_f32_e32 v171, v47, v247
	v_fma_f32 v133, v46, v215, -v171
	v_mul_f32_e32 v171, v46, v247
	v_fma_f32 v137, v47, v215, v171
	v_mul_f32_e32 v171, v41, v248
	v_fma_f32 v134, v40, v216, -v171
	v_mul_f32_e32 v171, v40, v248
	v_fma_f32 v138, v41, v216, v171
	v_mul_f32_e32 v171, v43, v249
	v_fma_f32 v135, v42, v217, -v171
	v_mul_f32_e32 v171, v42, v249
	v_fma_f32 v139, v43, v217, v171
	v_mul_f32_e32 v132, s30, v132
	v_mul_f32_e32 v136, s30, v136
	v_mul_f32_e32 v133, s30, v133
	v_mul_f32_e32 v137, s30, v137
	v_mul_f32_e32 v134, s30, v134
	v_mul_f32_e32 v138, s30, v138
	v_mul_f32_e32 v135, s30, v135
	v_mul_f32_e32 v139, s30, v139
	v_cvt_pk_bf16_f32 v128, v132, v136
	v_cvt_pk_bf16_f32 v129, v133, v137
	v_cvt_pk_bf16_f32 v130, v134, v138
	v_cvt_pk_bf16_f32 v131, v135, v139
	global_store_dwordx4 v168, v[128:131], s[4:5] nt
	s_nop 1
	v_mul_f32_e32 v171, v37, v246
	v_fma_f32 v132, v36, v214, -v171
	v_mul_f32_e32 v171, v36, v246
	v_fma_f32 v136, v37, v214, v171
	v_mul_f32_e32 v171, v39, v247
	v_fma_f32 v133, v38, v215, -v171
	v_mul_f32_e32 v171, v38, v247
	v_fma_f32 v137, v39, v215, v171
	v_mul_f32_e32 v171, v33, v248
	v_fma_f32 v134, v32, v216, -v171
	v_mul_f32_e32 v171, v32, v248
	v_fma_f32 v138, v33, v216, v171
	v_mul_f32_e32 v171, v35, v249
	v_fma_f32 v135, v34, v217, -v171
	v_mul_f32_e32 v171, v34, v249
	v_fma_f32 v139, v35, v217, v171
	v_mul_f32_e32 v132, s30, v132
	v_mul_f32_e32 v136, s30, v136
	v_mul_f32_e32 v133, s30, v133
	v_mul_f32_e32 v137, s30, v137
	v_mul_f32_e32 v134, s30, v134
	v_mul_f32_e32 v138, s30, v138
	v_mul_f32_e32 v135, s30, v135
	v_mul_f32_e32 v139, s30, v139
	v_cvt_pk_bf16_f32 v128, v132, v136
	v_cvt_pk_bf16_f32 v129, v133, v137
	v_cvt_pk_bf16_f32 v130, v134, v138
	v_cvt_pk_bf16_f32 v131, v135, v139
	global_store_dwordx4 v168, v[128:131], s[4:5] offset:256 nt
	s_add_u32 s4, s4, 0x58000
	s_addc_u32 s5, s5, 0
	s_nop 1
	v_mul_f32_e32 v171, v29, v140
	v_fma_f32 v132, v28, v218, -v171
	v_mul_f32_e32 v171, v28, v140
	v_fma_f32 v136, v29, v218, v171
	v_mul_f32_e32 v171, v31, v141
	v_fma_f32 v133, v30, v219, -v171
	v_mul_f32_e32 v171, v30, v141
	v_fma_f32 v137, v31, v219, v171
	v_mul_f32_e32 v171, v25, v142
	v_fma_f32 v134, v24, v220, -v171
	v_mul_f32_e32 v171, v24, v142
	v_fma_f32 v138, v25, v220, v171
	v_mul_f32_e32 v171, v27, v143
	v_fma_f32 v135, v26, v221, -v171
	v_mul_f32_e32 v171, v26, v143
	v_fma_f32 v139, v27, v221, v171
	v_mul_f32_e32 v132, s30, v132
	v_mul_f32_e32 v136, s30, v136
	v_mul_f32_e32 v133, s30, v133
	v_mul_f32_e32 v137, s30, v137
	v_mul_f32_e32 v134, s30, v134
	v_mul_f32_e32 v138, s30, v138
	v_mul_f32_e32 v135, s30, v135
	v_mul_f32_e32 v139, s30, v139
	v_cvt_pk_bf16_f32 v128, v132, v136
	v_cvt_pk_bf16_f32 v129, v133, v137
	v_cvt_pk_bf16_f32 v130, v134, v138
	v_cvt_pk_bf16_f32 v131, v135, v139
	global_store_dwordx4 v168, v[128:131], s[4:5] nt
	s_nop 1
	v_mul_f32_e32 v171, v21, v140
	v_fma_f32 v132, v20, v218, -v171
	v_mul_f32_e32 v171, v20, v140
	v_fma_f32 v136, v21, v218, v171
	v_mul_f32_e32 v171, v23, v141
	v_fma_f32 v133, v22, v219, -v171
	v_mul_f32_e32 v171, v22, v141
	v_fma_f32 v137, v23, v219, v171
	v_mul_f32_e32 v171, v17, v142
	v_fma_f32 v134, v16, v220, -v171
	v_mul_f32_e32 v171, v16, v142
	v_fma_f32 v138, v17, v220, v171
	v_mul_f32_e32 v171, v19, v143
	v_fma_f32 v135, v18, v221, -v171
	v_mul_f32_e32 v171, v18, v143
	v_fma_f32 v139, v19, v221, v171
	v_mul_f32_e32 v132, s30, v132
	v_mul_f32_e32 v136, s30, v136
	v_mul_f32_e32 v133, s30, v133
	v_mul_f32_e32 v137, s30, v137
	v_mul_f32_e32 v134, s30, v134
	v_mul_f32_e32 v138, s30, v138
	v_mul_f32_e32 v135, s30, v135
	v_mul_f32_e32 v139, s30, v139
	v_cvt_pk_bf16_f32 v128, v132, v136
	v_cvt_pk_bf16_f32 v129, v133, v137
	v_cvt_pk_bf16_f32 v130, v134, v138
	v_cvt_pk_bf16_f32 v131, v135, v139
	global_store_dwordx4 v168, v[128:131], s[4:5] offset:256 nt
	s_add_u32 s4, s4, 0x58000
	s_addc_u32 s5, s5, 0
	s_nop 1
	v_mul_f32_e32 v171, v13, v144
	v_fma_f32 v132, v12, v222, -v171
	v_mul_f32_e32 v171, v12, v144
	v_fma_f32 v136, v13, v222, v171
	v_mul_f32_e32 v171, v15, v145
	v_fma_f32 v133, v14, v223, -v171
	v_mul_f32_e32 v171, v14, v145
	v_fma_f32 v137, v15, v223, v171
	v_mul_f32_e32 v171, v9, v146
	v_fma_f32 v134, v8, v224, -v171
	v_mul_f32_e32 v171, v8, v146
	v_fma_f32 v138, v9, v224, v171
	v_mul_f32_e32 v171, v11, v147
	v_fma_f32 v135, v10, v225, -v171
	v_mul_f32_e32 v171, v10, v147
	v_fma_f32 v139, v11, v225, v171
	v_mul_f32_e32 v132, s30, v132
	v_mul_f32_e32 v136, s30, v136
	v_mul_f32_e32 v133, s30, v133
	v_mul_f32_e32 v137, s30, v137
	v_mul_f32_e32 v134, s30, v134
	v_mul_f32_e32 v138, s30, v138
	v_mul_f32_e32 v135, s30, v135
	v_mul_f32_e32 v139, s30, v139
	v_cvt_pk_bf16_f32 v128, v132, v136
	v_cvt_pk_bf16_f32 v129, v133, v137
	v_cvt_pk_bf16_f32 v130, v134, v138
	v_cvt_pk_bf16_f32 v131, v135, v139
	global_store_dwordx4 v168, v[128:131], s[4:5] nt
	s_nop 1
	v_mul_f32_e32 v171, v5, v144
	v_fma_f32 v132, v4, v222, -v171
	v_mul_f32_e32 v171, v4, v144
	v_fma_f32 v136, v5, v222, v171
	v_mul_f32_e32 v171, v7, v145
	v_fma_f32 v133, v6, v223, -v171
	v_mul_f32_e32 v171, v6, v145
	v_fma_f32 v137, v7, v223, v171
	v_mul_f32_e32 v171, v1, v146
	v_fma_f32 v134, v0, v224, -v171
	v_mul_f32_e32 v171, v0, v146
	v_fma_f32 v138, v1, v224, v171
	v_mul_f32_e32 v171, v3, v147
	v_fma_f32 v135, v2, v225, -v171
	v_mul_f32_e32 v171, v2, v147
	v_fma_f32 v139, v3, v225, v171
	v_mul_f32_e32 v132, s30, v132
	v_mul_f32_e32 v136, s30, v136
	v_mul_f32_e32 v133, s30, v133
	v_mul_f32_e32 v137, s30, v137
	v_mul_f32_e32 v134, s30, v134
	v_mul_f32_e32 v138, s30, v138
	v_mul_f32_e32 v135, s30, v135
	v_mul_f32_e32 v139, s30, v139
	v_cvt_pk_bf16_f32 v128, v132, v136
	v_cvt_pk_bf16_f32 v129, v133, v137
	v_cvt_pk_bf16_f32 v130, v134, v138
	v_cvt_pk_bf16_f32 v131, v135, v139
	global_store_dwordx4 v168, v[128:131], s[4:5] offset:256 nt
	s_branch .Lepi4_done
.Lepi4_plain:
	s_lshl_b32 s8, s90, 8
	s_add_i32 s8, s8, s57
	v_mul_u32_u24_e32 v168, 0x5800, v184
	v_lshl_add_u32 v168, v185, 4, v168
	s_mul_i32 s20, s8, 0x5800
	s_lshl_b32 s6, s82, 9
	s_add_u32 s20, s20, s6
	s_lshl_b32 s6, s59, 1
	s_add_u32 s20, s20, s6
	s_add_u32 s4, s0, s20
	s_addc_u32 s5, s1, 0
	s_nop 1
	v_mul_f32_e32 v132, s30, v124
	v_mul_f32_e32 v136, s30, v125
	v_mul_f32_e32 v133, s30, v126
	v_mul_f32_e32 v137, s30, v127
	v_mul_f32_e32 v134, s30, v120
	v_mul_f32_e32 v138, s30, v121
	v_mul_f32_e32 v135, s30, v122
	v_mul_f32_e32 v139, s30, v123
	v_cvt_pk_bf16_f32 v128, v132, v136
	v_cvt_pk_bf16_f32 v129, v133, v137
	v_cvt_pk_bf16_f32 v130, v134, v138
	v_cvt_pk_bf16_f32 v131, v135, v139
	global_store_dwordx4 v168, v[128:131], s[4:5] nt
	s_nop 1
	v_mul_f32_e32 v132, s30, v116
	v_mul_f32_e32 v136, s30, v117
	v_mul_f32_e32 v133, s30, v118
	v_mul_f32_e32 v137, s30, v119
	v_mul_f32_e32 v134, s30, v112
	v_mul_f32_e32 v138, s30, v113
	v_mul_f32_e32 v135, s30, v114
	v_mul_f32_e32 v139, s30, v115
	v_cvt_pk_bf16_f32 v128, v132, v136
	v_cvt_pk_bf16_f32 v129, v133, v137
	v_cvt_pk_bf16_f32 v130, v134, v138
	v_cvt_pk_bf16_f32 v131, v135, v139
	global_store_dwordx4 v168, v[128:131], s[4:5] offset:256 nt
	s_add_u32 s4, s4, 0x58000
	s_addc_u32 s5, s5, 0
	s_nop 1
	v_mul_f32_e32 v132, s30, v108
	v_mul_f32_e32 v136, s30, v109
	v_mul_f32_e32 v133, s30, v110
	v_mul_f32_e32 v137, s30, v111
	v_mul_f32_e32 v134, s30, v104
	v_mul_f32_e32 v138, s30, v105
	v_mul_f32_e32 v135, s30, v106
	v_mul_f32_e32 v139, s30, v107
	v_cvt_pk_bf16_f32 v128, v132, v136
	v_cvt_pk_bf16_f32 v129, v133, v137
	v_cvt_pk_bf16_f32 v130, v134, v138
	v_cvt_pk_bf16_f32 v131, v135, v139
	global_store_dwordx4 v168, v[128:131], s[4:5] nt
	s_nop 1
	v_mul_f32_e32 v132, s30, v100
	v_mul_f32_e32 v136, s30, v101
	v_mul_f32_e32 v133, s30, v102
	v_mul_f32_e32 v137, s30, v103
	v_mul_f32_e32 v134, s30, v96
	v_mul_f32_e32 v138, s30, v97
	v_mul_f32_e32 v135, s30, v98
	v_mul_f32_e32 v139, s30, v99
	v_cvt_pk_bf16_f32 v128, v132, v136
	v_cvt_pk_bf16_f32 v129, v133, v137
	v_cvt_pk_bf16_f32 v130, v134, v138
	v_cvt_pk_bf16_f32 v131, v135, v139
	global_store_dwordx4 v168, v[128:131], s[4:5] offset:256 nt
	s_add_u32 s4, s4, 0x58000
	s_addc_u32 s5, s5, 0
	s_nop 1
	v_mul_f32_e32 v132, s30, v92
	v_mul_f32_e32 v136, s30, v93
	v_mul_f32_e32 v133, s30, v94
	v_mul_f32_e32 v137, s30, v95
	v_mul_f32_e32 v134, s30, v88
	v_mul_f32_e32 v138, s30, v89
	v_mul_f32_e32 v135, s30, v90
	v_mul_f32_e32 v139, s30, v91
	v_cvt_pk_bf16_f32 v128, v132, v136
	v_cvt_pk_bf16_f32 v129, v133, v137
	v_cvt_pk_bf16_f32 v130, v134, v138
	v_cvt_pk_bf16_f32 v131, v135, v139
	global_store_dwordx4 v168, v[128:131], s[4:5] nt
	s_nop 1
	v_mul_f32_e32 v132, s30, v84
	v_mul_f32_e32 v136, s30, v85
	v_mul_f32_e32 v133, s30, v86
	v_mul_f32_e32 v137, s30, v87
	v_mul_f32_e32 v134, s30, v80
	v_mul_f32_e32 v138, s30, v81
	v_mul_f32_e32 v135, s30, v82
	v_mul_f32_e32 v139, s30, v83
	v_cvt_pk_bf16_f32 v128, v132, v136
	v_cvt_pk_bf16_f32 v129, v133, v137
	v_cvt_pk_bf16_f32 v130, v134, v138
	v_cvt_pk_bf16_f32 v131, v135, v139
	global_store_dwordx4 v168, v[128:131], s[4:5] offset:256 nt
	s_add_u32 s4, s4, 0x58000
	s_addc_u32 s5, s5, 0
	s_nop 1
	v_mul_f32_e32 v132, s30, v76
	v_mul_f32_e32 v136, s30, v77
	v_mul_f32_e32 v133, s30, v78
	v_mul_f32_e32 v137, s30, v79
	v_mul_f32_e32 v134, s30, v72
	v_mul_f32_e32 v138, s30, v73
	v_mul_f32_e32 v135, s30, v74
	v_mul_f32_e32 v139, s30, v75
	v_cvt_pk_bf16_f32 v128, v132, v136
	v_cvt_pk_bf16_f32 v129, v133, v137
	v_cvt_pk_bf16_f32 v130, v134, v138
	v_cvt_pk_bf16_f32 v131, v135, v139
	global_store_dwordx4 v168, v[128:131], s[4:5] nt
	s_nop 1
	v_mul_f32_e32 v132, s30, v68
	v_mul_f32_e32 v136, s30, v69
	v_mul_f32_e32 v133, s30, v70
	v_mul_f32_e32 v137, s30, v71
	v_mul_f32_e32 v134, s30, v64
	v_mul_f32_e32 v138, s30, v65
	v_mul_f32_e32 v135, s30, v66
	v_mul_f32_e32 v139, s30, v67
	v_cvt_pk_bf16_f32 v128, v132, v136
	v_cvt_pk_bf16_f32 v129, v133, v137
	v_cvt_pk_bf16_f32 v130, v134, v138
	v_cvt_pk_bf16_f32 v131, v135, v139
	global_store_dwordx4 v168, v[128:131], s[4:5] offset:256 nt
	s_add_u32 s4, s4, 0x1b8000
	s_addc_u32 s5, s5, 0
	s_nop 1
	v_mul_f32_e32 v132, s30, v60
	v_mul_f32_e32 v136, s30, v61
	v_mul_f32_e32 v133, s30, v62
	v_mul_f32_e32 v137, s30, v63
	v_mul_f32_e32 v134, s30, v56
	v_mul_f32_e32 v138, s30, v57
	v_mul_f32_e32 v135, s30, v58
	v_mul_f32_e32 v139, s30, v59
	v_cvt_pk_bf16_f32 v128, v132, v136
	v_cvt_pk_bf16_f32 v129, v133, v137
	v_cvt_pk_bf16_f32 v130, v134, v138
	v_cvt_pk_bf16_f32 v131, v135, v139
	global_store_dwordx4 v168, v[128:131], s[4:5] nt
	s_nop 1
	v_mul_f32_e32 v132, s30, v52
	v_mul_f32_e32 v136, s30, v53
	v_mul_f32_e32 v133, s30, v54
	v_mul_f32_e32 v137, s30, v55
	v_mul_f32_e32 v134, s30, v48
	v_mul_f32_e32 v138, s30, v49
	v_mul_f32_e32 v135, s30, v50
	v_mul_f32_e32 v139, s30, v51
	v_cvt_pk_bf16_f32 v128, v132, v136
	v_cvt_pk_bf16_f32 v129, v133, v137
	v_cvt_pk_bf16_f32 v130, v134, v138
	v_cvt_pk_bf16_f32 v131, v135, v139
	global_store_dwordx4 v168, v[128:131], s[4:5] offset:256 nt
	s_add_u32 s4, s4, 0x58000
	s_addc_u32 s5, s5, 0
	s_nop 1
	v_mul_f32_e32 v132, s30, v44
	v_mul_f32_e32 v136, s30, v45
	v_mul_f32_e32 v133, s30, v46
	v_mul_f32_e32 v137, s30, v47
	v_mul_f32_e32 v134, s30, v40
	v_mul_f32_e32 v138, s30, v41
	v_mul_f32_e32 v135, s30, v42
	v_mul_f32_e32 v139, s30, v43
	v_cvt_pk_bf16_f32 v128, v132, v136
	v_cvt_pk_bf16_f32 v129, v133, v137
	v_cvt_pk_bf16_f32 v130, v134, v138
	v_cvt_pk_bf16_f32 v131, v135, v139
	global_store_dwordx4 v168, v[128:131], s[4:5] nt
	s_nop 1
	v_mul_f32_e32 v132, s30, v36
	v_mul_f32_e32 v136, s30, v37
	v_mul_f32_e32 v133, s30, v38
	v_mul_f32_e32 v137, s30, v39
	v_mul_f32_e32 v134, s30, v32
	v_mul_f32_e32 v138, s30, v33
	v_mul_f32_e32 v135, s30, v34
	v_mul_f32_e32 v139, s30, v35
	v_cvt_pk_bf16_f32 v128, v132, v136
	v_cvt_pk_bf16_f32 v129, v133, v137
	v_cvt_pk_bf16_f32 v130, v134, v138
	v_cvt_pk_bf16_f32 v131, v135, v139
	global_store_dwordx4 v168, v[128:131], s[4:5] offset:256 nt
	s_add_u32 s4, s4, 0x58000
	s_addc_u32 s5, s5, 0
	s_nop 1
	v_mul_f32_e32 v132, s30, v28
	v_mul_f32_e32 v136, s30, v29
	v_mul_f32_e32 v133, s30, v30
	v_mul_f32_e32 v137, s30, v31
	v_mul_f32_e32 v134, s30, v24
	v_mul_f32_e32 v138, s30, v25
	v_mul_f32_e32 v135, s30, v26
	v_mul_f32_e32 v139, s30, v27
	v_cvt_pk_bf16_f32 v128, v132, v136
	v_cvt_pk_bf16_f32 v129, v133, v137
	v_cvt_pk_bf16_f32 v130, v134, v138
	v_cvt_pk_bf16_f32 v131, v135, v139
	global_store_dwordx4 v168, v[128:131], s[4:5] nt
	s_nop 1
	v_mul_f32_e32 v132, s30, v20
	v_mul_f32_e32 v136, s30, v21
	v_mul_f32_e32 v133, s30, v22
	v_mul_f32_e32 v137, s30, v23
	v_mul_f32_e32 v134, s30, v16
	v_mul_f32_e32 v138, s30, v17
	v_mul_f32_e32 v135, s30, v18
	v_mul_f32_e32 v139, s30, v19
	v_cvt_pk_bf16_f32 v128, v132, v136
	v_cvt_pk_bf16_f32 v129, v133, v137
	v_cvt_pk_bf16_f32 v130, v134, v138
	v_cvt_pk_bf16_f32 v131, v135, v139
	global_store_dwordx4 v168, v[128:131], s[4:5] offset:256 nt
	s_add_u32 s4, s4, 0x58000
	s_addc_u32 s5, s5, 0
	s_nop 1
	v_mul_f32_e32 v132, s30, v12
	v_mul_f32_e32 v136, s30, v13
	v_mul_f32_e32 v133, s30, v14
	v_mul_f32_e32 v137, s30, v15
	v_mul_f32_e32 v134, s30, v8
	v_mul_f32_e32 v138, s30, v9
	v_mul_f32_e32 v135, s30, v10
	v_mul_f32_e32 v139, s30, v11
	v_cvt_pk_bf16_f32 v128, v132, v136
	v_cvt_pk_bf16_f32 v129, v133, v137
	v_cvt_pk_bf16_f32 v130, v134, v138
	v_cvt_pk_bf16_f32 v131, v135, v139
	global_store_dwordx4 v168, v[128:131], s[4:5] nt
	s_nop 1
	v_mul_f32_e32 v132, s30, v4
	v_mul_f32_e32 v136, s30, v5
	v_mul_f32_e32 v133, s30, v6
	v_mul_f32_e32 v137, s30, v7
	v_mul_f32_e32 v134, s30, v0
	v_mul_f32_e32 v138, s30, v1
	v_mul_f32_e32 v135, s30, v2
	v_mul_f32_e32 v139, s30, v3
	v_cvt_pk_bf16_f32 v128, v132, v136
	v_cvt_pk_bf16_f32 v129, v133, v137
	v_cvt_pk_bf16_f32 v130, v134, v138
	v_cvt_pk_bf16_f32 v131, v135, v139
	global_store_dwordx4 v168, v[128:131], s[4:5] offset:256 nt

.LBB0_551:
	s_andn2_b64 vcc, exec, s[4:5]
	s_cbranch_vccnz .LBB0_585
	v_add_u32_e32 v169, s57, v184
	s_lshl_b32 s6, s90, 8
	v_lshl_add_u32 v140, v185, 3, s59
	v_add_u32_e32 v144, s6, v169
	v_ashrrev_i32_e32 v128, 1, v140
	v_lshlrev_b32_e32 v131, 8, v185
	v_ashrrev_i32_e32 v145, 31, v144
	v_ashrrev_i32_e32 v129, 31, v128
	v_lshlrev_b32_e32 v130, 5, v140
	v_and_b32_e32 v131, 0x100, v131
	v_lshlrev_b64 v[132:133], 8, v[144:145]
	v_and_or_b32 v168, v130, s42, v131
	v_lshl_add_u64 v[130:131], s[12:13], 0, v[132:133]
	v_lshlrev_b64 v[142:143], 2, v[128:129]
	v_lshl_add_u64 v[132:133], s[14:15], 0, v[132:133]
	v_lshl_add_u64 v[128:129], v[130:131], 0, v[142:143]
	v_lshl_add_u64 v[132:133], v[132:133], 0, v[142:143]
	global_load_dwordx4 v[128:131], v[128:129], off
	v_lshlrev_b32_e32 v136, 7, v144
	global_load_dwordx4 v[132:135], v[132:133], off
	v_and_b32_e32 v136, 0xfffff000, v136
	v_lshlrev_b32_e32 v137, 3, v184
	v_add_u32_e32 v136, v168, v136
	v_and_b32_e32 v145, 0xf8, v137
	v_or_b32_e32 v170, v136, v145
	s_lshl_b32 s20, s82, 9
	v_ashrrev_i32_e32 v141, 31, v140
	v_cmp_gt_i32_e32 vcc, s56, v144
	s_waitcnt vmcnt(0)
	v_pk_mul_f32 v[136:137], v[120:121], v[134:135] op_sel_hi:[1,0]
	s_nop 0
	v_pk_fma_f32 v[138:139], v[120:121], v[130:131], v[136:137] op_sel:[0,0,1] op_sel_hi:[1,0,0] neg_lo:[0,0,1] neg_hi:[0,0,1]
	v_pk_fma_f32 v[136:137], v[120:121], v[130:131], v[136:137] op_sel:[0,0,1] op_sel_hi:[1,0,0]
	v_mov_b32_e32 v146, v135
	v_mov_b32_e32 v136, v131
	v_pk_mul_f32 v[146:147], v[122:123], v[146:147] op_sel_hi:[1,0]
	v_mov_b32_e32 v139, v137
	v_pk_fma_f32 v[172:173], v[122:123], v[136:137], v[146:147] op_sel:[0,0,1] op_sel_hi:[1,0,0] neg_lo:[0,0,1] neg_hi:[0,0,1]
	v_pk_fma_f32 v[146:147], v[122:123], v[136:137], v[146:147] op_sel:[0,0,1] op_sel_hi:[1,0,0]
	v_pk_mul_f32 v[174:175], v[124:125], v[132:133] op_sel_hi:[1,0]
	v_mov_b32_e32 v173, v147
	v_pk_mul_f32 v[186:187], v[126:127], v[132:133] op_sel:[0,1]
	v_pk_mul_f32 v[146:147], v[172:173], s[30:31] op_sel_hi:[1,0]
	v_pk_mul_f32 v[138:139], v[138:139], s[30:31] op_sel_hi:[1,0]
	v_pk_fma_f32 v[176:177], v[124:125], v[128:129], v[174:175] op_sel:[0,0,1] op_sel_hi:[1,0,0] neg_lo:[0,0,1] neg_hi:[0,0,1]
	v_pk_fma_f32 v[174:175], v[124:125], v[128:129], v[174:175] op_sel:[0,0,1] op_sel_hi:[1,0,0]
	v_pk_fma_f32 v[188:189], v[126:127], v[128:129], v[186:187] op_sel:[0,1,1] op_sel_hi:[1,1,0] neg_lo:[0,0,1] neg_hi:[0,0,1]
	v_pk_fma_f32 v[186:187], v[126:127], v[128:129], v[186:187] op_sel:[0,1,1] op_sel_hi:[1,1,0]
	v_cvt_pk_bf16_f32 v138, v138, v139
	v_cvt_pk_bf16_f32 v139, v146, v147
	v_mov_b64_e32 v[146:147], s[0:1]
	v_mov_b32_e32 v189, v187
	v_mov_b32_e32 v177, v175
	v_mad_i64_i32 v[146:147], s[4:5], v144, s28, v[146:147]
	v_pk_mul_f32 v[186:187], v[188:189], s[30:31] op_sel_hi:[1,0]
	v_pk_mul_f32 v[174:175], v[176:177], s[30:31] op_sel_hi:[1,0]
	v_lshl_add_u64 v[146:147], v[146:147], 0, s[20:21]
	v_cvt_pk_bf16_f32 v136, v174, v175
	v_cvt_pk_bf16_f32 v137, v186, v187
	v_lshl_add_u64 v[146:147], v[140:141], 1, v[146:147]
	global_store_dwordx4 v[146:147], v[136:139], off nt
	s_and_saveexec_b64 s[4:5], vcc
	s_cbranch_execz .LBB0_554
	s_lshl_b32 s7, s82, 21
	s_add_i32 s7, s7, 0xff800000
	v_readlane_b32 s8, v252, 56
	v_add_u32_e32 v156, s7, v170
	v_readlane_b32 s9, v252, 57
	s_nop 1
	v_lshl_add_u64 v[172:173], v[156:157], 1, s[8:9]
	global_store_dwordx4 v[172:173], v[136:139], off nt
.LBB0_554:
	s_or_b64 exec, exec, s[4:5]
	s_nop 0
	v_mov_b32_e32 v138, v134
	v_mov_b32_e32 v139, v134
	v_mov_b32_e32 v134, v135
	v_mov_b32_e32 v136, v130
	v_mov_b32_e32 v137, v130
	v_mov_b32_e32 v130, v131
	v_mov_b32_e32 v174, v132
	v_mov_b32_e32 v175, v132
	v_mov_b32_e32 v132, v133
	v_pk_mul_f32 v[138:139], v[112:113], v[138:139]
	v_pk_mul_f32 v[134:135], v[114:115], v[134:135]
	v_mov_b32_e32 v172, v128
	v_mov_b32_e32 v173, v128
	v_mov_b32_e32 v128, v129
	v_pk_fma_f32 v[176:177], v[112:113], v[136:137], v[138:139] op_sel:[0,0,1] op_sel_hi:[1,1,0] neg_lo:[0,0,1] neg_hi:[0,0,1]
	v_pk_fma_f32 v[136:137], v[112:113], v[136:137], v[138:139] op_sel:[0,0,1] op_sel_hi:[1,1,0]
	v_pk_fma_f32 v[138:139], v[114:115], v[130:131], v[134:135] op_sel:[0,0,1] op_sel_hi:[1,1,0] neg_lo:[0,0,1] neg_hi:[0,0,1]
	v_pk_fma_f32 v[130:131], v[114:115], v[130:131], v[134:135] op_sel:[0,0,1] op_sel_hi:[1,1,0]
	v_pk_mul_f32 v[134:135], v[116:117], v[174:175]
	v_pk_mul_f32 v[132:133], v[118:119], v[132:133]
	v_pk_fma_f32 v[174:175], v[116:117], v[172:173], v[134:135] op_sel:[0,0,1] op_sel_hi:[1,1,0] neg_lo:[0,0,1] neg_hi:[0,0,1]
	v_pk_fma_f32 v[134:135], v[116:117], v[172:173], v[134:135] op_sel:[0,0,1] op_sel_hi:[1,1,0]
	v_pk_fma_f32 v[172:173], v[118:119], v[128:129], v[132:133] op_sel:[0,0,1] op_sel_hi:[1,1,0] neg_lo:[0,0,1] neg_hi:[0,0,1]
	v_pk_fma_f32 v[128:129], v[118:119], v[128:129], v[132:133] op_sel:[0,0,1] op_sel_hi:[1,1,0]
	v_mov_b32_e32 v175, v135
	v_mov_b32_e32 v173, v129
	v_mov_b32_e32 v139, v131
	v_mov_b32_e32 v177, v137
	v_pk_mul_f32 v[132:133], v[172:173], s[30:31] op_sel_hi:[1,0]
	v_pk_mul_f32 v[128:129], v[174:175], s[30:31] op_sel_hi:[1,0]
	v_pk_mul_f32 v[134:135], v[138:139], s[30:31] op_sel_hi:[1,0]
	v_pk_mul_f32 v[130:131], v[176:177], s[30:31] op_sel_hi:[1,0]
	v_cvt_pk_bf16_f32 v128, v128, v129
	v_cvt_pk_bf16_f32 v129, v132, v133
	v_cvt_pk_bf16_f32 v130, v130, v131
	v_cvt_pk_bf16_f32 v131, v134, v135
	global_store_dwordx4 v[146:147], v[128:131], off offset:256 nt
	s_and_saveexec_b64 s[4:5], vcc
	s_cbranch_execz .LBB0_556
	s_lshl_b32 s7, s82, 21
	s_add_i32 s7, s7, 0xff900000
	v_readlane_b32 s8, v252, 56
	v_add_u32_e32 v156, s7, v170
	v_readlane_b32 s9, v252, 57
	s_nop 1
	v_lshl_add_u64 v[132:133], v[156:157], 1, s[8:9]
	global_store_dwordx4 v[132:133], v[128:131], off nt
.LBB0_556:
	s_or_b64 exec, exec, s[4:5]
	v_add_u32_e32 v136, 16, v169
	v_add_u32_e32 v146, s6, v136
	v_ashrrev_i32_e32 v147, 31, v146
	v_lshlrev_b64 v[132:133], 8, v[146:147]
	v_lshl_add_u64 v[128:129], s[12:13], 0, v[132:133]
	v_lshl_add_u64 v[132:133], s[14:15], 0, v[132:133]
	v_lshl_add_u64 v[128:129], v[128:129], 0, v[142:143]
	v_lshl_add_u64 v[132:133], v[132:133], 0, v[142:143]
	global_load_dwordx4 v[128:131], v[128:129], off
	v_lshlrev_b32_e32 v137, 7, v146
	global_load_dwordx4 v[132:135], v[132:133], off
	v_and_b32_e32 v137, 0xfffff000, v137
	v_add_u32_e32 v137, v137, v168
	v_lshlrev_b32_e32 v136, 3, v136
	v_and_or_b32 v170, v136, s43, v137
	s_lshl_b32 s7, s82, 8
	v_cmp_gt_i32_e32 vcc, s56, v146
	s_lshl_b32 s20, s7, 1
	s_waitcnt vmcnt(0)
	v_pk_mul_f32 v[136:137], v[104:105], v[134:135] op_sel_hi:[1,0]
	s_nop 0
	v_pk_fma_f32 v[138:139], v[104:105], v[130:131], v[136:137] op_sel:[0,0,1] op_sel_hi:[1,0,0] neg_lo:[0,0,1] neg_hi:[0,0,1]
	v_pk_fma_f32 v[136:137], v[104:105], v[130:131], v[136:137] op_sel:[0,0,1] op_sel_hi:[1,0,0]
	v_mov_b32_e32 v156, v135
	v_mov_b32_e32 v136, v131
	v_pk_mul_f32 v[172:173], v[106:107], v[156:157] op_sel_hi:[1,0]
	v_mov_b32_e32 v139, v137
	v_pk_fma_f32 v[174:175], v[106:107], v[136:137], v[172:173] op_sel:[0,0,1] op_sel_hi:[1,0,0] neg_lo:[0,0,1] neg_hi:[0,0,1]
	v_pk_fma_f32 v[172:173], v[106:107], v[136:137], v[172:173] op_sel:[0,0,1] op_sel_hi:[1,0,0]
	v_pk_mul_f32 v[176:177], v[108:109], v[132:133] op_sel_hi:[1,0]
	v_mov_b32_e32 v175, v173
	v_pk_mul_f32 v[188:189], v[110:111], v[132:133] op_sel:[0,1]
	v_pk_mul_f32 v[172:173], v[174:175], s[30:31] op_sel_hi:[1,0]
	v_pk_mul_f32 v[138:139], v[138:139], s[30:31] op_sel_hi:[1,0]
	v_pk_fma_f32 v[186:187], v[108:109], v[128:129], v[176:177] op_sel:[0,0,1] op_sel_hi:[1,0,0] neg_lo:[0,0,1] neg_hi:[0,0,1]
	v_pk_fma_f32 v[176:177], v[108:109], v[128:129], v[176:177] op_sel:[0,0,1] op_sel_hi:[1,0,0]
	v_pk_fma_f32 v[190:191], v[110:111], v[128:129], v[188:189] op_sel:[0,1,1] op_sel_hi:[1,1,0] neg_lo:[0,0,1] neg_hi:[0,0,1]
	v_pk_fma_f32 v[188:189], v[110:111], v[128:129], v[188:189] op_sel:[0,1,1] op_sel_hi:[1,1,0]
	v_cvt_pk_bf16_f32 v138, v138, v139
	v_cvt_pk_bf16_f32 v139, v172, v173
	v_mov_b64_e32 v[172:173], s[0:1]
	v_mov_b32_e32 v191, v189
	v_mov_b32_e32 v187, v177
	v_mad_i64_i32 v[146:147], s[4:5], v146, s28, v[172:173]
	v_pk_mul_f32 v[188:189], v[190:191], s[30:31] op_sel_hi:[1,0]
	v_pk_mul_f32 v[176:177], v[186:187], s[30:31] op_sel_hi:[1,0]
	v_lshl_add_u64 v[146:147], v[146:147], 0, s[20:21]
	v_cvt_pk_bf16_f32 v136, v176, v177
	v_cvt_pk_bf16_f32 v137, v188, v189
	v_lshl_add_u64 v[146:147], v[140:141], 1, v[146:147]
	global_store_dwordx4 v[146:147], v[136:139], off nt
	s_and_saveexec_b64 s[4:5], vcc
	s_cbranch_execz .LBB0_558
	s_lshl_b32 s7, s82, 21
	s_add_i32 s7, s7, 0xff800000
	v_readlane_b32 s8, v252, 56
	v_add_u32_e32 v156, s7, v170
	v_readlane_b32 s9, v252, 57
	s_nop 1
	v_lshl_add_u64 v[172:173], v[156:157], 1, s[8:9]
	global_store_dwordx4 v[172:173], v[136:139], off nt
.LBB0_558:
	s_or_b64 exec, exec, s[4:5]
	s_nop 0
	v_mov_b32_e32 v138, v134
	v_mov_b32_e32 v139, v134
	v_mov_b32_e32 v134, v135
	v_mov_b32_e32 v136, v130
	v_mov_b32_e32 v137, v130
	v_mov_b32_e32 v130, v131
	v_mov_b32_e32 v174, v132
	v_mov_b32_e32 v175, v132
	v_mov_b32_e32 v132, v133
	v_pk_mul_f32 v[138:139], v[96:97], v[138:139]
	v_pk_mul_f32 v[134:135], v[98:99], v[134:135]
	v_mov_b32_e32 v172, v128
	v_mov_b32_e32 v173, v128
	v_mov_b32_e32 v128, v129
	v_pk_fma_f32 v[176:177], v[96:97], v[136:137], v[138:139] op_sel:[0,0,1] op_sel_hi:[1,1,0] neg_lo:[0,0,1] neg_hi:[0,0,1]
	v_pk_fma_f32 v[136:137], v[96:97], v[136:137], v[138:139] op_sel:[0,0,1] op_sel_hi:[1,1,0]
	v_pk_fma_f32 v[138:139], v[98:99], v[130:131], v[134:135] op_sel:[0,0,1] op_sel_hi:[1,1,0] neg_lo:[0,0,1] neg_hi:[0,0,1]
	v_pk_fma_f32 v[130:131], v[98:99], v[130:131], v[134:135] op_sel:[0,0,1] op_sel_hi:[1,1,0]
	v_pk_mul_f32 v[134:135], v[100:101], v[174:175]
	v_pk_mul_f32 v[132:133], v[102:103], v[132:133]
	v_pk_fma_f32 v[174:175], v[100:101], v[172:173], v[134:135] op_sel:[0,0,1] op_sel_hi:[1,1,0] neg_lo:[0,0,1] neg_hi:[0,0,1]
	v_pk_fma_f32 v[134:135], v[100:101], v[172:173], v[134:135] op_sel:[0,0,1] op_sel_hi:[1,1,0]
	v_pk_fma_f32 v[172:173], v[102:103], v[128:129], v[132:133] op_sel:[0,0,1] op_sel_hi:[1,1,0] neg_lo:[0,0,1] neg_hi:[0,0,1]
	v_pk_fma_f32 v[128:129], v[102:103], v[128:129], v[132:133] op_sel:[0,0,1] op_sel_hi:[1,1,0]
	v_mov_b32_e32 v175, v135
	v_mov_b32_e32 v173, v129
	v_mov_b32_e32 v139, v131
	v_mov_b32_e32 v177, v137
	v_pk_mul_f32 v[132:133], v[172:173], s[30:31] op_sel_hi:[1,0]
	v_pk_mul_f32 v[128:129], v[174:175], s[30:31] op_sel_hi:[1,0]
	v_pk_mul_f32 v[134:135], v[138:139], s[30:31] op_sel_hi:[1,0]
	v_pk_mul_f32 v[130:131], v[176:177], s[30:31] op_sel_hi:[1,0]
	v_cvt_pk_bf16_f32 v128, v128, v129
	v_cvt_pk_bf16_f32 v129, v132, v133
	v_cvt_pk_bf16_f32 v130, v130, v131
	v_cvt_pk_bf16_f32 v131, v134, v135
	global_store_dwordx4 v[146:147], v[128:131], off offset:256 nt
	s_and_saveexec_b64 s[4:5], vcc
	s_cbranch_execz .LBB0_560
	s_lshl_b32 s7, s82, 21
	s_add_i32 s7, s7, 0xff900000
	v_readlane_b32 s8, v252, 56
	v_add_u32_e32 v156, s7, v170
	v_readlane_b32 s9, v252, 57
	s_nop 1
	v_lshl_add_u64 v[132:133], v[156:157], 1, s[8:9]
	global_store_dwordx4 v[132:133], v[128:131], off nt
.LBB0_560:
	s_or_b64 exec, exec, s[4:5]
	v_add_u32_e32 v146, 32, v144
	v_ashrrev_i32_e32 v147, 31, v146
	v_lshlrev_b64 v[132:133], 8, v[146:147]
	v_lshl_add_u64 v[128:129], s[12:13], 0, v[132:133]
	v_lshl_add_u64 v[132:133], s[14:15], 0, v[132:133]
	v_lshl_add_u64 v[128:129], v[128:129], 0, v[142:143]
	v_lshl_add_u64 v[132:133], v[132:133], 0, v[142:143]
	global_load_dwordx4 v[128:131], v[128:129], off
	v_lshlrev_b32_e32 v136, 7, v146
	global_load_dwordx4 v[132:135], v[132:133], off
	v_and_b32_e32 v136, 0xfffff000, v136
	v_add_u32_e32 v136, v136, v168
	v_or_b32_e32 v170, v136, v145
	v_cmp_gt_i32_e32 vcc, s56, v146
	s_waitcnt vmcnt(0)
	v_pk_mul_f32 v[136:137], v[88:89], v[134:135] op_sel_hi:[1,0]
	s_nop 0
	v_pk_fma_f32 v[138:139], v[88:89], v[130:131], v[136:137] op_sel:[0,0,1] op_sel_hi:[1,0,0] neg_lo:[0,0,1] neg_hi:[0,0,1]
	v_pk_fma_f32 v[136:137], v[88:89], v[130:131], v[136:137] op_sel:[0,0,1] op_sel_hi:[1,0,0]
	v_mov_b32_e32 v156, v135
	v_mov_b32_e32 v136, v131
	v_pk_mul_f32 v[172:173], v[90:91], v[156:157] op_sel_hi:[1,0]
	v_mov_b32_e32 v139, v137
	v_pk_fma_f32 v[174:175], v[90:91], v[136:137], v[172:173] op_sel:[0,0,1] op_sel_hi:[1,0,0] neg_lo:[0,0,1] neg_hi:[0,0,1]
	v_pk_fma_f32 v[172:173], v[90:91], v[136:137], v[172:173] op_sel:[0,0,1] op_sel_hi:[1,0,0]
	v_pk_mul_f32 v[176:177], v[92:93], v[132:133] op_sel_hi:[1,0]
	v_mov_b32_e32 v175, v173
	v_pk_mul_f32 v[188:189], v[94:95], v[132:133] op_sel:[0,1]
	v_pk_mul_f32 v[172:173], v[174:175], s[30:31] op_sel_hi:[1,0]
	v_pk_mul_f32 v[138:139], v[138:139], s[30:31] op_sel_hi:[1,0]
	v_pk_fma_f32 v[186:187], v[92:93], v[128:129], v[176:177] op_sel:[0,0,1] op_sel_hi:[1,0,0] neg_lo:[0,0,1] neg_hi:[0,0,1]
	v_pk_fma_f32 v[176:177], v[92:93], v[128:129], v[176:177] op_sel:[0,0,1] op_sel_hi:[1,0,0]
	v_pk_fma_f32 v[190:191], v[94:95], v[128:129], v[188:189] op_sel:[0,1,1] op_sel_hi:[1,1,0] neg_lo:[0,0,1] neg_hi:[0,0,1]
	v_pk_fma_f32 v[188:189], v[94:95], v[128:129], v[188:189] op_sel:[0,1,1] op_sel_hi:[1,1,0]
	v_cvt_pk_bf16_f32 v138, v138, v139
	v_cvt_pk_bf16_f32 v139, v172, v173
	v_mov_b64_e32 v[172:173], s[0:1]
	v_mov_b32_e32 v191, v189
	v_mov_b32_e32 v187, v177
	v_mad_i64_i32 v[146:147], s[4:5], v146, s28, v[172:173]
	v_pk_mul_f32 v[188:189], v[190:191], s[30:31] op_sel_hi:[1,0]
	v_pk_mul_f32 v[176:177], v[186:187], s[30:31] op_sel_hi:[1,0]
	v_lshl_add_u64 v[146:147], v[146:147], 0, s[20:21]
	v_cvt_pk_bf16_f32 v136, v176, v177
	v_cvt_pk_bf16_f32 v137, v188, v189
	v_lshl_add_u64 v[146:147], v[140:141], 1, v[146:147]
	global_store_dwordx4 v[146:147], v[136:139], off nt
	s_and_saveexec_b64 s[4:5], vcc
	s_cbranch_execz .LBB0_562
	s_lshl_b32 s7, s82, 21
	s_add_i32 s7, s7, 0xff800000
	v_readlane_b32 s8, v252, 56
	v_add_u32_e32 v156, s7, v170
	v_readlane_b32 s9, v252, 57
	s_nop 1
	v_lshl_add_u64 v[172:173], v[156:157], 1, s[8:9]
	global_store_dwordx4 v[172:173], v[136:139], off nt
.LBB0_562:
	s_or_b64 exec, exec, s[4:5]
	s_nop 0
	v_mov_b32_e32 v138, v134
	v_mov_b32_e32 v139, v134
	v_mov_b32_e32 v134, v135
	v_mov_b32_e32 v136, v130
	v_mov_b32_e32 v137, v130
	v_mov_b32_e32 v130, v131
	v_mov_b32_e32 v174, v132
	v_mov_b32_e32 v175, v132
	v_mov_b32_e32 v132, v133
	v_pk_mul_f32 v[138:139], v[80:81], v[138:139]
	v_pk_mul_f32 v[134:135], v[82:83], v[134:135]
	v_mov_b32_e32 v172, v128
	v_mov_b32_e32 v173, v128
	v_mov_b32_e32 v128, v129
	v_pk_fma_f32 v[176:177], v[80:81], v[136:137], v[138:139] op_sel:[0,0,1] op_sel_hi:[1,1,0] neg_lo:[0,0,1] neg_hi:[0,0,1]
	v_pk_fma_f32 v[136:137], v[80:81], v[136:137], v[138:139] op_sel:[0,0,1] op_sel_hi:[1,1,0]
	v_pk_fma_f32 v[138:139], v[82:83], v[130:131], v[134:135] op_sel:[0,0,1] op_sel_hi:[1,1,0] neg_lo:[0,0,1] neg_hi:[0,0,1]
	v_pk_fma_f32 v[130:131], v[82:83], v[130:131], v[134:135] op_sel:[0,0,1] op_sel_hi:[1,1,0]
	v_pk_mul_f32 v[134:135], v[84:85], v[174:175]
	v_pk_mul_f32 v[132:133], v[86:87], v[132:133]
	v_pk_fma_f32 v[174:175], v[84:85], v[172:173], v[134:135] op_sel:[0,0,1] op_sel_hi:[1,1,0] neg_lo:[0,0,1] neg_hi:[0,0,1]
	v_pk_fma_f32 v[134:135], v[84:85], v[172:173], v[134:135] op_sel:[0,0,1] op_sel_hi:[1,1,0]
	v_pk_fma_f32 v[172:173], v[86:87], v[128:129], v[132:133] op_sel:[0,0,1] op_sel_hi:[1,1,0] neg_lo:[0,0,1] neg_hi:[0,0,1]
	v_pk_fma_f32 v[128:129], v[86:87], v[128:129], v[132:133] op_sel:[0,0,1] op_sel_hi:[1,1,0]
	v_mov_b32_e32 v175, v135
	v_mov_b32_e32 v173, v129
	v_mov_b32_e32 v139, v131
	v_mov_b32_e32 v177, v137
	v_pk_mul_f32 v[132:133], v[172:173], s[30:31] op_sel_hi:[1,0]
	v_pk_mul_f32 v[128:129], v[174:175], s[30:31] op_sel_hi:[1,0]
	v_pk_mul_f32 v[134:135], v[138:139], s[30:31] op_sel_hi:[1,0]
	v_pk_mul_f32 v[130:131], v[176:177], s[30:31] op_sel_hi:[1,0]
	v_cvt_pk_bf16_f32 v128, v128, v129
	v_cvt_pk_bf16_f32 v129, v132, v133
	v_cvt_pk_bf16_f32 v130, v130, v131
	v_cvt_pk_bf16_f32 v131, v134, v135
	global_store_dwordx4 v[146:147], v[128:131], off offset:256 nt
	s_and_saveexec_b64 s[4:5], vcc
	s_cbranch_execz .LBB0_564
	s_lshl_b32 s7, s82, 21
	s_add_i32 s7, s7, 0xff900000
	v_readlane_b32 s8, v252, 56
	v_add_u32_e32 v156, s7, v170
	v_readlane_b32 s9, v252, 57
	s_nop 1
	v_lshl_add_u64 v[132:133], v[156:157], 1, s[8:9]
	global_store_dwordx4 v[132:133], v[128:131], off nt
.LBB0_564:
	s_or_b64 exec, exec, s[4:5]
	v_add_u32_e32 v136, 48, v169
	v_add_u32_e32 v146, s6, v136
	v_ashrrev_i32_e32 v147, 31, v146
	v_lshlrev_b64 v[132:133], 8, v[146:147]
	v_lshl_add_u64 v[128:129], s[12:13], 0, v[132:133]
	v_lshl_add_u64 v[132:133], s[14:15], 0, v[132:133]
	v_lshl_add_u64 v[128:129], v[128:129], 0, v[142:143]
	v_lshl_add_u64 v[132:133], v[132:133], 0, v[142:143]
	global_load_dwordx4 v[128:131], v[128:129], off
	v_lshlrev_b32_e32 v137, 7, v146
	global_load_dwordx4 v[132:135], v[132:133], off
	v_and_b32_e32 v137, 0xfffff000, v137
	v_add_u32_e32 v137, v137, v168
	v_lshlrev_b32_e32 v136, 3, v136
	v_and_or_b32 v170, v136, s43, v137
	v_cmp_gt_i32_e32 vcc, s56, v146
	s_waitcnt vmcnt(0)
	v_pk_mul_f32 v[136:137], v[72:73], v[134:135] op_sel_hi:[1,0]
	s_nop 0
	v_pk_fma_f32 v[138:139], v[72:73], v[130:131], v[136:137] op_sel:[0,0,1] op_sel_hi:[1,0,0] neg_lo:[0,0,1] neg_hi:[0,0,1]
	v_pk_fma_f32 v[136:137], v[72:73], v[130:131], v[136:137] op_sel:[0,0,1] op_sel_hi:[1,0,0]
	v_mov_b32_e32 v156, v135
	v_mov_b32_e32 v136, v131
	v_pk_mul_f32 v[172:173], v[74:75], v[156:157] op_sel_hi:[1,0]
	v_mov_b32_e32 v139, v137
	v_pk_fma_f32 v[174:175], v[74:75], v[136:137], v[172:173] op_sel:[0,0,1] op_sel_hi:[1,0,0] neg_lo:[0,0,1] neg_hi:[0,0,1]
	v_pk_fma_f32 v[172:173], v[74:75], v[136:137], v[172:173] op_sel:[0,0,1] op_sel_hi:[1,0,0]
	v_pk_mul_f32 v[176:177], v[76:77], v[132:133] op_sel_hi:[1,0]
	v_mov_b32_e32 v175, v173
	v_pk_mul_f32 v[188:189], v[78:79], v[132:133] op_sel:[0,1]
	v_pk_mul_f32 v[172:173], v[174:175], s[30:31] op_sel_hi:[1,0]
	v_pk_mul_f32 v[138:139], v[138:139], s[30:31] op_sel_hi:[1,0]
	v_pk_fma_f32 v[186:187], v[76:77], v[128:129], v[176:177] op_sel:[0,0,1] op_sel_hi:[1,0,0] neg_lo:[0,0,1] neg_hi:[0,0,1]
	v_pk_fma_f32 v[176:177], v[76:77], v[128:129], v[176:177] op_sel:[0,0,1] op_sel_hi:[1,0,0]
	v_pk_fma_f32 v[190:191], v[78:79], v[128:129], v[188:189] op_sel:[0,1,1] op_sel_hi:[1,1,0] neg_lo:[0,0,1] neg_hi:[0,0,1]
	v_pk_fma_f32 v[188:189], v[78:79], v[128:129], v[188:189] op_sel:[0,1,1] op_sel_hi:[1,1,0]
	v_cvt_pk_bf16_f32 v138, v138, v139
	v_cvt_pk_bf16_f32 v139, v172, v173
	v_mov_b64_e32 v[172:173], s[0:1]
	v_mov_b32_e32 v191, v189
	v_mov_b32_e32 v187, v177
	v_mad_i64_i32 v[146:147], s[4:5], v146, s28, v[172:173]
	v_pk_mul_f32 v[188:189], v[190:191], s[30:31] op_sel_hi:[1,0]
	v_pk_mul_f32 v[176:177], v[186:187], s[30:31] op_sel_hi:[1,0]
	v_lshl_add_u64 v[146:147], v[146:147], 0, s[20:21]
	v_cvt_pk_bf16_f32 v136, v176, v177
	v_cvt_pk_bf16_f32 v137, v188, v189
	v_lshl_add_u64 v[146:147], v[140:141], 1, v[146:147]
	global_store_dwordx4 v[146:147], v[136:139], off nt
	s_and_saveexec_b64 s[4:5], vcc
	s_cbranch_execz .LBB0_566
	s_lshl_b32 s7, s82, 21
	s_add_i32 s7, s7, 0xff800000
	v_readlane_b32 s8, v252, 56
	v_add_u32_e32 v156, s7, v170
	v_readlane_b32 s9, v252, 57
	s_nop 1
	v_lshl_add_u64 v[172:173], v[156:157], 1, s[8:9]
	global_store_dwordx4 v[172:173], v[136:139], off nt
.LBB0_566:
	s_or_b64 exec, exec, s[4:5]
	s_nop 0
	v_mov_b32_e32 v138, v134
	v_mov_b32_e32 v139, v134
	v_mov_b32_e32 v134, v135
	v_mov_b32_e32 v136, v130
	v_mov_b32_e32 v137, v130
	v_mov_b32_e32 v130, v131
	v_mov_b32_e32 v174, v132
	v_mov_b32_e32 v175, v132
	v_mov_b32_e32 v132, v133
	v_pk_mul_f32 v[138:139], v[64:65], v[138:139]
	v_pk_mul_f32 v[134:135], v[66:67], v[134:135]
	v_mov_b32_e32 v172, v128
	v_mov_b32_e32 v173, v128
	v_mov_b32_e32 v128, v129
	v_pk_fma_f32 v[176:177], v[64:65], v[136:137], v[138:139] op_sel:[0,0,1] op_sel_hi:[1,1,0] neg_lo:[0,0,1] neg_hi:[0,0,1]
	v_pk_fma_f32 v[136:137], v[64:65], v[136:137], v[138:139] op_sel:[0,0,1] op_sel_hi:[1,1,0]
	v_pk_fma_f32 v[138:139], v[66:67], v[130:131], v[134:135] op_sel:[0,0,1] op_sel_hi:[1,1,0] neg_lo:[0,0,1] neg_hi:[0,0,1]
	v_pk_fma_f32 v[130:131], v[66:67], v[130:131], v[134:135] op_sel:[0,0,1] op_sel_hi:[1,1,0]
	v_pk_mul_f32 v[134:135], v[68:69], v[174:175]
	v_pk_mul_f32 v[132:133], v[70:71], v[132:133]
	v_pk_fma_f32 v[174:175], v[68:69], v[172:173], v[134:135] op_sel:[0,0,1] op_sel_hi:[1,1,0] neg_lo:[0,0,1] neg_hi:[0,0,1]
	v_pk_fma_f32 v[134:135], v[68:69], v[172:173], v[134:135] op_sel:[0,0,1] op_sel_hi:[1,1,0]
	v_pk_fma_f32 v[172:173], v[70:71], v[128:129], v[132:133] op_sel:[0,0,1] op_sel_hi:[1,1,0] neg_lo:[0,0,1] neg_hi:[0,0,1]
	v_pk_fma_f32 v[128:129], v[70:71], v[128:129], v[132:133] op_sel:[0,0,1] op_sel_hi:[1,1,0]
	v_mov_b32_e32 v175, v135
	v_mov_b32_e32 v173, v129
	v_mov_b32_e32 v139, v131
	v_mov_b32_e32 v177, v137
	v_pk_mul_f32 v[132:133], v[172:173], s[30:31] op_sel_hi:[1,0]
	v_pk_mul_f32 v[128:129], v[174:175], s[30:31] op_sel_hi:[1,0]
	v_pk_mul_f32 v[134:135], v[138:139], s[30:31] op_sel_hi:[1,0]
	v_pk_mul_f32 v[130:131], v[176:177], s[30:31] op_sel_hi:[1,0]
	v_cvt_pk_bf16_f32 v128, v128, v129
	v_cvt_pk_bf16_f32 v129, v132, v133
	v_cvt_pk_bf16_f32 v130, v130, v131
	v_cvt_pk_bf16_f32 v131, v134, v135
	global_store_dwordx4 v[146:147], v[128:131], off offset:256 nt
	s_and_saveexec_b64 s[4:5], vcc
	s_cbranch_execz .LBB0_568
	s_lshl_b32 s7, s82, 21
	s_add_i32 s7, s7, 0xff900000
	v_readlane_b32 s8, v252, 56
	v_add_u32_e32 v156, s7, v170
	v_readlane_b32 s9, v252, 57
	s_nop 1
	v_lshl_add_u64 v[132:133], v[156:157], 1, s[8:9]
	global_store_dwordx4 v[132:133], v[128:131], off nt
.LBB0_568:
	s_or_b64 exec, exec, s[4:5]
	v_add_u32_e32 v146, 0x80, v144
	v_ashrrev_i32_e32 v147, 31, v146
	v_lshlrev_b64 v[132:133], 8, v[146:147]
	v_lshl_add_u64 v[128:129], s[12:13], 0, v[132:133]
	v_lshl_add_u64 v[132:133], s[14:15], 0, v[132:133]
	v_lshl_add_u64 v[128:129], v[128:129], 0, v[142:143]
	v_lshl_add_u64 v[132:133], v[132:133], 0, v[142:143]
	global_load_dwordx4 v[128:131], v[128:129], off
	v_lshlrev_b32_e32 v136, 7, v146
	global_load_dwordx4 v[132:135], v[132:133], off
	v_and_b32_e32 v136, 0xfffff000, v136
	v_add_u32_e32 v136, v136, v168
	v_or_b32_e32 v170, v136, v145
	v_cmp_gt_i32_e32 vcc, s56, v146
	s_waitcnt vmcnt(0)
	v_pk_mul_f32 v[136:137], v[56:57], v[134:135] op_sel_hi:[1,0]
	s_nop 0
	v_pk_fma_f32 v[138:139], v[56:57], v[130:131], v[136:137] op_sel:[0,0,1] op_sel_hi:[1,0,0] neg_lo:[0,0,1] neg_hi:[0,0,1]
	v_pk_fma_f32 v[136:137], v[56:57], v[130:131], v[136:137] op_sel:[0,0,1] op_sel_hi:[1,0,0]
	v_mov_b32_e32 v156, v135
	v_mov_b32_e32 v136, v131
	v_pk_mul_f32 v[172:173], v[58:59], v[156:157] op_sel_hi:[1,0]
	v_mov_b32_e32 v139, v137
	v_pk_fma_f32 v[174:175], v[58:59], v[136:137], v[172:173] op_sel:[0,0,1] op_sel_hi:[1,0,0] neg_lo:[0,0,1] neg_hi:[0,0,1]
	v_pk_fma_f32 v[172:173], v[58:59], v[136:137], v[172:173] op_sel:[0,0,1] op_sel_hi:[1,0,0]
	v_pk_mul_f32 v[176:177], v[60:61], v[132:133] op_sel_hi:[1,0]
	v_mov_b32_e32 v175, v173
	v_pk_mul_f32 v[188:189], v[62:63], v[132:133] op_sel:[0,1]
	v_pk_mul_f32 v[172:173], v[174:175], s[30:31] op_sel_hi:[1,0]
	v_pk_mul_f32 v[138:139], v[138:139], s[30:31] op_sel_hi:[1,0]
	v_pk_fma_f32 v[186:187], v[60:61], v[128:129], v[176:177] op_sel:[0,0,1] op_sel_hi:[1,0,0] neg_lo:[0,0,1] neg_hi:[0,0,1]
	v_pk_fma_f32 v[176:177], v[60:61], v[128:129], v[176:177] op_sel:[0,0,1] op_sel_hi:[1,0,0]
	v_pk_fma_f32 v[190:191], v[62:63], v[128:129], v[188:189] op_sel:[0,1,1] op_sel_hi:[1,1,0] neg_lo:[0,0,1] neg_hi:[0,0,1]
	v_pk_fma_f32 v[188:189], v[62:63], v[128:129], v[188:189] op_sel:[0,1,1] op_sel_hi:[1,1,0]
	v_cvt_pk_bf16_f32 v138, v138, v139
	v_cvt_pk_bf16_f32 v139, v172, v173
	v_mov_b64_e32 v[172:173], s[0:1]
	v_mov_b32_e32 v191, v189
	v_mov_b32_e32 v187, v177
	v_mad_i64_i32 v[146:147], s[4:5], v146, s28, v[172:173]
	v_pk_mul_f32 v[188:189], v[190:191], s[30:31] op_sel_hi:[1,0]
	v_pk_mul_f32 v[176:177], v[186:187], s[30:31] op_sel_hi:[1,0]
	v_lshl_add_u64 v[146:147], v[146:147], 0, s[20:21]
	v_cvt_pk_bf16_f32 v136, v176, v177
	v_cvt_pk_bf16_f32 v137, v188, v189
	v_lshl_add_u64 v[146:147], v[140:141], 1, v[146:147]
	global_store_dwordx4 v[146:147], v[136:139], off nt
	s_and_saveexec_b64 s[4:5], vcc
	s_cbranch_execz .LBB0_570
	s_lshl_b32 s7, s82, 21
	s_add_i32 s7, s7, 0xff800000
	v_readlane_b32 s8, v252, 56
	v_add_u32_e32 v156, s7, v170
	v_readlane_b32 s9, v252, 57
	s_nop 1
	v_lshl_add_u64 v[172:173], v[156:157], 1, s[8:9]
	global_store_dwordx4 v[172:173], v[136:139], off nt
.LBB0_570:
	s_or_b64 exec, exec, s[4:5]
	s_nop 0
	v_mov_b32_e32 v138, v134
	v_mov_b32_e32 v139, v134
	v_mov_b32_e32 v134, v135
	v_mov_b32_e32 v136, v130
	v_mov_b32_e32 v137, v130
	v_mov_b32_e32 v130, v131
	v_mov_b32_e32 v174, v132
	v_mov_b32_e32 v175, v132
	v_mov_b32_e32 v132, v133
	v_pk_mul_f32 v[138:139], v[48:49], v[138:139]
	v_pk_mul_f32 v[134:135], v[50:51], v[134:135]
	v_mov_b32_e32 v172, v128
	v_mov_b32_e32 v173, v128
	v_mov_b32_e32 v128, v129
	v_pk_fma_f32 v[176:177], v[48:49], v[136:137], v[138:139] op_sel:[0,0,1] op_sel_hi:[1,1,0] neg_lo:[0,0,1] neg_hi:[0,0,1]
	v_pk_fma_f32 v[136:137], v[48:49], v[136:137], v[138:139] op_sel:[0,0,1] op_sel_hi:[1,1,0]
	v_pk_fma_f32 v[138:139], v[50:51], v[130:131], v[134:135] op_sel:[0,0,1] op_sel_hi:[1,1,0] neg_lo:[0,0,1] neg_hi:[0,0,1]
	v_pk_fma_f32 v[130:131], v[50:51], v[130:131], v[134:135] op_sel:[0,0,1] op_sel_hi:[1,1,0]
	v_pk_mul_f32 v[134:135], v[52:53], v[174:175]
	v_pk_mul_f32 v[132:133], v[54:55], v[132:133]
	v_pk_fma_f32 v[174:175], v[52:53], v[172:173], v[134:135] op_sel:[0,0,1] op_sel_hi:[1,1,0] neg_lo:[0,0,1] neg_hi:[0,0,1]
	v_pk_fma_f32 v[134:135], v[52:53], v[172:173], v[134:135] op_sel:[0,0,1] op_sel_hi:[1,1,0]
	v_pk_fma_f32 v[172:173], v[54:55], v[128:129], v[132:133] op_sel:[0,0,1] op_sel_hi:[1,1,0] neg_lo:[0,0,1] neg_hi:[0,0,1]
	v_pk_fma_f32 v[128:129], v[54:55], v[128:129], v[132:133] op_sel:[0,0,1] op_sel_hi:[1,1,0]
	v_mov_b32_e32 v175, v135
	v_mov_b32_e32 v173, v129
	v_mov_b32_e32 v139, v131
	v_mov_b32_e32 v177, v137
	v_pk_mul_f32 v[132:133], v[172:173], s[30:31] op_sel_hi:[1,0]
	v_pk_mul_f32 v[128:129], v[174:175], s[30:31] op_sel_hi:[1,0]
	v_pk_mul_f32 v[134:135], v[138:139], s[30:31] op_sel_hi:[1,0]
	v_pk_mul_f32 v[130:131], v[176:177], s[30:31] op_sel_hi:[1,0]
	v_cvt_pk_bf16_f32 v128, v128, v129
	v_cvt_pk_bf16_f32 v129, v132, v133
	v_cvt_pk_bf16_f32 v130, v130, v131
	v_cvt_pk_bf16_f32 v131, v134, v135
	global_store_dwordx4 v[146:147], v[128:131], off offset:256 nt
	s_and_saveexec_b64 s[4:5], vcc
	s_cbranch_execz .LBB0_572
	s_lshl_b32 s7, s82, 21
	s_add_i32 s7, s7, 0xff900000
	v_readlane_b32 s8, v252, 56
	v_add_u32_e32 v156, s7, v170
	v_readlane_b32 s9, v252, 57
	s_nop 1
	v_lshl_add_u64 v[132:133], v[156:157], 1, s[8:9]
	global_store_dwordx4 v[132:133], v[128:131], off nt
.LBB0_572:
	s_or_b64 exec, exec, s[4:5]
	v_add_u32_e32 v136, 0x90, v169
	v_add_u32_e32 v146, s6, v136
	v_ashrrev_i32_e32 v147, 31, v146
	v_lshlrev_b64 v[132:133], 8, v[146:147]
	v_lshl_add_u64 v[128:129], s[12:13], 0, v[132:133]
	v_lshl_add_u64 v[132:133], s[14:15], 0, v[132:133]
	v_lshl_add_u64 v[128:129], v[128:129], 0, v[142:143]
	v_lshl_add_u64 v[132:133], v[132:133], 0, v[142:143]
	global_load_dwordx4 v[128:131], v[128:129], off
	v_lshlrev_b32_e32 v137, 7, v146
	global_load_dwordx4 v[132:135], v[132:133], off
	v_and_b32_e32 v137, 0xfffff000, v137
	v_add_u32_e32 v137, v137, v168
	v_lshlrev_b32_e32 v136, 3, v136
	v_and_or_b32 v170, v136, s43, v137
	v_cmp_gt_i32_e32 vcc, s56, v146
	s_waitcnt vmcnt(0)
	v_pk_mul_f32 v[136:137], v[40:41], v[134:135] op_sel_hi:[1,0]
	s_nop 0
	v_pk_fma_f32 v[138:139], v[40:41], v[130:131], v[136:137] op_sel:[0,0,1] op_sel_hi:[1,0,0] neg_lo:[0,0,1] neg_hi:[0,0,1]
	v_pk_fma_f32 v[136:137], v[40:41], v[130:131], v[136:137] op_sel:[0,0,1] op_sel_hi:[1,0,0]
	v_mov_b32_e32 v156, v135
	v_mov_b32_e32 v136, v131
	v_pk_mul_f32 v[172:173], v[42:43], v[156:157] op_sel_hi:[1,0]
	v_mov_b32_e32 v139, v137
	v_pk_fma_f32 v[174:175], v[42:43], v[136:137], v[172:173] op_sel:[0,0,1] op_sel_hi:[1,0,0] neg_lo:[0,0,1] neg_hi:[0,0,1]
	v_pk_fma_f32 v[172:173], v[42:43], v[136:137], v[172:173] op_sel:[0,0,1] op_sel_hi:[1,0,0]
	v_pk_mul_f32 v[176:177], v[44:45], v[132:133] op_sel_hi:[1,0]
	v_mov_b32_e32 v175, v173
	v_pk_mul_f32 v[188:189], v[46:47], v[132:133] op_sel:[0,1]
	v_pk_mul_f32 v[172:173], v[174:175], s[30:31] op_sel_hi:[1,0]
	v_pk_mul_f32 v[138:139], v[138:139], s[30:31] op_sel_hi:[1,0]
	v_pk_fma_f32 v[186:187], v[44:45], v[128:129], v[176:177] op_sel:[0,0,1] op_sel_hi:[1,0,0] neg_lo:[0,0,1] neg_hi:[0,0,1]
	v_pk_fma_f32 v[176:177], v[44:45], v[128:129], v[176:177] op_sel:[0,0,1] op_sel_hi:[1,0,0]
	v_pk_fma_f32 v[190:191], v[46:47], v[128:129], v[188:189] op_sel:[0,1,1] op_sel_hi:[1,1,0] neg_lo:[0,0,1] neg_hi:[0,0,1]
	v_pk_fma_f32 v[188:189], v[46:47], v[128:129], v[188:189] op_sel:[0,1,1] op_sel_hi:[1,1,0]
	v_cvt_pk_bf16_f32 v138, v138, v139
	v_cvt_pk_bf16_f32 v139, v172, v173
	v_mov_b64_e32 v[172:173], s[0:1]
	v_mov_b32_e32 v191, v189
	v_mov_b32_e32 v187, v177
	v_mad_i64_i32 v[146:147], s[4:5], v146, s28, v[172:173]
	v_pk_mul_f32 v[188:189], v[190:191], s[30:31] op_sel_hi:[1,0]
	v_pk_mul_f32 v[176:177], v[186:187], s[30:31] op_sel_hi:[1,0]
	v_lshl_add_u64 v[146:147], v[146:147], 0, s[20:21]
	v_cvt_pk_bf16_f32 v136, v176, v177
	v_cvt_pk_bf16_f32 v137, v188, v189
	v_lshl_add_u64 v[146:147], v[140:141], 1, v[146:147]
	global_store_dwordx4 v[146:147], v[136:139], off nt
	s_and_saveexec_b64 s[4:5], vcc
	s_cbranch_execz .LBB0_574
	s_lshl_b32 s7, s82, 21
	s_add_i32 s7, s7, 0xff800000
	v_readlane_b32 s8, v252, 56
	v_add_u32_e32 v156, s7, v170
	v_readlane_b32 s9, v252, 57
	s_nop 1
	v_lshl_add_u64 v[172:173], v[156:157], 1, s[8:9]
	global_store_dwordx4 v[172:173], v[136:139], off nt
.LBB0_574:
	s_or_b64 exec, exec, s[4:5]
	s_nop 0
	v_mov_b32_e32 v138, v134
	v_mov_b32_e32 v139, v134
	v_mov_b32_e32 v134, v135
	v_mov_b32_e32 v136, v130
	v_mov_b32_e32 v137, v130
	v_mov_b32_e32 v130, v131
	v_mov_b32_e32 v174, v132
	v_mov_b32_e32 v175, v132
	v_mov_b32_e32 v132, v133
	v_pk_mul_f32 v[138:139], v[32:33], v[138:139]
	v_pk_mul_f32 v[134:135], v[34:35], v[134:135]
	v_mov_b32_e32 v172, v128
	v_mov_b32_e32 v173, v128
	v_mov_b32_e32 v128, v129
	v_pk_fma_f32 v[176:177], v[32:33], v[136:137], v[138:139] op_sel:[0,0,1] op_sel_hi:[1,1,0] neg_lo:[0,0,1] neg_hi:[0,0,1]
	v_pk_fma_f32 v[136:137], v[32:33], v[136:137], v[138:139] op_sel:[0,0,1] op_sel_hi:[1,1,0]
	v_pk_fma_f32 v[138:139], v[34:35], v[130:131], v[134:135] op_sel:[0,0,1] op_sel_hi:[1,1,0] neg_lo:[0,0,1] neg_hi:[0,0,1]
	v_pk_fma_f32 v[130:131], v[34:35], v[130:131], v[134:135] op_sel:[0,0,1] op_sel_hi:[1,1,0]
	v_pk_mul_f32 v[134:135], v[36:37], v[174:175]
	v_pk_mul_f32 v[132:133], v[38:39], v[132:133]
	v_pk_fma_f32 v[174:175], v[36:37], v[172:173], v[134:135] op_sel:[0,0,1] op_sel_hi:[1,1,0] neg_lo:[0,0,1] neg_hi:[0,0,1]
	v_pk_fma_f32 v[134:135], v[36:37], v[172:173], v[134:135] op_sel:[0,0,1] op_sel_hi:[1,1,0]
	v_pk_fma_f32 v[172:173], v[38:39], v[128:129], v[132:133] op_sel:[0,0,1] op_sel_hi:[1,1,0] neg_lo:[0,0,1] neg_hi:[0,0,1]
	v_pk_fma_f32 v[128:129], v[38:39], v[128:129], v[132:133] op_sel:[0,0,1] op_sel_hi:[1,1,0]
	v_mov_b32_e32 v175, v135
	v_mov_b32_e32 v173, v129
	v_mov_b32_e32 v139, v131
	v_mov_b32_e32 v177, v137
	v_pk_mul_f32 v[132:133], v[172:173], s[30:31] op_sel_hi:[1,0]
	v_pk_mul_f32 v[128:129], v[174:175], s[30:31] op_sel_hi:[1,0]
	v_pk_mul_f32 v[134:135], v[138:139], s[30:31] op_sel_hi:[1,0]
	v_pk_mul_f32 v[130:131], v[176:177], s[30:31] op_sel_hi:[1,0]
	v_cvt_pk_bf16_f32 v128, v128, v129
	v_cvt_pk_bf16_f32 v129, v132, v133
	v_cvt_pk_bf16_f32 v130, v130, v131
	v_cvt_pk_bf16_f32 v131, v134, v135
	global_store_dwordx4 v[146:147], v[128:131], off offset:256 nt
	s_and_saveexec_b64 s[4:5], vcc
	s_cbranch_execz .LBB0_576
	s_lshl_b32 s7, s82, 21
	s_add_i32 s7, s7, 0xff900000
	v_readlane_b32 s8, v252, 56
	v_add_u32_e32 v156, s7, v170
	v_readlane_b32 s9, v252, 57
	s_nop 1
	v_lshl_add_u64 v[132:133], v[156:157], 1, s[8:9]
	global_store_dwordx4 v[132:133], v[128:131], off nt
.LBB0_576:
	s_or_b64 exec, exec, s[4:5]
	v_add_u32_e32 v170, 0xa0, v144
	v_ashrrev_i32_e32 v171, 31, v170
	v_lshlrev_b64 v[132:133], 8, v[170:171]
	v_lshl_add_u64 v[128:129], s[12:13], 0, v[132:133]
	v_lshl_add_u64 v[132:133], s[14:15], 0, v[132:133]
	v_lshl_add_u64 v[128:129], v[128:129], 0, v[142:143]
	v_lshl_add_u64 v[132:133], v[132:133], 0, v[142:143]
	global_load_dwordx4 v[128:131], v[128:129], off
	v_lshlrev_b32_e32 v136, 7, v170
	global_load_dwordx4 v[132:135], v[132:133], off
	v_and_b32_e32 v136, 0xfffff000, v136
	v_add_u32_e32 v136, v136, v168
	v_or_b32_e32 v146, v136, v145
	v_cmp_gt_i32_e32 vcc, s56, v170
	s_waitcnt vmcnt(0)
	v_pk_mul_f32 v[136:137], v[24:25], v[134:135] op_sel_hi:[1,0]
	s_nop 0
	v_pk_fma_f32 v[138:139], v[24:25], v[130:131], v[136:137] op_sel:[0,0,1] op_sel_hi:[1,0,0] neg_lo:[0,0,1] neg_hi:[0,0,1]
	v_pk_fma_f32 v[136:137], v[24:25], v[130:131], v[136:137] op_sel:[0,0,1] op_sel_hi:[1,0,0]
	v_mov_b32_e32 v144, v135
	v_mov_b32_e32 v136, v131
	v_pk_mul_f32 v[144:145], v[26:27], v[144:145] op_sel_hi:[1,0]
	v_mov_b32_e32 v139, v137
	v_pk_fma_f32 v[172:173], v[26:27], v[136:137], v[144:145] op_sel:[0,0,1] op_sel_hi:[1,0,0] neg_lo:[0,0,1] neg_hi:[0,0,1]
	v_pk_fma_f32 v[144:145], v[26:27], v[136:137], v[144:145] op_sel:[0,0,1] op_sel_hi:[1,0,0]
	v_pk_mul_f32 v[174:175], v[28:29], v[132:133] op_sel_hi:[1,0]
	v_mov_b32_e32 v173, v145
	v_pk_mul_f32 v[186:187], v[30:31], v[132:133] op_sel:[0,1]
	v_pk_mul_f32 v[144:145], v[172:173], s[30:31] op_sel_hi:[1,0]
	v_pk_mul_f32 v[138:139], v[138:139], s[30:31] op_sel_hi:[1,0]
	v_pk_fma_f32 v[176:177], v[28:29], v[128:129], v[174:175] op_sel:[0,0,1] op_sel_hi:[1,0,0] neg_lo:[0,0,1] neg_hi:[0,0,1]
	v_pk_fma_f32 v[174:175], v[28:29], v[128:129], v[174:175] op_sel:[0,0,1] op_sel_hi:[1,0,0]
	v_pk_fma_f32 v[188:189], v[30:31], v[128:129], v[186:187] op_sel:[0,1,1] op_sel_hi:[1,1,0] neg_lo:[0,0,1] neg_hi:[0,0,1]
	v_pk_fma_f32 v[186:187], v[30:31], v[128:129], v[186:187] op_sel:[0,1,1] op_sel_hi:[1,1,0]
	v_cvt_pk_bf16_f32 v138, v138, v139
	v_cvt_pk_bf16_f32 v139, v144, v145
	v_mov_b64_e32 v[144:145], s[0:1]
	v_mov_b32_e32 v189, v187
	v_mov_b32_e32 v177, v175
	v_mad_i64_i32 v[144:145], s[4:5], v170, s28, v[144:145]
	v_pk_mul_f32 v[186:187], v[188:189], s[30:31] op_sel_hi:[1,0]
	v_pk_mul_f32 v[174:175], v[176:177], s[30:31] op_sel_hi:[1,0]
	v_lshl_add_u64 v[144:145], v[144:145], 0, s[20:21]
	v_cvt_pk_bf16_f32 v136, v174, v175
	v_cvt_pk_bf16_f32 v137, v186, v187
	v_lshl_add_u64 v[144:145], v[140:141], 1, v[144:145]
	global_store_dwordx4 v[144:145], v[136:139], off nt
	s_and_saveexec_b64 s[4:5], vcc
	s_cbranch_execz .LBB0_578
	s_lshl_b32 s7, s82, 21
	s_add_i32 s7, s7, 0xff800000
	v_readlane_b32 s8, v252, 56
	v_add_u32_e32 v156, s7, v146
	v_readlane_b32 s9, v252, 57
	s_nop 1
	v_lshl_add_u64 v[170:171], v[156:157], 1, s[8:9]
	global_store_dwordx4 v[170:171], v[136:139], off nt
.LBB0_578:
	s_or_b64 exec, exec, s[4:5]
	s_nop 0
	v_mov_b32_e32 v138, v134
	v_mov_b32_e32 v139, v134
	v_mov_b32_e32 v134, v135
	v_mov_b32_e32 v136, v130
	v_mov_b32_e32 v137, v130
	v_mov_b32_e32 v130, v131
	v_mov_b32_e32 v172, v132
	v_mov_b32_e32 v173, v132
	v_mov_b32_e32 v132, v133
	v_pk_mul_f32 v[138:139], v[16:17], v[138:139]
	v_pk_mul_f32 v[134:135], v[18:19], v[134:135]
	v_mov_b32_e32 v170, v128
	v_mov_b32_e32 v171, v128
	v_mov_b32_e32 v128, v129
	v_pk_fma_f32 v[174:175], v[16:17], v[136:137], v[138:139] op_sel:[0,0,1] op_sel_hi:[1,1,0] neg_lo:[0,0,1] neg_hi:[0,0,1]
	v_pk_fma_f32 v[136:137], v[16:17], v[136:137], v[138:139] op_sel:[0,0,1] op_sel_hi:[1,1,0]
	v_pk_fma_f32 v[138:139], v[18:19], v[130:131], v[134:135] op_sel:[0,0,1] op_sel_hi:[1,1,0] neg_lo:[0,0,1] neg_hi:[0,0,1]
	v_pk_fma_f32 v[130:131], v[18:19], v[130:131], v[134:135] op_sel:[0,0,1] op_sel_hi:[1,1,0]
	v_pk_mul_f32 v[134:135], v[20:21], v[172:173]
	v_pk_mul_f32 v[132:133], v[22:23], v[132:133]
	v_pk_fma_f32 v[172:173], v[20:21], v[170:171], v[134:135] op_sel:[0,0,1] op_sel_hi:[1,1,0] neg_lo:[0,0,1] neg_hi:[0,0,1]
	v_pk_fma_f32 v[134:135], v[20:21], v[170:171], v[134:135] op_sel:[0,0,1] op_sel_hi:[1,1,0]
	v_pk_fma_f32 v[170:171], v[22:23], v[128:129], v[132:133] op_sel:[0,0,1] op_sel_hi:[1,1,0] neg_lo:[0,0,1] neg_hi:[0,0,1]
	v_pk_fma_f32 v[128:129], v[22:23], v[128:129], v[132:133] op_sel:[0,0,1] op_sel_hi:[1,1,0]
	v_mov_b32_e32 v173, v135
	v_mov_b32_e32 v171, v129
	v_mov_b32_e32 v139, v131
	v_mov_b32_e32 v175, v137
	v_pk_mul_f32 v[132:133], v[170:171], s[30:31] op_sel_hi:[1,0]
	v_pk_mul_f32 v[128:129], v[172:173], s[30:31] op_sel_hi:[1,0]
	v_pk_mul_f32 v[134:135], v[138:139], s[30:31] op_sel_hi:[1,0]
	v_pk_mul_f32 v[130:131], v[174:175], s[30:31] op_sel_hi:[1,0]
	v_cvt_pk_bf16_f32 v128, v128, v129
	v_cvt_pk_bf16_f32 v129, v132, v133
	v_cvt_pk_bf16_f32 v130, v130, v131
	v_cvt_pk_bf16_f32 v131, v134, v135
	global_store_dwordx4 v[144:145], v[128:131], off offset:256 nt
	s_and_saveexec_b64 s[4:5], vcc
	s_cbranch_execz .LBB0_580
	s_lshl_b32 s7, s82, 21
	s_add_i32 s7, s7, 0xff900000
	v_readlane_b32 s8, v252, 56
	v_add_u32_e32 v156, s7, v146
	v_readlane_b32 s9, v252, 57
	s_nop 1
	v_lshl_add_u64 v[132:133], v[156:157], 1, s[8:9]
	global_store_dwordx4 v[132:133], v[128:131], off nt
.LBB0_580:
	s_or_b64 exec, exec, s[4:5]
	v_add_u32_e32 v136, 0xb0, v169
	v_add_u32_e32 v144, s6, v136
	v_ashrrev_i32_e32 v145, 31, v144
	v_lshlrev_b64 v[132:133], 8, v[144:145]
	v_lshl_add_u64 v[128:129], s[12:13], 0, v[132:133]
	v_lshl_add_u64 v[132:133], s[14:15], 0, v[132:133]
	v_lshl_add_u64 v[128:129], v[128:129], 0, v[142:143]
	v_lshl_add_u64 v[132:133], v[132:133], 0, v[142:143]
	global_load_dwordx4 v[128:131], v[128:129], off
	v_lshlrev_b32_e32 v137, 7, v144
	global_load_dwordx4 v[132:135], v[132:133], off
	v_and_b32_e32 v137, 0xfffff000, v137
	v_add_u32_e32 v137, v137, v168
	v_lshlrev_b32_e32 v136, 3, v136
	v_and_or_b32 v142, v136, s43, v137
	v_cmp_gt_i32_e32 vcc, s56, v144
	s_waitcnt vmcnt(0)
	v_pk_mul_f32 v[136:137], v[8:9], v[134:135] op_sel_hi:[1,0]
	s_nop 0
	v_pk_fma_f32 v[138:139], v[8:9], v[130:131], v[136:137] op_sel:[0,0,1] op_sel_hi:[1,0,0] neg_lo:[0,0,1] neg_hi:[0,0,1]
	v_pk_fma_f32 v[136:137], v[8:9], v[130:131], v[136:137] op_sel:[0,0,1] op_sel_hi:[1,0,0]
	v_mov_b32_e32 v146, v135
	v_mov_b32_e32 v136, v131
	v_pk_mul_f32 v[146:147], v[10:11], v[146:147] op_sel_hi:[1,0]
	v_mov_b32_e32 v139, v137
	v_pk_fma_f32 v[168:169], v[10:11], v[136:137], v[146:147] op_sel:[0,0,1] op_sel_hi:[1,0,0] neg_lo:[0,0,1] neg_hi:[0,0,1]
	v_pk_fma_f32 v[146:147], v[10:11], v[136:137], v[146:147] op_sel:[0,0,1] op_sel_hi:[1,0,0]
	v_pk_mul_f32 v[170:171], v[12:13], v[132:133] op_sel_hi:[1,0]
	v_mov_b32_e32 v169, v147
	v_pk_mul_f32 v[174:175], v[14:15], v[132:133] op_sel:[0,1]
	v_pk_mul_f32 v[146:147], v[168:169], s[30:31] op_sel_hi:[1,0]
	v_pk_mul_f32 v[138:139], v[138:139], s[30:31] op_sel_hi:[1,0]
	v_pk_fma_f32 v[172:173], v[12:13], v[128:129], v[170:171] op_sel:[0,0,1] op_sel_hi:[1,0,0] neg_lo:[0,0,1] neg_hi:[0,0,1]
	v_pk_fma_f32 v[170:171], v[12:13], v[128:129], v[170:171] op_sel:[0,0,1] op_sel_hi:[1,0,0]
	v_pk_fma_f32 v[176:177], v[14:15], v[128:129], v[174:175] op_sel:[0,1,1] op_sel_hi:[1,1,0] neg_lo:[0,0,1] neg_hi:[0,0,1]
	v_pk_fma_f32 v[174:175], v[14:15], v[128:129], v[174:175] op_sel:[0,1,1] op_sel_hi:[1,1,0]
	v_cvt_pk_bf16_f32 v138, v138, v139
	v_cvt_pk_bf16_f32 v139, v146, v147
	v_mov_b64_e32 v[146:147], s[0:1]
	v_mov_b32_e32 v177, v175
	v_mov_b32_e32 v173, v171
	v_mad_i64_i32 v[144:145], s[4:5], v144, s28, v[146:147]
	v_pk_mul_f32 v[174:175], v[176:177], s[30:31] op_sel_hi:[1,0]
	v_pk_mul_f32 v[170:171], v[172:173], s[30:31] op_sel_hi:[1,0]
	v_lshl_add_u64 v[144:145], v[144:145], 0, s[20:21]
	v_cvt_pk_bf16_f32 v136, v170, v171
	v_cvt_pk_bf16_f32 v137, v174, v175
	v_lshl_add_u64 v[140:141], v[140:141], 1, v[144:145]
	global_store_dwordx4 v[140:141], v[136:139], off nt
	s_and_saveexec_b64 s[4:5], vcc
	s_cbranch_execz .LBB0_582
	s_lshl_b32 s6, s82, 21
	s_add_i32 s6, s6, 0xff800000
	v_add_u32_e32 v156, s6, v142
	v_readlane_b32 s6, v252, 56
	v_readlane_b32 s7, v252, 57
	s_nop 1
	v_lshl_add_u64 v[144:145], v[156:157], 1, s[6:7]
	global_store_dwordx4 v[144:145], v[136:139], off nt
.LBB0_582:
	s_or_b64 exec, exec, s[4:5]
	s_nop 0
	v_mov_b32_e32 v138, v134
	v_mov_b32_e32 v139, v134
	v_mov_b32_e32 v134, v135
	v_mov_b32_e32 v136, v130
	v_mov_b32_e32 v137, v130
	v_mov_b32_e32 v130, v131
	v_mov_b32_e32 v146, v132
	v_mov_b32_e32 v147, v132
	v_mov_b32_e32 v132, v133
	v_pk_mul_f32 v[138:139], v[0:1], v[138:139]
	v_pk_mul_f32 v[134:135], v[2:3], v[134:135]
	v_mov_b32_e32 v144, v128
	v_mov_b32_e32 v145, v128
	v_mov_b32_e32 v128, v129
	v_pk_fma_f32 v[168:169], v[0:1], v[136:137], v[138:139] op_sel:[0,0,1] op_sel_hi:[1,1,0] neg_lo:[0,0,1] neg_hi:[0,0,1]
	v_pk_fma_f32 v[136:137], v[0:1], v[136:137], v[138:139] op_sel:[0,0,1] op_sel_hi:[1,1,0]
	v_pk_fma_f32 v[138:139], v[2:3], v[130:131], v[134:135] op_sel:[0,0,1] op_sel_hi:[1,1,0] neg_lo:[0,0,1] neg_hi:[0,0,1]
	v_pk_fma_f32 v[130:131], v[2:3], v[130:131], v[134:135] op_sel:[0,0,1] op_sel_hi:[1,1,0]
	v_pk_mul_f32 v[134:135], v[4:5], v[146:147]
	v_pk_mul_f32 v[132:133], v[6:7], v[132:133]
	v_pk_fma_f32 v[146:147], v[4:5], v[144:145], v[134:135] op_sel:[0,0,1] op_sel_hi:[1,1,0] neg_lo:[0,0,1] neg_hi:[0,0,1]
	v_pk_fma_f32 v[134:135], v[4:5], v[144:145], v[134:135] op_sel:[0,0,1] op_sel_hi:[1,1,0]
	v_pk_fma_f32 v[144:145], v[6:7], v[128:129], v[132:133] op_sel:[0,0,1] op_sel_hi:[1,1,0] neg_lo:[0,0,1] neg_hi:[0,0,1]
	v_pk_fma_f32 v[128:129], v[6:7], v[128:129], v[132:133] op_sel:[0,0,1] op_sel_hi:[1,1,0]
	v_mov_b32_e32 v147, v135
	v_mov_b32_e32 v145, v129
	v_mov_b32_e32 v139, v131
	v_mov_b32_e32 v169, v137
	v_pk_mul_f32 v[132:133], v[144:145], s[30:31] op_sel_hi:[1,0]
	v_pk_mul_f32 v[128:129], v[146:147], s[30:31] op_sel_hi:[1,0]
	v_pk_mul_f32 v[134:135], v[138:139], s[30:31] op_sel_hi:[1,0]
	v_pk_mul_f32 v[130:131], v[168:169], s[30:31] op_sel_hi:[1,0]
	v_cvt_pk_bf16_f32 v128, v128, v129
	v_cvt_pk_bf16_f32 v129, v132, v133
	v_cvt_pk_bf16_f32 v130, v130, v131
	v_cvt_pk_bf16_f32 v131, v134, v135
	global_store_dwordx4 v[140:141], v[128:131], off offset:256 nt
	s_and_saveexec_b64 s[4:5], vcc
	s_cbranch_execz .LBB0_584
	s_lshl_b32 s6, s82, 21
	s_add_i32 s6, s6, 0xff900000
	v_add_u32_e32 v156, s6, v142
	v_readlane_b32 s6, v252, 56
	v_readlane_b32 s7, v252, 57
	s_nop 1
	v_lshl_add_u64 v[132:133], v[156:157], 1, s[6:7]
	global_store_dwordx4 v[132:133], v[128:131], off nt

.LBB0_586:
	s_andn2_b64 vcc, exec, s[4:5]
	s_cbranch_vccnz .LBB0_588
	s_lshl_b32 s4, s90, 8
	s_add_i32 s4, s4, s57
	v_lshl_add_u32 v130, v185, 3, s59
	v_add_u32_e32 v128, s4, v184
	v_ashrrev_i32_e32 v132, 1, v130
	v_ashrrev_i32_e32 v129, 31, v128
	v_ashrrev_i32_e32 v133, 31, v132
	v_lshlrev_b64 v[134:135], 8, v[128:129]
	v_lshl_add_u64 v[138:139], s[12:13], 0, v[134:135]
	v_lshlrev_b64 v[136:137], 2, v[132:133]
	v_lshl_add_u64 v[132:133], v[138:139], 0, v[136:137]
	global_load_dwordx4 v[138:141], v[132:133], off
	v_lshl_add_u64 v[132:133], s[14:15], 0, v[134:135]
	v_lshl_add_u64 v[132:133], v[132:133], 0, v[136:137]
	global_load_dwordx4 v[142:145], v[132:133], off
	v_add_u32_e32 v250, v134, v136
	v_add_u32_e32 v251, 0x1000, v250
	global_load_dwordx4 v[190:193], v251, s[12:13]
	global_load_dwordx4 v[194:197], v251, s[14:15]
	v_add_u32_e32 v251, 0x2000, v250
	global_load_dwordx4 v[198:201], v251, s[12:13]
	global_load_dwordx4 v[202:205], v251, s[14:15]
	v_add_u32_e32 v251, 0x3000, v250
	global_load_dwordx4 v[210:213], v251, s[12:13]
	global_load_dwordx4 v[214:217], v251, s[14:15]
	v_add_u32_e32 v251, 0x8000, v250
	global_load_dwordx4 v[218:221], v251, s[12:13]
	global_load_dwordx4 v[222:225], v251, s[14:15]
	v_add_u32_e32 v251, 0x9000, v250
	global_load_dwordx4 v[226:229], v251, s[12:13]
	global_load_dwordx4 v[230:233], v251, s[14:15]
	v_add_u32_e32 v251, 0xa000, v250
	global_load_dwordx4 v[234:237], v251, s[12:13]
	global_load_dwordx4 v[238:241], v251, s[14:15]
	v_add_u32_e32 v251, 0xb000, v250
	global_load_dwordx4 v[242:245], v251, s[12:13]
	global_load_dwordx4 v[246:249], v251, s[14:15]
	v_ashrrev_i32_e32 v131, 31, v130
	s_waitcnt vmcnt(14)
	v_mov_b32_e32 v146, v141
	v_mov_b32_e32 v156, v145
	v_pk_mul_f32 v[132:133], v[120:121], v[144:145] op_sel_hi:[1,0]
	v_pk_mul_f32 v[168:169], v[122:123], v[156:157] op_sel_hi:[1,0]
	v_pk_fma_f32 v[134:135], v[120:121], v[140:141], v[132:133] op_sel:[0,0,1] op_sel_hi:[1,1,0] neg_lo:[0,0,1] neg_hi:[0,0,1]
	v_pk_fma_f32 v[132:133], v[120:121], v[140:141], v[132:133] op_sel:[0,0,1] op_sel_hi:[1,0,0]
	v_pk_fma_f32 v[170:171], v[122:123], v[146:147], v[168:169] op_sel:[0,0,1] op_sel_hi:[1,0,0]
	v_pk_fma_f32 v[172:173], v[122:123], v[146:147], v[168:169] op_sel:[0,0,1] op_sel_hi:[1,0,0] neg_lo:[0,0,1] neg_hi:[0,0,1]
	v_cvt_pk_bf16_f32 v170, v134, v133
	v_mov_b64_e32 v[132:133], s[0:1]
	v_mad_i64_i32 v[134:135], s[4:5], v128, s28, v[132:133]
	s_lshl_b32 s4, s82, 8
	s_ashr_i32 s5, s4, 31
	v_pk_mul_f32 v[168:169], v[124:125], v[142:143] op_sel_hi:[1,0]
	v_pk_mul_f32 v[176:177], v[126:127], v[142:143] op_sel:[0,1]
	s_lshl_b64 s[4:5], s[4:5], 1
	v_pk_fma_f32 v[174:175], v[124:125], v[138:139], v[168:169] op_sel:[0,0,1] op_sel_hi:[1,1,0] neg_lo:[0,0,1] neg_hi:[0,0,1]
	v_pk_fma_f32 v[168:169], v[124:125], v[138:139], v[168:169] op_sel:[0,0,1] op_sel_hi:[1,0,0]
	v_pk_fma_f32 v[186:187], v[126:127], v[138:139], v[176:177] op_sel:[0,1,1] op_sel_hi:[1,1,0] neg_lo:[0,0,1] neg_hi:[0,0,1]
	v_pk_fma_f32 v[176:177], v[126:127], v[138:139], v[176:177] op_sel:[0,1,1] op_sel_hi:[1,1,0]
	v_cvt_pk_bf16_f32 v171, v172, v171
	v_lshl_add_u64 v[172:173], v[134:135], 0, s[4:5]
	v_lshlrev_b64 v[134:135], 1, v[130:131]
	v_cvt_pk_bf16_f32 v168, v174, v169
	v_cvt_pk_bf16_f32 v169, v186, v177
	v_lshl_add_u64 v[130:131], v[172:173], 0, v[134:135]
	v_pk_mul_f32 v[144:145], v[112:113], v[144:145] op_sel_hi:[1,0]
	global_store_dwordx4 v[130:131], v[168:171], off nt
	s_nop 1
	v_pk_fma_f32 v[168:169], v[112:113], v[140:141], v[144:145] op_sel:[0,0,1] op_sel_hi:[1,1,0] neg_lo:[0,0,1] neg_hi:[0,0,1]
	v_pk_fma_f32 v[140:141], v[112:113], v[140:141], v[144:145] op_sel:[0,0,1] op_sel_hi:[1,0,0]
	v_pk_mul_f32 v[144:145], v[114:115], v[156:157] op_sel_hi:[1,0]
	v_cvt_pk_bf16_f32 v140, v168, v141
	v_pk_fma_f32 v[170:171], v[114:115], v[146:147], v[144:145] op_sel:[0,0,1] op_sel_hi:[1,0,0] neg_lo:[0,0,1] neg_hi:[0,0,1]
	v_pk_fma_f32 v[144:145], v[114:115], v[146:147], v[144:145] op_sel:[0,0,1] op_sel_hi:[1,0,0]
	v_pk_mul_f32 v[146:147], v[116:117], v[142:143] op_sel_hi:[1,0]
	v_pk_mul_f32 v[142:143], v[118:119], v[142:143] op_sel:[0,1]
	v_pk_fma_f32 v[172:173], v[116:117], v[138:139], v[146:147] op_sel:[0,0,1] op_sel_hi:[1,1,0] neg_lo:[0,0,1] neg_hi:[0,0,1]
	v_pk_fma_f32 v[146:147], v[116:117], v[138:139], v[146:147] op_sel:[0,0,1] op_sel_hi:[1,0,0]
	v_pk_fma_f32 v[174:175], v[118:119], v[138:139], v[142:143] op_sel:[0,1,1] op_sel_hi:[1,1,0] neg_lo:[0,0,1] neg_hi:[0,0,1]
	v_pk_fma_f32 v[138:139], v[118:119], v[138:139], v[142:143] op_sel:[0,1,1] op_sel_hi:[1,1,0]
	v_cvt_pk_bf16_f32 v141, v170, v145
	v_cvt_pk_bf16_f32 v138, v172, v147
	v_cvt_pk_bf16_f32 v139, v174, v139
	global_store_dwordx4 v[130:131], v[138:141], off offset:256 nt
	v_add_u32_e32 v130, 16, v128
	v_ashrrev_i32_e32 v131, 31, v130
	v_lshlrev_b64 v[142:143], 8, v[130:131]
	v_lshl_add_u64 v[138:139], s[12:13], 0, v[142:143]
	v_lshl_add_u64 v[142:143], s[14:15], 0, v[142:143]
	v_lshl_add_u64 v[138:139], v[138:139], 0, v[136:137]
	v_lshl_add_u64 v[142:143], v[142:143], 0, v[136:137]
	v_mad_i64_i32 v[130:131], s[6:7], v130, s28, v[132:133]
	v_lshl_add_u64 v[130:131], v[130:131], 0, s[4:5]
	v_lshl_add_u64 v[130:131], v[130:131], 0, v[134:135]
	s_waitcnt vmcnt(14)
	v_mov_b32_e32 v138, v190
	v_mov_b32_e32 v139, v191
	v_mov_b32_e32 v140, v192
	v_mov_b32_e32 v141, v193
	v_mov_b32_e32 v142, v194
	v_mov_b32_e32 v143, v195
	v_mov_b32_e32 v144, v196
	v_mov_b32_e32 v145, v197
	v_pk_mul_f32 v[146:147], v[104:105], v[144:145] op_sel_hi:[1,0]
	s_nop 0
	v_pk_fma_f32 v[170:171], v[104:105], v[140:141], v[146:147] op_sel:[0,0,1] op_sel_hi:[1,1,0] neg_lo:[0,0,1] neg_hi:[0,0,1]
	v_pk_fma_f32 v[146:147], v[104:105], v[140:141], v[146:147] op_sel:[0,0,1] op_sel_hi:[1,0,0]
	v_mov_b32_e32 v156, v145
	v_mov_b32_e32 v146, v141
	v_pk_mul_f32 v[168:169], v[106:107], v[156:157] op_sel_hi:[1,0]
	v_pk_mul_f32 v[186:187], v[110:111], v[142:143] op_sel:[0,1]
	v_pk_fma_f32 v[172:173], v[106:107], v[146:147], v[168:169] op_sel:[0,0,1] op_sel_hi:[1,0,0] neg_lo:[0,0,1] neg_hi:[0,0,1]
	v_pk_fma_f32 v[174:175], v[106:107], v[146:147], v[168:169] op_sel:[0,0,1] op_sel_hi:[1,0,0]
	v_pk_mul_f32 v[168:169], v[108:109], v[142:143] op_sel_hi:[1,0]
	v_pk_fma_f32 v[188:189], v[110:111], v[138:139], v[186:187] op_sel:[0,1,1] op_sel_hi:[1,1,0] neg_lo:[0,0,1] neg_hi:[0,0,1]
	v_pk_fma_f32 v[176:177], v[108:109], v[138:139], v[168:169] op_sel:[0,0,1] op_sel_hi:[1,1,0] neg_lo:[0,0,1] neg_hi:[0,0,1]
	v_pk_fma_f32 v[168:169], v[108:109], v[138:139], v[168:169] op_sel:[0,0,1] op_sel_hi:[1,0,0]
	v_pk_fma_f32 v[186:187], v[110:111], v[138:139], v[186:187] op_sel:[0,1,1] op_sel_hi:[1,1,0]
	v_cvt_pk_bf16_f32 v168, v176, v169
	v_cvt_pk_bf16_f32 v169, v188, v187
	v_cvt_pk_bf16_f32 v170, v170, v147
	v_cvt_pk_bf16_f32 v171, v172, v175
	v_pk_mul_f32 v[144:145], v[96:97], v[144:145] op_sel_hi:[1,0]
	global_store_dwordx4 v[130:131], v[168:171], off nt
	s_nop 1
	v_pk_fma_f32 v[168:169], v[96:97], v[140:141], v[144:145] op_sel:[0,0,1] op_sel_hi:[1,1,0] neg_lo:[0,0,1] neg_hi:[0,0,1]
	v_pk_fma_f32 v[140:141], v[96:97], v[140:141], v[144:145] op_sel:[0,0,1] op_sel_hi:[1,0,0]
	v_pk_mul_f32 v[144:145], v[98:99], v[156:157] op_sel_hi:[1,0]
	v_cvt_pk_bf16_f32 v140, v168, v141
	v_pk_fma_f32 v[170:171], v[98:99], v[146:147], v[144:145] op_sel:[0,0,1] op_sel_hi:[1,0,0] neg_lo:[0,0,1] neg_hi:[0,0,1]
	v_pk_fma_f32 v[144:145], v[98:99], v[146:147], v[144:145] op_sel:[0,0,1] op_sel_hi:[1,0,0]
	v_pk_mul_f32 v[146:147], v[100:101], v[142:143] op_sel_hi:[1,0]
	v_pk_mul_f32 v[142:143], v[102:103], v[142:143] op_sel:[0,1]
	v_pk_fma_f32 v[172:173], v[100:101], v[138:139], v[146:147] op_sel:[0,0,1] op_sel_hi:[1,1,0] neg_lo:[0,0,1] neg_hi:[0,0,1]
	v_pk_fma_f32 v[146:147], v[100:101], v[138:139], v[146:147] op_sel:[0,0,1] op_sel_hi:[1,0,0]
	v_pk_fma_f32 v[174:175], v[102:103], v[138:139], v[142:143] op_sel:[0,1,1] op_sel_hi:[1,1,0] neg_lo:[0,0,1] neg_hi:[0,0,1]
	v_pk_fma_f32 v[138:139], v[102:103], v[138:139], v[142:143] op_sel:[0,1,1] op_sel_hi:[1,1,0]
	v_cvt_pk_bf16_f32 v141, v170, v145
	v_cvt_pk_bf16_f32 v138, v172, v147
	v_cvt_pk_bf16_f32 v139, v174, v139
	global_store_dwordx4 v[130:131], v[138:141], off offset:256 nt
	v_add_u32_e32 v130, 32, v128
	v_ashrrev_i32_e32 v131, 31, v130
	v_lshlrev_b64 v[142:143], 8, v[130:131]
	v_lshl_add_u64 v[138:139], s[12:13], 0, v[142:143]
	v_lshl_add_u64 v[142:143], s[14:15], 0, v[142:143]
	v_lshl_add_u64 v[138:139], v[138:139], 0, v[136:137]
	v_lshl_add_u64 v[142:143], v[142:143], 0, v[136:137]
	v_mad_i64_i32 v[130:131], s[6:7], v130, s28, v[132:133]
	v_lshl_add_u64 v[130:131], v[130:131], 0, s[4:5]
	v_lshl_add_u64 v[130:131], v[130:131], 0, v[134:135]
	s_waitcnt vmcnt(14)
	v_mov_b32_e32 v138, v198
	v_mov_b32_e32 v139, v199
	v_mov_b32_e32 v140, v200
	v_mov_b32_e32 v141, v201
	v_mov_b32_e32 v142, v202
	v_mov_b32_e32 v143, v203
	v_mov_b32_e32 v144, v204
	v_mov_b32_e32 v145, v205
	v_pk_mul_f32 v[146:147], v[88:89], v[144:145] op_sel_hi:[1,0]
	s_nop 0
	v_pk_fma_f32 v[170:171], v[88:89], v[140:141], v[146:147] op_sel:[0,0,1] op_sel_hi:[1,1,0] neg_lo:[0,0,1] neg_hi:[0,0,1]
	v_pk_fma_f32 v[146:147], v[88:89], v[140:141], v[146:147] op_sel:[0,0,1] op_sel_hi:[1,0,0]
	v_mov_b32_e32 v156, v145
	v_mov_b32_e32 v146, v141
	v_pk_mul_f32 v[168:169], v[90:91], v[156:157] op_sel_hi:[1,0]
	v_pk_mul_f32 v[186:187], v[94:95], v[142:143] op_sel:[0,1]
	v_pk_fma_f32 v[172:173], v[90:91], v[146:147], v[168:169] op_sel:[0,0,1] op_sel_hi:[1,0,0] neg_lo:[0,0,1] neg_hi:[0,0,1]
	v_pk_fma_f32 v[174:175], v[90:91], v[146:147], v[168:169] op_sel:[0,0,1] op_sel_hi:[1,0,0]
	v_pk_mul_f32 v[168:169], v[92:93], v[142:143] op_sel_hi:[1,0]
	v_pk_fma_f32 v[188:189], v[94:95], v[138:139], v[186:187] op_sel:[0,1,1] op_sel_hi:[1,1,0] neg_lo:[0,0,1] neg_hi:[0,0,1]
	v_pk_fma_f32 v[176:177], v[92:93], v[138:139], v[168:169] op_sel:[0,0,1] op_sel_hi:[1,1,0] neg_lo:[0,0,1] neg_hi:[0,0,1]
	v_pk_fma_f32 v[168:169], v[92:93], v[138:139], v[168:169] op_sel:[0,0,1] op_sel_hi:[1,0,0]
	v_pk_fma_f32 v[186:187], v[94:95], v[138:139], v[186:187] op_sel:[0,1,1] op_sel_hi:[1,1,0]
	v_cvt_pk_bf16_f32 v168, v176, v169
	v_cvt_pk_bf16_f32 v169, v188, v187
	v_cvt_pk_bf16_f32 v170, v170, v147
	v_cvt_pk_bf16_f32 v171, v172, v175
	v_pk_mul_f32 v[144:145], v[80:81], v[144:145] op_sel_hi:[1,0]
	global_store_dwordx4 v[130:131], v[168:171], off nt
	s_nop 1
	v_pk_fma_f32 v[168:169], v[80:81], v[140:141], v[144:145] op_sel:[0,0,1] op_sel_hi:[1,1,0] neg_lo:[0,0,1] neg_hi:[0,0,1]
	v_pk_fma_f32 v[140:141], v[80:81], v[140:141], v[144:145] op_sel:[0,0,1] op_sel_hi:[1,0,0]
	v_pk_mul_f32 v[144:145], v[82:83], v[156:157] op_sel_hi:[1,0]
	v_cvt_pk_bf16_f32 v140, v168, v141
	v_pk_fma_f32 v[170:171], v[82:83], v[146:147], v[144:145] op_sel:[0,0,1] op_sel_hi:[1,0,0] neg_lo:[0,0,1] neg_hi:[0,0,1]
	v_pk_fma_f32 v[144:145], v[82:83], v[146:147], v[144:145] op_sel:[0,0,1] op_sel_hi:[1,0,0]
	v_pk_mul_f32 v[146:147], v[84:85], v[142:143] op_sel_hi:[1,0]
	v_pk_mul_f32 v[142:143], v[86:87], v[142:143] op_sel:[0,1]
	v_pk_fma_f32 v[172:173], v[84:85], v[138:139], v[146:147] op_sel:[0,0,1] op_sel_hi:[1,1,0] neg_lo:[0,0,1] neg_hi:[0,0,1]
	v_pk_fma_f32 v[146:147], v[84:85], v[138:139], v[146:147] op_sel:[0,0,1] op_sel_hi:[1,0,0]
	v_pk_fma_f32 v[174:175], v[86:87], v[138:139], v[142:143] op_sel:[0,1,1] op_sel_hi:[1,1,0] neg_lo:[0,0,1] neg_hi:[0,0,1]
	v_pk_fma_f32 v[138:139], v[86:87], v[138:139], v[142:143] op_sel:[0,1,1] op_sel_hi:[1,1,0]
	v_cvt_pk_bf16_f32 v141, v170, v145
	v_cvt_pk_bf16_f32 v138, v172, v147
	v_cvt_pk_bf16_f32 v139, v174, v139
	global_store_dwordx4 v[130:131], v[138:141], off offset:256 nt
	v_add_u32_e32 v130, 48, v128
	v_ashrrev_i32_e32 v131, 31, v130
	v_lshlrev_b64 v[142:143], 8, v[130:131]
	v_lshl_add_u64 v[138:139], s[12:13], 0, v[142:143]
	v_lshl_add_u64 v[142:143], s[14:15], 0, v[142:143]
	v_lshl_add_u64 v[138:139], v[138:139], 0, v[136:137]
	v_lshl_add_u64 v[142:143], v[142:143], 0, v[136:137]
	v_mad_i64_i32 v[130:131], s[6:7], v130, s28, v[132:133]
	v_lshl_add_u64 v[130:131], v[130:131], 0, s[4:5]
	v_lshl_add_u64 v[130:131], v[130:131], 0, v[134:135]
	s_waitcnt vmcnt(14)
	v_mov_b32_e32 v138, v210
	v_mov_b32_e32 v139, v211
	v_mov_b32_e32 v140, v212
	v_mov_b32_e32 v141, v213
	v_mov_b32_e32 v142, v214
	v_mov_b32_e32 v143, v215
	v_mov_b32_e32 v144, v216
	v_mov_b32_e32 v145, v217
	v_pk_mul_f32 v[146:147], v[72:73], v[144:145] op_sel_hi:[1,0]
	s_nop 0
	v_pk_fma_f32 v[170:171], v[72:73], v[140:141], v[146:147] op_sel:[0,0,1] op_sel_hi:[1,1,0] neg_lo:[0,0,1] neg_hi:[0,0,1]
	v_pk_fma_f32 v[146:147], v[72:73], v[140:141], v[146:147] op_sel:[0,0,1] op_sel_hi:[1,0,0]
	v_mov_b32_e32 v156, v145
	v_mov_b32_e32 v146, v141
	v_pk_mul_f32 v[168:169], v[74:75], v[156:157] op_sel_hi:[1,0]
	v_pk_mul_f32 v[186:187], v[78:79], v[142:143] op_sel:[0,1]
	v_pk_fma_f32 v[172:173], v[74:75], v[146:147], v[168:169] op_sel:[0,0,1] op_sel_hi:[1,0,0] neg_lo:[0,0,1] neg_hi:[0,0,1]
	v_pk_fma_f32 v[174:175], v[74:75], v[146:147], v[168:169] op_sel:[0,0,1] op_sel_hi:[1,0,0]
	v_pk_mul_f32 v[168:169], v[76:77], v[142:143] op_sel_hi:[1,0]
	v_pk_fma_f32 v[188:189], v[78:79], v[138:139], v[186:187] op_sel:[0,1,1] op_sel_hi:[1,1,0] neg_lo:[0,0,1] neg_hi:[0,0,1]
	v_pk_fma_f32 v[176:177], v[76:77], v[138:139], v[168:169] op_sel:[0,0,1] op_sel_hi:[1,1,0] neg_lo:[0,0,1] neg_hi:[0,0,1]
	v_pk_fma_f32 v[168:169], v[76:77], v[138:139], v[168:169] op_sel:[0,0,1] op_sel_hi:[1,0,0]
	v_pk_fma_f32 v[186:187], v[78:79], v[138:139], v[186:187] op_sel:[0,1,1] op_sel_hi:[1,1,0]
	v_cvt_pk_bf16_f32 v168, v176, v169
	v_cvt_pk_bf16_f32 v169, v188, v187
	v_cvt_pk_bf16_f32 v170, v170, v147
	v_cvt_pk_bf16_f32 v171, v172, v175
	v_pk_mul_f32 v[144:145], v[64:65], v[144:145] op_sel_hi:[1,0]
	global_store_dwordx4 v[130:131], v[168:171], off nt
	s_nop 1
	v_pk_fma_f32 v[168:169], v[64:65], v[140:141], v[144:145] op_sel:[0,0,1] op_sel_hi:[1,1,0] neg_lo:[0,0,1] neg_hi:[0,0,1]
	v_pk_fma_f32 v[140:141], v[64:65], v[140:141], v[144:145] op_sel:[0,0,1] op_sel_hi:[1,0,0]
	v_pk_mul_f32 v[144:145], v[66:67], v[156:157] op_sel_hi:[1,0]
	v_cvt_pk_bf16_f32 v140, v168, v141
	v_pk_fma_f32 v[170:171], v[66:67], v[146:147], v[144:145] op_sel:[0,0,1] op_sel_hi:[1,0,0] neg_lo:[0,0,1] neg_hi:[0,0,1]
	v_pk_fma_f32 v[144:145], v[66:67], v[146:147], v[144:145] op_sel:[0,0,1] op_sel_hi:[1,0,0]
	v_pk_mul_f32 v[146:147], v[68:69], v[142:143] op_sel_hi:[1,0]
	v_pk_mul_f32 v[142:143], v[70:71], v[142:143] op_sel:[0,1]
	v_pk_fma_f32 v[172:173], v[68:69], v[138:139], v[146:147] op_sel:[0,0,1] op_sel_hi:[1,1,0] neg_lo:[0,0,1] neg_hi:[0,0,1]
	v_pk_fma_f32 v[146:147], v[68:69], v[138:139], v[146:147] op_sel:[0,0,1] op_sel_hi:[1,0,0]
	v_pk_fma_f32 v[174:175], v[70:71], v[138:139], v[142:143] op_sel:[0,1,1] op_sel_hi:[1,1,0] neg_lo:[0,0,1] neg_hi:[0,0,1]
	v_pk_fma_f32 v[138:139], v[70:71], v[138:139], v[142:143] op_sel:[0,1,1] op_sel_hi:[1,1,0]
	v_cvt_pk_bf16_f32 v141, v170, v145
	v_cvt_pk_bf16_f32 v138, v172, v147
	v_cvt_pk_bf16_f32 v139, v174, v139
	global_store_dwordx4 v[130:131], v[138:141], off offset:256 nt
	v_add_u32_e32 v130, 0x80, v128
	v_ashrrev_i32_e32 v131, 31, v130
	v_lshlrev_b64 v[142:143], 8, v[130:131]
	v_lshl_add_u64 v[138:139], s[12:13], 0, v[142:143]
	v_lshl_add_u64 v[142:143], s[14:15], 0, v[142:143]
	v_lshl_add_u64 v[138:139], v[138:139], 0, v[136:137]
	v_lshl_add_u64 v[142:143], v[142:143], 0, v[136:137]
	v_mad_i64_i32 v[130:131], s[6:7], v130, s28, v[132:133]
	v_lshl_add_u64 v[130:131], v[130:131], 0, s[4:5]
	v_lshl_add_u64 v[130:131], v[130:131], 0, v[134:135]
	s_waitcnt vmcnt(14)
	v_mov_b32_e32 v138, v218
	v_mov_b32_e32 v139, v219
	v_mov_b32_e32 v140, v220
	v_mov_b32_e32 v141, v221
	v_mov_b32_e32 v142, v222
	v_mov_b32_e32 v143, v223
	v_mov_b32_e32 v144, v224
	v_mov_b32_e32 v145, v225
	v_pk_mul_f32 v[146:147], v[56:57], v[144:145] op_sel_hi:[1,0]
	s_nop 0
	v_pk_fma_f32 v[170:171], v[56:57], v[140:141], v[146:147] op_sel:[0,0,1] op_sel_hi:[1,1,0] neg_lo:[0,0,1] neg_hi:[0,0,1]
	v_pk_fma_f32 v[146:147], v[56:57], v[140:141], v[146:147] op_sel:[0,0,1] op_sel_hi:[1,0,0]
	v_mov_b32_e32 v156, v145
	v_mov_b32_e32 v146, v141
	v_pk_mul_f32 v[168:169], v[58:59], v[156:157] op_sel_hi:[1,0]
	v_pk_mul_f32 v[186:187], v[62:63], v[142:143] op_sel:[0,1]
	v_pk_fma_f32 v[172:173], v[58:59], v[146:147], v[168:169] op_sel:[0,0,1] op_sel_hi:[1,0,0] neg_lo:[0,0,1] neg_hi:[0,0,1]
	v_pk_fma_f32 v[174:175], v[58:59], v[146:147], v[168:169] op_sel:[0,0,1] op_sel_hi:[1,0,0]
	v_pk_mul_f32 v[168:169], v[60:61], v[142:143] op_sel_hi:[1,0]
	v_pk_fma_f32 v[188:189], v[62:63], v[138:139], v[186:187] op_sel:[0,1,1] op_sel_hi:[1,1,0] neg_lo:[0,0,1] neg_hi:[0,0,1]
	v_pk_fma_f32 v[176:177], v[60:61], v[138:139], v[168:169] op_sel:[0,0,1] op_sel_hi:[1,1,0] neg_lo:[0,0,1] neg_hi:[0,0,1]
	v_pk_fma_f32 v[168:169], v[60:61], v[138:139], v[168:169] op_sel:[0,0,1] op_sel_hi:[1,0,0]
	v_pk_fma_f32 v[186:187], v[62:63], v[138:139], v[186:187] op_sel:[0,1,1] op_sel_hi:[1,1,0]
	v_cvt_pk_bf16_f32 v168, v176, v169
	v_cvt_pk_bf16_f32 v169, v188, v187
	v_cvt_pk_bf16_f32 v170, v170, v147
	v_cvt_pk_bf16_f32 v171, v172, v175
	v_pk_mul_f32 v[144:145], v[48:49], v[144:145] op_sel_hi:[1,0]
	global_store_dwordx4 v[130:131], v[168:171], off nt
	s_nop 1
	v_pk_fma_f32 v[168:169], v[48:49], v[140:141], v[144:145] op_sel:[0,0,1] op_sel_hi:[1,1,0] neg_lo:[0,0,1] neg_hi:[0,0,1]
	v_pk_fma_f32 v[140:141], v[48:49], v[140:141], v[144:145] op_sel:[0,0,1] op_sel_hi:[1,0,0]
	v_pk_mul_f32 v[144:145], v[50:51], v[156:157] op_sel_hi:[1,0]
	v_cvt_pk_bf16_f32 v140, v168, v141
	v_pk_fma_f32 v[170:171], v[50:51], v[146:147], v[144:145] op_sel:[0,0,1] op_sel_hi:[1,0,0] neg_lo:[0,0,1] neg_hi:[0,0,1]
	v_pk_fma_f32 v[144:145], v[50:51], v[146:147], v[144:145] op_sel:[0,0,1] op_sel_hi:[1,0,0]
	v_pk_mul_f32 v[146:147], v[52:53], v[142:143] op_sel_hi:[1,0]
	v_pk_mul_f32 v[142:143], v[54:55], v[142:143] op_sel:[0,1]
	v_pk_fma_f32 v[172:173], v[52:53], v[138:139], v[146:147] op_sel:[0,0,1] op_sel_hi:[1,1,0] neg_lo:[0,0,1] neg_hi:[0,0,1]
	v_pk_fma_f32 v[146:147], v[52:53], v[138:139], v[146:147] op_sel:[0,0,1] op_sel_hi:[1,0,0]
	v_pk_fma_f32 v[174:175], v[54:55], v[138:139], v[142:143] op_sel:[0,1,1] op_sel_hi:[1,1,0] neg_lo:[0,0,1] neg_hi:[0,0,1]
	v_pk_fma_f32 v[138:139], v[54:55], v[138:139], v[142:143] op_sel:[0,1,1] op_sel_hi:[1,1,0]
	v_cvt_pk_bf16_f32 v141, v170, v145
	v_cvt_pk_bf16_f32 v138, v172, v147
	v_cvt_pk_bf16_f32 v139, v174, v139
	global_store_dwordx4 v[130:131], v[138:141], off offset:256 nt
	v_add_u32_e32 v130, 0x90, v128
	v_ashrrev_i32_e32 v131, 31, v130
	v_lshlrev_b64 v[142:143], 8, v[130:131]
	v_lshl_add_u64 v[138:139], s[12:13], 0, v[142:143]
	v_lshl_add_u64 v[142:143], s[14:15], 0, v[142:143]
	v_lshl_add_u64 v[138:139], v[138:139], 0, v[136:137]
	v_lshl_add_u64 v[142:143], v[142:143], 0, v[136:137]
	v_mad_i64_i32 v[130:131], s[6:7], v130, s28, v[132:133]
	v_lshl_add_u64 v[130:131], v[130:131], 0, s[4:5]
	v_lshl_add_u64 v[130:131], v[130:131], 0, v[134:135]
	s_waitcnt vmcnt(14)
	v_mov_b32_e32 v138, v226
	v_mov_b32_e32 v139, v227
	v_mov_b32_e32 v140, v228
	v_mov_b32_e32 v141, v229
	v_mov_b32_e32 v142, v230
	v_mov_b32_e32 v143, v231
	v_mov_b32_e32 v144, v232
	v_mov_b32_e32 v145, v233
	v_pk_mul_f32 v[146:147], v[40:41], v[144:145] op_sel_hi:[1,0]
	s_nop 0
	v_pk_fma_f32 v[170:171], v[40:41], v[140:141], v[146:147] op_sel:[0,0,1] op_sel_hi:[1,1,0] neg_lo:[0,0,1] neg_hi:[0,0,1]
	v_pk_fma_f32 v[146:147], v[40:41], v[140:141], v[146:147] op_sel:[0,0,1] op_sel_hi:[1,0,0]
	v_mov_b32_e32 v156, v145
	v_mov_b32_e32 v146, v141
	v_pk_mul_f32 v[168:169], v[42:43], v[156:157] op_sel_hi:[1,0]
	v_pk_mul_f32 v[186:187], v[46:47], v[142:143] op_sel:[0,1]
	v_pk_fma_f32 v[172:173], v[42:43], v[146:147], v[168:169] op_sel:[0,0,1] op_sel_hi:[1,0,0] neg_lo:[0,0,1] neg_hi:[0,0,1]
	v_pk_fma_f32 v[174:175], v[42:43], v[146:147], v[168:169] op_sel:[0,0,1] op_sel_hi:[1,0,0]
	v_pk_mul_f32 v[168:169], v[44:45], v[142:143] op_sel_hi:[1,0]
	v_pk_fma_f32 v[188:189], v[46:47], v[138:139], v[186:187] op_sel:[0,1,1] op_sel_hi:[1,1,0] neg_lo:[0,0,1] neg_hi:[0,0,1]
	v_pk_fma_f32 v[176:177], v[44:45], v[138:139], v[168:169] op_sel:[0,0,1] op_sel_hi:[1,1,0] neg_lo:[0,0,1] neg_hi:[0,0,1]
	v_pk_fma_f32 v[168:169], v[44:45], v[138:139], v[168:169] op_sel:[0,0,1] op_sel_hi:[1,0,0]
	v_pk_fma_f32 v[186:187], v[46:47], v[138:139], v[186:187] op_sel:[0,1,1] op_sel_hi:[1,1,0]
	v_cvt_pk_bf16_f32 v168, v176, v169
	v_cvt_pk_bf16_f32 v169, v188, v187
	v_cvt_pk_bf16_f32 v170, v170, v147
	v_cvt_pk_bf16_f32 v171, v172, v175
	v_pk_mul_f32 v[144:145], v[32:33], v[144:145] op_sel_hi:[1,0]
	global_store_dwordx4 v[130:131], v[168:171], off nt
	s_nop 1
	v_pk_fma_f32 v[168:169], v[32:33], v[140:141], v[144:145] op_sel:[0,0,1] op_sel_hi:[1,1,0] neg_lo:[0,0,1] neg_hi:[0,0,1]
	v_pk_fma_f32 v[140:141], v[32:33], v[140:141], v[144:145] op_sel:[0,0,1] op_sel_hi:[1,0,0]
	v_pk_mul_f32 v[144:145], v[34:35], v[156:157] op_sel_hi:[1,0]
	v_cvt_pk_bf16_f32 v140, v168, v141
	v_pk_fma_f32 v[170:171], v[34:35], v[146:147], v[144:145] op_sel:[0,0,1] op_sel_hi:[1,0,0] neg_lo:[0,0,1] neg_hi:[0,0,1]
	v_pk_fma_f32 v[144:145], v[34:35], v[146:147], v[144:145] op_sel:[0,0,1] op_sel_hi:[1,0,0]
	v_pk_mul_f32 v[146:147], v[36:37], v[142:143] op_sel_hi:[1,0]
	v_pk_mul_f32 v[142:143], v[38:39], v[142:143] op_sel:[0,1]
	v_pk_fma_f32 v[172:173], v[36:37], v[138:139], v[146:147] op_sel:[0,0,1] op_sel_hi:[1,1,0] neg_lo:[0,0,1] neg_hi:[0,0,1]
	v_pk_fma_f32 v[146:147], v[36:37], v[138:139], v[146:147] op_sel:[0,0,1] op_sel_hi:[1,0,0]
	v_pk_fma_f32 v[174:175], v[38:39], v[138:139], v[142:143] op_sel:[0,1,1] op_sel_hi:[1,1,0] neg_lo:[0,0,1] neg_hi:[0,0,1]
	v_pk_fma_f32 v[138:139], v[38:39], v[138:139], v[142:143] op_sel:[0,1,1] op_sel_hi:[1,1,0]
	v_cvt_pk_bf16_f32 v141, v170, v145
	v_cvt_pk_bf16_f32 v138, v172, v147
	v_cvt_pk_bf16_f32 v139, v174, v139
	global_store_dwordx4 v[130:131], v[138:141], off offset:256 nt
	v_add_u32_e32 v130, 0xa0, v128
	v_ashrrev_i32_e32 v131, 31, v130
	v_lshlrev_b64 v[142:143], 8, v[130:131]
	v_lshl_add_u64 v[138:139], s[12:13], 0, v[142:143]
	v_lshl_add_u64 v[142:143], s[14:15], 0, v[142:143]
	v_lshl_add_u64 v[138:139], v[138:139], 0, v[136:137]
	v_lshl_add_u64 v[142:143], v[142:143], 0, v[136:137]
	v_mad_i64_i32 v[130:131], s[6:7], v130, s28, v[132:133]
	v_lshl_add_u64 v[130:131], v[130:131], 0, s[4:5]
	v_lshl_add_u64 v[130:131], v[130:131], 0, v[134:135]
	s_waitcnt vmcnt(14)
	v_mov_b32_e32 v138, v234
	v_mov_b32_e32 v139, v235
	v_mov_b32_e32 v140, v236
	v_mov_b32_e32 v141, v237
	v_mov_b32_e32 v142, v238
	v_mov_b32_e32 v143, v239
	v_mov_b32_e32 v144, v240
	v_mov_b32_e32 v145, v241
	v_pk_mul_f32 v[146:147], v[24:25], v[144:145] op_sel_hi:[1,0]
	s_nop 0
	v_pk_fma_f32 v[170:171], v[24:25], v[140:141], v[146:147] op_sel:[0,0,1] op_sel_hi:[1,1,0] neg_lo:[0,0,1] neg_hi:[0,0,1]
	v_pk_fma_f32 v[146:147], v[24:25], v[140:141], v[146:147] op_sel:[0,0,1] op_sel_hi:[1,0,0]
	v_mov_b32_e32 v156, v145
	v_mov_b32_e32 v146, v141
	v_pk_mul_f32 v[168:169], v[26:27], v[156:157] op_sel_hi:[1,0]
	v_pk_mul_f32 v[186:187], v[30:31], v[142:143] op_sel:[0,1]
	v_pk_fma_f32 v[172:173], v[26:27], v[146:147], v[168:169] op_sel:[0,0,1] op_sel_hi:[1,0,0] neg_lo:[0,0,1] neg_hi:[0,0,1]
	v_pk_fma_f32 v[174:175], v[26:27], v[146:147], v[168:169] op_sel:[0,0,1] op_sel_hi:[1,0,0]
	v_pk_mul_f32 v[168:169], v[28:29], v[142:143] op_sel_hi:[1,0]
	v_pk_fma_f32 v[188:189], v[30:31], v[138:139], v[186:187] op_sel:[0,1,1] op_sel_hi:[1,1,0] neg_lo:[0,0,1] neg_hi:[0,0,1]
	v_pk_fma_f32 v[176:177], v[28:29], v[138:139], v[168:169] op_sel:[0,0,1] op_sel_hi:[1,1,0] neg_lo:[0,0,1] neg_hi:[0,0,1]
	v_pk_fma_f32 v[168:169], v[28:29], v[138:139], v[168:169] op_sel:[0,0,1] op_sel_hi:[1,0,0]
	v_pk_fma_f32 v[186:187], v[30:31], v[138:139], v[186:187] op_sel:[0,1,1] op_sel_hi:[1,1,0]
	v_cvt_pk_bf16_f32 v168, v176, v169
	v_cvt_pk_bf16_f32 v169, v188, v187
	v_cvt_pk_bf16_f32 v170, v170, v147
	v_cvt_pk_bf16_f32 v171, v172, v175
	v_pk_mul_f32 v[144:145], v[16:17], v[144:145] op_sel_hi:[1,0]
	global_store_dwordx4 v[130:131], v[168:171], off nt
	s_nop 1
	v_pk_fma_f32 v[168:169], v[16:17], v[140:141], v[144:145] op_sel:[0,0,1] op_sel_hi:[1,1,0] neg_lo:[0,0,1] neg_hi:[0,0,1]
	v_pk_fma_f32 v[140:141], v[16:17], v[140:141], v[144:145] op_sel:[0,0,1] op_sel_hi:[1,0,0]
	v_pk_mul_f32 v[144:145], v[18:19], v[156:157] op_sel_hi:[1,0]
	v_cvt_pk_bf16_f32 v140, v168, v141
	v_pk_fma_f32 v[170:171], v[18:19], v[146:147], v[144:145] op_sel:[0,0,1] op_sel_hi:[1,0,0] neg_lo:[0,0,1] neg_hi:[0,0,1]
	v_pk_fma_f32 v[144:145], v[18:19], v[146:147], v[144:145] op_sel:[0,0,1] op_sel_hi:[1,0,0]
	v_pk_mul_f32 v[146:147], v[20:21], v[142:143] op_sel_hi:[1,0]
	v_pk_mul_f32 v[142:143], v[22:23], v[142:143] op_sel:[0,1]
	v_pk_fma_f32 v[172:173], v[20:21], v[138:139], v[146:147] op_sel:[0,0,1] op_sel_hi:[1,1,0] neg_lo:[0,0,1] neg_hi:[0,0,1]
	v_pk_fma_f32 v[146:147], v[20:21], v[138:139], v[146:147] op_sel:[0,0,1] op_sel_hi:[1,0,0]
	v_pk_fma_f32 v[174:175], v[22:23], v[138:139], v[142:143] op_sel:[0,1,1] op_sel_hi:[1,1,0] neg_lo:[0,0,1] neg_hi:[0,0,1]
	v_pk_fma_f32 v[138:139], v[22:23], v[138:139], v[142:143] op_sel:[0,1,1] op_sel_hi:[1,1,0]
	v_add_u32_e32 v144, 0xb0, v128
	v_cvt_pk_bf16_f32 v138, v172, v147
	v_cvt_pk_bf16_f32 v139, v174, v139
	v_cvt_pk_bf16_f32 v141, v170, v145
	v_ashrrev_i32_e32 v145, 31, v144
	global_store_dwordx4 v[130:131], v[138:141], off offset:256 nt
	v_mad_i64_i32 v[132:133], s[6:7], v144, s28, v[132:133]
	s_nop 0
	v_lshlrev_b64 v[138:139], 8, v[144:145]
	v_lshl_add_u64 v[128:129], s[12:13], 0, v[138:139]
	v_lshl_add_u64 v[138:139], s[14:15], 0, v[138:139]
	v_lshl_add_u64 v[128:129], v[128:129], 0, v[136:137]
	v_lshl_add_u64 v[136:137], v[138:139], 0, v[136:137]
	v_lshl_add_u64 v[132:133], v[132:133], 0, s[4:5]
	v_lshl_add_u64 v[132:133], v[132:133], 0, v[134:135]
	s_waitcnt vmcnt(14)
	v_mov_b32_e32 v128, v242
	v_mov_b32_e32 v129, v243
	v_mov_b32_e32 v130, v244
	v_mov_b32_e32 v131, v245
	v_mov_b32_e32 v136, v246
	v_mov_b32_e32 v137, v247
	v_mov_b32_e32 v138, v248
	v_mov_b32_e32 v139, v249
	v_pk_mul_f32 v[140:141], v[8:9], v[138:139] op_sel_hi:[1,0]
	s_nop 0
	v_pk_fma_f32 v[146:147], v[8:9], v[130:131], v[140:141] op_sel:[0,0,1] op_sel_hi:[1,0,0]
	v_mov_b32_e32 v156, v139
	v_pk_fma_f32 v[142:143], v[8:9], v[130:131], v[140:141] op_sel:[0,0,1] op_sel_hi:[1,1,0] neg_lo:[0,0,1] neg_hi:[0,0,1]
	v_mov_b32_e32 v146, v131
	v_pk_mul_f32 v[140:141], v[10:11], v[156:157] op_sel_hi:[1,0]
	v_pk_mul_f32 v[174:175], v[14:15], v[136:137] op_sel:[0,1]
	v_pk_fma_f32 v[168:169], v[10:11], v[146:147], v[140:141] op_sel:[0,0,1] op_sel_hi:[1,0,0] neg_lo:[0,0,1] neg_hi:[0,0,1]
	v_pk_fma_f32 v[170:171], v[10:11], v[146:147], v[140:141] op_sel:[0,0,1] op_sel_hi:[1,0,0]
	v_pk_mul_f32 v[140:141], v[12:13], v[136:137] op_sel_hi:[1,0]
	v_pk_fma_f32 v[176:177], v[14:15], v[128:129], v[174:175] op_sel:[0,1,1] op_sel_hi:[1,1,0] neg_lo:[0,0,1] neg_hi:[0,0,1]
	v_pk_fma_f32 v[172:173], v[12:13], v[128:129], v[140:141] op_sel:[0,0,1] op_sel_hi:[1,1,0] neg_lo:[0,0,1] neg_hi:[0,0,1]
	v_pk_fma_f32 v[140:141], v[12:13], v[128:129], v[140:141] op_sel:[0,0,1] op_sel_hi:[1,0,0]
	v_pk_fma_f32 v[174:175], v[14:15], v[128:129], v[174:175] op_sel:[0,1,1] op_sel_hi:[1,1,0]
	v_cvt_pk_bf16_f32 v140, v172, v141
	v_cvt_pk_bf16_f32 v141, v176, v175
	v_cvt_pk_bf16_f32 v142, v142, v147
	v_cvt_pk_bf16_f32 v143, v168, v171
	v_pk_mul_f32 v[134:135], v[0:1], v[138:139] op_sel_hi:[1,0]
	global_store_dwordx4 v[132:133], v[140:143], off nt
	v_pk_fma_f32 v[138:139], v[0:1], v[130:131], v[134:135] op_sel:[0,0,1] op_sel_hi:[1,1,0] neg_lo:[0,0,1] neg_hi:[0,0,1]
	v_pk_fma_f32 v[130:131], v[0:1], v[130:131], v[134:135] op_sel:[0,0,1] op_sel_hi:[1,0,0]
	v_pk_mul_f32 v[134:135], v[2:3], v[156:157] op_sel_hi:[1,0]
	v_pk_mul_f32 v[142:143], v[4:5], v[136:137] op_sel_hi:[1,0]
	v_pk_mul_f32 v[136:137], v[6:7], v[136:137] op_sel:[0,1]
	v_pk_fma_f32 v[140:141], v[2:3], v[146:147], v[134:135] op_sel:[0,0,1] op_sel_hi:[1,0,0] neg_lo:[0,0,1] neg_hi:[0,0,1]
	v_pk_fma_f32 v[134:135], v[2:3], v[146:147], v[134:135] op_sel:[0,0,1] op_sel_hi:[1,0,0]
	v_pk_fma_f32 v[144:145], v[4:5], v[128:129], v[142:143] op_sel:[0,0,1] op_sel_hi:[1,1,0] neg_lo:[0,0,1] neg_hi:[0,0,1]
	v_pk_fma_f32 v[142:143], v[4:5], v[128:129], v[142:143] op_sel:[0,0,1] op_sel_hi:[1,0,0]
	v_pk_fma_f32 v[146:147], v[6:7], v[128:129], v[136:137] op_sel:[0,1,1] op_sel_hi:[1,1,0] neg_lo:[0,0,1] neg_hi:[0,0,1]
	v_pk_fma_f32 v[128:129], v[6:7], v[128:129], v[136:137] op_sel:[0,1,1] op_sel_hi:[1,1,0]
	v_cvt_pk_bf16_f32 v130, v138, v131
	v_cvt_pk_bf16_f32 v128, v144, v143
	v_cvt_pk_bf16_f32 v129, v146, v129
	v_cvt_pk_bf16_f32 v131, v140, v135
	global_store_dwordx4 v[132:133], v[128:131], off offset:256 nt

.LBB0_589:
	s_andn2_b64 vcc, exec, s[4:5]
	s_cbranch_vccnz .LBB0_251
	s_sub_i32 s4, s90, 33
	s_lshl_b32 s8, s4, 2
	s_sub_i32 s5, s82, s8
	v_add_u32_e32 v144, s57, v184
	s_lshl_b32 s9, s4, 8
	s_lshl_b32 s5, s5, 8
	v_add_u32_e32 v128, s9, v144
	s_addk_i32 s5, 0xd400
	v_lshl_add_u32 v142, v185, 3, s59
	v_ashrrev_i32_e32 v129, 31, v128
	v_add_u32_e32 v132, s5, v142
	v_lshlrev_b64 v[134:135], 11, v[128:129]
	v_ashrrev_i32_e32 v136, 5, v144
	v_ashrrev_i32_e32 v137, 31, v136
	v_lshl_add_u64 v[138:139], s[22:23], 0, v[134:135]
	v_ashrrev_i32_e32 v133, 31, v132
	v_lshlrev_b32_e32 v130, 5, v185
	v_and_b32_e32 v131, 31, v184
	v_lshl_add_u64 v[140:141], v[132:133], 1, v[138:139]
	v_mov_b64_e32 v[138:139], 0x14c0000
	v_lshlrev_b64 v[136:137], 9, v[136:137]
	v_lshlrev_b32_e32 v146, 2, v142
	v_and_or_b32 v147, v130, 32, v131
	v_cvt_pk_bf16_f32 v128, v124, v125
	v_cvt_pk_bf16_f32 v129, v126, v127
	v_cvt_pk_bf16_f32 v130, v120, v121
	v_cvt_pk_bf16_f32 v131, v122, v123
	v_cmp_gt_i32_e32 vcc, s76, v132
	v_ashrrev_i32_e32 v145, 7, v132
	v_and_or_b32 v139, v146, s77, v136
	v_mov_b64_e32 v[142:143], 0x14c0000
	global_store_dwordx4 v[140:141], v[128:131], off nt
	s_and_saveexec_b64 s[4:5], vcc
	s_cbranch_execz .LBB0_592
	v_add_u32_e32 v142, s8, v145
	v_ashrrev_i32_e32 v143, 31, v142
	v_lshlrev_b64 v[142:143], 16, v[142:143]
	v_or_b32_e32 v136, v139, v147
	v_lshl_add_u64 v[142:143], s[74:75], 0, v[142:143]
	v_lshl_add_u64 v[142:143], v[136:137], 4, v[142:143]
	global_store_dwordx4 v[142:143], v[128:131], off nt
	v_mov_b64_e32 v[142:143], 0x1480000
.LBB0_592:
	s_or_b64 exec, exec, s[4:5]
	v_readlane_b32 s4, v252, 0
	v_lshlrev_b32_e32 v156, 2, v142
	v_readlane_b32 s6, v252, 2
	v_readlane_b32 s7, v252, 3
	v_and_b32_e32 v130, 0x1f8, v132
	v_readlane_b32 s5, v252, 1
	v_lshl_add_u64 v[128:129], s[6:7], 0, v[156:157]
	v_lshl_add_u64 v[128:129], v[128:129], 0, v[134:135]
	v_lshlrev_b32_e32 v156, 2, v130
	v_lshl_add_u64 v[128:129], v[128:129], 0, v[156:157]
	global_store_dwordx4 v[128:129], v[124:127], off nt
	global_store_dwordx4 v[128:129], v[120:123], off offset:16 nt
	s_nop 0
	v_add_u32_e32 v126, 0x80, v132
	v_ashrrev_i32_e32 v124, 7, v126
	v_cvt_pk_bf16_f32 v120, v116, v117
	v_cvt_pk_bf16_f32 v121, v118, v119
	v_cvt_pk_bf16_f32 v122, v112, v113
	v_cvt_pk_bf16_f32 v123, v114, v115
	v_cmp_gt_i32_e64 s[4:5], s76, v126
	v_add_u32_e32 v124, s8, v124
	global_store_dwordx4 v[140:141], v[120:123], off offset:256 nt
	s_and_saveexec_b64 s[6:7], s[4:5]
	s_cbranch_execz .LBB0_594
	v_ashrrev_i32_e32 v125, 31, v124
	v_lshlrev_b64 v[128:129], 16, v[124:125]
	v_or_b32_e32 v136, v139, v147
	v_lshl_add_u64 v[128:129], s[74:75], 0, v[128:129]
	v_lshl_add_u64 v[128:129], v[136:137], 4, v[128:129]
	v_mov_b64_e32 v[138:139], 0x1480000
	global_store_dwordx4 v[128:129], v[120:123], off nt
.LBB0_594:
	s_or_b64 exec, exec, s[6:7]
	v_readlane_b32 s84, v252, 0
	v_lshlrev_b32_e32 v120, 2, v138
	v_mov_b32_e32 v121, v157
	v_readlane_b32 s86, v252, 2
	v_readlane_b32 s87, v252, 3
	v_xor_b32_e32 v130, 16, v147
	v_mov_b64_e32 v[128:129], 0x14c0000
	v_lshl_add_u64 v[120:121], s[86:87], 0, v[120:121]
	v_lshl_add_u64 v[122:123], v[120:121], 0, v[134:135]
	v_and_b32_e32 v120, 0x1f8, v126
	v_lshlrev_b32_e32 v120, 2, v120
	v_mov_b32_e32 v121, v157
	v_lshl_add_u64 v[122:123], v[122:123], 0, v[120:121]
	global_store_dwordx4 v[122:123], v[116:119], off nt
	global_store_dwordx4 v[122:123], v[112:115], off offset:16 nt
	v_readlane_b32 s85, v252, 1
	s_nop 0
	v_add_u32_e32 v114, 16, v144
	v_add_u32_e32 v112, s9, v114
	v_ashrrev_i32_e32 v113, 31, v112
	v_ashrrev_i32_e32 v118, 5, v114
	v_lshlrev_b64 v[116:117], 11, v[112:113]
	v_ashrrev_i32_e32 v119, 31, v118
	v_lshl_add_u64 v[122:123], s[22:23], 0, v[116:117]
	v_lshlrev_b64 v[118:119], 9, v[118:119]
	v_cvt_pk_bf16_f32 v112, v108, v109
	v_cvt_pk_bf16_f32 v113, v110, v111
	v_cvt_pk_bf16_f32 v114, v104, v105
	v_cvt_pk_bf16_f32 v115, v106, v107
	v_lshl_add_u64 v[126:127], v[132:133], 1, v[122:123]
	v_mov_b64_e32 v[122:123], 0x14c0000
	v_and_or_b32 v121, v146, s77, v118
	global_store_dwordx4 v[126:127], v[112:115], off nt
	s_and_saveexec_b64 s[6:7], vcc
	s_cbranch_execz .LBB0_596
	v_add_u32_e32 v128, s8, v145
	v_ashrrev_i32_e32 v129, 31, v128
	v_lshlrev_b64 v[128:129], 16, v[128:129]
	v_or_b32_e32 v118, v121, v130
	v_lshl_add_u64 v[128:129], s[74:75], 0, v[128:129]
	v_lshl_add_u64 v[128:129], v[118:119], 4, v[128:129]
	global_store_dwordx4 v[128:129], v[112:115], off nt
	v_mov_b64_e32 v[128:129], 0x1480000
.LBB0_596:
	s_or_b64 exec, exec, s[6:7]
	v_readlane_b32 s84, v252, 0
	v_lshlrev_b32_e32 v112, 2, v128
	v_mov_b32_e32 v113, v157
	v_readlane_b32 s86, v252, 2
	v_readlane_b32 s87, v252, 3
	v_readlane_b32 s85, v252, 1
	s_nop 0
	v_lshl_add_u64 v[112:113], s[86:87], 0, v[112:113]
	v_lshl_add_u64 v[112:113], v[112:113], 0, v[116:117]
	v_lshl_add_u64 v[112:113], v[112:113], 0, v[156:157]
	global_store_dwordx4 v[112:113], v[108:111], off nt
	global_store_dwordx4 v[112:113], v[104:107], off offset:16 nt
	s_nop 1
	v_cvt_pk_bf16_f32 v104, v100, v101
	v_cvt_pk_bf16_f32 v105, v102, v103
	v_cvt_pk_bf16_f32 v106, v96, v97
	v_cvt_pk_bf16_f32 v107, v98, v99
	global_store_dwordx4 v[126:127], v[104:107], off offset:256 nt
	s_and_saveexec_b64 s[6:7], s[4:5]
	s_cbranch_execz .LBB0_598
	v_ashrrev_i32_e32 v125, 31, v124
	v_lshlrev_b64 v[108:109], 16, v[124:125]
	v_or_b32_e32 v118, v121, v130
	v_lshl_add_u64 v[108:109], s[74:75], 0, v[108:109]
	v_lshl_add_u64 v[108:109], v[118:119], 4, v[108:109]
	v_mov_b64_e32 v[122:123], 0x1480000
	global_store_dwordx4 v[108:109], v[104:107], off nt
.LBB0_598:
	s_or_b64 exec, exec, s[6:7]
	v_readlane_b32 s84, v252, 0
	v_lshlrev_b32_e32 v104, 2, v122
	v_mov_b32_e32 v105, v157
	v_readlane_b32 s86, v252, 2
	v_readlane_b32 s87, v252, 3
	v_mov_b32_e32 v121, v157
	v_and_or_b32 v110, v146, s77, v147
	v_lshl_add_u64 v[104:105], s[86:87], 0, v[104:105]
	v_lshl_add_u64 v[104:105], v[104:105], 0, v[116:117]
	v_lshl_add_u64 v[104:105], v[104:105], 0, v[120:121]
	global_store_dwordx4 v[104:105], v[100:103], off nt
	global_store_dwordx4 v[104:105], v[96:99], off offset:16 nt
	v_mov_b64_e32 v[108:109], 0x14c0000
	v_readlane_b32 s85, v252, 1
	v_add_u32_e32 v98, 32, v144
	v_add_u32_e32 v96, s9, v98
	v_ashrrev_i32_e32 v97, 31, v96
	v_lshlrev_b64 v[100:101], 11, v[96:97]
	v_ashrrev_i32_e32 v102, 5, v98
	v_ashrrev_i32_e32 v103, 31, v102
	v_lshl_add_u64 v[104:105], s[22:23], 0, v[100:101]
	v_cvt_pk_bf16_f32 v96, v92, v93
	v_cvt_pk_bf16_f32 v97, v94, v95
	v_cvt_pk_bf16_f32 v98, v88, v89
	v_cvt_pk_bf16_f32 v99, v90, v91
	v_lshl_add_u64 v[106:107], v[132:133], 1, v[104:105]
	v_mov_b64_e32 v[104:105], 0x14c0000
	v_lshlrev_b64 v[102:103], 13, v[102:103]
	global_store_dwordx4 v[106:107], v[96:99], off nt
	s_and_saveexec_b64 s[6:7], vcc
	s_cbranch_execz .LBB0_600
	v_add_u32_e32 v108, s8, v145
	v_ashrrev_i32_e32 v109, 31, v108
	v_lshlrev_b64 v[108:109], 16, v[108:109]
	v_lshl_add_u64 v[108:109], s[74:75], 0, v[108:109]
	v_lshlrev_b32_e32 v112, 4, v110
	v_mov_b32_e32 v113, v157
	v_lshl_add_u64 v[108:109], v[108:109], 0, v[102:103]
	v_lshl_add_u64 v[108:109], v[108:109], 0, v[112:113]
	global_store_dwordx4 v[108:109], v[96:99], off nt
	v_mov_b64_e32 v[108:109], 0x1480000
.LBB0_600:
	s_or_b64 exec, exec, s[6:7]
	v_readlane_b32 s84, v252, 0
	v_lshlrev_b32_e32 v96, 2, v108
	v_mov_b32_e32 v97, v157
	v_readlane_b32 s86, v252, 2
	v_readlane_b32 s87, v252, 3
	v_readlane_b32 s85, v252, 1
	s_nop 0
	v_lshl_add_u64 v[96:97], s[86:87], 0, v[96:97]
	v_lshl_add_u64 v[96:97], v[96:97], 0, v[100:101]
	v_lshl_add_u64 v[96:97], v[96:97], 0, v[156:157]
	global_store_dwordx4 v[96:97], v[92:95], off nt
	global_store_dwordx4 v[96:97], v[88:91], off offset:16 nt
	s_nop 1
	v_cvt_pk_bf16_f32 v88, v84, v85
	v_cvt_pk_bf16_f32 v89, v86, v87
	v_cvt_pk_bf16_f32 v90, v80, v81
	v_cvt_pk_bf16_f32 v91, v82, v83
	global_store_dwordx4 v[106:107], v[88:91], off offset:256 nt
	s_and_saveexec_b64 s[6:7], s[4:5]
	s_cbranch_execz .LBB0_602
	v_ashrrev_i32_e32 v125, 31, v124
	v_lshlrev_b64 v[92:93], 16, v[124:125]
	v_lshl_add_u64 v[92:93], s[74:75], 0, v[92:93]
	v_lshlrev_b32_e32 v94, 4, v110
	v_mov_b32_e32 v95, v157
	v_lshl_add_u64 v[92:93], v[92:93], 0, v[102:103]
	v_lshl_add_u64 v[92:93], v[92:93], 0, v[94:95]
	v_mov_b64_e32 v[104:105], 0x1480000
	global_store_dwordx4 v[92:93], v[88:91], off nt
.LBB0_602:
	s_or_b64 exec, exec, s[6:7]
	v_readlane_b32 s84, v252, 0
	v_lshlrev_b32_e32 v88, 2, v104
	v_mov_b32_e32 v89, v157
	v_readlane_b32 s86, v252, 2
	v_readlane_b32 s87, v252, 3
	v_mov_b32_e32 v121, v157
	v_mov_b64_e32 v[92:93], 0x14c0000
	v_lshl_add_u64 v[88:89], s[86:87], 0, v[88:89]
	v_lshl_add_u64 v[88:89], v[88:89], 0, v[100:101]
	v_lshl_add_u64 v[88:89], v[88:89], 0, v[120:121]
	global_store_dwordx4 v[88:89], v[84:87], off nt
	global_store_dwordx4 v[88:89], v[80:83], off offset:16 nt
	v_readlane_b32 s85, v252, 1
	s_nop 0
	v_add_u32_e32 v82, 48, v144
	v_add_u32_e32 v80, s9, v82
	v_ashrrev_i32_e32 v81, 31, v80
	v_lshlrev_b64 v[84:85], 11, v[80:81]
	v_ashrrev_i32_e32 v86, 5, v82
	v_ashrrev_i32_e32 v87, 31, v86
	v_lshl_add_u64 v[88:89], s[22:23], 0, v[84:85]
	v_lshl_add_u64 v[90:91], v[132:133], 1, v[88:89]
	v_mov_b64_e32 v[88:89], 0x14c0000
	v_lshlrev_b64 v[86:87], 9, v[86:87]
	v_cvt_pk_bf16_f32 v80, v76, v77
	v_cvt_pk_bf16_f32 v81, v78, v79
	v_cvt_pk_bf16_f32 v82, v72, v73
	v_cvt_pk_bf16_f32 v83, v74, v75
	v_and_or_b32 v89, v146, s77, v86
	global_store_dwordx4 v[90:91], v[80:83], off nt
	s_and_saveexec_b64 s[6:7], vcc
	s_cbranch_execz .LBB0_604
	v_add_u32_e32 v92, s8, v145
	v_ashrrev_i32_e32 v93, 31, v92
	v_lshlrev_b64 v[92:93], 16, v[92:93]
	v_or_b32_e32 v86, v89, v130
	v_lshl_add_u64 v[92:93], s[74:75], 0, v[92:93]
	v_lshl_add_u64 v[92:93], v[86:87], 4, v[92:93]
	global_store_dwordx4 v[92:93], v[80:83], off nt
	v_mov_b64_e32 v[92:93], 0x1480000
.LBB0_604:
	s_or_b64 exec, exec, s[6:7]
	v_readlane_b32 s84, v252, 0
	v_lshlrev_b32_e32 v80, 2, v92
	v_mov_b32_e32 v81, v157
	v_readlane_b32 s86, v252, 2
	v_readlane_b32 s87, v252, 3
	v_readlane_b32 s85, v252, 1
	s_nop 0
	v_lshl_add_u64 v[80:81], s[86:87], 0, v[80:81]
	v_lshl_add_u64 v[80:81], v[80:81], 0, v[84:85]
	v_lshl_add_u64 v[80:81], v[80:81], 0, v[156:157]
	global_store_dwordx4 v[80:81], v[76:79], off nt
	global_store_dwordx4 v[80:81], v[72:75], off offset:16 nt
	s_nop 1
	v_cvt_pk_bf16_f32 v72, v68, v69
	v_cvt_pk_bf16_f32 v73, v70, v71
	v_cvt_pk_bf16_f32 v74, v64, v65
	v_cvt_pk_bf16_f32 v75, v66, v67
	global_store_dwordx4 v[90:91], v[72:75], off offset:256 nt
	s_and_saveexec_b64 s[6:7], s[4:5]
	s_cbranch_execz .LBB0_606
	v_ashrrev_i32_e32 v125, 31, v124
	v_lshlrev_b64 v[76:77], 16, v[124:125]
	v_or_b32_e32 v86, v89, v130
	v_lshl_add_u64 v[76:77], s[74:75], 0, v[76:77]
	v_lshl_add_u64 v[76:77], v[86:87], 4, v[76:77]
	v_mov_b64_e32 v[88:89], 0x1480000
	global_store_dwordx4 v[76:77], v[72:75], off nt
.LBB0_606:
	s_or_b64 exec, exec, s[6:7]
	v_readlane_b32 s84, v252, 0
	v_lshlrev_b32_e32 v72, 2, v88
	v_mov_b32_e32 v73, v157
	v_readlane_b32 s86, v252, 2
	v_readlane_b32 s87, v252, 3
	v_mov_b32_e32 v121, v157
	v_mov_b64_e32 v[76:77], 0x14c0000
	v_lshl_add_u64 v[72:73], s[86:87], 0, v[72:73]
	v_lshl_add_u64 v[72:73], v[72:73], 0, v[84:85]
	v_lshl_add_u64 v[72:73], v[72:73], 0, v[120:121]
	global_store_dwordx4 v[72:73], v[68:71], off nt
	global_store_dwordx4 v[72:73], v[64:67], off offset:16 nt
	v_readlane_b32 s85, v252, 1
	s_nop 0
	v_add_u32_e32 v66, 0x80, v144
	v_add_u32_e32 v64, s9, v66
	v_ashrrev_i32_e32 v65, 31, v64
	v_lshlrev_b64 v[68:69], 11, v[64:65]
	v_ashrrev_i32_e32 v70, 5, v66
	v_ashrrev_i32_e32 v71, 31, v70
	v_lshl_add_u64 v[72:73], s[22:23], 0, v[68:69]
	v_cvt_pk_bf16_f32 v64, v60, v61
	v_cvt_pk_bf16_f32 v65, v62, v63
	v_cvt_pk_bf16_f32 v66, v56, v57
	v_cvt_pk_bf16_f32 v67, v58, v59
	v_lshl_add_u64 v[74:75], v[132:133], 1, v[72:73]
	v_mov_b64_e32 v[72:73], 0x14c0000
	v_lshlrev_b64 v[70:71], 13, v[70:71]
	global_store_dwordx4 v[74:75], v[64:67], off nt
	s_and_saveexec_b64 s[6:7], vcc
	s_cbranch_execz .LBB0_608
	v_add_u32_e32 v76, s8, v145
	v_ashrrev_i32_e32 v77, 31, v76
	v_lshlrev_b64 v[76:77], 16, v[76:77]
	v_lshl_add_u64 v[76:77], s[74:75], 0, v[76:77]
	v_lshlrev_b32_e32 v78, 4, v110
	v_mov_b32_e32 v79, v157
	v_lshl_add_u64 v[76:77], v[76:77], 0, v[70:71]
	v_lshl_add_u64 v[76:77], v[76:77], 0, v[78:79]
	global_store_dwordx4 v[76:77], v[64:67], off nt
	v_mov_b64_e32 v[76:77], 0x1480000
.LBB0_608:
	s_or_b64 exec, exec, s[6:7]
	v_readlane_b32 s84, v252, 0
	v_lshlrev_b32_e32 v64, 2, v76
	v_mov_b32_e32 v65, v157
	v_readlane_b32 s86, v252, 2
	v_readlane_b32 s87, v252, 3
	v_readlane_b32 s85, v252, 1
	s_nop 0
	v_lshl_add_u64 v[64:65], s[86:87], 0, v[64:65]
	v_lshl_add_u64 v[64:65], v[64:65], 0, v[68:69]
	v_lshl_add_u64 v[64:65], v[64:65], 0, v[156:157]
	global_store_dwordx4 v[64:65], v[60:63], off nt
	global_store_dwordx4 v[64:65], v[56:59], off offset:16 nt
	s_nop 1
	v_cvt_pk_bf16_f32 v56, v52, v53
	v_cvt_pk_bf16_f32 v57, v54, v55
	v_cvt_pk_bf16_f32 v58, v48, v49
	v_cvt_pk_bf16_f32 v59, v50, v51
	global_store_dwordx4 v[74:75], v[56:59], off offset:256 nt
	s_and_saveexec_b64 s[6:7], s[4:5]
	s_cbranch_execz .LBB0_610
	v_ashrrev_i32_e32 v125, 31, v124
	v_lshlrev_b64 v[60:61], 16, v[124:125]
	v_lshl_add_u64 v[60:61], s[74:75], 0, v[60:61]
	v_lshlrev_b32_e32 v62, 4, v110
	v_mov_b32_e32 v63, v157
	v_lshl_add_u64 v[60:61], v[60:61], 0, v[70:71]
	v_lshl_add_u64 v[60:61], v[60:61], 0, v[62:63]
	v_mov_b64_e32 v[72:73], 0x1480000
	global_store_dwordx4 v[60:61], v[56:59], off nt
.LBB0_610:
	s_or_b64 exec, exec, s[6:7]
	v_readlane_b32 s84, v252, 0
	v_lshlrev_b32_e32 v56, 2, v72
	v_mov_b32_e32 v57, v157
	v_readlane_b32 s86, v252, 2
	v_readlane_b32 s87, v252, 3
	v_mov_b32_e32 v121, v157
	v_mov_b64_e32 v[60:61], 0x14c0000
	v_lshl_add_u64 v[56:57], s[86:87], 0, v[56:57]
	v_lshl_add_u64 v[56:57], v[56:57], 0, v[68:69]
	v_lshl_add_u64 v[56:57], v[56:57], 0, v[120:121]
	global_store_dwordx4 v[56:57], v[52:55], off nt
	global_store_dwordx4 v[56:57], v[48:51], off offset:16 nt
	v_readlane_b32 s85, v252, 1
	s_nop 0
	v_add_u32_e32 v50, 0x90, v144
	v_add_u32_e32 v48, s9, v50
	v_ashrrev_i32_e32 v49, 31, v48
	v_lshlrev_b64 v[52:53], 11, v[48:49]
	v_ashrrev_i32_e32 v54, 5, v50
	v_ashrrev_i32_e32 v55, 31, v54
	v_lshl_add_u64 v[56:57], s[22:23], 0, v[52:53]
	v_lshl_add_u64 v[58:59], v[132:133], 1, v[56:57]
	v_mov_b64_e32 v[56:57], 0x14c0000
	v_lshlrev_b64 v[54:55], 9, v[54:55]
	v_cvt_pk_bf16_f32 v48, v44, v45
	v_cvt_pk_bf16_f32 v49, v46, v47
	v_cvt_pk_bf16_f32 v50, v40, v41
	v_cvt_pk_bf16_f32 v51, v42, v43
	v_and_or_b32 v57, v146, s77, v54
	global_store_dwordx4 v[58:59], v[48:51], off nt
	s_and_saveexec_b64 s[6:7], vcc
	s_cbranch_execz .LBB0_612
	v_add_u32_e32 v60, s8, v145
	v_ashrrev_i32_e32 v61, 31, v60
	v_lshlrev_b64 v[60:61], 16, v[60:61]
	v_or_b32_e32 v54, v57, v130
	v_lshl_add_u64 v[60:61], s[74:75], 0, v[60:61]
	v_lshl_add_u64 v[60:61], v[54:55], 4, v[60:61]
	global_store_dwordx4 v[60:61], v[48:51], off nt
	v_mov_b64_e32 v[60:61], 0x1480000
.LBB0_612:
	s_or_b64 exec, exec, s[6:7]
	v_readlane_b32 s84, v252, 0
	v_lshlrev_b32_e32 v48, 2, v60
	v_mov_b32_e32 v49, v157
	v_readlane_b32 s86, v252, 2
	v_readlane_b32 s87, v252, 3
	v_readlane_b32 s85, v252, 1
	s_nop 0
	v_lshl_add_u64 v[48:49], s[86:87], 0, v[48:49]
	v_lshl_add_u64 v[48:49], v[48:49], 0, v[52:53]
	v_lshl_add_u64 v[48:49], v[48:49], 0, v[156:157]
	global_store_dwordx4 v[48:49], v[44:47], off nt
	global_store_dwordx4 v[48:49], v[40:43], off offset:16 nt
	s_nop 1
	v_cvt_pk_bf16_f32 v40, v36, v37
	v_cvt_pk_bf16_f32 v41, v38, v39
	v_cvt_pk_bf16_f32 v42, v32, v33
	v_cvt_pk_bf16_f32 v43, v34, v35
	global_store_dwordx4 v[58:59], v[40:43], off offset:256 nt
	s_and_saveexec_b64 s[6:7], s[4:5]
	s_cbranch_execz .LBB0_614
	v_ashrrev_i32_e32 v125, 31, v124
	v_lshlrev_b64 v[44:45], 16, v[124:125]
	v_or_b32_e32 v54, v57, v130
	v_lshl_add_u64 v[44:45], s[74:75], 0, v[44:45]
	v_lshl_add_u64 v[44:45], v[54:55], 4, v[44:45]
	v_mov_b64_e32 v[56:57], 0x1480000
	global_store_dwordx4 v[44:45], v[40:43], off nt
.LBB0_614:
	s_or_b64 exec, exec, s[6:7]
	v_readlane_b32 s84, v252, 0
	v_lshlrev_b32_e32 v40, 2, v56
	v_mov_b32_e32 v41, v157
	v_readlane_b32 s86, v252, 2
	v_readlane_b32 s87, v252, 3
	v_mov_b32_e32 v121, v157
	v_mov_b64_e32 v[44:45], 0x14c0000
	v_lshl_add_u64 v[40:41], s[86:87], 0, v[40:41]
	v_lshl_add_u64 v[40:41], v[40:41], 0, v[52:53]
	v_lshl_add_u64 v[40:41], v[40:41], 0, v[120:121]
	global_store_dwordx4 v[40:41], v[36:39], off nt
	global_store_dwordx4 v[40:41], v[32:35], off offset:16 nt
	v_readlane_b32 s85, v252, 1
	s_nop 0
	v_add_u32_e32 v34, 0xa0, v144
	v_add_u32_e32 v32, s9, v34
	v_ashrrev_i32_e32 v33, 31, v32
	v_lshlrev_b64 v[36:37], 11, v[32:33]
	v_ashrrev_i32_e32 v38, 5, v34
	v_ashrrev_i32_e32 v39, 31, v38
	v_lshl_add_u64 v[40:41], s[22:23], 0, v[36:37]
	v_cvt_pk_bf16_f32 v32, v28, v29
	v_cvt_pk_bf16_f32 v33, v30, v31
	v_cvt_pk_bf16_f32 v34, v24, v25
	v_cvt_pk_bf16_f32 v35, v26, v27
	v_lshl_add_u64 v[42:43], v[132:133], 1, v[40:41]
	v_mov_b64_e32 v[40:41], 0x14c0000
	v_lshlrev_b64 v[38:39], 13, v[38:39]
	global_store_dwordx4 v[42:43], v[32:35], off nt
	s_and_saveexec_b64 s[6:7], vcc
	s_cbranch_execz .LBB0_616
	v_add_u32_e32 v44, s8, v145
	v_ashrrev_i32_e32 v45, 31, v44
	v_lshlrev_b64 v[44:45], 16, v[44:45]
	v_lshl_add_u64 v[44:45], s[74:75], 0, v[44:45]
	v_lshlrev_b32_e32 v46, 4, v110
	v_mov_b32_e32 v47, v157
	v_lshl_add_u64 v[44:45], v[44:45], 0, v[38:39]
	v_lshl_add_u64 v[44:45], v[44:45], 0, v[46:47]
	global_store_dwordx4 v[44:45], v[32:35], off nt
	v_mov_b64_e32 v[44:45], 0x1480000
.LBB0_616:
	s_or_b64 exec, exec, s[6:7]
	v_readlane_b32 s84, v252, 0
	v_lshlrev_b32_e32 v32, 2, v44
	v_mov_b32_e32 v33, v157
	v_readlane_b32 s86, v252, 2
	v_readlane_b32 s87, v252, 3
	v_readlane_b32 s85, v252, 1
	s_nop 0
	v_lshl_add_u64 v[32:33], s[86:87], 0, v[32:33]
	v_lshl_add_u64 v[32:33], v[32:33], 0, v[36:37]
	v_lshl_add_u64 v[32:33], v[32:33], 0, v[156:157]
	global_store_dwordx4 v[32:33], v[28:31], off nt
	global_store_dwordx4 v[32:33], v[24:27], off offset:16 nt
	s_nop 1
	v_cvt_pk_bf16_f32 v24, v20, v21
	v_cvt_pk_bf16_f32 v25, v22, v23
	v_cvt_pk_bf16_f32 v26, v16, v17
	v_cvt_pk_bf16_f32 v27, v18, v19
	global_store_dwordx4 v[42:43], v[24:27], off offset:256 nt
	s_and_saveexec_b64 s[6:7], s[4:5]
	s_cbranch_execz .LBB0_618
	v_ashrrev_i32_e32 v125, 31, v124
	v_lshlrev_b64 v[28:29], 16, v[124:125]
	v_lshl_add_u64 v[28:29], s[74:75], 0, v[28:29]
	v_lshlrev_b32_e32 v30, 4, v110
	v_mov_b32_e32 v31, v157
	v_lshl_add_u64 v[28:29], v[28:29], 0, v[38:39]
	v_lshl_add_u64 v[28:29], v[28:29], 0, v[30:31]
	v_mov_b64_e32 v[40:41], 0x1480000
	global_store_dwordx4 v[28:29], v[24:27], off nt
.LBB0_618:
	s_or_b64 exec, exec, s[6:7]
	v_readlane_b32 s84, v252, 0
	v_lshlrev_b32_e32 v24, 2, v40
	v_mov_b32_e32 v25, v157
	v_readlane_b32 s86, v252, 2
	v_readlane_b32 s87, v252, 3
	v_mov_b32_e32 v121, v157
	v_mov_b64_e32 v[28:29], 0x14c0000
	v_lshl_add_u64 v[24:25], s[86:87], 0, v[24:25]
	v_lshl_add_u64 v[24:25], v[24:25], 0, v[36:37]
	v_lshl_add_u64 v[24:25], v[24:25], 0, v[120:121]
	global_store_dwordx4 v[24:25], v[20:23], off nt
	global_store_dwordx4 v[24:25], v[16:19], off offset:16 nt
	v_readlane_b32 s85, v252, 1
	s_nop 0
	v_add_u32_e32 v18, 0xb0, v144
	v_add_u32_e32 v16, s9, v18
	v_ashrrev_i32_e32 v17, 31, v16
	v_lshlrev_b64 v[20:21], 11, v[16:17]
	v_ashrrev_i32_e32 v22, 5, v18
	v_ashrrev_i32_e32 v23, 31, v22
	v_lshl_add_u64 v[24:25], s[22:23], 0, v[20:21]
	v_lshl_add_u64 v[26:27], v[132:133], 1, v[24:25]
	v_mov_b64_e32 v[24:25], 0x14c0000
	v_lshlrev_b64 v[22:23], 9, v[22:23]
	v_cvt_pk_bf16_f32 v16, v12, v13
	v_cvt_pk_bf16_f32 v17, v14, v15
	v_cvt_pk_bf16_f32 v18, v8, v9
	v_cvt_pk_bf16_f32 v19, v10, v11
	v_and_or_b32 v25, v146, s77, v22
	global_store_dwordx4 v[26:27], v[16:19], off nt
	s_and_saveexec_b64 s[6:7], vcc
	s_cbranch_execz .LBB0_620
	v_add_u32_e32 v28, s8, v145
	v_ashrrev_i32_e32 v29, 31, v28
	v_lshlrev_b64 v[28:29], 16, v[28:29]
	v_or_b32_e32 v22, v25, v130
	v_lshl_add_u64 v[28:29], s[74:75], 0, v[28:29]
	v_lshl_add_u64 v[28:29], v[22:23], 4, v[28:29]
	global_store_dwordx4 v[28:29], v[16:19], off nt
	v_mov_b64_e32 v[28:29], 0x1480000
.LBB0_620:
	s_or_b64 exec, exec, s[6:7]
	v_readlane_b32 s8, v252, 0
	v_lshlrev_b32_e32 v16, 2, v28
	v_mov_b32_e32 v17, v157
	v_readlane_b32 s10, v252, 2
	v_readlane_b32 s11, v252, 3
	v_readlane_b32 s9, v252, 1
	s_nop 0
	v_lshl_add_u64 v[16:17], s[10:11], 0, v[16:17]
	v_lshl_add_u64 v[16:17], v[16:17], 0, v[20:21]
	v_lshl_add_u64 v[16:17], v[16:17], 0, v[156:157]
	global_store_dwordx4 v[16:17], v[12:15], off nt
	global_store_dwordx4 v[16:17], v[8:11], off offset:16 nt
	s_nop 1
	v_cvt_pk_bf16_f32 v8, v4, v5
	v_cvt_pk_bf16_f32 v9, v6, v7
	v_cvt_pk_bf16_f32 v10, v0, v1
	v_cvt_pk_bf16_f32 v11, v2, v3
	global_store_dwordx4 v[26:27], v[8:11], off offset:256 nt
	s_and_saveexec_b64 s[6:7], s[4:5]
	s_cbranch_execz .LBB0_250
	v_ashrrev_i32_e32 v125, 31, v124
	v_lshlrev_b64 v[12:13], 16, v[124:125]
	v_or_b32_e32 v22, v25, v130
	v_lshl_add_u64 v[12:13], s[74:75], 0, v[12:13]
	v_lshl_add_u64 v[12:13], v[22:23], 4, v[12:13]
	v_mov_b64_e32 v[24:25], 0x1480000
	global_store_dwordx4 v[12:13], v[8:11], off nt
	s_branch .LBB0_250

.LBB0_974:
	ds_read_b128 v[150:153], v147
	ds_read_b128 v[154:157], v147 offset:1024
	ds_read_b128 v[158:161], v147 offset:2048
	ds_read_b128 v[162:165], v147 offset:3072
	s_add_u32 s16, s14, 0x100
	s_addc_u32 s17, s15, 0
	s_cmp_eq_u32 s44, 52
	s_cselect_b32 s21, s3, s17
	s_cselect_b32 s20, s2, s16
	s_cselect_b32 s19, s5, s43
	s_cselect_b32 s18, s4, s42
	v_lshl_add_u64 v[198:199], s[14:15], 0, v[136:137]
	s_add_i32 m0, s24, 0xc000
	ds_read_b128 v[166:169], v148
	ds_read_b128 v[170:173], v148 offset:1024
	ds_read_b128 v[174:177], v148 offset:2048
	ds_read_b128 v[178:181], v148 offset:3072
	ds_read_b128 v[182:185], v148 offset:4096
	ds_read_b128 v[186:189], v148 offset:5120
	ds_read_b128 v[190:193], v148 offset:6144
	ds_read_b128 v[194:197], v148 offset:7168
	global_load_lds_dwordx4 v[198:199], off
	v_lshl_add_u64 v[198:199], s[14:15], 0, v[138:139]
	s_add_i32 m0, s24, 0xe000
	s_nop 0
	global_load_lds_dwordx4 v[198:199], off
	s_waitcnt lgkmcnt(8)
	s_barrier
	s_waitcnt lgkmcnt(0)
	s_setprio 1
	s_waitcnt lgkmcnt(0)
	v_mfma_f32_16x16x32_bf16 v[124:127], v[150:153], v[166:169], v[124:127]
	v_mfma_f32_16x16x32_bf16 v[120:123], v[158:161], v[166:169], v[120:123]
	v_mfma_f32_16x16x32_bf16 v[116:119], v[150:153], v[174:177], v[116:119]
	v_mfma_f32_16x16x32_bf16 v[112:115], v[158:161], v[174:177], v[112:115]
	v_mfma_f32_16x16x32_bf16 v[100:103], v[150:153], v[182:185], v[100:103]
	v_mfma_f32_16x16x32_bf16 v[96:99], v[158:161], v[182:185], v[96:99]
	v_mfma_f32_16x16x32_bf16 v[84:87], v[150:153], v[190:193], v[84:87]
	v_mfma_f32_16x16x32_bf16 v[80:83], v[158:161], v[190:193], v[80:83]
	v_mfma_f32_16x16x32_bf16 v[124:127], v[154:157], v[170:173], v[124:127]
	v_mfma_f32_16x16x32_bf16 v[120:123], v[162:165], v[170:173], v[120:123]
	v_mfma_f32_16x16x32_bf16 v[116:119], v[154:157], v[178:181], v[116:119]
	v_mfma_f32_16x16x32_bf16 v[112:115], v[162:165], v[178:181], v[112:115]
	v_mfma_f32_16x16x32_bf16 v[100:103], v[154:157], v[186:189], v[100:103]
	v_mfma_f32_16x16x32_bf16 v[96:99], v[162:165], v[186:189], v[96:99]
	v_mfma_f32_16x16x32_bf16 v[84:87], v[154:157], v[194:197], v[84:87]
	v_mfma_f32_16x16x32_bf16 v[80:83], v[162:165], v[194:197], v[80:83]
	s_setprio 0
	s_barrier
	s_add_i32 s14, s35, s23
	v_lshl_add_u64 v[206:207], s[18:19], 0, v[130:131]
	s_mov_b32 m0, s14
	ds_read_b128 v[198:201], v149
	ds_read_b128 v[202:205], v149 offset:1024
	ds_read_b128 v[210:213], v149 offset:2048
	ds_read_b128 v[214:217], v149 offset:3072
	global_load_lds_dwordx4 v[206:207], off
	v_lshl_add_u64 v[218:219], s[18:19], 0, v[134:135]
	s_add_i32 m0, s14, 0x2000
	s_nop 0
	global_load_lds_dwordx4 v[218:219], off
	s_barrier
	s_waitcnt lgkmcnt(0)
	s_setprio 1
	s_waitcnt lgkmcnt(0)
	v_mfma_f32_16x16x32_bf16 v[108:111], v[198:201], v[166:169], v[108:111]
	v_mfma_f32_16x16x32_bf16 v[104:107], v[210:213], v[166:169], v[104:107]
	v_mfma_f32_16x16x32_bf16 v[92:95], v[198:201], v[174:177], v[92:95]
	v_mfma_f32_16x16x32_bf16 v[88:91], v[210:213], v[174:177], v[88:91]
	v_mfma_f32_16x16x32_bf16 v[76:79], v[198:201], v[182:185], v[76:79]
	v_mfma_f32_16x16x32_bf16 v[72:75], v[210:213], v[182:185], v[72:75]
	v_mfma_f32_16x16x32_bf16 v[68:71], v[198:201], v[190:193], v[68:71]
	v_mfma_f32_16x16x32_bf16 v[64:67], v[210:213], v[190:193], v[64:67]
	v_mfma_f32_16x16x32_bf16 v[108:111], v[202:205], v[170:173], v[108:111]
	v_mfma_f32_16x16x32_bf16 v[104:107], v[214:217], v[170:173], v[104:107]
	v_mfma_f32_16x16x32_bf16 v[92:95], v[202:205], v[178:181], v[92:95]
	v_mfma_f32_16x16x32_bf16 v[88:91], v[214:217], v[178:181], v[88:91]
	v_mfma_f32_16x16x32_bf16 v[76:79], v[202:205], v[186:189], v[76:79]
	v_mfma_f32_16x16x32_bf16 v[72:75], v[214:217], v[186:189], v[72:75]
	v_mfma_f32_16x16x32_bf16 v[68:71], v[202:205], v[194:197], v[68:71]
	v_mfma_f32_16x16x32_bf16 v[64:67], v[214:217], v[194:197], v[64:67]
	s_setprio 0
	s_mov_b32 m0, s24
	v_lshl_add_u64 v[220:221], s[20:21], 0, v[128:129]
	s_barrier
	ds_read_b128 v[166:169], v148 offset:16384
	ds_read_b128 v[170:173], v148 offset:17408
	ds_read_b128 v[174:177], v148 offset:18432
	ds_read_b128 v[178:181], v148 offset:19456
	ds_read_b128 v[182:185], v148 offset:20480
	ds_read_b128 v[186:189], v148 offset:21504
	ds_read_b128 v[190:193], v148 offset:22528
	ds_read_b128 v[194:197], v148 offset:23552
	global_load_lds_dwordx4 v[220:221], off
	v_lshl_add_u64 v[222:223], s[20:21], 0, v[132:133]
	s_mov_b32 m0, s25
	s_nop 0
	global_load_lds_dwordx4 v[222:223], off
	s_barrier
	s_waitcnt lgkmcnt(0)
	s_setprio 1
	s_waitcnt lgkmcnt(0)
	v_mfma_f32_16x16x32_bf16 v[60:63], v[150:153], v[166:169], v[60:63]
	v_mfma_f32_16x16x32_bf16 v[56:59], v[158:161], v[166:169], v[56:59]
	v_mfma_f32_16x16x32_bf16 v[52:55], v[150:153], v[174:177], v[52:55]
	v_mfma_f32_16x16x32_bf16 v[48:51], v[158:161], v[174:177], v[48:51]
	v_mfma_f32_16x16x32_bf16 v[36:39], v[150:153], v[182:185], v[36:39]
	v_mfma_f32_16x16x32_bf16 v[32:35], v[158:161], v[182:185], v[32:35]
	v_mfma_f32_16x16x32_bf16 v[20:23], v[150:153], v[190:193], v[20:23]
	v_mfma_f32_16x16x32_bf16 v[16:19], v[158:161], v[190:193], v[16:19]
	v_mfma_f32_16x16x32_bf16 v[60:63], v[154:157], v[170:173], v[60:63]
	v_mfma_f32_16x16x32_bf16 v[56:59], v[162:165], v[170:173], v[56:59]
	v_mfma_f32_16x16x32_bf16 v[52:55], v[154:157], v[178:181], v[52:55]
	v_mfma_f32_16x16x32_bf16 v[48:51], v[162:165], v[178:181], v[48:51]
	v_mfma_f32_16x16x32_bf16 v[36:39], v[154:157], v[186:189], v[36:39]
	v_mfma_f32_16x16x32_bf16 v[32:35], v[162:165], v[186:189], v[32:35]
	v_mfma_f32_16x16x32_bf16 v[20:23], v[154:157], v[194:197], v[20:23]
	v_mfma_f32_16x16x32_bf16 v[16:19], v[162:165], v[194:197], v[16:19]
	s_setprio 0
	s_barrier
	s_add_u32 s14, s18, 0xe0000
	s_addc_u32 s15, s19, 0
	s_add_i32 s45, s36, s23
	v_lshl_add_u64 v[150:151], s[14:15], 0, v[130:131]
	s_mov_b32 m0, s45
	s_nop 0
	global_load_lds_dwordx4 v[150:151], off
	v_lshl_add_u64 v[150:151], s[14:15], 0, v[134:135]
	s_add_i32 m0, s45, 0x2000
	s_nop 0
	global_load_lds_dwordx4 v[150:151], off
	s_waitcnt vmcnt(6)
	s_barrier
	s_setprio 1
	v_mfma_f32_16x16x32_bf16 v[44:47], v[198:201], v[166:169], v[44:47]
	v_mfma_f32_16x16x32_bf16 v[40:43], v[210:213], v[166:169], v[40:43]
	v_mfma_f32_16x16x32_bf16 v[28:31], v[198:201], v[174:177], v[28:31]
	v_mfma_f32_16x16x32_bf16 v[24:27], v[210:213], v[174:177], v[24:27]
	v_mfma_f32_16x16x32_bf16 v[12:15], v[198:201], v[182:185], v[12:15]
	v_mfma_f32_16x16x32_bf16 v[8:11], v[210:213], v[182:185], v[8:11]
	v_mfma_f32_16x16x32_bf16 v[4:7], v[198:201], v[190:193], v[4:7]
	v_mfma_f32_16x16x32_bf16 v[0:3], v[210:213], v[190:193], v[0:3]
	v_mfma_f32_16x16x32_bf16 v[44:47], v[202:205], v[170:173], v[44:47]
	v_mfma_f32_16x16x32_bf16 v[40:43], v[214:217], v[170:173], v[40:43]
	v_mfma_f32_16x16x32_bf16 v[28:31], v[202:205], v[178:181], v[28:31]
	v_mfma_f32_16x16x32_bf16 v[24:27], v[214:217], v[178:181], v[24:27]
	v_mfma_f32_16x16x32_bf16 v[12:15], v[202:205], v[186:189], v[12:15]
	v_mfma_f32_16x16x32_bf16 v[8:11], v[214:217], v[186:189], v[8:11]
	v_mfma_f32_16x16x32_bf16 v[4:7], v[202:205], v[194:197], v[4:7]
	v_mfma_f32_16x16x32_bf16 v[0:3], v[214:217], v[194:197], v[0:3]
	s_setprio 0
	s_add_i32 s45, 0, 0x18000
	v_add_u32_e32 v162, s45, v146
	s_barrier
	ds_read_b128 v[150:153], v162
	ds_read_b128 v[154:157], v162 offset:1024
	ds_read_b128 v[158:161], v162 offset:2048
	ds_read_b128 v[162:165], v162 offset:3072
	s_add_u32 s14, s20, 0xe0000
	s_addc_u32 s15, s21, 0
	s_mov_b32 m0, s26
	v_lshl_add_u64 v[198:199], s[14:15], 0, v[128:129]
	ds_read_b128 v[166:169], v148 offset:32768
	ds_read_b128 v[170:173], v148 offset:33792
	ds_read_b128 v[174:177], v148 offset:34816
	ds_read_b128 v[178:181], v148 offset:35840
	ds_read_b128 v[182:185], v148 offset:36864
	ds_read_b128 v[186:189], v148 offset:37888
	ds_read_b128 v[190:193], v148 offset:38912
	ds_read_b128 v[194:197], v148 offset:39936
	global_load_lds_dwordx4 v[198:199], off
	v_lshl_add_u64 v[198:199], s[14:15], 0, v[132:133]
	s_mov_b32 m0, s27
	s_nop 0
	global_load_lds_dwordx4 v[198:199], off
	s_waitcnt lgkmcnt(8)
	s_barrier
	s_waitcnt lgkmcnt(0)
	s_setprio 1
	s_waitcnt lgkmcnt(0)
	v_mfma_f32_16x16x32_bf16 v[124:127], v[150:153], v[166:169], v[124:127]
	v_mfma_f32_16x16x32_bf16 v[120:123], v[158:161], v[166:169], v[120:123]
	v_mfma_f32_16x16x32_bf16 v[116:119], v[150:153], v[174:177], v[116:119]
	v_mfma_f32_16x16x32_bf16 v[112:115], v[158:161], v[174:177], v[112:115]
	v_mfma_f32_16x16x32_bf16 v[100:103], v[150:153], v[182:185], v[100:103]
	v_mfma_f32_16x16x32_bf16 v[96:99], v[158:161], v[182:185], v[96:99]
	v_mfma_f32_16x16x32_bf16 v[84:87], v[150:153], v[190:193], v[84:87]
	v_mfma_f32_16x16x32_bf16 v[80:83], v[158:161], v[190:193], v[80:83]
	v_mfma_f32_16x16x32_bf16 v[124:127], v[154:157], v[170:173], v[124:127]
	v_mfma_f32_16x16x32_bf16 v[120:123], v[162:165], v[170:173], v[120:123]
	v_mfma_f32_16x16x32_bf16 v[116:119], v[154:157], v[178:181], v[116:119]
	v_mfma_f32_16x16x32_bf16 v[112:115], v[162:165], v[178:181], v[112:115]
	v_mfma_f32_16x16x32_bf16 v[100:103], v[154:157], v[186:189], v[100:103]
	v_mfma_f32_16x16x32_bf16 v[96:99], v[162:165], v[186:189], v[96:99]
	v_mfma_f32_16x16x32_bf16 v[84:87], v[154:157], v[194:197], v[84:87]
	v_mfma_f32_16x16x32_bf16 v[80:83], v[162:165], v[194:197], v[80:83]
	s_setprio 0
	s_barrier
	s_add_i32 s20, 0, 0x1c000
	s_add_i32 s14, s45, s23
	v_add_u32_e32 v214, s20, v146
	v_lshl_add_u64 v[206:207], v[206:207], 0, s[8:9]
	s_mov_b32 m0, s14
	ds_read_b128 v[198:201], v214
	ds_read_b128 v[202:205], v214 offset:1024
	ds_read_b128 v[210:213], v214 offset:2048
	ds_read_b128 v[214:217], v214 offset:3072
	global_load_lds_dwordx4 v[206:207], off
	v_lshl_add_u64 v[206:207], v[218:219], 0, s[8:9]
	s_add_i32 m0, s14, 0x2000
	s_nop 0
	global_load_lds_dwordx4 v[206:207], off
	s_barrier
	s_waitcnt lgkmcnt(0)
	s_setprio 1
	s_waitcnt lgkmcnt(0)
	v_mfma_f32_16x16x32_bf16 v[108:111], v[198:201], v[166:169], v[108:111]
	v_mfma_f32_16x16x32_bf16 v[104:107], v[210:213], v[166:169], v[104:107]
	v_mfma_f32_16x16x32_bf16 v[92:95], v[198:201], v[174:177], v[92:95]
	v_mfma_f32_16x16x32_bf16 v[88:91], v[210:213], v[174:177], v[88:91]
	v_mfma_f32_16x16x32_bf16 v[76:79], v[198:201], v[182:185], v[76:79]
	v_mfma_f32_16x16x32_bf16 v[72:75], v[210:213], v[182:185], v[72:75]
	v_mfma_f32_16x16x32_bf16 v[68:71], v[198:201], v[190:193], v[68:71]
	v_mfma_f32_16x16x32_bf16 v[64:67], v[210:213], v[190:193], v[64:67]
	v_mfma_f32_16x16x32_bf16 v[108:111], v[202:205], v[170:173], v[108:111]
	v_mfma_f32_16x16x32_bf16 v[104:107], v[214:217], v[170:173], v[104:107]
	v_mfma_f32_16x16x32_bf16 v[92:95], v[202:205], v[178:181], v[92:95]
	v_mfma_f32_16x16x32_bf16 v[88:91], v[214:217], v[178:181], v[88:91]
	v_mfma_f32_16x16x32_bf16 v[76:79], v[202:205], v[186:189], v[76:79]
	v_mfma_f32_16x16x32_bf16 v[72:75], v[214:217], v[186:189], v[72:75]
	v_mfma_f32_16x16x32_bf16 v[68:71], v[202:205], v[194:197], v[68:71]
	v_mfma_f32_16x16x32_bf16 v[64:67], v[214:217], v[194:197], v[64:67]
	s_setprio 0
	s_mov_b32 m0, s31
	v_lshl_add_u64 v[206:207], v[220:221], 0, s[8:9]
	s_barrier
	ds_read_b128 v[166:169], v148 offset:49152
	ds_read_b128 v[170:173], v148 offset:50176
	ds_read_b128 v[174:177], v148 offset:51200
	ds_read_b128 v[178:181], v148 offset:52224
	ds_read_b128 v[182:185], v148 offset:53248
	ds_read_b128 v[186:189], v148 offset:54272
	ds_read_b128 v[190:193], v148 offset:55296
	ds_read_b128 v[194:197], v148 offset:56320
	global_load_lds_dwordx4 v[206:207], off
	v_lshl_add_u64 v[206:207], v[222:223], 0, s[8:9]
	s_mov_b32 m0, s33
	s_nop 0
	global_load_lds_dwordx4 v[206:207], off
	s_barrier
	s_waitcnt lgkmcnt(0)
	s_setprio 1
	s_waitcnt lgkmcnt(0)
	v_mfma_f32_16x16x32_bf16 v[60:63], v[150:153], v[166:169], v[60:63]
	v_mfma_f32_16x16x32_bf16 v[56:59], v[158:161], v[166:169], v[56:59]
	v_mfma_f32_16x16x32_bf16 v[52:55], v[150:153], v[174:177], v[52:55]
	v_mfma_f32_16x16x32_bf16 v[48:51], v[158:161], v[174:177], v[48:51]
	v_mfma_f32_16x16x32_bf16 v[36:39], v[150:153], v[182:185], v[36:39]
	v_mfma_f32_16x16x32_bf16 v[32:35], v[158:161], v[182:185], v[32:35]
	v_mfma_f32_16x16x32_bf16 v[20:23], v[150:153], v[190:193], v[20:23]
	v_mfma_f32_16x16x32_bf16 v[16:19], v[158:161], v[190:193], v[16:19]
	v_mfma_f32_16x16x32_bf16 v[60:63], v[154:157], v[170:173], v[60:63]
	v_mfma_f32_16x16x32_bf16 v[56:59], v[162:165], v[170:173], v[56:59]
	v_mfma_f32_16x16x32_bf16 v[52:55], v[154:157], v[178:181], v[52:55]
	v_mfma_f32_16x16x32_bf16 v[48:51], v[162:165], v[178:181], v[48:51]
	v_mfma_f32_16x16x32_bf16 v[36:39], v[154:157], v[186:189], v[36:39]
	v_mfma_f32_16x16x32_bf16 v[32:35], v[162:165], v[186:189], v[32:35]
	v_mfma_f32_16x16x32_bf16 v[20:23], v[154:157], v[194:197], v[20:23]
	v_mfma_f32_16x16x32_bf16 v[16:19], v[162:165], v[194:197], v[16:19]
	s_setprio 0
	s_barrier
	s_add_u32 s14, s18, 0xe0080
	s_addc_u32 s15, s19, 0
	s_add_i32 s18, s20, s23
	v_lshl_add_u64 v[150:151], s[14:15], 0, v[130:131]
	s_mov_b32 m0, s18
	s_nop 0
	global_load_lds_dwordx4 v[150:151], off
	v_lshl_add_u64 v[150:151], s[14:15], 0, v[134:135]
	s_add_i32 m0, s18, 0x2000
	s_nop 0
	global_load_lds_dwordx4 v[150:151], off
	s_waitcnt vmcnt(6)
	s_barrier
	s_setprio 1
	v_mfma_f32_16x16x32_bf16 v[44:47], v[198:201], v[166:169], v[44:47]
	v_mfma_f32_16x16x32_bf16 v[40:43], v[210:213], v[166:169], v[40:43]
	v_mfma_f32_16x16x32_bf16 v[28:31], v[198:201], v[174:177], v[28:31]
	v_mfma_f32_16x16x32_bf16 v[24:27], v[210:213], v[174:177], v[24:27]
	v_mfma_f32_16x16x32_bf16 v[12:15], v[198:201], v[182:185], v[12:15]
	v_mfma_f32_16x16x32_bf16 v[8:11], v[210:213], v[182:185], v[8:11]
	v_mfma_f32_16x16x32_bf16 v[4:7], v[198:201], v[190:193], v[4:7]
	v_mfma_f32_16x16x32_bf16 v[0:3], v[210:213], v[190:193], v[0:3]
	v_mfma_f32_16x16x32_bf16 v[44:47], v[202:205], v[170:173], v[44:47]
	v_mfma_f32_16x16x32_bf16 v[40:43], v[214:217], v[170:173], v[40:43]
	v_mfma_f32_16x16x32_bf16 v[28:31], v[202:205], v[178:181], v[28:31]
	v_mfma_f32_16x16x32_bf16 v[24:27], v[214:217], v[178:181], v[24:27]
	v_mfma_f32_16x16x32_bf16 v[12:15], v[202:205], v[186:189], v[12:15]
	v_mfma_f32_16x16x32_bf16 v[8:11], v[214:217], v[186:189], v[8:11]
	v_mfma_f32_16x16x32_bf16 v[4:7], v[202:205], v[194:197], v[4:7]
	v_mfma_f32_16x16x32_bf16 v[0:3], v[214:217], v[194:197], v[0:3]
	s_setprio 0
	s_add_i32 s44, s44, 2
	s_add_u32 s42, s42, 0x100
	s_addc_u32 s43, s43, 0
	s_cmp_gt_u32 s44, 53
	s_mov_b64 s[14:15], s[16:17]
	s_barrier
	s_cbranch_scc0 .LBB0_974
	v_mov_b32_e32 v150, v145
	v_mov_b32_e32 v151, v144
	s_lshl_b32 s14, s34, 8
	s_add_i32 s14, s14, s29
	v_add_u32_e32 v150, s14, v150
	s_lshl_b32 s14, s41, 8
	s_or_b32 s14, s14, s30
	v_lshl_add_u32 v152, v151, 3, s14
	v_ashrrev_i32_e32 v151, 31, v150
	v_lshlrev_b64 v[150:151], 12, v[150:151]
	v_ashrrev_i32_e32 v153, 31, v152
	v_lshl_add_u64 v[150:151], s[10:11], 0, v[150:151]
	v_lshl_add_u64 v[150:151], v[152:153], 1, v[150:151]
	v_cvt_pk_bf16_f32 v108, v108, v109
	v_cvt_pk_bf16_f32 v109, v110, v111
	v_cvt_pk_bf16_f32 v110, v104, v105
	v_cvt_pk_bf16_f32 v111, v106, v107
	s_mov_b64 s[14:15], 0x10000
	global_store_dwordx4 v[150:151], v[108:111], off offset:256 nt
	v_cvt_pk_bf16_f32 v92, v92, v93
	v_cvt_pk_bf16_f32 v93, v94, v95
	v_lshl_add_u64 v[108:109], v[150:151], 0, s[14:15]
	s_mov_b32 s14, 0x10000
	v_add_co_u32_e32 v110, vcc, s14, v150
	v_cvt_pk_bf16_f32 v94, v88, v89
	v_cvt_pk_bf16_f32 v95, v90, v91
	s_mov_b64 s[14:15], 0x20000
	v_addc_co_u32_e32 v111, vcc, 0, v151, vcc
	global_store_dwordx4 v[108:109], v[92:95], off offset:256 nt
	v_cvt_pk_bf16_f32 v76, v76, v77
	v_cvt_pk_bf16_f32 v77, v78, v79
	v_lshl_add_u64 v[92:93], v[150:151], 0, s[14:15]
	s_mov_b32 s14, 0x20000
	v_add_co_u32_e32 v94, vcc, s14, v150
	v_cvt_pk_bf16_f32 v78, v72, v73
	v_cvt_pk_bf16_f32 v79, v74, v75
	s_mov_b64 s[14:15], 0x30000
	v_addc_co_u32_e32 v95, vcc, 0, v151, vcc
	global_store_dwordx4 v[92:93], v[76:79], off offset:256 nt
	v_cvt_pk_bf16_f32 v68, v68, v69
	v_cvt_pk_bf16_f32 v69, v70, v71
	v_lshl_add_u64 v[76:77], v[150:151], 0, s[14:15]
	s_mov_b32 s14, 0x30000
	v_add_co_u32_e32 v78, vcc, s14, v150
	s_mov_b64 s[14:15], 0x80000
	s_nop 0
	v_addc_co_u32_e32 v79, vcc, 0, v151, vcc
	v_cvt_pk_bf16_f32 v70, v64, v65
	v_lshl_add_u64 v[64:65], v[150:151], 0, s[14:15]
	s_mov_b32 s14, 0x80000
	v_cvt_pk_bf16_f32 v60, v60, v61
	v_cvt_pk_bf16_f32 v61, v62, v63
	v_cvt_pk_bf16_f32 v62, v56, v57
	v_add_co_u32_e32 v56, vcc, s14, v150
	v_cvt_pk_bf16_f32 v44, v44, v45
	v_cvt_pk_bf16_f32 v45, v46, v47
	v_cvt_pk_bf16_f32 v46, v40, v41
	v_cvt_pk_bf16_f32 v47, v42, v43
	s_mov_b64 s[14:15], 0x90000
	v_addc_co_u32_e32 v57, vcc, 0, v151, vcc
	global_store_dwordx4 v[64:65], v[44:47], off offset:256 nt
	v_cvt_pk_bf16_f32 v28, v28, v29
	v_cvt_pk_bf16_f32 v29, v30, v31
	v_lshl_add_u64 v[44:45], v[150:151], 0, s[14:15]
	s_mov_b32 s14, 0x90000
	v_add_co_u32_e32 v46, vcc, s14, v150
	v_cvt_pk_bf16_f32 v30, v24, v25
	s_nop 0
	v_addc_co_u32_e32 v47, vcc, 0, v151, vcc
	v_cvt_pk_bf16_f32 v31, v26, v27
	global_store_dwordx4 v[44:45], v[28:31], off offset:256 nt
	s_mov_b64 s[14:15], 0xa0000
	v_cvt_pk_bf16_f32 v12, v12, v13
	v_add_co_u32_e32 v30, vcc, s37, v150
	v_lshl_add_u64 v[28:29], v[150:151], 0, s[14:15]
	s_nop 0
	v_addc_co_u32_e32 v31, vcc, 0, v151, vcc
	v_cvt_pk_bf16_f32 v13, v14, v15
	v_cvt_pk_bf16_f32 v14, v8, v9
	v_cvt_pk_bf16_f32 v15, v10, v11
	global_store_dwordx4 v[28:29], v[12:15], off offset:256 nt
	v_cvt_pk_bf16_f32 v124, v124, v125
	v_cvt_pk_bf16_f32 v125, v126, v127
	v_add_co_u32_e32 v14, vcc, s38, v150
	v_cvt_pk_bf16_f32 v126, v120, v121
	s_nop 0
	v_addc_co_u32_e32 v15, vcc, 0, v151, vcc
	v_cvt_pk_bf16_f32 v127, v122, v123
	v_cvt_pk_bf16_f32 v104, v116, v117
	v_cvt_pk_bf16_f32 v105, v118, v119
	v_cvt_pk_bf16_f32 v106, v112, v113
	v_cvt_pk_bf16_f32 v107, v114, v115
	v_cvt_pk_bf16_f32 v88, v100, v101
	v_cvt_pk_bf16_f32 v89, v102, v103
	v_cvt_pk_bf16_f32 v90, v96, v97
	v_cvt_pk_bf16_f32 v91, v98, v99
	v_cvt_pk_bf16_f32 v72, v84, v85
	v_cvt_pk_bf16_f32 v73, v86, v87
	v_cvt_pk_bf16_f32 v74, v80, v81
	v_cvt_pk_bf16_f32 v75, v82, v83
	v_cvt_pk_bf16_f32 v71, v66, v67
	v_cvt_pk_bf16_f32 v63, v58, v59
	v_cvt_pk_bf16_f32 v40, v52, v53
	v_cvt_pk_bf16_f32 v41, v54, v55
	v_cvt_pk_bf16_f32 v42, v48, v49
	v_cvt_pk_bf16_f32 v43, v50, v51
	v_cvt_pk_bf16_f32 v24, v36, v37
	v_cvt_pk_bf16_f32 v25, v38, v39
	v_cvt_pk_bf16_f32 v26, v32, v33
	v_cvt_pk_bf16_f32 v27, v34, v35
	v_lshl_add_u64 v[12:13], v[150:151], 0, s[12:13]
	v_cvt_pk_bf16_f32 v8, v20, v21
	v_cvt_pk_bf16_f32 v9, v22, v23
	v_cvt_pk_bf16_f32 v10, v16, v17
	v_cvt_pk_bf16_f32 v11, v18, v19
	v_cvt_pk_bf16_f32 v4, v4, v5
	v_cvt_pk_bf16_f32 v5, v6, v7
	v_cvt_pk_bf16_f32 v6, v0, v1
	v_cvt_pk_bf16_f32 v7, v2, v3
	s_and_b64 vcc, exec, s[0:1]
	s_mov_b32 s41, s39
	s_mov_b32 s34, s40
	s_mov_b64 s[16:17], s[4:5]
	s_mov_b64 s[14:15], s[2:3]
	global_store_dwordx4 v[150:151], v[124:127], off nt
	global_store_dwordx4 v[110:111], v[104:107], off nt
	global_store_dwordx4 v[94:95], v[88:91], off nt
	global_store_dwordx4 v[78:79], v[72:75], off nt
	global_store_dwordx4 v[76:77], v[68:71], off offset:256 nt
	global_store_dwordx4 v[56:57], v[60:63], off nt
	global_store_dwordx4 v[46:47], v[40:43], off nt
	global_store_dwordx4 v[30:31], v[24:27], off nt
	global_store_dwordx4 v[14:15], v[8:11], off nt
	global_store_dwordx4 v[12:13], v[4:7], off offset:256 nt
	s_cbranch_vccz .LBB0_963
	s_waitcnt vmcnt(0)
	s_cmpk_gt_u32 s22, 0xff
	s_cbranch_scc1 .LBB0_978
	s_barrier

.LBB0_1200:
	s_waitcnt lgkmcnt(0)
	ds_read_b128 v[144:147], v151
	ds_read_b128 v[156:159], v151 offset:1024
	ds_read_b128 v[160:163], v151 offset:2048
	ds_read_b128 v[164:167], v151 offset:3072
	s_add_u32 s30, s28, 0xfff80080
	s_addc_u32 s31, s29, -1
	s_cmp_eq_u32 s56, 28
	s_cselect_b32 s35, s4, s31
	s_cselect_b32 s34, s7, s30
	s_cselect_b32 s31, s21, s55
	s_cselect_b32 s30, s23, s54
	v_lshl_add_u64 v[200:201], s[28:29], 0, v[136:137]
	s_add_i32 m0, s17, 0xc000
	ds_read_b128 v[168:171], v152
	ds_read_b128 v[172:175], v152 offset:1024
	ds_read_b128 v[176:179], v152 offset:2048
	ds_read_b128 v[180:183], v152 offset:3072
	ds_read_b128 v[184:187], v152 offset:4096
	ds_read_b128 v[188:191], v152 offset:5120
	ds_read_b128 v[192:195], v152 offset:6144
	ds_read_b128 v[196:199], v152 offset:7168
	global_load_lds_dwordx4 v[200:201], off
	v_lshl_add_u64 v[200:201], s[28:29], 0, v[138:139]
	s_add_i32 m0, s17, 0xe000
	s_nop 0
	global_load_lds_dwordx4 v[200:201], off
	s_waitcnt lgkmcnt(8)
	s_barrier
	s_waitcnt lgkmcnt(0)
	s_setprio 1
	s_waitcnt lgkmcnt(0)
	v_mfma_f32_16x16x32_bf16 v[124:127], v[144:147], v[168:171], v[124:127]
	v_mfma_f32_16x16x32_bf16 v[120:123], v[160:163], v[168:171], v[120:123]
	v_mfma_f32_16x16x32_bf16 v[116:119], v[144:147], v[176:179], v[116:119]
	v_mfma_f32_16x16x32_bf16 v[112:115], v[160:163], v[176:179], v[112:115]
	v_mfma_f32_16x16x32_bf16 v[100:103], v[144:147], v[184:187], v[100:103]
	v_mfma_f32_16x16x32_bf16 v[96:99], v[160:163], v[184:187], v[96:99]
	v_mfma_f32_16x16x32_bf16 v[84:87], v[144:147], v[192:195], v[84:87]
	v_mfma_f32_16x16x32_bf16 v[80:83], v[160:163], v[192:195], v[80:83]
	v_mfma_f32_16x16x32_bf16 v[124:127], v[156:159], v[172:175], v[124:127]
	v_mfma_f32_16x16x32_bf16 v[120:123], v[164:167], v[172:175], v[120:123]
	v_mfma_f32_16x16x32_bf16 v[116:119], v[156:159], v[180:183], v[116:119]
	v_mfma_f32_16x16x32_bf16 v[112:115], v[164:167], v[180:183], v[112:115]
	v_mfma_f32_16x16x32_bf16 v[100:103], v[156:159], v[188:191], v[100:103]
	v_mfma_f32_16x16x32_bf16 v[96:99], v[164:167], v[188:191], v[96:99]
	v_mfma_f32_16x16x32_bf16 v[84:87], v[156:159], v[196:199], v[84:87]
	v_mfma_f32_16x16x32_bf16 v[80:83], v[164:167], v[196:199], v[80:83]
	s_setprio 0
	s_barrier
	s_add_i32 s57, s45, s33
	v_lshl_add_u64 v[218:219], s[30:31], 0, v[130:131]
	s_mov_b32 m0, s57
	ds_read_b128 v[200:203], v153
	ds_read_b128 v[204:207], v153 offset:1024
	ds_read_b128 v[210:213], v153 offset:2048
	ds_read_b128 v[214:217], v153 offset:3072
	global_load_lds_dwordx4 v[218:219], off
	v_lshl_add_u64 v[220:221], s[30:31], 0, v[134:135]
	s_add_i32 m0, s57, 0x2000
	s_nop 0
	global_load_lds_dwordx4 v[220:221], off
	s_barrier
	s_waitcnt lgkmcnt(0)
	s_setprio 1
	s_waitcnt lgkmcnt(0)
	v_mfma_f32_16x16x32_bf16 v[108:111], v[200:203], v[168:171], v[108:111]
	v_mfma_f32_16x16x32_bf16 v[104:107], v[210:213], v[168:171], v[104:107]
	v_mfma_f32_16x16x32_bf16 v[92:95], v[200:203], v[176:179], v[92:95]
	v_mfma_f32_16x16x32_bf16 v[88:91], v[210:213], v[176:179], v[88:91]
	v_mfma_f32_16x16x32_bf16 v[76:79], v[200:203], v[184:187], v[76:79]
	v_mfma_f32_16x16x32_bf16 v[72:75], v[210:213], v[184:187], v[72:75]
	v_mfma_f32_16x16x32_bf16 v[68:71], v[200:203], v[192:195], v[68:71]
	v_mfma_f32_16x16x32_bf16 v[64:67], v[210:213], v[192:195], v[64:67]
	v_mfma_f32_16x16x32_bf16 v[108:111], v[204:207], v[172:175], v[108:111]
	v_mfma_f32_16x16x32_bf16 v[104:107], v[214:217], v[172:175], v[104:107]
	v_mfma_f32_16x16x32_bf16 v[92:95], v[204:207], v[180:183], v[92:95]
	v_mfma_f32_16x16x32_bf16 v[88:91], v[214:217], v[180:183], v[88:91]
	v_mfma_f32_16x16x32_bf16 v[76:79], v[204:207], v[188:191], v[76:79]
	v_mfma_f32_16x16x32_bf16 v[72:75], v[214:217], v[188:191], v[72:75]
	v_mfma_f32_16x16x32_bf16 v[68:71], v[204:207], v[196:199], v[68:71]
	v_mfma_f32_16x16x32_bf16 v[64:67], v[214:217], v[196:199], v[64:67]
	s_setprio 0
	s_mov_b32 m0, s17
	v_lshl_add_u64 v[222:223], s[34:35], 0, v[128:129]
	s_barrier
	ds_read_b128 v[168:171], v152 offset:16384
	ds_read_b128 v[172:175], v152 offset:17408
	ds_read_b128 v[176:179], v152 offset:18432
	ds_read_b128 v[180:183], v152 offset:19456
	ds_read_b128 v[184:187], v152 offset:20480
	ds_read_b128 v[188:191], v152 offset:21504
	ds_read_b128 v[192:195], v152 offset:22528
	ds_read_b128 v[196:199], v152 offset:23552
	global_load_lds_dwordx4 v[222:223], off
	v_lshl_add_u64 v[224:225], s[34:35], 0, v[132:133]
	s_mov_b32 m0, s38
	s_nop 0
	global_load_lds_dwordx4 v[224:225], off
	s_barrier
	s_waitcnt lgkmcnt(0)
	s_setprio 1
	s_waitcnt lgkmcnt(0)
	v_mfma_f32_16x16x32_bf16 v[60:63], v[144:147], v[168:171], v[60:63]
	v_mfma_f32_16x16x32_bf16 v[56:59], v[160:163], v[168:171], v[56:59]
	v_mfma_f32_16x16x32_bf16 v[52:55], v[144:147], v[176:179], v[52:55]
	v_mfma_f32_16x16x32_bf16 v[48:51], v[160:163], v[176:179], v[48:51]
	v_mfma_f32_16x16x32_bf16 v[36:39], v[144:147], v[184:187], v[36:39]
	v_mfma_f32_16x16x32_bf16 v[32:35], v[160:163], v[184:187], v[32:35]
	v_mfma_f32_16x16x32_bf16 v[20:23], v[144:147], v[192:195], v[20:23]
	v_mfma_f32_16x16x32_bf16 v[16:19], v[160:163], v[192:195], v[16:19]
	v_mfma_f32_16x16x32_bf16 v[60:63], v[156:159], v[172:175], v[60:63]
	v_mfma_f32_16x16x32_bf16 v[56:59], v[164:167], v[172:175], v[56:59]
	v_mfma_f32_16x16x32_bf16 v[52:55], v[156:159], v[180:183], v[52:55]
	v_mfma_f32_16x16x32_bf16 v[48:51], v[164:167], v[180:183], v[48:51]
	v_mfma_f32_16x16x32_bf16 v[36:39], v[156:159], v[188:191], v[36:39]
	v_mfma_f32_16x16x32_bf16 v[32:35], v[164:167], v[188:191], v[32:35]
	v_mfma_f32_16x16x32_bf16 v[20:23], v[156:159], v[196:199], v[20:23]
	v_mfma_f32_16x16x32_bf16 v[16:19], v[164:167], v[196:199], v[16:19]
	s_setprio 0
	s_barrier
	s_add_u32 s60, s30, 0x80000
	s_addc_u32 s61, s31, 0
	s_add_i32 s57, s51, s33
	v_lshl_add_u64 v[144:145], s[60:61], 0, v[130:131]
	s_mov_b32 m0, s57
	s_nop 0
	global_load_lds_dwordx4 v[144:145], off
	v_lshl_add_u64 v[144:145], s[60:61], 0, v[134:135]
	s_add_i32 m0, s57, 0x2000
	s_nop 0
	global_load_lds_dwordx4 v[144:145], off
	s_waitcnt vmcnt(6)
	s_barrier
	s_setprio 1
	v_mfma_f32_16x16x32_bf16 v[44:47], v[200:203], v[168:171], v[44:47]
	v_mfma_f32_16x16x32_bf16 v[40:43], v[210:213], v[168:171], v[40:43]
	v_mfma_f32_16x16x32_bf16 v[28:31], v[200:203], v[176:179], v[28:31]
	v_mfma_f32_16x16x32_bf16 v[24:27], v[210:213], v[176:179], v[24:27]
	v_mfma_f32_16x16x32_bf16 v[12:15], v[200:203], v[184:187], v[12:15]
	v_mfma_f32_16x16x32_bf16 v[8:11], v[210:213], v[184:187], v[8:11]
	v_mfma_f32_16x16x32_bf16 v[4:7], v[200:203], v[192:195], v[4:7]
	v_mfma_f32_16x16x32_bf16 v[0:3], v[210:213], v[192:195], v[0:3]
	v_mfma_f32_16x16x32_bf16 v[44:47], v[204:207], v[172:175], v[44:47]
	v_mfma_f32_16x16x32_bf16 v[40:43], v[214:217], v[172:175], v[40:43]
	v_mfma_f32_16x16x32_bf16 v[28:31], v[204:207], v[180:183], v[28:31]
	v_mfma_f32_16x16x32_bf16 v[24:27], v[214:217], v[180:183], v[24:27]
	v_mfma_f32_16x16x32_bf16 v[12:15], v[204:207], v[188:191], v[12:15]
	v_mfma_f32_16x16x32_bf16 v[8:11], v[214:217], v[188:191], v[8:11]
	v_mfma_f32_16x16x32_bf16 v[4:7], v[204:207], v[196:199], v[4:7]
	v_mfma_f32_16x16x32_bf16 v[0:3], v[214:217], v[196:199], v[0:3]
	s_setprio 0
	s_add_i32 s57, 0, 0x18000
	v_add_u32_e32 v155, s57, v150
	s_barrier
	ds_read_b128 v[144:147], v155
	ds_read_b128 v[156:159], v155 offset:1024
	ds_read_b128 v[160:163], v155 offset:2048
	ds_read_b128 v[164:167], v155 offset:3072
	s_add_u32 s34, s34, 0x80000
	s_addc_u32 s35, s35, 0
	s_mov_b32 m0, s39
	v_lshl_add_u64 v[200:201], s[34:35], 0, v[128:129]
	ds_read_b128 v[168:171], v152 offset:32768
	ds_read_b128 v[172:175], v152 offset:33792
	ds_read_b128 v[176:179], v152 offset:34816
	ds_read_b128 v[180:183], v152 offset:35840
	ds_read_b128 v[184:187], v152 offset:36864
	ds_read_b128 v[188:191], v152 offset:37888
	ds_read_b128 v[192:195], v152 offset:38912
	ds_read_b128 v[196:199], v152 offset:39936
	global_load_lds_dwordx4 v[200:201], off
	v_lshl_add_u64 v[200:201], s[34:35], 0, v[132:133]
	s_mov_b32 m0, s40
	s_nop 0
	global_load_lds_dwordx4 v[200:201], off
	s_waitcnt lgkmcnt(8)
	s_barrier
	s_waitcnt lgkmcnt(0)
	s_setprio 1
	s_waitcnt lgkmcnt(0)
	v_mfma_f32_16x16x32_bf16 v[124:127], v[144:147], v[168:171], v[124:127]
	v_mfma_f32_16x16x32_bf16 v[120:123], v[160:163], v[168:171], v[120:123]
	v_mfma_f32_16x16x32_bf16 v[116:119], v[144:147], v[176:179], v[116:119]
	v_mfma_f32_16x16x32_bf16 v[112:115], v[160:163], v[176:179], v[112:115]
	v_mfma_f32_16x16x32_bf16 v[100:103], v[144:147], v[184:187], v[100:103]
	v_mfma_f32_16x16x32_bf16 v[96:99], v[160:163], v[184:187], v[96:99]
	v_mfma_f32_16x16x32_bf16 v[84:87], v[144:147], v[192:195], v[84:87]
	v_mfma_f32_16x16x32_bf16 v[80:83], v[160:163], v[192:195], v[80:83]
	v_mfma_f32_16x16x32_bf16 v[124:127], v[156:159], v[172:175], v[124:127]
	v_mfma_f32_16x16x32_bf16 v[120:123], v[164:167], v[172:175], v[120:123]
	v_mfma_f32_16x16x32_bf16 v[116:119], v[156:159], v[180:183], v[116:119]
	v_mfma_f32_16x16x32_bf16 v[112:115], v[164:167], v[180:183], v[112:115]
	v_mfma_f32_16x16x32_bf16 v[100:103], v[156:159], v[188:191], v[100:103]
	v_mfma_f32_16x16x32_bf16 v[96:99], v[164:167], v[188:191], v[96:99]
	v_mfma_f32_16x16x32_bf16 v[84:87], v[156:159], v[196:199], v[84:87]
	v_mfma_f32_16x16x32_bf16 v[80:83], v[164:167], v[196:199], v[80:83]
	s_setprio 0
	s_barrier
	s_add_i32 s34, 0, 0x1c000
	s_add_i32 s35, s57, s33
	v_add_u32_e32 v155, s34, v150
	v_lshl_add_u64 v[218:219], v[218:219], 0, s[8:9]
	s_mov_b32 m0, s35
	ds_read_b128 v[200:203], v155
	ds_read_b128 v[204:207], v155 offset:1024
	ds_read_b128 v[210:213], v155 offset:2048
	ds_read_b128 v[214:217], v155 offset:3072
	global_load_lds_dwordx4 v[218:219], off
	v_lshl_add_u64 v[218:219], v[220:221], 0, s[8:9]
	s_add_i32 m0, s35, 0x2000
	s_nop 0
	global_load_lds_dwordx4 v[218:219], off
	s_barrier
	s_waitcnt lgkmcnt(0)
	s_setprio 1
	s_waitcnt lgkmcnt(0)
	v_mfma_f32_16x16x32_bf16 v[108:111], v[200:203], v[168:171], v[108:111]
	v_mfma_f32_16x16x32_bf16 v[104:107], v[210:213], v[168:171], v[104:107]
	v_mfma_f32_16x16x32_bf16 v[92:95], v[200:203], v[176:179], v[92:95]
	v_mfma_f32_16x16x32_bf16 v[88:91], v[210:213], v[176:179], v[88:91]
	v_mfma_f32_16x16x32_bf16 v[76:79], v[200:203], v[184:187], v[76:79]
	v_mfma_f32_16x16x32_bf16 v[72:75], v[210:213], v[184:187], v[72:75]
	v_mfma_f32_16x16x32_bf16 v[68:71], v[200:203], v[192:195], v[68:71]
	v_mfma_f32_16x16x32_bf16 v[64:67], v[210:213], v[192:195], v[64:67]
	v_mfma_f32_16x16x32_bf16 v[108:111], v[204:207], v[172:175], v[108:111]
	v_mfma_f32_16x16x32_bf16 v[104:107], v[214:217], v[172:175], v[104:107]
	v_mfma_f32_16x16x32_bf16 v[92:95], v[204:207], v[180:183], v[92:95]
	v_mfma_f32_16x16x32_bf16 v[88:91], v[214:217], v[180:183], v[88:91]
	v_mfma_f32_16x16x32_bf16 v[76:79], v[204:207], v[188:191], v[76:79]
	v_mfma_f32_16x16x32_bf16 v[72:75], v[214:217], v[188:191], v[72:75]
	v_mfma_f32_16x16x32_bf16 v[68:71], v[204:207], v[196:199], v[68:71]
	v_mfma_f32_16x16x32_bf16 v[64:67], v[214:217], v[196:199], v[64:67]
	s_setprio 0
	s_mov_b32 m0, s43
	v_lshl_add_u64 v[218:219], v[222:223], 0, s[8:9]
	s_barrier
	ds_read_b128 v[168:171], v152 offset:49152
	ds_read_b128 v[172:175], v152 offset:50176
	ds_read_b128 v[176:179], v152 offset:51200
	ds_read_b128 v[180:183], v152 offset:52224
	ds_read_b128 v[184:187], v152 offset:53248
	ds_read_b128 v[188:191], v152 offset:54272
	ds_read_b128 v[192:195], v152 offset:55296
	ds_read_b128 v[196:199], v152 offset:56320
	global_load_lds_dwordx4 v[218:219], off
	v_lshl_add_u64 v[218:219], v[224:225], 0, s[8:9]
	s_mov_b32 m0, s44
	s_nop 0
	global_load_lds_dwordx4 v[218:219], off
	s_barrier
	s_waitcnt lgkmcnt(0)
	s_setprio 1
	s_waitcnt lgkmcnt(0)
	v_mfma_f32_16x16x32_bf16 v[60:63], v[144:147], v[168:171], v[60:63]
	v_mfma_f32_16x16x32_bf16 v[56:59], v[160:163], v[168:171], v[56:59]
	v_mfma_f32_16x16x32_bf16 v[52:55], v[144:147], v[176:179], v[52:55]
	v_mfma_f32_16x16x32_bf16 v[48:51], v[160:163], v[176:179], v[48:51]
	v_mfma_f32_16x16x32_bf16 v[36:39], v[144:147], v[184:187], v[36:39]
	v_mfma_f32_16x16x32_bf16 v[32:35], v[160:163], v[184:187], v[32:35]
	v_mfma_f32_16x16x32_bf16 v[20:23], v[144:147], v[192:195], v[20:23]
	v_mfma_f32_16x16x32_bf16 v[16:19], v[160:163], v[192:195], v[16:19]
	v_mfma_f32_16x16x32_bf16 v[60:63], v[156:159], v[172:175], v[60:63]
	v_mfma_f32_16x16x32_bf16 v[56:59], v[164:167], v[172:175], v[56:59]
	v_mfma_f32_16x16x32_bf16 v[52:55], v[156:159], v[180:183], v[52:55]
	v_mfma_f32_16x16x32_bf16 v[48:51], v[164:167], v[180:183], v[48:51]
	v_mfma_f32_16x16x32_bf16 v[36:39], v[156:159], v[188:191], v[36:39]
	v_mfma_f32_16x16x32_bf16 v[32:35], v[164:167], v[188:191], v[32:35]
	v_mfma_f32_16x16x32_bf16 v[20:23], v[156:159], v[196:199], v[20:23]
	v_mfma_f32_16x16x32_bf16 v[16:19], v[164:167], v[196:199], v[16:19]
	s_setprio 0
	s_barrier
	s_add_u32 s30, s30, 0x80080
	s_addc_u32 s31, s31, 0
	s_add_i32 s34, s34, s33
	v_lshl_add_u64 v[144:145], s[30:31], 0, v[130:131]
	s_mov_b32 m0, s34
	s_nop 0
	global_load_lds_dwordx4 v[144:145], off
	v_lshl_add_u64 v[144:145], s[30:31], 0, v[134:135]
	s_add_i32 m0, s34, 0x2000
	s_nop 0
	global_load_lds_dwordx4 v[144:145], off
	s_waitcnt vmcnt(6)
	s_barrier
	s_setprio 1
	v_mfma_f32_16x16x32_bf16 v[44:47], v[200:203], v[168:171], v[44:47]
	v_mfma_f32_16x16x32_bf16 v[40:43], v[210:213], v[168:171], v[40:43]
	v_mfma_f32_16x16x32_bf16 v[28:31], v[200:203], v[176:179], v[28:31]
	v_mfma_f32_16x16x32_bf16 v[24:27], v[210:213], v[176:179], v[24:27]
	v_mfma_f32_16x16x32_bf16 v[12:15], v[200:203], v[184:187], v[12:15]
	v_mfma_f32_16x16x32_bf16 v[8:11], v[210:213], v[184:187], v[8:11]
	v_mfma_f32_16x16x32_bf16 v[4:7], v[200:203], v[192:195], v[4:7]
	v_mfma_f32_16x16x32_bf16 v[0:3], v[210:213], v[192:195], v[0:3]
	v_mfma_f32_16x16x32_bf16 v[44:47], v[204:207], v[172:175], v[44:47]
	v_mfma_f32_16x16x32_bf16 v[40:43], v[214:217], v[172:175], v[40:43]
	v_mfma_f32_16x16x32_bf16 v[28:31], v[204:207], v[180:183], v[28:31]
	v_mfma_f32_16x16x32_bf16 v[24:27], v[214:217], v[180:183], v[24:27]
	v_mfma_f32_16x16x32_bf16 v[12:15], v[204:207], v[188:191], v[12:15]
	v_mfma_f32_16x16x32_bf16 v[8:11], v[214:217], v[188:191], v[8:11]
	v_mfma_f32_16x16x32_bf16 v[4:7], v[204:207], v[196:199], v[4:7]
	v_mfma_f32_16x16x32_bf16 v[0:3], v[214:217], v[196:199], v[0:3]
	s_setprio 0
	s_add_i32 s56, s56, 2
	s_add_u32 s28, s28, 0x100
	s_addc_u32 s29, s29, 0
	s_add_u32 s54, s54, 0x100
	s_addc_u32 s55, s55, 0
	s_cmp_gt_u32 s56, 29
	s_barrier
	s_cbranch_scc0 .LBB0_1200
	v_mov_b32_e32 v155, v148
	v_mov_b32_e32 v156, v149
	s_cmp_gt_i32 s6, 7
	s_mov_b64 s[28:29], -1
	s_cbranch_scc0 .LBB0_1231
	s_cmp_gt_u32 s6, 15
	s_cbranch_scc0 .LBB0_1212
	s_cmp_gt_u32 s6, 23
	s_cbranch_scc0 .LBB0_1209
	s_lshl_b32 s4, s16, 8
	s_add_i32 s4, s4, s41
	v_lshl_add_u32 v144, v156, 3, s42
	v_add_u32_e32 v157, s4, v155
	v_ashrrev_i32_e32 v145, 31, v144
	v_mad_i64_i32 v[146:147], s[28:29], v157, s52, 0
	s_cmp_gt_u32 s6, 25
	s_mov_b64 s[28:29], -1
	v_lshl_add_u64 v[146:147], s[14:15], 0, v[146:147]
	v_lshlrev_b64 v[144:145], 1, v[144:145]
	v_add_u32_e32 v163, 16, v157
	v_add_u32_e32 v162, 32, v157
	v_add_u32_e32 v161, 48, v157
	v_add_u32_e32 v160, 0x80, v157
	v_add_u32_e32 v159, 0x90, v157
	v_add_u32_e32 v158, 0xa0, v157
	v_add_u32_e32 v157, 0xb0, v157
	s_cbranch_scc0 .LBB0_1206
	s_lshl_b32 s4, s6, 9
	v_lshl_add_u64 v[168:169], v[146:147], 0, s[4:5]
	v_cvt_pk_bf16_f32 v164, v124, v125
	v_cvt_pk_bf16_f32 v165, v126, v127
	v_cvt_pk_bf16_f32 v166, v120, v121
	v_cvt_pk_bf16_f32 v167, v122, v123
	v_lshl_add_u64 v[168:169], v[168:169], 0, v[144:145]
	global_store_dwordx4 v[168:169], v[164:167], off nt
	s_nop 1
	v_cvt_pk_bf16_f32 v164, v108, v109
	v_cvt_pk_bf16_f32 v165, v110, v111
	v_cvt_pk_bf16_f32 v166, v104, v105
	v_cvt_pk_bf16_f32 v167, v106, v107
	global_store_dwordx4 v[168:169], v[164:167], off offset:256 nt
	v_mov_b64_e32 v[168:169], s[14:15]
	v_mad_i64_i32 v[170:171], s[28:29], v163, s52, v[168:169]
	v_lshl_add_u64 v[170:171], v[170:171], 0, s[4:5]
	v_cvt_pk_bf16_f32 v164, v116, v117
	v_cvt_pk_bf16_f32 v165, v118, v119
	v_cvt_pk_bf16_f32 v166, v112, v113
	v_cvt_pk_bf16_f32 v167, v114, v115
	v_lshl_add_u64 v[170:171], v[170:171], 0, v[144:145]
	global_store_dwordx4 v[170:171], v[164:167], off nt
	s_nop 1
	v_cvt_pk_bf16_f32 v164, v92, v93
	v_cvt_pk_bf16_f32 v165, v94, v95
	v_cvt_pk_bf16_f32 v166, v88, v89
	v_cvt_pk_bf16_f32 v167, v90, v91
	global_store_dwordx4 v[170:171], v[164:167], off offset:256 nt
	v_mad_i64_i32 v[170:171], s[28:29], v162, s52, v[168:169]
	v_lshl_add_u64 v[170:171], v[170:171], 0, s[4:5]
	v_cvt_pk_bf16_f32 v164, v100, v101
	v_cvt_pk_bf16_f32 v165, v102, v103
	v_cvt_pk_bf16_f32 v166, v96, v97
	v_cvt_pk_bf16_f32 v167, v98, v99
	v_lshl_add_u64 v[170:171], v[170:171], 0, v[144:145]
	global_store_dwordx4 v[170:171], v[164:167], off nt
	s_nop 1
	v_cvt_pk_bf16_f32 v164, v76, v77
	v_cvt_pk_bf16_f32 v165, v78, v79
	v_cvt_pk_bf16_f32 v166, v72, v73
	v_cvt_pk_bf16_f32 v167, v74, v75
	global_store_dwordx4 v[170:171], v[164:167], off offset:256 nt
	v_mad_i64_i32 v[170:171], s[28:29], v161, s52, v[168:169]
	v_lshl_add_u64 v[170:171], v[170:171], 0, s[4:5]
	v_cvt_pk_bf16_f32 v164, v84, v85
	v_cvt_pk_bf16_f32 v165, v86, v87
	v_cvt_pk_bf16_f32 v166, v80, v81
	v_cvt_pk_bf16_f32 v167, v82, v83
	v_lshl_add_u64 v[170:171], v[170:171], 0, v[144:145]
	global_store_dwordx4 v[170:171], v[164:167], off nt
	s_nop 1
	v_cvt_pk_bf16_f32 v164, v68, v69
	v_cvt_pk_bf16_f32 v165, v70, v71
	v_cvt_pk_bf16_f32 v166, v64, v65
	v_cvt_pk_bf16_f32 v167, v66, v67
	global_store_dwordx4 v[170:171], v[164:167], off offset:256 nt
	v_mad_i64_i32 v[170:171], s[28:29], v160, s52, v[168:169]
	v_lshl_add_u64 v[170:171], v[170:171], 0, s[4:5]
	v_cvt_pk_bf16_f32 v164, v60, v61
	v_cvt_pk_bf16_f32 v165, v62, v63
	v_cvt_pk_bf16_f32 v166, v56, v57
	v_cvt_pk_bf16_f32 v167, v58, v59
	v_lshl_add_u64 v[170:171], v[170:171], 0, v[144:145]
	global_store_dwordx4 v[170:171], v[164:167], off nt
	s_nop 1
	v_cvt_pk_bf16_f32 v164, v44, v45
	v_cvt_pk_bf16_f32 v165, v46, v47
	v_cvt_pk_bf16_f32 v166, v40, v41
	v_cvt_pk_bf16_f32 v167, v42, v43
	global_store_dwordx4 v[170:171], v[164:167], off offset:256 nt
	v_mad_i64_i32 v[170:171], s[28:29], v159, s52, v[168:169]
	v_lshl_add_u64 v[170:171], v[170:171], 0, s[4:5]
	v_cvt_pk_bf16_f32 v164, v52, v53
	v_cvt_pk_bf16_f32 v165, v54, v55
	v_cvt_pk_bf16_f32 v166, v48, v49
	v_cvt_pk_bf16_f32 v167, v50, v51
	v_lshl_add_u64 v[170:171], v[170:171], 0, v[144:145]
	global_store_dwordx4 v[170:171], v[164:167], off nt
	s_nop 1
	v_cvt_pk_bf16_f32 v164, v28, v29
	v_cvt_pk_bf16_f32 v165, v30, v31
	v_cvt_pk_bf16_f32 v166, v24, v25
	v_cvt_pk_bf16_f32 v167, v26, v27
	global_store_dwordx4 v[170:171], v[164:167], off offset:256 nt
	v_mad_i64_i32 v[170:171], s[28:29], v158, s52, v[168:169]
	v_lshl_add_u64 v[170:171], v[170:171], 0, s[4:5]
	v_cvt_pk_bf16_f32 v164, v36, v37
	v_cvt_pk_bf16_f32 v165, v38, v39
	v_cvt_pk_bf16_f32 v166, v32, v33
	v_cvt_pk_bf16_f32 v167, v34, v35
	v_lshl_add_u64 v[170:171], v[170:171], 0, v[144:145]
	v_mad_i64_i32 v[168:169], s[28:29], v157, s52, v[168:169]
	global_store_dwordx4 v[170:171], v[164:167], off nt
	v_lshl_add_u64 v[168:169], v[168:169], 0, s[4:5]
	v_lshl_add_u64 v[168:169], v[168:169], 0, v[144:145]
	v_cvt_pk_bf16_f32 v164, v12, v13
	v_cvt_pk_bf16_f32 v165, v14, v15
	v_cvt_pk_bf16_f32 v166, v8, v9
	v_cvt_pk_bf16_f32 v167, v10, v11
	global_store_dwordx4 v[170:171], v[164:167], off offset:256 nt
	s_mov_b64 s[28:29], 0
	s_nop 0
	v_cvt_pk_bf16_f32 v164, v20, v21
	v_cvt_pk_bf16_f32 v165, v22, v23
	v_cvt_pk_bf16_f32 v166, v16, v17
	v_cvt_pk_bf16_f32 v167, v18, v19
	global_store_dwordx4 v[168:169], v[164:167], off nt
	s_nop 1
	v_cvt_pk_bf16_f32 v164, v4, v5
	v_cvt_pk_bf16_f32 v165, v6, v7
	v_cvt_pk_bf16_f32 v166, v0, v1
	v_cvt_pk_bf16_f32 v167, v2, v3
	global_store_dwordx4 v[168:169], v[164:167], off offset:256 nt
.LBB0_1206:
	s_andn2_b64 vcc, exec, s[28:29]
	s_cbranch_vccnz .LBB0_1208
	s_lshl_b32 s4, s6, 9
	v_pk_mul_f32 v[164:165], v[124:125], s[18:19] op_sel_hi:[1,0]
	v_pk_mul_f32 v[166:167], v[120:121], s[18:19] op_sel_hi:[1,0]
	v_pk_mul_f32 v[168:169], v[126:127], s[18:19] op_sel_hi:[1,0]
	v_pk_mul_f32 v[170:171], v[122:123], s[18:19] op_sel_hi:[1,0]
	v_lshl_add_u64 v[146:147], v[146:147], 0, s[4:5]
	v_cvt_pk_bf16_f32 v164, v164, v165
	v_cvt_pk_bf16_f32 v165, v168, v169
	v_cvt_pk_bf16_f32 v166, v166, v167
	v_cvt_pk_bf16_f32 v167, v170, v171
	v_lshl_add_u64 v[146:147], v[146:147], 0, v[144:145]
	global_store_dwordx4 v[146:147], v[164:167], off nt
	v_pk_mul_f32 v[168:169], v[110:111], s[18:19] op_sel_hi:[1,0]
	v_pk_mul_f32 v[170:171], v[106:107], s[18:19] op_sel_hi:[1,0]
	v_pk_mul_f32 v[164:165], v[108:109], s[18:19] op_sel_hi:[1,0]
	v_pk_mul_f32 v[166:167], v[104:105], s[18:19] op_sel_hi:[1,0]
	v_cvt_pk_bf16_f32 v164, v164, v165
	v_cvt_pk_bf16_f32 v165, v168, v169
	v_cvt_pk_bf16_f32 v166, v166, v167
	v_cvt_pk_bf16_f32 v167, v170, v171
	global_store_dwordx4 v[146:147], v[164:167], off offset:256 nt
	v_pk_mul_f32 v[146:147], v[116:117], s[18:19] op_sel_hi:[1,0]
	v_pk_mul_f32 v[168:169], v[118:119], s[18:19] op_sel_hi:[1,0]
	v_cvt_pk_bf16_f32 v164, v146, v147
	v_mov_b64_e32 v[146:147], s[14:15]
	v_cvt_pk_bf16_f32 v165, v168, v169
	v_mad_i64_i32 v[168:169], s[28:29], v163, s52, v[146:147]
	v_pk_mul_f32 v[166:167], v[112:113], s[18:19] op_sel_hi:[1,0]
	v_pk_mul_f32 v[170:171], v[114:115], s[18:19] op_sel_hi:[1,0]
	v_lshl_add_u64 v[168:169], v[168:169], 0, s[4:5]
	v_cvt_pk_bf16_f32 v166, v166, v167
	v_cvt_pk_bf16_f32 v167, v170, v171
	v_lshl_add_u64 v[168:169], v[168:169], 0, v[144:145]
	global_store_dwordx4 v[168:169], v[164:167], off nt
	v_pk_mul_f32 v[170:171], v[94:95], s[18:19] op_sel_hi:[1,0]
	v_pk_mul_f32 v[172:173], v[90:91], s[18:19] op_sel_hi:[1,0]
	v_pk_mul_f32 v[164:165], v[92:93], s[18:19] op_sel_hi:[1,0]
	v_pk_mul_f32 v[166:167], v[88:89], s[18:19] op_sel_hi:[1,0]
	v_cvt_pk_bf16_f32 v164, v164, v165
	v_cvt_pk_bf16_f32 v165, v170, v171
	v_cvt_pk_bf16_f32 v166, v166, v167
	v_cvt_pk_bf16_f32 v167, v172, v173
	v_mad_i64_i32 v[162:163], s[28:29], v162, s52, v[146:147]
	global_store_dwordx4 v[168:169], v[164:167], off offset:256 nt
	v_pk_mul_f32 v[168:169], v[102:103], s[18:19] op_sel_hi:[1,0]
	v_pk_mul_f32 v[170:171], v[98:99], s[18:19] op_sel_hi:[1,0]
	v_pk_mul_f32 v[164:165], v[100:101], s[18:19] op_sel_hi:[1,0]
	v_pk_mul_f32 v[166:167], v[96:97], s[18:19] op_sel_hi:[1,0]
	v_lshl_add_u64 v[162:163], v[162:163], 0, s[4:5]
	v_cvt_pk_bf16_f32 v164, v164, v165
	v_cvt_pk_bf16_f32 v165, v168, v169
	v_cvt_pk_bf16_f32 v166, v166, v167
	v_cvt_pk_bf16_f32 v167, v170, v171
	v_lshl_add_u64 v[168:169], v[162:163], 0, v[144:145]
	global_store_dwordx4 v[168:169], v[164:167], off nt
	v_pk_mul_f32 v[162:163], v[76:77], s[18:19] op_sel_hi:[1,0]
	v_pk_mul_f32 v[170:171], v[74:75], s[18:19] op_sel_hi:[1,0]
	v_pk_mul_f32 v[164:165], v[72:73], s[18:19] op_sel_hi:[1,0]
	v_pk_mul_f32 v[166:167], v[78:79], s[18:19] op_sel_hi:[1,0]
	v_cvt_pk_bf16_f32 v162, v162, v163
	v_cvt_pk_bf16_f32 v163, v166, v167
	v_cvt_pk_bf16_f32 v164, v164, v165
	v_cvt_pk_bf16_f32 v165, v170, v171
	global_store_dwordx4 v[168:169], v[162:165], off offset:256 nt
	v_pk_mul_f32 v[166:167], v[86:87], s[18:19] op_sel_hi:[1,0]
	v_pk_mul_f32 v[168:169], v[82:83], s[18:19] op_sel_hi:[1,0]
	v_pk_mul_f32 v[162:163], v[84:85], s[18:19] op_sel_hi:[1,0]
	v_pk_mul_f32 v[164:165], v[80:81], s[18:19] op_sel_hi:[1,0]
	v_cvt_pk_bf16_f32 v162, v162, v163
	v_cvt_pk_bf16_f32 v163, v166, v167
	v_mad_i64_i32 v[166:167], s[28:29], v161, s52, v[146:147]
	v_lshl_add_u64 v[166:167], v[166:167], 0, s[4:5]
	v_cvt_pk_bf16_f32 v164, v164, v165
	v_cvt_pk_bf16_f32 v165, v168, v169
	v_lshl_add_u64 v[166:167], v[166:167], 0, v[144:145]
	global_store_dwordx4 v[166:167], v[162:165], off nt
	v_pk_mul_f32 v[168:169], v[70:71], s[18:19] op_sel_hi:[1,0]
	v_pk_mul_f32 v[170:171], v[66:67], s[18:19] op_sel_hi:[1,0]
	v_pk_mul_f32 v[162:163], v[68:69], s[18:19] op_sel_hi:[1,0]
	v_pk_mul_f32 v[164:165], v[64:65], s[18:19] op_sel_hi:[1,0]
	v_cvt_pk_bf16_f32 v162, v162, v163
	v_cvt_pk_bf16_f32 v163, v168, v169
	v_cvt_pk_bf16_f32 v164, v164, v165
	v_cvt_pk_bf16_f32 v165, v170, v171
	v_mad_i64_i32 v[160:161], s[28:29], v160, s52, v[146:147]
	global_store_dwordx4 v[166:167], v[162:165], off offset:256 nt
	v_pk_mul_f32 v[166:167], v[62:63], s[18:19] op_sel_hi:[1,0]
	v_pk_mul_f32 v[168:169], v[58:59], s[18:19] op_sel_hi:[1,0]
	v_pk_mul_f32 v[162:163], v[60:61], s[18:19] op_sel_hi:[1,0]
	v_pk_mul_f32 v[164:165], v[56:57], s[18:19] op_sel_hi:[1,0]
	v_lshl_add_u64 v[160:161], v[160:161], 0, s[4:5]
	v_cvt_pk_bf16_f32 v162, v162, v163
	v_cvt_pk_bf16_f32 v163, v166, v167
	v_cvt_pk_bf16_f32 v164, v164, v165
	v_cvt_pk_bf16_f32 v165, v168, v169
	v_lshl_add_u64 v[166:167], v[160:161], 0, v[144:145]
	global_store_dwordx4 v[166:167], v[162:165], off nt
	v_pk_mul_f32 v[160:161], v[44:45], s[18:19] op_sel_hi:[1,0]
	v_pk_mul_f32 v[168:169], v[42:43], s[18:19] op_sel_hi:[1,0]
	v_pk_mul_f32 v[162:163], v[40:41], s[18:19] op_sel_hi:[1,0]
	v_pk_mul_f32 v[164:165], v[46:47], s[18:19] op_sel_hi:[1,0]
	v_cvt_pk_bf16_f32 v160, v160, v161
	v_cvt_pk_bf16_f32 v161, v164, v165
	v_cvt_pk_bf16_f32 v162, v162, v163
	v_cvt_pk_bf16_f32 v163, v168, v169
	global_store_dwordx4 v[166:167], v[160:163], off offset:256 nt
	v_pk_mul_f32 v[164:165], v[54:55], s[18:19] op_sel_hi:[1,0]
	v_pk_mul_f32 v[166:167], v[50:51], s[18:19] op_sel_hi:[1,0]
	v_pk_mul_f32 v[160:161], v[52:53], s[18:19] op_sel_hi:[1,0]
	v_pk_mul_f32 v[162:163], v[48:49], s[18:19] op_sel_hi:[1,0]
	v_cvt_pk_bf16_f32 v160, v160, v161
	v_cvt_pk_bf16_f32 v161, v164, v165
	v_mad_i64_i32 v[164:165], s[28:29], v159, s52, v[146:147]
	v_lshl_add_u64 v[164:165], v[164:165], 0, s[4:5]
	v_cvt_pk_bf16_f32 v162, v162, v163
	v_cvt_pk_bf16_f32 v163, v166, v167
	v_lshl_add_u64 v[164:165], v[164:165], 0, v[144:145]
	global_store_dwordx4 v[164:165], v[160:163], off nt
	v_pk_mul_f32 v[166:167], v[30:31], s[18:19] op_sel_hi:[1,0]
	v_pk_mul_f32 v[168:169], v[26:27], s[18:19] op_sel_hi:[1,0]
	v_pk_mul_f32 v[160:161], v[28:29], s[18:19] op_sel_hi:[1,0]
	v_pk_mul_f32 v[162:163], v[24:25], s[18:19] op_sel_hi:[1,0]
	v_cvt_pk_bf16_f32 v160, v160, v161
	v_cvt_pk_bf16_f32 v161, v166, v167
	v_cvt_pk_bf16_f32 v162, v162, v163
	v_cvt_pk_bf16_f32 v163, v168, v169
	v_mad_i64_i32 v[158:159], s[28:29], v158, s52, v[146:147]
	global_store_dwordx4 v[164:165], v[160:163], off offset:256 nt
	v_pk_mul_f32 v[164:165], v[38:39], s[18:19] op_sel_hi:[1,0]
	v_pk_mul_f32 v[166:167], v[34:35], s[18:19] op_sel_hi:[1,0]
	v_pk_mul_f32 v[160:161], v[36:37], s[18:19] op_sel_hi:[1,0]
	v_pk_mul_f32 v[162:163], v[32:33], s[18:19] op_sel_hi:[1,0]
	v_lshl_add_u64 v[158:159], v[158:159], 0, s[4:5]
	v_cvt_pk_bf16_f32 v160, v160, v161
	v_cvt_pk_bf16_f32 v161, v164, v165
	v_cvt_pk_bf16_f32 v162, v162, v163
	v_cvt_pk_bf16_f32 v163, v166, v167
	v_lshl_add_u64 v[164:165], v[158:159], 0, v[144:145]
	global_store_dwordx4 v[164:165], v[160:163], off nt
	v_pk_mul_f32 v[158:159], v[12:13], s[18:19] op_sel_hi:[1,0]
	v_pk_mul_f32 v[166:167], v[10:11], s[18:19] op_sel_hi:[1,0]
	v_pk_mul_f32 v[160:161], v[8:9], s[18:19] op_sel_hi:[1,0]
	v_pk_mul_f32 v[162:163], v[14:15], s[18:19] op_sel_hi:[1,0]
	v_cvt_pk_bf16_f32 v158, v158, v159
	v_cvt_pk_bf16_f32 v159, v162, v163
	v_cvt_pk_bf16_f32 v160, v160, v161
	v_cvt_pk_bf16_f32 v161, v166, v167
	v_mad_i64_i32 v[146:147], s[28:29], v157, s52, v[146:147]
	global_store_dwordx4 v[164:165], v[158:161], off offset:256 nt
	v_pk_mul_f32 v[162:163], v[22:23], s[18:19] op_sel_hi:[1,0]
	v_pk_mul_f32 v[164:165], v[18:19], s[18:19] op_sel_hi:[1,0]
	v_pk_mul_f32 v[158:159], v[20:21], s[18:19] op_sel_hi:[1,0]
	v_pk_mul_f32 v[160:161], v[16:17], s[18:19] op_sel_hi:[1,0]
	v_lshl_add_u64 v[146:147], v[146:147], 0, s[4:5]
	v_cvt_pk_bf16_f32 v158, v158, v159
	v_cvt_pk_bf16_f32 v159, v162, v163
	v_cvt_pk_bf16_f32 v160, v160, v161
	v_cvt_pk_bf16_f32 v161, v164, v165
	v_lshl_add_u64 v[162:163], v[146:147], 0, v[144:145]
	global_store_dwordx4 v[162:163], v[158:161], off nt
	v_pk_mul_f32 v[144:145], v[4:5], s[18:19] op_sel_hi:[1,0]
	v_pk_mul_f32 v[146:147], v[0:1], s[18:19] op_sel_hi:[1,0]
	v_pk_mul_f32 v[158:159], v[6:7], s[18:19] op_sel_hi:[1,0]
	v_pk_mul_f32 v[160:161], v[2:3], s[18:19] op_sel_hi:[1,0]
	v_cvt_pk_bf16_f32 v144, v144, v145
	v_cvt_pk_bf16_f32 v145, v158, v159
	v_cvt_pk_bf16_f32 v146, v146, v147
	v_cvt_pk_bf16_f32 v147, v160, v161
	global_store_dwordx4 v[162:163], v[144:147], off offset:256 nt

.LBB0_1209:
	s_andn2_b64 vcc, exec, s[28:29]
	s_cbranch_vccnz .LBB0_1211
	s_lshl_b32 s4, s16, 8
	s_add_i32 s4, s4, s41
	v_lshl_add_u32 v158, v156, 3, s42
	v_add_u32_e32 v157, s4, v155
	v_mov_b64_e32 v[160:161], s[14:15]
	v_ashrrev_i32_e32 v159, 31, v158
	v_mad_i64_i32 v[162:163], s[28:29], v157, s52, v[160:161]
	s_lshl_b32 s4, s6, 9
	v_lshl_add_u64 v[162:163], v[162:163], 0, s[4:5]
	v_lshlrev_b64 v[158:159], 1, v[158:159]
	v_cvt_pk_bf16_f32 v144, v124, v125
	v_cvt_pk_bf16_f32 v145, v126, v127
	v_cvt_pk_bf16_f32 v146, v120, v121
	v_cvt_pk_bf16_f32 v147, v122, v123
	v_lshl_add_u64 v[162:163], v[162:163], 0, v[158:159]
	global_store_dwordx4 v[162:163], v[144:147], off nt
	s_nop 1
	v_cvt_pk_bf16_f32 v144, v108, v109
	v_cvt_pk_bf16_f32 v145, v110, v111
	v_cvt_pk_bf16_f32 v146, v104, v105
	v_cvt_pk_bf16_f32 v147, v106, v107
	global_store_dwordx4 v[162:163], v[144:147], off offset:256 nt
	v_add_u32_e32 v162, 16, v157
	v_mad_i64_i32 v[162:163], s[28:29], v162, s52, v[160:161]
	v_lshl_add_u64 v[162:163], v[162:163], 0, s[4:5]
	v_cvt_pk_bf16_f32 v144, v116, v117
	v_cvt_pk_bf16_f32 v145, v118, v119
	v_cvt_pk_bf16_f32 v146, v112, v113
	v_cvt_pk_bf16_f32 v147, v114, v115
	v_lshl_add_u64 v[162:163], v[162:163], 0, v[158:159]
	global_store_dwordx4 v[162:163], v[144:147], off nt
	s_nop 1
	v_cvt_pk_bf16_f32 v144, v92, v93
	v_cvt_pk_bf16_f32 v145, v94, v95
	v_cvt_pk_bf16_f32 v146, v88, v89
	v_cvt_pk_bf16_f32 v147, v90, v91
	global_store_dwordx4 v[162:163], v[144:147], off offset:256 nt
	v_add_u32_e32 v162, 32, v157
	v_mad_i64_i32 v[162:163], s[28:29], v162, s52, v[160:161]
	v_lshl_add_u64 v[162:163], v[162:163], 0, s[4:5]
	v_cvt_pk_bf16_f32 v144, v100, v101
	v_cvt_pk_bf16_f32 v145, v102, v103
	v_cvt_pk_bf16_f32 v146, v96, v97
	v_cvt_pk_bf16_f32 v147, v98, v99
	v_lshl_add_u64 v[162:163], v[162:163], 0, v[158:159]
	global_store_dwordx4 v[162:163], v[144:147], off nt
	s_nop 1
	v_cvt_pk_bf16_f32 v144, v76, v77
	v_cvt_pk_bf16_f32 v145, v78, v79
	v_cvt_pk_bf16_f32 v146, v72, v73
	v_cvt_pk_bf16_f32 v147, v74, v75
	global_store_dwordx4 v[162:163], v[144:147], off offset:256 nt
	v_add_u32_e32 v162, 48, v157
	v_mad_i64_i32 v[162:163], s[28:29], v162, s52, v[160:161]
	v_lshl_add_u64 v[162:163], v[162:163], 0, s[4:5]
	v_cvt_pk_bf16_f32 v144, v84, v85
	v_cvt_pk_bf16_f32 v145, v86, v87
	v_cvt_pk_bf16_f32 v146, v80, v81
	v_cvt_pk_bf16_f32 v147, v82, v83
	v_lshl_add_u64 v[162:163], v[162:163], 0, v[158:159]
	global_store_dwordx4 v[162:163], v[144:147], off nt
	s_nop 1
	v_cvt_pk_bf16_f32 v144, v68, v69
	v_cvt_pk_bf16_f32 v145, v70, v71
	v_cvt_pk_bf16_f32 v146, v64, v65
	v_cvt_pk_bf16_f32 v147, v66, v67
	global_store_dwordx4 v[162:163], v[144:147], off offset:256 nt
	v_add_u32_e32 v162, 0x80, v157
	v_mad_i64_i32 v[162:163], s[28:29], v162, s52, v[160:161]
	v_lshl_add_u64 v[162:163], v[162:163], 0, s[4:5]
	v_cvt_pk_bf16_f32 v144, v60, v61
	v_cvt_pk_bf16_f32 v145, v62, v63
	v_cvt_pk_bf16_f32 v146, v56, v57
	v_cvt_pk_bf16_f32 v147, v58, v59
	v_lshl_add_u64 v[162:163], v[162:163], 0, v[158:159]
	global_store_dwordx4 v[162:163], v[144:147], off nt
	s_nop 1
	v_cvt_pk_bf16_f32 v144, v44, v45
	v_cvt_pk_bf16_f32 v145, v46, v47
	v_cvt_pk_bf16_f32 v146, v40, v41
	v_cvt_pk_bf16_f32 v147, v42, v43
	global_store_dwordx4 v[162:163], v[144:147], off offset:256 nt
	v_add_u32_e32 v162, 0x90, v157
	v_mad_i64_i32 v[162:163], s[28:29], v162, s52, v[160:161]
	v_lshl_add_u64 v[162:163], v[162:163], 0, s[4:5]
	v_cvt_pk_bf16_f32 v144, v52, v53
	v_cvt_pk_bf16_f32 v145, v54, v55
	v_cvt_pk_bf16_f32 v146, v48, v49
	v_cvt_pk_bf16_f32 v147, v50, v51
	v_lshl_add_u64 v[162:163], v[162:163], 0, v[158:159]
	global_store_dwordx4 v[162:163], v[144:147], off nt
	s_nop 1
	v_cvt_pk_bf16_f32 v144, v28, v29
	v_cvt_pk_bf16_f32 v145, v30, v31
	v_cvt_pk_bf16_f32 v146, v24, v25
	v_cvt_pk_bf16_f32 v147, v26, v27
	global_store_dwordx4 v[162:163], v[144:147], off offset:256 nt
	v_add_u32_e32 v162, 0xa0, v157
	v_mad_i64_i32 v[162:163], s[28:29], v162, s52, v[160:161]
	v_lshl_add_u64 v[162:163], v[162:163], 0, s[4:5]
	v_add_u32_e32 v157, 0xb0, v157
	v_cvt_pk_bf16_f32 v144, v36, v37
	v_cvt_pk_bf16_f32 v145, v38, v39
	v_cvt_pk_bf16_f32 v146, v32, v33
	v_cvt_pk_bf16_f32 v147, v34, v35
	v_lshl_add_u64 v[162:163], v[162:163], 0, v[158:159]
	v_mad_i64_i32 v[160:161], s[28:29], v157, s52, v[160:161]
	global_store_dwordx4 v[162:163], v[144:147], off nt
	v_lshl_add_u64 v[160:161], v[160:161], 0, s[4:5]
	v_lshl_add_u64 v[158:159], v[160:161], 0, v[158:159]
	v_cvt_pk_bf16_f32 v144, v12, v13
	v_cvt_pk_bf16_f32 v145, v14, v15
	v_cvt_pk_bf16_f32 v146, v8, v9
	v_cvt_pk_bf16_f32 v147, v10, v11
	global_store_dwordx4 v[162:163], v[144:147], off offset:256 nt
	s_nop 1
	v_cvt_pk_bf16_f32 v144, v20, v21
	v_cvt_pk_bf16_f32 v145, v22, v23
	v_cvt_pk_bf16_f32 v146, v16, v17
	v_cvt_pk_bf16_f32 v147, v18, v19
	global_store_dwordx4 v[158:159], v[144:147], off nt
	s_nop 1
	v_cvt_pk_bf16_f32 v144, v4, v5
	v_cvt_pk_bf16_f32 v145, v6, v7
	v_cvt_pk_bf16_f32 v146, v0, v1
	v_cvt_pk_bf16_f32 v147, v2, v3
	global_store_dwordx4 v[158:159], v[144:147], off offset:256 nt

.LBB0_1212:
	s_andn2_b64 vcc, exec, s[28:29]
	s_cbranch_vccnz .LBB0_1230
	v_and_b32_e32 v147, 64, v154
	v_xor_b32_e32 v146, 16, v154
	v_add_u32_e32 v157, 64, v147
	v_cmp_lt_i32_e32 vcc, v146, v157
	v_mul_f32_e32 v158, 0x3d372713, v120
	v_mul_f32_e32 v158, v120, v158
	v_cndmask_b32_e32 v146, v154, v146, vcc
	v_lshlrev_b32_e32 v147, 2, v146
	v_xor_b32_e32 v146, 32, v154
	v_cmp_lt_i32_e32 vcc, v146, v157
	v_mul_f32_e32 v157, 0x3d372713, v124
	v_mul_f32_e32 v157, v124, v157
	v_fma_f32 v157, v124, v157, v124
	v_mul_f32_e32 v157, 0x3f4c422a, v157
	v_fma_f32 v158, v120, v158, v120
	v_mul_f32_e32 v157, -2.0, v157
	v_mul_f32_e32 v158, 0x3f4c422a, v158
	v_mul_f32_e32 v157, 0x3fb8aa3b, v157
	v_mul_f32_e32 v158, -2.0, v158
	v_exp_f32_e32 v157, v157
	v_mul_f32_e32 v158, 0x3fb8aa3b, v158
	v_exp_f32_e32 v159, v158
	v_mul_f32_e32 v164, 0x3d372713, v126
	v_mul_f32_e32 v164, v126, v164
	v_mul_f32_e32 v168, 0x3d372713, v127
	v_fma_f32 v164, v126, v164, v126
	v_mul_f32_e32 v168, v127, v168
	v_add_f32_e32 v157, 1.0, v157
	v_mul_f32_e32 v164, 0x3f4c422a, v164
	v_fma_f32 v168, v127, v168, v127
	v_rcp_f32_e32 v158, v157
	v_add_f32_e32 v157, 1.0, v159
	v_mul_f32_e32 v159, 0x3d372713, v125
	v_mul_f32_e32 v164, -2.0, v164
	v_mul_f32_e32 v168, 0x3f4c422a, v168
	v_mul_f32_e32 v159, v125, v159
	v_mul_f32_e32 v160, 0x3d372713, v121
	v_mul_f32_e32 v164, 0x3fb8aa3b, v164
	v_mul_f32_e32 v168, -2.0, v168
	v_fma_f32 v159, v125, v159, v125
	v_mul_f32_e32 v160, v121, v160
	v_exp_f32_e32 v166, v164
	v_mul_f32_e32 v164, 0x3d372713, v122
	v_mul_f32_e32 v168, 0x3fb8aa3b, v168
	v_mul_f32_e32 v159, 0x3f4c422a, v159
	v_fma_f32 v160, v121, v160, v121
	v_mul_f32_e32 v164, v122, v164
	v_exp_f32_e32 v169, v168
	v_mul_f32_e32 v168, 0x3d372713, v123
	v_mul_f32_e32 v159, -2.0, v159
	v_mul_f32_e32 v160, 0x3f4c422a, v160
	v_fma_f32 v164, v122, v164, v122
	v_mul_f32_e32 v168, v123, v168
	v_mul_f32_e32 v159, 0x3fb8aa3b, v159
	v_mul_f32_e32 v160, -2.0, v160
	v_mul_f32_e32 v164, 0x3f4c422a, v164
	v_fma_f32 v168, v123, v168, v123
	v_exp_f32_e32 v159, v159
	v_mul_f32_e32 v160, 0x3fb8aa3b, v160
	v_mul_f32_e32 v164, -2.0, v164
	v_mul_f32_e32 v168, 0x3f4c422a, v168
	v_exp_f32_e32 v161, v160
	v_mul_f32_e32 v164, 0x3fb8aa3b, v164
	v_mul_f32_e32 v168, -2.0, v168
	v_exp_f32_e32 v167, v164
	v_mul_f32_e32 v168, 0x3fb8aa3b, v168
	v_exp_f32_e32 v170, v168
	v_rcp_f32_e32 v160, v157
	v_add_f32_e32 v157, 1.0, v159
	v_rcp_f32_e32 v159, v157
	v_add_f32_e32 v157, 1.0, v161
	v_rcp_f32_e32 v161, v157
	v_add_f32_e32 v167, 1.0, v167
	v_rcp_f32_e32 v168, v167
	v_add_f32_e32 v167, 1.0, v169
	v_add_f32_e32 v169, 1.0, v170
	v_add_f32_e32 v166, 1.0, v166
	v_rcp_f32_e32 v169, v169
	v_rcp_f32_e32 v166, v166
	v_rcp_f32_e32 v167, v167
	v_pk_mul_f32 v[160:161], v[120:121], v[160:161]
	v_pk_mul_f32 v[162:163], v[124:125], v[158:159]
	v_pk_fma_f32 v[158:159], v[124:125], v[158:159], v[160:161]
	v_pk_mul_f32 v[168:169], v[122:123], v[168:169]
	v_add_f32_e32 v158, 0, v158
	v_add_f32_e32 v172, v159, v158
	v_pk_fma_f32 v[158:159], v[126:127], v[166:167], v[168:169]
	v_pk_mul_f32 v[170:171], v[126:127], v[166:167]
	v_add_f32_e32 v158, v158, v172
	v_pk_mul_f32 v[166:167], v[168:169], v[168:169]
	v_add_f32_e32 v174, v159, v158
	v_pk_fma_f32 v[166:167], v[170:171], v[170:171], v[166:167]
	v_cvt_pk_bf16_f32 v159, v170, v171
	v_mul_f32_e32 v170, 0x3d372713, v109
	v_mul_f32_e32 v170, v109, v170
	v_fma_f32 v170, v109, v170, v109
	v_mul_f32_e32 v170, 0x3f4c422a, v170
	v_mul_f32_e32 v170, -2.0, v170
	v_pk_mul_f32 v[164:165], v[160:161], v[160:161]
	v_cvt_pk_bf16_f32 v160, v160, v161
	v_cvt_pk_bf16_f32 v161, v168, v169
	v_mul_f32_e32 v169, 0x3d372713, v104
	v_mul_f32_e32 v170, 0x3fb8aa3b, v170
	v_mul_f32_e32 v169, v104, v169
	v_exp_f32_e32 v171, v170
	v_mul_f32_e32 v170, 0x3d372713, v105
	v_mul_f32_e32 v168, 0x3d372713, v108
	v_fma_f32 v169, v104, v169, v104
	v_mul_f32_e32 v170, v105, v170
	v_mul_f32_e32 v168, v108, v168
	v_mul_f32_e32 v169, 0x3f4c422a, v169
	v_fma_f32 v170, v105, v170, v105
	v_fma_f32 v168, v108, v168, v108
	v_mul_f32_e32 v169, -2.0, v169
	v_mul_f32_e32 v170, 0x3f4c422a, v170
	v_mul_f32_e32 v168, 0x3f4c422a, v168
	v_mul_f32_e32 v169, 0x3fb8aa3b, v169
	v_mul_f32_e32 v170, -2.0, v170
	v_mul_f32_e32 v168, -2.0, v168
	v_exp_f32_e32 v169, v169
	v_mul_f32_e32 v170, 0x3fb8aa3b, v170
	v_mul_f32_e32 v168, 0x3fb8aa3b, v168
	v_exp_f32_e32 v172, v170
	v_exp_f32_e32 v168, v168
	v_add_f32_e32 v169, 1.0, v169
	v_rcp_f32_e32 v170, v169
	v_add_f32_e32 v169, 1.0, v171
	v_add_f32_e32 v171, 1.0, v172
	v_add_f32_e32 v168, 1.0, v168
	v_rcp_f32_e32 v171, v171
	v_rcp_f32_e32 v168, v168
	v_rcp_f32_e32 v169, v169
	v_mul_f32_e32 v178, 0x3d372713, v111
	v_pk_mul_f32 v[170:171], v[104:105], v[170:171]
	v_mul_f32_e32 v178, v111, v178
	v_pk_mul_f32 v[172:173], v[108:109], v[168:169]
	v_pk_fma_f32 v[168:169], v[108:109], v[168:169], v[170:171]
	v_fma_f32 v178, v111, v178, v111
	v_add_f32_e32 v168, v174, v168
	v_mul_f32_e32 v174, 0x3d372713, v110
	v_mul_f32_e32 v174, v110, v174
	v_fma_f32 v174, v110, v174, v110
	v_mul_f32_e32 v174, 0x3f4c422a, v174
	v_mul_f32_e32 v174, -2.0, v174
	v_mul_f32_e32 v178, 0x3f4c422a, v178
	v_mul_f32_e32 v174, 0x3fb8aa3b, v174
	v_mul_f32_e32 v178, -2.0, v178
	v_exp_f32_e32 v176, v174
	v_mul_f32_e32 v174, 0x3d372713, v106
	v_mul_f32_e32 v178, 0x3fb8aa3b, v178
	v_mul_f32_e32 v174, v106, v174
	v_exp_f32_e32 v179, v178
	v_mul_f32_e32 v178, 0x3d372713, v107
	v_fma_f32 v174, v106, v174, v106
	v_mul_f32_e32 v178, v107, v178
	v_mul_f32_e32 v174, 0x3f4c422a, v174
	v_fma_f32 v178, v107, v178, v107
	v_mul_f32_e32 v174, -2.0, v174
	v_mul_f32_e32 v178, 0x3f4c422a, v178
	v_mul_f32_e32 v174, 0x3fb8aa3b, v174
	v_mul_f32_e32 v178, -2.0, v178
	v_exp_f32_e32 v177, v174
	v_mul_f32_e32 v178, 0x3fb8aa3b, v178
	v_exp_f32_e32 v180, v178
	v_add_f32_e32 v176, 1.0, v176
	v_add_f32_e32 v177, 1.0, v177
	v_rcp_f32_e32 v178, v177
	v_add_f32_e32 v177, 1.0, v179
	v_add_f32_e32 v179, 1.0, v180
	v_rcp_f32_e32 v179, v179
	v_rcp_f32_e32 v176, v176
	v_rcp_f32_e32 v177, v177
	v_pk_fma_f32 v[164:165], v[162:163], v[162:163], v[164:165]
	v_pk_mul_f32 v[174:175], v[170:171], v[170:171]
	v_add_f32_e32 v164, v164, v165
	v_pk_mul_f32 v[178:179], v[106:107], v[178:179]
	v_add_f32_e32 v164, v166, v164
	v_pk_fma_f32 v[174:175], v[172:173], v[172:173], v[174:175]
	v_add_f32_e32 v180, v169, v168
	v_pk_mul_f32 v[168:169], v[110:111], v[176:177]
	v_pk_fma_f32 v[176:177], v[110:111], v[176:177], v[178:179]
	v_add_f32_e32 v164, v167, v164
	v_add_f32_e32 v176, v176, v180
	v_pk_mul_f32 v[180:181], v[178:179], v[178:179]
	v_add_f32_e32 v164, v164, v174
	v_pk_fma_f32 v[180:181], v[168:169], v[168:169], v[180:181]
	v_add_f32_e32 v164, v175, v164
	v_add_f32_e32 v164, v180, v164
	s_lshl_b32 s4, s16, 8
	v_add_f32_e32 v176, v177, v176
	v_add_f32_e32 v164, v181, v164
	s_add_i32 s4, s4, s41
	ds_bpermute_b32 v165, v147, v176
	ds_bpermute_b32 v174, v147, v164
	v_add_u32_e32 v157, s4, v155
	v_cvt_pk_bf16_f32 v158, v162, v163
	v_mov_b64_e32 v[162:163], s[14:15]
	v_lshl_add_u32 v144, v156, 3, s42
	v_mad_i64_i32 v[162:163], s[28:29], v157, s52, v[162:163]
	s_lshl_b32 s4, s6, 9
	v_ashrrev_i32_e32 v145, 31, v144
	v_lshl_add_u64 v[162:163], v[162:163], 0, s[4:5]
	v_cndmask_b32_e32 v146, v154, v146, vcc
	v_lshl_add_u64 v[166:167], v[144:145], 1, v[162:163]
	v_lshlrev_b32_e32 v146, 2, v146
	global_store_dwordx4 v[166:167], v[158:161], off nt
	v_cmp_eq_u32_e32 vcc, 0, v156
	v_cvt_pk_bf16_f32 v162, v172, v173
	s_waitcnt lgkmcnt(0)
	v_add_f32_e32 v158, v176, v165
	v_add_f32_e32 v159, v164, v174
	ds_bpermute_b32 v160, v146, v158
	ds_bpermute_b32 v161, v146, v159
	v_cvt_pk_bf16_f32 v163, v168, v169
	v_cvt_pk_bf16_f32 v164, v170, v171
	v_cvt_pk_bf16_f32 v165, v178, v179
	global_store_dwordx4 v[166:167], v[162:165], off offset:256 nt
	s_and_saveexec_b64 s[28:29], vcc
	s_cbranch_execz .LBB0_1215
	s_waitcnt lgkmcnt(0)
	v_add_f32_e32 v160, v158, v160
	v_lshlrev_b32_e32 v158, 1, v157
	v_add_f32_e32 v161, v159, v161
	v_ashrrev_i32_e32 v159, 31, v158
	v_lshl_add_u64 v[158:159], v[158:159], 2, s[48:49]
	global_atomic_add_f32 v[158:159], v160, off
	global_atomic_add_f32 v[158:159], v161, off offset:4
.LBB0_1215:
	s_or_b64 exec, exec, s[28:29]
	v_mul_f32_e32 v158, 0x3d372713, v116
	v_mul_f32_e32 v158, v116, v158
	v_mul_f32_e32 v159, 0x3d372713, v112
	v_fma_f32 v158, v116, v158, v116
	v_mul_f32_e32 v159, v112, v159
	v_mul_f32_e32 v158, 0x3f4c422a, v158
	v_fma_f32 v159, v112, v159, v112
	v_mul_f32_e32 v158, -2.0, v158
	v_mul_f32_e32 v159, 0x3f4c422a, v159
	v_mul_f32_e32 v158, 0x3fb8aa3b, v158
	v_mul_f32_e32 v159, -2.0, v159
	v_exp_f32_e32 v158, v158
	v_mul_f32_e32 v159, 0x3fb8aa3b, v159
	v_exp_f32_e32 v159, v159
	s_waitcnt lgkmcnt(0)
	v_mul_f32_e32 v161, 0x3d372713, v113
	v_add_f32_e32 v158, 1.0, v158
	v_rcp_f32_e32 v160, v158
	v_add_f32_e32 v158, 1.0, v159
	v_mul_f32_e32 v159, 0x3d372713, v117
	v_mul_f32_e32 v159, v117, v159
	v_fma_f32 v159, v117, v159, v117
	v_mul_f32_e32 v161, v113, v161
	v_mul_f32_e32 v159, 0x3f4c422a, v159
	v_fma_f32 v161, v113, v161, v113
	v_mul_f32_e32 v159, -2.0, v159
	v_mul_f32_e32 v161, 0x3f4c422a, v161
	v_mul_f32_e32 v159, 0x3fb8aa3b, v159
	v_mul_f32_e32 v161, -2.0, v161
	v_exp_f32_e32 v159, v159
	v_mul_f32_e32 v161, 0x3fb8aa3b, v161
	v_exp_f32_e32 v163, v161
	v_rcp_f32_e32 v162, v158
	v_add_f32_e32 v158, 1.0, v159
	v_rcp_f32_e32 v161, v158
	v_add_f32_e32 v158, 1.0, v163
	v_rcp_f32_e32 v163, v158
	v_mul_f32_e32 v166, 0x3d372713, v114
	v_pk_mul_f32 v[164:165], v[116:117], v[160:161]
	v_mul_f32_e32 v166, v114, v166
	v_pk_mul_f32 v[162:163], v[112:113], v[162:163]
	v_fma_f32 v166, v114, v166, v114
	v_pk_fma_f32 v[160:161], v[116:117], v[160:161], v[162:163]
	v_mul_f32_e32 v166, 0x3f4c422a, v166
	v_add_f32_e32 v159, 0, v160
	v_mul_f32_e32 v160, 0x3d372713, v118
	v_mul_f32_e32 v160, v118, v160
	v_fma_f32 v160, v118, v160, v118
	v_mul_f32_e32 v160, 0x3f4c422a, v160
	v_mul_f32_e32 v160, -2.0, v160
	v_mul_f32_e32 v160, 0x3fb8aa3b, v160
	v_mul_f32_e32 v166, -2.0, v166
	v_exp_f32_e32 v160, v160
	v_mul_f32_e32 v166, 0x3fb8aa3b, v166
	v_exp_f32_e32 v169, v166
	v_mul_f32_e32 v170, 0x3d372713, v115
	v_add_f32_e32 v160, 1.0, v160
	v_rcp_f32_e32 v168, v160
	v_add_f32_e32 v160, 1.0, v169
	v_mul_f32_e32 v169, 0x3d372713, v119
	v_mul_f32_e32 v169, v119, v169
	v_fma_f32 v169, v119, v169, v119
	v_mul_f32_e32 v170, v115, v170
	v_mul_f32_e32 v169, 0x3f4c422a, v169
	v_fma_f32 v170, v115, v170, v115
	v_mul_f32_e32 v169, -2.0, v169
	v_mul_f32_e32 v170, 0x3f4c422a, v170
	v_mul_f32_e32 v169, 0x3fb8aa3b, v169
	v_mul_f32_e32 v170, -2.0, v170
	v_exp_f32_e32 v169, v169
	v_mul_f32_e32 v170, 0x3fb8aa3b, v170
	v_exp_f32_e32 v171, v170
	v_rcp_f32_e32 v170, v160
	v_add_f32_e32 v160, 1.0, v169
	v_rcp_f32_e32 v169, v160
	v_add_f32_e32 v160, 1.0, v171
	v_rcp_f32_e32 v171, v160
	v_add_f32_e32 v159, v161, v159
	v_pk_mul_f32 v[172:173], v[118:119], v[168:169]
	v_pk_mul_f32 v[166:167], v[162:163], v[162:163]
	v_pk_mul_f32 v[170:171], v[114:115], v[170:171]
	v_cvt_pk_bf16_f32 v162, v162, v163
	v_pk_fma_f32 v[160:161], v[118:119], v[168:169], v[170:171]
	v_pk_mul_f32 v[168:169], v[170:171], v[170:171]
	v_add_f32_e32 v159, v160, v159
	v_pk_fma_f32 v[168:169], v[172:173], v[172:173], v[168:169]
	v_add_f32_e32 v159, v161, v159
	v_cvt_pk_bf16_f32 v161, v172, v173
	v_mul_f32_e32 v172, 0x3d372713, v93
	v_mul_f32_e32 v172, v93, v172
	v_fma_f32 v172, v93, v172, v93
	v_mul_f32_e32 v172, 0x3f4c422a, v172
	v_mul_f32_e32 v172, -2.0, v172
	v_cvt_pk_bf16_f32 v163, v170, v171
	v_mul_f32_e32 v171, 0x3d372713, v88
	v_mul_f32_e32 v172, 0x3fb8aa3b, v172
	v_mul_f32_e32 v171, v88, v171
	v_exp_f32_e32 v173, v172
	v_mul_f32_e32 v172, 0x3d372713, v89
	v_mul_f32_e32 v170, 0x3d372713, v92
	v_fma_f32 v171, v88, v171, v88
	v_mul_f32_e32 v172, v89, v172
	v_mul_f32_e32 v170, v92, v170
	v_mul_f32_e32 v171, 0x3f4c422a, v171
	v_fma_f32 v172, v89, v172, v89
	v_fma_f32 v170, v92, v170, v92
	v_mul_f32_e32 v171, -2.0, v171
	v_mul_f32_e32 v172, 0x3f4c422a, v172
	v_mul_f32_e32 v170, 0x3f4c422a, v170
	v_mul_f32_e32 v171, 0x3fb8aa3b, v171
	v_mul_f32_e32 v172, -2.0, v172
	v_mul_f32_e32 v170, -2.0, v170
	v_exp_f32_e32 v171, v171
	v_mul_f32_e32 v172, 0x3fb8aa3b, v172
	v_mul_f32_e32 v170, 0x3fb8aa3b, v170
	v_exp_f32_e32 v174, v172
	v_exp_f32_e32 v170, v170
	v_add_f32_e32 v171, 1.0, v171
	v_rcp_f32_e32 v172, v171
	v_add_f32_e32 v171, 1.0, v173
	v_add_f32_e32 v173, 1.0, v174
	v_add_f32_e32 v170, 1.0, v170
	v_rcp_f32_e32 v173, v173
	v_rcp_f32_e32 v170, v170
	v_rcp_f32_e32 v171, v171
	v_mul_f32_e32 v176, 0x3d372713, v90
	v_pk_mul_f32 v[172:173], v[88:89], v[172:173]
	v_mul_f32_e32 v176, v90, v176
	v_pk_mul_f32 v[174:175], v[92:93], v[170:171]
	v_pk_fma_f32 v[170:171], v[92:93], v[170:171], v[172:173]
	v_fma_f32 v176, v90, v176, v90
	v_add_f32_e32 v159, v159, v170
	v_mul_f32_e32 v170, 0x3d372713, v94
	v_mul_f32_e32 v170, v94, v170
	v_fma_f32 v170, v94, v170, v94
	v_mul_f32_e32 v170, 0x3f4c422a, v170
	v_mul_f32_e32 v170, -2.0, v170
	v_mul_f32_e32 v176, 0x3f4c422a, v176
	v_mul_f32_e32 v170, 0x3fb8aa3b, v170
	v_mul_f32_e32 v176, -2.0, v176
	v_exp_f32_e32 v170, v170
	v_mul_f32_e32 v176, 0x3fb8aa3b, v176
	v_exp_f32_e32 v179, v176
	v_mul_f32_e32 v180, 0x3d372713, v91
	v_add_f32_e32 v170, 1.0, v170
	v_rcp_f32_e32 v178, v170
	v_add_f32_e32 v170, 1.0, v179
	v_mul_f32_e32 v179, 0x3d372713, v95
	v_mul_f32_e32 v179, v95, v179
	v_fma_f32 v179, v95, v179, v95
	v_mul_f32_e32 v180, v91, v180
	v_mul_f32_e32 v179, 0x3f4c422a, v179
	v_fma_f32 v180, v91, v180, v91
	v_mul_f32_e32 v179, -2.0, v179
	v_mul_f32_e32 v180, 0x3f4c422a, v180
	v_mul_f32_e32 v179, 0x3fb8aa3b, v179
	v_mul_f32_e32 v180, -2.0, v180
	v_exp_f32_e32 v179, v179
	v_mul_f32_e32 v180, 0x3fb8aa3b, v180
	v_exp_f32_e32 v181, v180
	v_rcp_f32_e32 v180, v170
	v_add_f32_e32 v170, 1.0, v179
	v_rcp_f32_e32 v179, v170
	v_add_f32_e32 v170, 1.0, v181
	v_rcp_f32_e32 v181, v170
	v_pk_fma_f32 v[166:167], v[164:165], v[164:165], v[166:167]
	v_pk_mul_f32 v[176:177], v[172:173], v[172:173]
	v_add_f32_e32 v166, v166, v167
	v_add_f32_e32 v166, v168, v166
	v_pk_fma_f32 v[176:177], v[174:175], v[174:175], v[176:177]
	v_pk_mul_f32 v[180:181], v[90:91], v[180:181]
	v_add_f32_e32 v166, v169, v166
	v_add_f32_e32 v159, v171, v159
	v_pk_mul_f32 v[170:171], v[94:95], v[178:179]
	v_pk_mul_f32 v[182:183], v[180:181], v[180:181]
	v_add_f32_e32 v166, v166, v176
	v_pk_fma_f32 v[178:179], v[94:95], v[178:179], v[180:181]
	v_pk_fma_f32 v[182:183], v[170:171], v[170:171], v[182:183]
	v_add_f32_e32 v166, v177, v166
	v_add_f32_e32 v159, v178, v159
	v_add_f32_e32 v166, v182, v166
	v_add_f32_e32 v159, v179, v159
	v_add_f32_e32 v166, v183, v166
	ds_bpermute_b32 v167, v147, v159
	ds_bpermute_b32 v176, v147, v166
	s_lshl_b32 s4, s6, 8
	v_add_u32_e32 v158, 16, v157
	v_cvt_pk_bf16_f32 v160, v164, v165
	v_mov_b64_e32 v[164:165], s[14:15]
	v_mad_i64_i32 v[164:165], s[28:29], v158, s52, v[164:165]
	s_lshl_b32 s4, s4, 1
	v_lshl_add_u64 v[164:165], v[164:165], 0, s[4:5]
	v_lshl_add_u64 v[168:169], v[144:145], 1, v[164:165]
	global_store_dwordx4 v[168:169], v[160:163], off nt
	s_waitcnt lgkmcnt(0)
	v_add_f32_e32 v159, v159, v167
	ds_bpermute_b32 v161, v146, v159
	v_add_f32_e32 v160, v166, v176
	ds_bpermute_b32 v162, v146, v160
	v_cvt_pk_bf16_f32 v164, v174, v175
	v_cvt_pk_bf16_f32 v165, v170, v171
	v_cvt_pk_bf16_f32 v166, v172, v173
	v_cvt_pk_bf16_f32 v167, v180, v181
	global_store_dwordx4 v[168:169], v[164:167], off offset:256 nt
	s_and_saveexec_b64 s[28:29], vcc
	s_cbranch_execz .LBB0_1217
	v_lshlrev_b32_e32 v158, 1, v158
	s_waitcnt lgkmcnt(0)
	v_add_f32_e32 v161, v159, v161
	v_ashrrev_i32_e32 v159, 31, v158
	v_lshl_add_u64 v[158:159], v[158:159], 2, s[48:49]
	v_add_f32_e32 v160, v160, v162
	global_atomic_add_f32 v[158:159], v161, off
	global_atomic_add_f32 v[158:159], v160, off offset:4
.LBB0_1217:
	s_or_b64 exec, exec, s[28:29]
	v_mul_f32_e32 v158, 0x3d372713, v100
	v_mul_f32_e32 v158, v100, v158
	v_mul_f32_e32 v159, 0x3d372713, v96
	v_fma_f32 v158, v100, v158, v100
	v_mul_f32_e32 v159, v96, v159
	v_mul_f32_e32 v158, 0x3f4c422a, v158
	v_fma_f32 v159, v96, v159, v96
	v_mul_f32_e32 v158, -2.0, v158
	v_mul_f32_e32 v159, 0x3f4c422a, v159
	v_mul_f32_e32 v158, 0x3fb8aa3b, v158
	v_mul_f32_e32 v159, -2.0, v159
	v_exp_f32_e32 v158, v158
	v_mul_f32_e32 v159, 0x3fb8aa3b, v159
	v_exp_f32_e32 v159, v159
	s_waitcnt lgkmcnt(0)
	v_mul_f32_e32 v161, 0x3d372713, v97
	v_add_f32_e32 v158, 1.0, v158
	v_rcp_f32_e32 v160, v158
	v_add_f32_e32 v158, 1.0, v159
	v_mul_f32_e32 v159, 0x3d372713, v101
	v_mul_f32_e32 v159, v101, v159
	v_fma_f32 v159, v101, v159, v101
	v_mul_f32_e32 v161, v97, v161
	v_mul_f32_e32 v159, 0x3f4c422a, v159
	v_fma_f32 v161, v97, v161, v97
	v_mul_f32_e32 v159, -2.0, v159
	v_mul_f32_e32 v161, 0x3f4c422a, v161
	v_mul_f32_e32 v159, 0x3fb8aa3b, v159
	v_mul_f32_e32 v161, -2.0, v161
	v_exp_f32_e32 v159, v159
	v_mul_f32_e32 v161, 0x3fb8aa3b, v161
	v_exp_f32_e32 v163, v161
	v_rcp_f32_e32 v162, v158
	v_add_f32_e32 v158, 1.0, v159
	v_rcp_f32_e32 v161, v158
	v_add_f32_e32 v158, 1.0, v163
	v_rcp_f32_e32 v163, v158
	v_mul_f32_e32 v166, 0x3d372713, v98
	v_pk_mul_f32 v[164:165], v[100:101], v[160:161]
	v_mul_f32_e32 v166, v98, v166
	v_pk_mul_f32 v[162:163], v[96:97], v[162:163]
	v_fma_f32 v166, v98, v166, v98
	v_pk_fma_f32 v[160:161], v[100:101], v[160:161], v[162:163]
	v_mul_f32_e32 v166, 0x3f4c422a, v166
	v_add_f32_e32 v159, 0, v160
	v_mul_f32_e32 v160, 0x3d372713, v102
	v_mul_f32_e32 v160, v102, v160
	v_fma_f32 v160, v102, v160, v102
	v_mul_f32_e32 v160, 0x3f4c422a, v160
	v_mul_f32_e32 v160, -2.0, v160
	v_mul_f32_e32 v160, 0x3fb8aa3b, v160
	v_mul_f32_e32 v166, -2.0, v166
	v_exp_f32_e32 v160, v160
	v_mul_f32_e32 v166, 0x3fb8aa3b, v166
	v_exp_f32_e32 v169, v166
	v_mul_f32_e32 v170, 0x3d372713, v99
	v_add_f32_e32 v160, 1.0, v160
	v_rcp_f32_e32 v168, v160
	v_add_f32_e32 v160, 1.0, v169
	v_mul_f32_e32 v169, 0x3d372713, v103
	v_mul_f32_e32 v169, v103, v169
	v_fma_f32 v169, v103, v169, v103
	v_mul_f32_e32 v170, v99, v170
	v_mul_f32_e32 v169, 0x3f4c422a, v169
	v_fma_f32 v170, v99, v170, v99
	v_mul_f32_e32 v169, -2.0, v169
	v_mul_f32_e32 v170, 0x3f4c422a, v170
	v_mul_f32_e32 v169, 0x3fb8aa3b, v169
	v_mul_f32_e32 v170, -2.0, v170
	v_exp_f32_e32 v169, v169
	v_mul_f32_e32 v170, 0x3fb8aa3b, v170
	v_exp_f32_e32 v171, v170
	v_rcp_f32_e32 v170, v160
	v_add_f32_e32 v160, 1.0, v169
	v_rcp_f32_e32 v169, v160
	v_add_f32_e32 v160, 1.0, v171
	v_rcp_f32_e32 v171, v160
	v_pk_mul_f32 v[166:167], v[162:163], v[162:163]
	v_add_f32_e32 v159, v161, v159
	v_pk_fma_f32 v[166:167], v[164:165], v[164:165], v[166:167]
	v_pk_mul_f32 v[170:171], v[98:99], v[170:171]
	v_pk_mul_f32 v[172:173], v[102:103], v[168:169]
	v_pk_fma_f32 v[160:161], v[102:103], v[168:169], v[170:171]
	v_pk_mul_f32 v[168:169], v[170:171], v[170:171]
	v_add_f32_e32 v159, v160, v159
	v_cvt_pk_bf16_f32 v160, v164, v165
	v_mul_f32_e32 v164, 0x3d372713, v76
	v_pk_fma_f32 v[168:169], v[172:173], v[172:173], v[168:169]
	v_add_f32_e32 v159, v161, v159
	v_cvt_pk_bf16_f32 v161, v172, v173
	v_mul_f32_e32 v164, v76, v164
	v_mul_f32_e32 v172, 0x3d372713, v77
	v_fma_f32 v164, v76, v164, v76
	v_mul_f32_e32 v172, v77, v172
	v_mul_f32_e32 v164, 0x3f4c422a, v164
	v_fma_f32 v172, v77, v172, v77
	v_mul_f32_e32 v164, -2.0, v164
	v_mul_f32_e32 v172, 0x3f4c422a, v172
	v_mul_f32_e32 v164, 0x3fb8aa3b, v164
	v_mul_f32_e32 v172, -2.0, v172
	v_cvt_pk_bf16_f32 v162, v162, v163
	v_cvt_pk_bf16_f32 v163, v170, v171
	v_exp_f32_e32 v170, v164
	v_mul_f32_e32 v164, 0x3d372713, v72
	v_mul_f32_e32 v172, 0x3fb8aa3b, v172
	v_mul_f32_e32 v164, v72, v164
	v_exp_f32_e32 v173, v172
	v_mul_f32_e32 v172, 0x3d372713, v73
	v_fma_f32 v164, v72, v164, v72
	v_mul_f32_e32 v172, v73, v172
	v_mul_f32_e32 v164, 0x3f4c422a, v164
	v_fma_f32 v172, v73, v172, v73
	v_mul_f32_e32 v164, -2.0, v164
	v_mul_f32_e32 v172, 0x3f4c422a, v172
	v_mul_f32_e32 v164, 0x3fb8aa3b, v164
	v_mul_f32_e32 v172, -2.0, v172
	v_exp_f32_e32 v171, v164
	v_mul_f32_e32 v172, 0x3fb8aa3b, v172
	v_exp_f32_e32 v174, v172
	v_add_f32_e32 v170, 1.0, v170
	v_add_f32_e32 v171, 1.0, v171
	v_rcp_f32_e32 v172, v171
	v_add_f32_e32 v171, 1.0, v173
	v_add_f32_e32 v173, 1.0, v174
	v_rcp_f32_e32 v173, v173
	v_rcp_f32_e32 v170, v170
	v_rcp_f32_e32 v171, v171
	v_mul_f32_e32 v176, 0x3d372713, v74
	v_pk_mul_f32 v[172:173], v[72:73], v[172:173]
	v_mul_f32_e32 v176, v74, v176
	v_pk_mul_f32 v[174:175], v[76:77], v[170:171]
	v_pk_fma_f32 v[170:171], v[76:77], v[170:171], v[172:173]
	v_fma_f32 v176, v74, v176, v74
	v_add_f32_e32 v159, v159, v170
	v_mul_f32_e32 v170, 0x3d372713, v78
	v_mul_f32_e32 v170, v78, v170
	v_fma_f32 v170, v78, v170, v78
	v_mul_f32_e32 v170, 0x3f4c422a, v170
	v_mul_f32_e32 v170, -2.0, v170
	v_mul_f32_e32 v176, 0x3f4c422a, v176
	v_mul_f32_e32 v170, 0x3fb8aa3b, v170
	v_mul_f32_e32 v176, -2.0, v176
	v_exp_f32_e32 v170, v170
	v_mul_f32_e32 v176, 0x3fb8aa3b, v176
	v_exp_f32_e32 v179, v176
	v_mul_f32_e32 v180, 0x3d372713, v75
	v_add_f32_e32 v170, 1.0, v170
	v_rcp_f32_e32 v178, v170
	v_add_f32_e32 v170, 1.0, v179
	v_mul_f32_e32 v179, 0x3d372713, v79
	v_mul_f32_e32 v179, v79, v179
	v_fma_f32 v179, v79, v179, v79
	v_mul_f32_e32 v180, v75, v180
	v_mul_f32_e32 v179, 0x3f4c422a, v179
	v_fma_f32 v180, v75, v180, v75
	v_mul_f32_e32 v179, -2.0, v179
	v_mul_f32_e32 v180, 0x3f4c422a, v180
	v_mul_f32_e32 v179, 0x3fb8aa3b, v179
	v_mul_f32_e32 v180, -2.0, v180
	v_exp_f32_e32 v179, v179
	v_mul_f32_e32 v180, 0x3fb8aa3b, v180
	v_exp_f32_e32 v181, v180
	v_rcp_f32_e32 v180, v170
	v_add_f32_e32 v170, 1.0, v179
	v_rcp_f32_e32 v179, v170
	v_add_f32_e32 v170, 1.0, v181
	v_rcp_f32_e32 v181, v170
	v_add_f32_e32 v166, v166, v167
	v_pk_mul_f32 v[176:177], v[172:173], v[172:173]
	v_add_f32_e32 v166, v168, v166
	v_pk_fma_f32 v[176:177], v[174:175], v[174:175], v[176:177]
	v_pk_mul_f32 v[180:181], v[74:75], v[180:181]
	v_add_f32_e32 v166, v169, v166
	v_add_f32_e32 v159, v171, v159
	v_pk_mul_f32 v[170:171], v[78:79], v[178:179]
	v_pk_mul_f32 v[182:183], v[180:181], v[180:181]
	v_add_f32_e32 v166, v166, v176
	v_pk_fma_f32 v[178:179], v[78:79], v[178:179], v[180:181]
	v_pk_fma_f32 v[182:183], v[170:171], v[170:171], v[182:183]
	v_add_f32_e32 v166, v177, v166
	v_add_f32_e32 v159, v178, v159
	v_add_f32_e32 v166, v182, v166
	v_add_f32_e32 v159, v179, v159
	v_add_f32_e32 v166, v183, v166
	ds_bpermute_b32 v167, v147, v159
	ds_bpermute_b32 v176, v147, v166
	v_add_u32_e32 v158, 32, v157
	v_mov_b64_e32 v[164:165], s[14:15]
	v_mad_i64_i32 v[164:165], s[28:29], v158, s52, v[164:165]
	v_lshl_add_u64 v[164:165], v[164:165], 0, s[4:5]
	v_lshl_add_u64 v[168:169], v[144:145], 1, v[164:165]
	global_store_dwordx4 v[168:169], v[160:163], off nt
	s_waitcnt lgkmcnt(0)
	v_add_f32_e32 v159, v159, v167
	ds_bpermute_b32 v161, v146, v159
	v_add_f32_e32 v160, v166, v176
	ds_bpermute_b32 v162, v146, v160
	v_cvt_pk_bf16_f32 v164, v174, v175
	v_cvt_pk_bf16_f32 v165, v170, v171
	v_cvt_pk_bf16_f32 v166, v172, v173
	v_cvt_pk_bf16_f32 v167, v180, v181
	global_store_dwordx4 v[168:169], v[164:167], off offset:256 nt
	s_and_saveexec_b64 s[28:29], vcc
	s_cbranch_execz .LBB0_1219
	v_lshlrev_b32_e32 v158, 1, v158
	s_waitcnt lgkmcnt(0)
	v_add_f32_e32 v161, v159, v161
	v_ashrrev_i32_e32 v159, 31, v158
	v_lshl_add_u64 v[158:159], v[158:159], 2, s[48:49]
	v_add_f32_e32 v160, v160, v162
	global_atomic_add_f32 v[158:159], v161, off
	global_atomic_add_f32 v[158:159], v160, off offset:4
.LBB0_1219:
	s_or_b64 exec, exec, s[28:29]
	v_mul_f32_e32 v158, 0x3d372713, v84
	v_mul_f32_e32 v158, v84, v158
	v_mul_f32_e32 v159, 0x3d372713, v80
	v_fma_f32 v158, v84, v158, v84
	v_mul_f32_e32 v159, v80, v159
	v_mul_f32_e32 v158, 0x3f4c422a, v158
	v_fma_f32 v159, v80, v159, v80
	v_mul_f32_e32 v158, -2.0, v158
	v_mul_f32_e32 v159, 0x3f4c422a, v159
	v_mul_f32_e32 v158, 0x3fb8aa3b, v158
	v_mul_f32_e32 v159, -2.0, v159
	v_exp_f32_e32 v158, v158
	v_mul_f32_e32 v159, 0x3fb8aa3b, v159
	v_exp_f32_e32 v159, v159
	s_waitcnt lgkmcnt(0)
	v_mul_f32_e32 v161, 0x3d372713, v81
	v_add_f32_e32 v158, 1.0, v158
	v_rcp_f32_e32 v160, v158
	v_add_f32_e32 v158, 1.0, v159
	v_mul_f32_e32 v159, 0x3d372713, v85
	v_mul_f32_e32 v159, v85, v159
	v_fma_f32 v159, v85, v159, v85
	v_mul_f32_e32 v161, v81, v161
	v_mul_f32_e32 v159, 0x3f4c422a, v159
	v_fma_f32 v161, v81, v161, v81
	v_mul_f32_e32 v159, -2.0, v159
	v_mul_f32_e32 v161, 0x3f4c422a, v161
	v_mul_f32_e32 v159, 0x3fb8aa3b, v159
	v_mul_f32_e32 v161, -2.0, v161
	v_exp_f32_e32 v159, v159
	v_mul_f32_e32 v161, 0x3fb8aa3b, v161
	v_exp_f32_e32 v163, v161
	v_rcp_f32_e32 v162, v158
	v_add_f32_e32 v158, 1.0, v159
	v_rcp_f32_e32 v161, v158
	v_add_f32_e32 v158, 1.0, v163
	v_rcp_f32_e32 v163, v158
	v_mul_f32_e32 v166, 0x3d372713, v82
	v_pk_mul_f32 v[164:165], v[84:85], v[160:161]
	v_mul_f32_e32 v166, v82, v166
	v_pk_mul_f32 v[162:163], v[80:81], v[162:163]
	v_fma_f32 v166, v82, v166, v82
	v_pk_fma_f32 v[160:161], v[84:85], v[160:161], v[162:163]
	v_mul_f32_e32 v166, 0x3f4c422a, v166
	v_add_f32_e32 v159, 0, v160
	v_mul_f32_e32 v160, 0x3d372713, v86
	v_mul_f32_e32 v160, v86, v160
	v_fma_f32 v160, v86, v160, v86
	v_mul_f32_e32 v160, 0x3f4c422a, v160
	v_mul_f32_e32 v160, -2.0, v160
	v_mul_f32_e32 v160, 0x3fb8aa3b, v160
	v_mul_f32_e32 v166, -2.0, v166
	v_exp_f32_e32 v160, v160
	v_mul_f32_e32 v166, 0x3fb8aa3b, v166
	v_exp_f32_e32 v169, v166
	v_mul_f32_e32 v170, 0x3d372713, v83
	v_add_f32_e32 v160, 1.0, v160
	v_rcp_f32_e32 v168, v160
	v_add_f32_e32 v160, 1.0, v169
	v_mul_f32_e32 v169, 0x3d372713, v87
	v_mul_f32_e32 v169, v87, v169
	v_fma_f32 v169, v87, v169, v87
	v_mul_f32_e32 v170, v83, v170
	v_mul_f32_e32 v169, 0x3f4c422a, v169
	v_fma_f32 v170, v83, v170, v83
	v_mul_f32_e32 v169, -2.0, v169
	v_mul_f32_e32 v170, 0x3f4c422a, v170
	v_mul_f32_e32 v169, 0x3fb8aa3b, v169
	v_mul_f32_e32 v170, -2.0, v170
	v_exp_f32_e32 v169, v169
	v_mul_f32_e32 v170, 0x3fb8aa3b, v170
	v_exp_f32_e32 v171, v170
	v_rcp_f32_e32 v170, v160
	v_add_f32_e32 v160, 1.0, v169
	v_rcp_f32_e32 v169, v160
	v_add_f32_e32 v160, 1.0, v171
	v_rcp_f32_e32 v171, v160
	v_pk_mul_f32 v[166:167], v[162:163], v[162:163]
	v_add_f32_e32 v159, v161, v159
	v_pk_fma_f32 v[166:167], v[164:165], v[164:165], v[166:167]
	v_pk_mul_f32 v[170:171], v[82:83], v[170:171]
	v_pk_mul_f32 v[172:173], v[86:87], v[168:169]
	v_pk_fma_f32 v[160:161], v[86:87], v[168:169], v[170:171]
	v_pk_mul_f32 v[168:169], v[170:171], v[170:171]
	v_add_f32_e32 v159, v160, v159
	v_cvt_pk_bf16_f32 v160, v164, v165
	v_mul_f32_e32 v164, 0x3d372713, v68
	v_pk_fma_f32 v[168:169], v[172:173], v[172:173], v[168:169]
	v_add_f32_e32 v159, v161, v159
	v_cvt_pk_bf16_f32 v161, v172, v173
	v_mul_f32_e32 v164, v68, v164
	v_mul_f32_e32 v172, 0x3d372713, v69
	v_fma_f32 v164, v68, v164, v68
	v_mul_f32_e32 v172, v69, v172
	v_mul_f32_e32 v164, 0x3f4c422a, v164
	v_fma_f32 v172, v69, v172, v69
	v_mul_f32_e32 v164, -2.0, v164
	v_mul_f32_e32 v172, 0x3f4c422a, v172
	v_mul_f32_e32 v164, 0x3fb8aa3b, v164
	v_mul_f32_e32 v172, -2.0, v172
	v_cvt_pk_bf16_f32 v162, v162, v163
	v_cvt_pk_bf16_f32 v163, v170, v171
	v_exp_f32_e32 v170, v164
	v_mul_f32_e32 v164, 0x3d372713, v64
	v_mul_f32_e32 v172, 0x3fb8aa3b, v172
	v_mul_f32_e32 v164, v64, v164
	v_exp_f32_e32 v173, v172
	v_mul_f32_e32 v172, 0x3d372713, v65
	v_fma_f32 v164, v64, v164, v64
	v_mul_f32_e32 v172, v65, v172
	v_mul_f32_e32 v164, 0x3f4c422a, v164
	v_fma_f32 v172, v65, v172, v65
	v_mul_f32_e32 v164, -2.0, v164
	v_mul_f32_e32 v172, 0x3f4c422a, v172
	v_mul_f32_e32 v164, 0x3fb8aa3b, v164
	v_mul_f32_e32 v172, -2.0, v172
	v_exp_f32_e32 v171, v164
	v_mul_f32_e32 v172, 0x3fb8aa3b, v172
	v_exp_f32_e32 v174, v172
	v_add_f32_e32 v170, 1.0, v170
	v_add_f32_e32 v171, 1.0, v171
	v_rcp_f32_e32 v172, v171
	v_add_f32_e32 v171, 1.0, v173
	v_add_f32_e32 v173, 1.0, v174
	v_rcp_f32_e32 v173, v173
	v_rcp_f32_e32 v170, v170
	v_rcp_f32_e32 v171, v171
	v_mul_f32_e32 v176, 0x3d372713, v66
	v_pk_mul_f32 v[172:173], v[64:65], v[172:173]
	v_mul_f32_e32 v176, v66, v176
	v_pk_mul_f32 v[174:175], v[68:69], v[170:171]
	v_pk_fma_f32 v[170:171], v[68:69], v[170:171], v[172:173]
	v_fma_f32 v176, v66, v176, v66
	v_add_f32_e32 v159, v159, v170
	v_mul_f32_e32 v170, 0x3d372713, v70
	v_mul_f32_e32 v170, v70, v170
	v_fma_f32 v170, v70, v170, v70
	v_mul_f32_e32 v170, 0x3f4c422a, v170
	v_mul_f32_e32 v170, -2.0, v170
	v_mul_f32_e32 v176, 0x3f4c422a, v176
	v_mul_f32_e32 v170, 0x3fb8aa3b, v170
	v_mul_f32_e32 v176, -2.0, v176
	v_exp_f32_e32 v170, v170
	v_mul_f32_e32 v176, 0x3fb8aa3b, v176
	v_exp_f32_e32 v179, v176
	v_mul_f32_e32 v180, 0x3d372713, v67
	v_add_f32_e32 v170, 1.0, v170
	v_rcp_f32_e32 v178, v170
	v_add_f32_e32 v170, 1.0, v179
	v_mul_f32_e32 v179, 0x3d372713, v71
	v_mul_f32_e32 v179, v71, v179
	v_fma_f32 v179, v71, v179, v71
	v_mul_f32_e32 v180, v67, v180
	v_mul_f32_e32 v179, 0x3f4c422a, v179
	v_fma_f32 v180, v67, v180, v67
	v_mul_f32_e32 v179, -2.0, v179
	v_mul_f32_e32 v180, 0x3f4c422a, v180
	v_mul_f32_e32 v179, 0x3fb8aa3b, v179
	v_mul_f32_e32 v180, -2.0, v180
	v_exp_f32_e32 v179, v179
	v_mul_f32_e32 v180, 0x3fb8aa3b, v180
	v_exp_f32_e32 v181, v180
	v_rcp_f32_e32 v180, v170
	v_add_f32_e32 v170, 1.0, v179
	v_rcp_f32_e32 v179, v170
	v_add_f32_e32 v170, 1.0, v181
	v_rcp_f32_e32 v181, v170
	v_add_f32_e32 v166, v166, v167
	v_pk_mul_f32 v[176:177], v[172:173], v[172:173]
	v_add_f32_e32 v166, v168, v166
	v_pk_fma_f32 v[176:177], v[174:175], v[174:175], v[176:177]
	v_pk_mul_f32 v[180:181], v[66:67], v[180:181]
	v_add_f32_e32 v166, v169, v166
	v_add_f32_e32 v159, v171, v159
	v_pk_mul_f32 v[170:171], v[70:71], v[178:179]
	v_pk_mul_f32 v[182:183], v[180:181], v[180:181]
	v_add_f32_e32 v166, v166, v176
	v_pk_fma_f32 v[178:179], v[70:71], v[178:179], v[180:181]
	v_pk_fma_f32 v[182:183], v[170:171], v[170:171], v[182:183]
	v_add_f32_e32 v166, v177, v166
	v_add_f32_e32 v159, v178, v159
	v_add_f32_e32 v166, v182, v166
	v_add_f32_e32 v159, v179, v159
	v_add_f32_e32 v166, v183, v166
	ds_bpermute_b32 v167, v147, v159
	ds_bpermute_b32 v176, v147, v166
	v_add_u32_e32 v158, 48, v157
	v_mov_b64_e32 v[164:165], s[14:15]
	v_mad_i64_i32 v[164:165], s[28:29], v158, s52, v[164:165]
	v_lshl_add_u64 v[164:165], v[164:165], 0, s[4:5]
	v_lshl_add_u64 v[168:169], v[144:145], 1, v[164:165]
	global_store_dwordx4 v[168:169], v[160:163], off nt
	s_waitcnt lgkmcnt(0)
	v_add_f32_e32 v159, v159, v167
	ds_bpermute_b32 v161, v146, v159
	v_add_f32_e32 v160, v166, v176
	ds_bpermute_b32 v162, v146, v160
	v_cvt_pk_bf16_f32 v164, v174, v175
	v_cvt_pk_bf16_f32 v165, v170, v171
	v_cvt_pk_bf16_f32 v166, v172, v173
	v_cvt_pk_bf16_f32 v167, v180, v181
	global_store_dwordx4 v[168:169], v[164:167], off offset:256 nt
	s_and_saveexec_b64 s[28:29], vcc
	s_cbranch_execz .LBB0_1221
	v_lshlrev_b32_e32 v158, 1, v158
	s_waitcnt lgkmcnt(0)
	v_add_f32_e32 v161, v159, v161
	v_ashrrev_i32_e32 v159, 31, v158
	v_lshl_add_u64 v[158:159], v[158:159], 2, s[48:49]
	v_add_f32_e32 v160, v160, v162
	global_atomic_add_f32 v[158:159], v161, off
	global_atomic_add_f32 v[158:159], v160, off offset:4
.LBB0_1221:
	s_or_b64 exec, exec, s[28:29]
	v_mul_f32_e32 v158, 0x3d372713, v60
	v_mul_f32_e32 v158, v60, v158
	v_mul_f32_e32 v159, 0x3d372713, v56
	v_fma_f32 v158, v60, v158, v60
	v_mul_f32_e32 v159, v56, v159
	v_mul_f32_e32 v158, 0x3f4c422a, v158
	v_fma_f32 v159, v56, v159, v56
	v_mul_f32_e32 v158, -2.0, v158
	v_mul_f32_e32 v159, 0x3f4c422a, v159
	v_mul_f32_e32 v158, 0x3fb8aa3b, v158
	v_mul_f32_e32 v159, -2.0, v159
	v_exp_f32_e32 v158, v158
	v_mul_f32_e32 v159, 0x3fb8aa3b, v159
	v_exp_f32_e32 v159, v159
	s_waitcnt lgkmcnt(0)
	v_mul_f32_e32 v161, 0x3d372713, v57
	v_add_f32_e32 v158, 1.0, v158
	v_rcp_f32_e32 v160, v158
	v_add_f32_e32 v158, 1.0, v159
	v_mul_f32_e32 v159, 0x3d372713, v61
	v_mul_f32_e32 v159, v61, v159
	v_fma_f32 v159, v61, v159, v61
	v_mul_f32_e32 v161, v57, v161
	v_mul_f32_e32 v159, 0x3f4c422a, v159
	v_fma_f32 v161, v57, v161, v57
	v_mul_f32_e32 v159, -2.0, v159
	v_mul_f32_e32 v161, 0x3f4c422a, v161
	v_mul_f32_e32 v159, 0x3fb8aa3b, v159
	v_mul_f32_e32 v161, -2.0, v161
	v_exp_f32_e32 v159, v159
	v_mul_f32_e32 v161, 0x3fb8aa3b, v161
	v_exp_f32_e32 v163, v161
	v_rcp_f32_e32 v162, v158
	v_add_f32_e32 v158, 1.0, v159
	v_rcp_f32_e32 v161, v158
	v_add_f32_e32 v158, 1.0, v163
	v_rcp_f32_e32 v163, v158
	v_mul_f32_e32 v166, 0x3d372713, v58
	v_pk_mul_f32 v[164:165], v[60:61], v[160:161]
	v_mul_f32_e32 v166, v58, v166
	v_pk_mul_f32 v[162:163], v[56:57], v[162:163]
	v_fma_f32 v166, v58, v166, v58
	v_pk_fma_f32 v[160:161], v[60:61], v[160:161], v[162:163]
	v_mul_f32_e32 v166, 0x3f4c422a, v166
	v_add_f32_e32 v159, 0, v160
	v_mul_f32_e32 v160, 0x3d372713, v62
	v_mul_f32_e32 v160, v62, v160
	v_fma_f32 v160, v62, v160, v62
	v_mul_f32_e32 v160, 0x3f4c422a, v160
	v_mul_f32_e32 v160, -2.0, v160
	v_mul_f32_e32 v160, 0x3fb8aa3b, v160
	v_mul_f32_e32 v166, -2.0, v166
	v_exp_f32_e32 v160, v160
	v_mul_f32_e32 v166, 0x3fb8aa3b, v166
	v_exp_f32_e32 v169, v166
	v_mul_f32_e32 v170, 0x3d372713, v59
	v_add_f32_e32 v160, 1.0, v160
	v_rcp_f32_e32 v168, v160
	v_add_f32_e32 v160, 1.0, v169
	v_mul_f32_e32 v169, 0x3d372713, v63
	v_mul_f32_e32 v169, v63, v169
	v_fma_f32 v169, v63, v169, v63
	v_mul_f32_e32 v170, v59, v170
	v_mul_f32_e32 v169, 0x3f4c422a, v169
	v_fma_f32 v170, v59, v170, v59
	v_mul_f32_e32 v169, -2.0, v169
	v_mul_f32_e32 v170, 0x3f4c422a, v170
	v_mul_f32_e32 v169, 0x3fb8aa3b, v169
	v_mul_f32_e32 v170, -2.0, v170
	v_exp_f32_e32 v169, v169
	v_mul_f32_e32 v170, 0x3fb8aa3b, v170
	v_exp_f32_e32 v171, v170
	v_rcp_f32_e32 v170, v160
	v_add_f32_e32 v160, 1.0, v169
	v_rcp_f32_e32 v169, v160
	v_add_f32_e32 v160, 1.0, v171
	v_rcp_f32_e32 v171, v160
	v_pk_mul_f32 v[166:167], v[162:163], v[162:163]
	v_add_f32_e32 v159, v161, v159
	v_pk_fma_f32 v[166:167], v[164:165], v[164:165], v[166:167]
	v_pk_mul_f32 v[170:171], v[58:59], v[170:171]
	v_pk_mul_f32 v[172:173], v[62:63], v[168:169]
	v_pk_fma_f32 v[160:161], v[62:63], v[168:169], v[170:171]
	v_pk_mul_f32 v[168:169], v[170:171], v[170:171]
	v_add_f32_e32 v159, v160, v159
	v_cvt_pk_bf16_f32 v160, v164, v165
	v_mul_f32_e32 v164, 0x3d372713, v44
	v_pk_fma_f32 v[168:169], v[172:173], v[172:173], v[168:169]
	v_add_f32_e32 v159, v161, v159
	v_cvt_pk_bf16_f32 v161, v172, v173
	v_mul_f32_e32 v164, v44, v164
	v_mul_f32_e32 v172, 0x3d372713, v45
	v_fma_f32 v164, v44, v164, v44
	v_mul_f32_e32 v172, v45, v172
	v_mul_f32_e32 v164, 0x3f4c422a, v164
	v_fma_f32 v172, v45, v172, v45
	v_mul_f32_e32 v164, -2.0, v164
	v_mul_f32_e32 v172, 0x3f4c422a, v172
	v_mul_f32_e32 v164, 0x3fb8aa3b, v164
	v_mul_f32_e32 v172, -2.0, v172
	v_cvt_pk_bf16_f32 v162, v162, v163
	v_cvt_pk_bf16_f32 v163, v170, v171
	v_exp_f32_e32 v170, v164
	v_mul_f32_e32 v164, 0x3d372713, v40
	v_mul_f32_e32 v172, 0x3fb8aa3b, v172
	v_mul_f32_e32 v164, v40, v164
	v_exp_f32_e32 v173, v172
	v_mul_f32_e32 v172, 0x3d372713, v41
	v_fma_f32 v164, v40, v164, v40
	v_mul_f32_e32 v172, v41, v172
	v_mul_f32_e32 v164, 0x3f4c422a, v164
	v_fma_f32 v172, v41, v172, v41
	v_mul_f32_e32 v164, -2.0, v164
	v_mul_f32_e32 v172, 0x3f4c422a, v172
	v_mul_f32_e32 v164, 0x3fb8aa3b, v164
	v_mul_f32_e32 v172, -2.0, v172
	v_exp_f32_e32 v171, v164
	v_mul_f32_e32 v172, 0x3fb8aa3b, v172
	v_exp_f32_e32 v174, v172
	v_add_f32_e32 v170, 1.0, v170
	v_add_f32_e32 v171, 1.0, v171
	v_rcp_f32_e32 v172, v171
	v_add_f32_e32 v171, 1.0, v173
	v_add_f32_e32 v173, 1.0, v174
	v_rcp_f32_e32 v173, v173
	v_rcp_f32_e32 v170, v170
	v_rcp_f32_e32 v171, v171
	v_mul_f32_e32 v176, 0x3d372713, v42
	v_pk_mul_f32 v[172:173], v[40:41], v[172:173]
	v_mul_f32_e32 v176, v42, v176
	v_pk_mul_f32 v[174:175], v[44:45], v[170:171]
	v_pk_fma_f32 v[170:171], v[44:45], v[170:171], v[172:173]
	v_fma_f32 v176, v42, v176, v42
	v_add_f32_e32 v159, v159, v170
	v_mul_f32_e32 v170, 0x3d372713, v46
	v_mul_f32_e32 v170, v46, v170
	v_fma_f32 v170, v46, v170, v46
	v_mul_f32_e32 v170, 0x3f4c422a, v170
	v_mul_f32_e32 v170, -2.0, v170
	v_mul_f32_e32 v176, 0x3f4c422a, v176
	v_mul_f32_e32 v170, 0x3fb8aa3b, v170
	v_mul_f32_e32 v176, -2.0, v176
	v_exp_f32_e32 v170, v170
	v_mul_f32_e32 v176, 0x3fb8aa3b, v176
	v_exp_f32_e32 v179, v176
	v_mul_f32_e32 v180, 0x3d372713, v43
	v_add_f32_e32 v170, 1.0, v170
	v_rcp_f32_e32 v178, v170
	v_add_f32_e32 v170, 1.0, v179
	v_mul_f32_e32 v179, 0x3d372713, v47
	v_mul_f32_e32 v179, v47, v179
	v_fma_f32 v179, v47, v179, v47
	v_mul_f32_e32 v180, v43, v180
	v_mul_f32_e32 v179, 0x3f4c422a, v179
	v_fma_f32 v180, v43, v180, v43
	v_mul_f32_e32 v179, -2.0, v179
	v_mul_f32_e32 v180, 0x3f4c422a, v180
	v_mul_f32_e32 v179, 0x3fb8aa3b, v179
	v_mul_f32_e32 v180, -2.0, v180
	v_exp_f32_e32 v179, v179
	v_mul_f32_e32 v180, 0x3fb8aa3b, v180
	v_exp_f32_e32 v181, v180
	v_rcp_f32_e32 v180, v170
	v_add_f32_e32 v170, 1.0, v179
	v_rcp_f32_e32 v179, v170
	v_add_f32_e32 v170, 1.0, v181
	v_rcp_f32_e32 v181, v170
	v_add_f32_e32 v166, v166, v167
	v_pk_mul_f32 v[176:177], v[172:173], v[172:173]
	v_add_f32_e32 v166, v168, v166
	v_pk_fma_f32 v[176:177], v[174:175], v[174:175], v[176:177]
	v_pk_mul_f32 v[180:181], v[42:43], v[180:181]
	v_add_f32_e32 v166, v169, v166
	v_add_f32_e32 v159, v171, v159
	v_pk_mul_f32 v[170:171], v[46:47], v[178:179]
	v_pk_mul_f32 v[182:183], v[180:181], v[180:181]
	v_add_f32_e32 v166, v166, v176
	v_pk_fma_f32 v[178:179], v[46:47], v[178:179], v[180:181]
	v_pk_fma_f32 v[182:183], v[170:171], v[170:171], v[182:183]
	v_add_f32_e32 v166, v177, v166
	v_add_f32_e32 v159, v178, v159
	v_add_f32_e32 v166, v182, v166
	v_add_f32_e32 v159, v179, v159
	v_add_f32_e32 v166, v183, v166
	ds_bpermute_b32 v167, v147, v159
	ds_bpermute_b32 v176, v147, v166
	v_add_u32_e32 v158, 0x80, v157
	v_mov_b64_e32 v[164:165], s[14:15]
	v_mad_i64_i32 v[164:165], s[28:29], v158, s52, v[164:165]
	v_lshl_add_u64 v[164:165], v[164:165], 0, s[4:5]
	v_lshl_add_u64 v[168:169], v[144:145], 1, v[164:165]
	global_store_dwordx4 v[168:169], v[160:163], off nt
	s_waitcnt lgkmcnt(0)
	v_add_f32_e32 v159, v159, v167
	ds_bpermute_b32 v161, v146, v159
	v_add_f32_e32 v160, v166, v176
	ds_bpermute_b32 v162, v146, v160
	v_cvt_pk_bf16_f32 v164, v174, v175
	v_cvt_pk_bf16_f32 v165, v170, v171
	v_cvt_pk_bf16_f32 v166, v172, v173
	v_cvt_pk_bf16_f32 v167, v180, v181
	global_store_dwordx4 v[168:169], v[164:167], off offset:256 nt
	s_and_saveexec_b64 s[28:29], vcc
	s_cbranch_execz .LBB0_1223
	v_lshlrev_b32_e32 v158, 1, v158
	s_waitcnt lgkmcnt(0)
	v_add_f32_e32 v161, v159, v161
	v_ashrrev_i32_e32 v159, 31, v158
	v_lshl_add_u64 v[158:159], v[158:159], 2, s[48:49]
	v_add_f32_e32 v160, v160, v162
	global_atomic_add_f32 v[158:159], v161, off
	global_atomic_add_f32 v[158:159], v160, off offset:4
.LBB0_1223:
	s_or_b64 exec, exec, s[28:29]
	v_mul_f32_e32 v158, 0x3d372713, v52
	v_mul_f32_e32 v158, v52, v158
	v_mul_f32_e32 v159, 0x3d372713, v48
	v_fma_f32 v158, v52, v158, v52
	v_mul_f32_e32 v159, v48, v159
	v_mul_f32_e32 v158, 0x3f4c422a, v158
	v_fma_f32 v159, v48, v159, v48
	v_mul_f32_e32 v158, -2.0, v158
	v_mul_f32_e32 v159, 0x3f4c422a, v159
	v_mul_f32_e32 v158, 0x3fb8aa3b, v158
	v_mul_f32_e32 v159, -2.0, v159
	v_exp_f32_e32 v158, v158
	v_mul_f32_e32 v159, 0x3fb8aa3b, v159
	v_exp_f32_e32 v159, v159
	s_waitcnt lgkmcnt(0)
	v_mul_f32_e32 v161, 0x3d372713, v49
	v_add_f32_e32 v158, 1.0, v158
	v_rcp_f32_e32 v160, v158
	v_add_f32_e32 v158, 1.0, v159
	v_mul_f32_e32 v159, 0x3d372713, v53
	v_mul_f32_e32 v159, v53, v159
	v_fma_f32 v159, v53, v159, v53
	v_mul_f32_e32 v161, v49, v161
	v_mul_f32_e32 v159, 0x3f4c422a, v159
	v_fma_f32 v161, v49, v161, v49
	v_mul_f32_e32 v159, -2.0, v159
	v_mul_f32_e32 v161, 0x3f4c422a, v161
	v_mul_f32_e32 v159, 0x3fb8aa3b, v159
	v_mul_f32_e32 v161, -2.0, v161
	v_exp_f32_e32 v159, v159
	v_mul_f32_e32 v161, 0x3fb8aa3b, v161
	v_exp_f32_e32 v163, v161
	v_rcp_f32_e32 v162, v158
	v_add_f32_e32 v158, 1.0, v159
	v_rcp_f32_e32 v161, v158
	v_add_f32_e32 v158, 1.0, v163
	v_rcp_f32_e32 v163, v158
	v_mul_f32_e32 v166, 0x3d372713, v50
	v_pk_mul_f32 v[164:165], v[52:53], v[160:161]
	v_mul_f32_e32 v166, v50, v166
	v_pk_mul_f32 v[162:163], v[48:49], v[162:163]
	v_fma_f32 v166, v50, v166, v50
	v_pk_fma_f32 v[160:161], v[52:53], v[160:161], v[162:163]
	v_mul_f32_e32 v166, 0x3f4c422a, v166
	v_add_f32_e32 v159, 0, v160
	v_mul_f32_e32 v160, 0x3d372713, v54
	v_mul_f32_e32 v160, v54, v160
	v_fma_f32 v160, v54, v160, v54
	v_mul_f32_e32 v160, 0x3f4c422a, v160
	v_mul_f32_e32 v160, -2.0, v160
	v_mul_f32_e32 v160, 0x3fb8aa3b, v160
	v_mul_f32_e32 v166, -2.0, v166
	v_exp_f32_e32 v160, v160
	v_mul_f32_e32 v166, 0x3fb8aa3b, v166
	v_exp_f32_e32 v169, v166
	v_mul_f32_e32 v170, 0x3d372713, v51
	v_add_f32_e32 v160, 1.0, v160
	v_rcp_f32_e32 v168, v160
	v_add_f32_e32 v160, 1.0, v169
	v_mul_f32_e32 v169, 0x3d372713, v55
	v_mul_f32_e32 v169, v55, v169
	v_fma_f32 v169, v55, v169, v55
	v_mul_f32_e32 v170, v51, v170
	v_mul_f32_e32 v169, 0x3f4c422a, v169
	v_fma_f32 v170, v51, v170, v51
	v_mul_f32_e32 v169, -2.0, v169
	v_mul_f32_e32 v170, 0x3f4c422a, v170
	v_mul_f32_e32 v169, 0x3fb8aa3b, v169
	v_mul_f32_e32 v170, -2.0, v170
	v_exp_f32_e32 v169, v169
	v_mul_f32_e32 v170, 0x3fb8aa3b, v170
	v_exp_f32_e32 v171, v170
	v_rcp_f32_e32 v170, v160
	v_add_f32_e32 v160, 1.0, v169
	v_rcp_f32_e32 v169, v160
	v_add_f32_e32 v160, 1.0, v171
	v_rcp_f32_e32 v171, v160
	v_pk_mul_f32 v[166:167], v[162:163], v[162:163]
	v_add_f32_e32 v159, v161, v159
	v_pk_fma_f32 v[166:167], v[164:165], v[164:165], v[166:167]
	v_pk_mul_f32 v[170:171], v[50:51], v[170:171]
	v_pk_mul_f32 v[172:173], v[54:55], v[168:169]
	v_pk_fma_f32 v[160:161], v[54:55], v[168:169], v[170:171]
	v_pk_mul_f32 v[168:169], v[170:171], v[170:171]
	v_add_f32_e32 v159, v160, v159
	v_cvt_pk_bf16_f32 v160, v164, v165
	v_mul_f32_e32 v164, 0x3d372713, v28
	v_pk_fma_f32 v[168:169], v[172:173], v[172:173], v[168:169]
	v_add_f32_e32 v159, v161, v159
	v_cvt_pk_bf16_f32 v161, v172, v173
	v_mul_f32_e32 v164, v28, v164
	v_mul_f32_e32 v172, 0x3d372713, v29
	v_fma_f32 v164, v28, v164, v28
	v_mul_f32_e32 v172, v29, v172
	v_mul_f32_e32 v164, 0x3f4c422a, v164
	v_fma_f32 v172, v29, v172, v29
	v_mul_f32_e32 v164, -2.0, v164
	v_mul_f32_e32 v172, 0x3f4c422a, v172
	v_mul_f32_e32 v164, 0x3fb8aa3b, v164
	v_mul_f32_e32 v172, -2.0, v172
	v_cvt_pk_bf16_f32 v162, v162, v163
	v_cvt_pk_bf16_f32 v163, v170, v171
	v_exp_f32_e32 v170, v164
	v_mul_f32_e32 v164, 0x3d372713, v24
	v_mul_f32_e32 v172, 0x3fb8aa3b, v172
	v_mul_f32_e32 v164, v24, v164
	v_exp_f32_e32 v173, v172
	v_mul_f32_e32 v172, 0x3d372713, v25
	v_fma_f32 v164, v24, v164, v24
	v_mul_f32_e32 v172, v25, v172
	v_mul_f32_e32 v164, 0x3f4c422a, v164
	v_fma_f32 v172, v25, v172, v25
	v_mul_f32_e32 v164, -2.0, v164
	v_mul_f32_e32 v172, 0x3f4c422a, v172
	v_mul_f32_e32 v164, 0x3fb8aa3b, v164
	v_mul_f32_e32 v172, -2.0, v172
	v_exp_f32_e32 v171, v164
	v_mul_f32_e32 v172, 0x3fb8aa3b, v172
	v_exp_f32_e32 v174, v172
	v_add_f32_e32 v170, 1.0, v170
	v_add_f32_e32 v171, 1.0, v171
	v_rcp_f32_e32 v172, v171
	v_add_f32_e32 v171, 1.0, v173
	v_add_f32_e32 v173, 1.0, v174
	v_rcp_f32_e32 v173, v173
	v_rcp_f32_e32 v170, v170
	v_rcp_f32_e32 v171, v171
	v_mul_f32_e32 v176, 0x3d372713, v26
	v_pk_mul_f32 v[172:173], v[24:25], v[172:173]
	v_mul_f32_e32 v176, v26, v176
	v_pk_mul_f32 v[174:175], v[28:29], v[170:171]
	v_pk_fma_f32 v[170:171], v[28:29], v[170:171], v[172:173]
	v_fma_f32 v176, v26, v176, v26
	v_add_f32_e32 v159, v159, v170
	v_mul_f32_e32 v170, 0x3d372713, v30
	v_mul_f32_e32 v170, v30, v170
	v_fma_f32 v170, v30, v170, v30
	v_mul_f32_e32 v170, 0x3f4c422a, v170
	v_mul_f32_e32 v170, -2.0, v170
	v_mul_f32_e32 v176, 0x3f4c422a, v176
	v_mul_f32_e32 v170, 0x3fb8aa3b, v170
	v_mul_f32_e32 v176, -2.0, v176
	v_exp_f32_e32 v170, v170
	v_mul_f32_e32 v176, 0x3fb8aa3b, v176
	v_exp_f32_e32 v179, v176
	v_mul_f32_e32 v180, 0x3d372713, v27
	v_add_f32_e32 v170, 1.0, v170
	v_rcp_f32_e32 v178, v170
	v_add_f32_e32 v170, 1.0, v179
	v_mul_f32_e32 v179, 0x3d372713, v31
	v_mul_f32_e32 v179, v31, v179
	v_fma_f32 v179, v31, v179, v31
	v_mul_f32_e32 v180, v27, v180
	v_mul_f32_e32 v179, 0x3f4c422a, v179
	v_fma_f32 v180, v27, v180, v27
	v_mul_f32_e32 v179, -2.0, v179
	v_mul_f32_e32 v180, 0x3f4c422a, v180
	v_mul_f32_e32 v179, 0x3fb8aa3b, v179
	v_mul_f32_e32 v180, -2.0, v180
	v_exp_f32_e32 v179, v179
	v_mul_f32_e32 v180, 0x3fb8aa3b, v180
	v_exp_f32_e32 v181, v180
	v_rcp_f32_e32 v180, v170
	v_add_f32_e32 v170, 1.0, v179
	v_rcp_f32_e32 v179, v170
	v_add_f32_e32 v170, 1.0, v181
	v_rcp_f32_e32 v181, v170
	v_add_f32_e32 v166, v166, v167
	v_pk_mul_f32 v[176:177], v[172:173], v[172:173]
	v_add_f32_e32 v166, v168, v166
	v_pk_fma_f32 v[176:177], v[174:175], v[174:175], v[176:177]
	v_pk_mul_f32 v[180:181], v[26:27], v[180:181]
	v_add_f32_e32 v166, v169, v166
	v_add_f32_e32 v159, v171, v159
	v_pk_mul_f32 v[170:171], v[30:31], v[178:179]
	v_pk_mul_f32 v[182:183], v[180:181], v[180:181]
	v_add_f32_e32 v166, v166, v176
	v_pk_fma_f32 v[178:179], v[30:31], v[178:179], v[180:181]
	v_pk_fma_f32 v[182:183], v[170:171], v[170:171], v[182:183]
	v_add_f32_e32 v166, v177, v166
	v_add_f32_e32 v159, v178, v159
	v_add_f32_e32 v166, v182, v166
	v_add_f32_e32 v159, v179, v159
	v_add_f32_e32 v166, v183, v166
	ds_bpermute_b32 v167, v147, v159
	ds_bpermute_b32 v176, v147, v166
	v_add_u32_e32 v158, 0x90, v157
	v_mov_b64_e32 v[164:165], s[14:15]
	v_mad_i64_i32 v[164:165], s[28:29], v158, s52, v[164:165]
	v_lshl_add_u64 v[164:165], v[164:165], 0, s[4:5]
	v_lshl_add_u64 v[168:169], v[144:145], 1, v[164:165]
	global_store_dwordx4 v[168:169], v[160:163], off nt
	s_waitcnt lgkmcnt(0)
	v_add_f32_e32 v159, v159, v167
	ds_bpermute_b32 v161, v146, v159
	v_add_f32_e32 v160, v166, v176
	ds_bpermute_b32 v162, v146, v160
	v_cvt_pk_bf16_f32 v164, v174, v175
	v_cvt_pk_bf16_f32 v165, v170, v171
	v_cvt_pk_bf16_f32 v166, v172, v173
	v_cvt_pk_bf16_f32 v167, v180, v181
	global_store_dwordx4 v[168:169], v[164:167], off offset:256 nt
	s_and_saveexec_b64 s[28:29], vcc
	s_cbranch_execz .LBB0_1225
	v_lshlrev_b32_e32 v158, 1, v158
	s_waitcnt lgkmcnt(0)
	v_add_f32_e32 v161, v159, v161
	v_ashrrev_i32_e32 v159, 31, v158
	v_lshl_add_u64 v[158:159], v[158:159], 2, s[48:49]
	v_add_f32_e32 v160, v160, v162
	global_atomic_add_f32 v[158:159], v161, off
	global_atomic_add_f32 v[158:159], v160, off offset:4
.LBB0_1225:
	s_or_b64 exec, exec, s[28:29]
	v_mul_f32_e32 v158, 0x3d372713, v36
	v_mul_f32_e32 v158, v36, v158
	v_mul_f32_e32 v159, 0x3d372713, v32
	v_fma_f32 v158, v36, v158, v36
	v_mul_f32_e32 v159, v32, v159
	v_mul_f32_e32 v158, 0x3f4c422a, v158
	v_fma_f32 v159, v32, v159, v32
	v_mul_f32_e32 v158, -2.0, v158
	v_mul_f32_e32 v159, 0x3f4c422a, v159
	v_mul_f32_e32 v158, 0x3fb8aa3b, v158
	v_mul_f32_e32 v159, -2.0, v159
	v_exp_f32_e32 v158, v158
	v_mul_f32_e32 v159, 0x3fb8aa3b, v159
	v_exp_f32_e32 v159, v159
	s_waitcnt lgkmcnt(0)
	v_mul_f32_e32 v161, 0x3d372713, v33
	v_add_f32_e32 v158, 1.0, v158
	v_rcp_f32_e32 v160, v158
	v_add_f32_e32 v158, 1.0, v159
	v_mul_f32_e32 v159, 0x3d372713, v37
	v_mul_f32_e32 v159, v37, v159
	v_fma_f32 v159, v37, v159, v37
	v_mul_f32_e32 v161, v33, v161
	v_mul_f32_e32 v159, 0x3f4c422a, v159
	v_fma_f32 v161, v33, v161, v33
	v_mul_f32_e32 v159, -2.0, v159
	v_mul_f32_e32 v161, 0x3f4c422a, v161
	v_mul_f32_e32 v159, 0x3fb8aa3b, v159
	v_mul_f32_e32 v161, -2.0, v161
	v_exp_f32_e32 v159, v159
	v_mul_f32_e32 v161, 0x3fb8aa3b, v161
	v_exp_f32_e32 v163, v161
	v_rcp_f32_e32 v162, v158
	v_add_f32_e32 v158, 1.0, v159
	v_rcp_f32_e32 v161, v158
	v_add_f32_e32 v158, 1.0, v163
	v_rcp_f32_e32 v163, v158
	v_mul_f32_e32 v166, 0x3d372713, v34
	v_pk_mul_f32 v[164:165], v[36:37], v[160:161]
	v_mul_f32_e32 v166, v34, v166
	v_pk_mul_f32 v[162:163], v[32:33], v[162:163]
	v_fma_f32 v166, v34, v166, v34
	v_pk_fma_f32 v[160:161], v[36:37], v[160:161], v[162:163]
	v_mul_f32_e32 v166, 0x3f4c422a, v166
	v_add_f32_e32 v159, 0, v160
	v_mul_f32_e32 v160, 0x3d372713, v38
	v_mul_f32_e32 v160, v38, v160
	v_fma_f32 v160, v38, v160, v38
	v_mul_f32_e32 v160, 0x3f4c422a, v160
	v_mul_f32_e32 v160, -2.0, v160
	v_mul_f32_e32 v160, 0x3fb8aa3b, v160
	v_mul_f32_e32 v166, -2.0, v166
	v_exp_f32_e32 v160, v160
	v_mul_f32_e32 v166, 0x3fb8aa3b, v166
	v_exp_f32_e32 v169, v166
	v_mul_f32_e32 v170, 0x3d372713, v35
	v_add_f32_e32 v160, 1.0, v160
	v_rcp_f32_e32 v168, v160
	v_add_f32_e32 v160, 1.0, v169
	v_mul_f32_e32 v169, 0x3d372713, v39
	v_mul_f32_e32 v169, v39, v169
	v_fma_f32 v169, v39, v169, v39
	v_mul_f32_e32 v170, v35, v170
	v_mul_f32_e32 v169, 0x3f4c422a, v169
	v_fma_f32 v170, v35, v170, v35
	v_mul_f32_e32 v169, -2.0, v169
	v_mul_f32_e32 v170, 0x3f4c422a, v170
	v_mul_f32_e32 v169, 0x3fb8aa3b, v169
	v_mul_f32_e32 v170, -2.0, v170
	v_exp_f32_e32 v169, v169
	v_mul_f32_e32 v170, 0x3fb8aa3b, v170
	v_exp_f32_e32 v171, v170
	v_rcp_f32_e32 v170, v160
	v_add_f32_e32 v160, 1.0, v169
	v_rcp_f32_e32 v169, v160
	v_add_f32_e32 v160, 1.0, v171
	v_rcp_f32_e32 v171, v160
	v_pk_mul_f32 v[166:167], v[162:163], v[162:163]
	v_add_f32_e32 v159, v161, v159
	v_pk_fma_f32 v[166:167], v[164:165], v[164:165], v[166:167]
	v_pk_mul_f32 v[170:171], v[34:35], v[170:171]
	v_pk_mul_f32 v[172:173], v[38:39], v[168:169]
	v_pk_fma_f32 v[160:161], v[38:39], v[168:169], v[170:171]
	v_pk_mul_f32 v[168:169], v[170:171], v[170:171]
	v_add_f32_e32 v159, v160, v159
	v_cvt_pk_bf16_f32 v160, v164, v165
	v_mul_f32_e32 v164, 0x3d372713, v12
	v_pk_fma_f32 v[168:169], v[172:173], v[172:173], v[168:169]
	v_add_f32_e32 v159, v161, v159
	v_cvt_pk_bf16_f32 v161, v172, v173
	v_mul_f32_e32 v164, v12, v164
	v_mul_f32_e32 v172, 0x3d372713, v13
	v_fma_f32 v164, v12, v164, v12
	v_mul_f32_e32 v172, v13, v172
	v_mul_f32_e32 v164, 0x3f4c422a, v164
	v_fma_f32 v172, v13, v172, v13
	v_mul_f32_e32 v164, -2.0, v164
	v_mul_f32_e32 v172, 0x3f4c422a, v172
	v_mul_f32_e32 v164, 0x3fb8aa3b, v164
	v_mul_f32_e32 v172, -2.0, v172
	v_cvt_pk_bf16_f32 v162, v162, v163
	v_cvt_pk_bf16_f32 v163, v170, v171
	v_exp_f32_e32 v170, v164
	v_mul_f32_e32 v164, 0x3d372713, v8
	v_mul_f32_e32 v172, 0x3fb8aa3b, v172
	v_mul_f32_e32 v164, v8, v164
	v_exp_f32_e32 v173, v172
	v_mul_f32_e32 v172, 0x3d372713, v9
	v_fma_f32 v164, v8, v164, v8
	v_mul_f32_e32 v172, v9, v172
	v_mul_f32_e32 v164, 0x3f4c422a, v164
	v_fma_f32 v172, v9, v172, v9
	v_mul_f32_e32 v164, -2.0, v164
	v_mul_f32_e32 v172, 0x3f4c422a, v172
	v_mul_f32_e32 v164, 0x3fb8aa3b, v164
	v_mul_f32_e32 v172, -2.0, v172
	v_exp_f32_e32 v171, v164
	v_mul_f32_e32 v172, 0x3fb8aa3b, v172
	v_exp_f32_e32 v174, v172
	v_add_f32_e32 v170, 1.0, v170
	v_add_f32_e32 v171, 1.0, v171
	v_rcp_f32_e32 v172, v171
	v_add_f32_e32 v171, 1.0, v173
	v_add_f32_e32 v173, 1.0, v174
	v_rcp_f32_e32 v173, v173
	v_rcp_f32_e32 v170, v170
	v_rcp_f32_e32 v171, v171
	v_mul_f32_e32 v176, 0x3d372713, v10
	v_pk_mul_f32 v[172:173], v[8:9], v[172:173]
	v_mul_f32_e32 v176, v10, v176
	v_pk_mul_f32 v[174:175], v[12:13], v[170:171]
	v_pk_fma_f32 v[170:171], v[12:13], v[170:171], v[172:173]
	v_fma_f32 v176, v10, v176, v10
	v_add_f32_e32 v159, v159, v170
	v_mul_f32_e32 v170, 0x3d372713, v14
	v_mul_f32_e32 v170, v14, v170
	v_fma_f32 v170, v14, v170, v14
	v_mul_f32_e32 v170, 0x3f4c422a, v170
	v_mul_f32_e32 v170, -2.0, v170
	v_mul_f32_e32 v176, 0x3f4c422a, v176
	v_mul_f32_e32 v170, 0x3fb8aa3b, v170
	v_mul_f32_e32 v176, -2.0, v176
	v_exp_f32_e32 v170, v170
	v_mul_f32_e32 v176, 0x3fb8aa3b, v176
	v_exp_f32_e32 v179, v176
	v_mul_f32_e32 v180, 0x3d372713, v11
	v_add_f32_e32 v170, 1.0, v170
	v_rcp_f32_e32 v178, v170
	v_add_f32_e32 v170, 1.0, v179
	v_mul_f32_e32 v179, 0x3d372713, v15
	v_mul_f32_e32 v179, v15, v179
	v_fma_f32 v179, v15, v179, v15
	v_mul_f32_e32 v180, v11, v180
	v_mul_f32_e32 v179, 0x3f4c422a, v179
	v_fma_f32 v180, v11, v180, v11
	v_mul_f32_e32 v179, -2.0, v179
	v_mul_f32_e32 v180, 0x3f4c422a, v180
	v_mul_f32_e32 v179, 0x3fb8aa3b, v179
	v_mul_f32_e32 v180, -2.0, v180
	v_exp_f32_e32 v179, v179
	v_mul_f32_e32 v180, 0x3fb8aa3b, v180
	v_exp_f32_e32 v181, v180
	v_rcp_f32_e32 v180, v170
	v_add_f32_e32 v170, 1.0, v179
	v_rcp_f32_e32 v179, v170
	v_add_f32_e32 v170, 1.0, v181
	v_rcp_f32_e32 v181, v170
	v_add_f32_e32 v166, v166, v167
	v_pk_mul_f32 v[176:177], v[172:173], v[172:173]
	v_add_f32_e32 v166, v168, v166
	v_pk_fma_f32 v[176:177], v[174:175], v[174:175], v[176:177]
	v_pk_mul_f32 v[180:181], v[10:11], v[180:181]
	v_add_f32_e32 v166, v169, v166
	v_add_f32_e32 v159, v171, v159
	v_pk_mul_f32 v[170:171], v[14:15], v[178:179]
	v_pk_mul_f32 v[182:183], v[180:181], v[180:181]
	v_add_f32_e32 v166, v166, v176
	v_pk_fma_f32 v[178:179], v[14:15], v[178:179], v[180:181]
	v_pk_fma_f32 v[182:183], v[170:171], v[170:171], v[182:183]
	v_add_f32_e32 v166, v177, v166
	v_add_f32_e32 v159, v178, v159
	v_add_f32_e32 v166, v182, v166
	v_add_f32_e32 v159, v179, v159
	v_add_f32_e32 v166, v183, v166
	ds_bpermute_b32 v167, v147, v159
	ds_bpermute_b32 v176, v147, v166
	v_add_u32_e32 v158, 0xa0, v157
	v_mov_b64_e32 v[164:165], s[14:15]
	v_mad_i64_i32 v[164:165], s[28:29], v158, s52, v[164:165]
	v_lshl_add_u64 v[164:165], v[164:165], 0, s[4:5]
	v_lshl_add_u64 v[168:169], v[144:145], 1, v[164:165]
	global_store_dwordx4 v[168:169], v[160:163], off nt
	s_waitcnt lgkmcnt(0)
	v_add_f32_e32 v159, v159, v167
	ds_bpermute_b32 v161, v146, v159
	v_add_f32_e32 v160, v166, v176
	ds_bpermute_b32 v162, v146, v160
	v_cvt_pk_bf16_f32 v164, v174, v175
	v_cvt_pk_bf16_f32 v165, v170, v171
	v_cvt_pk_bf16_f32 v166, v172, v173
	v_cvt_pk_bf16_f32 v167, v180, v181
	global_store_dwordx4 v[168:169], v[164:167], off offset:256 nt
	s_and_saveexec_b64 s[28:29], vcc
	s_cbranch_execz .LBB0_1227
	v_lshlrev_b32_e32 v158, 1, v158
	s_waitcnt lgkmcnt(0)
	v_add_f32_e32 v161, v159, v161
	v_ashrrev_i32_e32 v159, 31, v158
	v_lshl_add_u64 v[158:159], v[158:159], 2, s[48:49]
	v_add_f32_e32 v160, v160, v162
	global_atomic_add_f32 v[158:159], v161, off
	global_atomic_add_f32 v[158:159], v160, off offset:4
.LBB0_1227:
	s_or_b64 exec, exec, s[28:29]
	v_mul_f32_e32 v160, 0x3d372713, v21
	v_mul_f32_e32 v160, v21, v160
	v_mul_f32_e32 v164, 0x3d372713, v22
	v_fma_f32 v160, v21, v160, v21
	v_mul_f32_e32 v164, v22, v164
	v_mul_f32_e32 v168, 0x3d372713, v23
	v_mul_f32_e32 v160, 0x3f4c422a, v160
	v_fma_f32 v164, v22, v164, v22
	v_mul_f32_e32 v168, v23, v168
	v_mul_f32_e32 v160, -2.0, v160
	v_mul_f32_e32 v164, 0x3f4c422a, v164
	v_fma_f32 v168, v23, v168, v23
	v_mul_f32_e32 v159, 0x3d372713, v16
	v_mul_f32_e32 v160, 0x3fb8aa3b, v160
	v_mul_f32_e32 v164, -2.0, v164
	v_mul_f32_e32 v168, 0x3f4c422a, v168
	v_mul_f32_e32 v159, v16, v159
	s_waitcnt lgkmcnt(0)
	v_exp_f32_e32 v161, v160
	v_mul_f32_e32 v160, 0x3d372713, v17
	v_mul_f32_e32 v164, 0x3fb8aa3b, v164
	v_mul_f32_e32 v168, -2.0, v168
	v_mul_f32_e32 v158, 0x3d372713, v20
	v_fma_f32 v159, v16, v159, v16
	v_mul_f32_e32 v160, v17, v160
	v_exp_f32_e32 v166, v164
	v_mul_f32_e32 v164, 0x3d372713, v18
	v_mul_f32_e32 v168, 0x3fb8aa3b, v168
	v_mul_f32_e32 v158, v20, v158
	v_mul_f32_e32 v159, 0x3f4c422a, v159
	v_fma_f32 v160, v17, v160, v17
	v_mul_f32_e32 v164, v18, v164
	v_exp_f32_e32 v169, v168
	v_mul_f32_e32 v168, 0x3d372713, v19
	v_fma_f32 v158, v20, v158, v20
	v_mul_f32_e32 v159, -2.0, v159
	v_mul_f32_e32 v160, 0x3f4c422a, v160
	v_fma_f32 v164, v18, v164, v18
	v_mul_f32_e32 v168, v19, v168
	v_mul_f32_e32 v158, 0x3f4c422a, v158
	v_mul_f32_e32 v159, 0x3fb8aa3b, v159
	v_mul_f32_e32 v160, -2.0, v160
	v_mul_f32_e32 v164, 0x3f4c422a, v164
	v_fma_f32 v168, v19, v168, v19
	v_mul_f32_e32 v158, -2.0, v158
	v_exp_f32_e32 v159, v159
	v_mul_f32_e32 v160, 0x3fb8aa3b, v160
	v_mul_f32_e32 v164, -2.0, v164
	v_mul_f32_e32 v168, 0x3f4c422a, v168
	v_mul_f32_e32 v158, 0x3fb8aa3b, v158
	v_exp_f32_e32 v162, v160
	v_mul_f32_e32 v164, 0x3fb8aa3b, v164
	v_mul_f32_e32 v168, -2.0, v168
	v_exp_f32_e32 v158, v158
	v_exp_f32_e32 v167, v164
	v_mul_f32_e32 v168, 0x3fb8aa3b, v168
	v_exp_f32_e32 v170, v168
	v_add_f32_e32 v159, 1.0, v159
	v_rcp_f32_e32 v160, v159
	v_add_f32_e32 v159, 1.0, v161
	v_add_f32_e32 v161, 1.0, v162
	v_add_f32_e32 v158, 1.0, v158
	v_rcp_f32_e32 v161, v161
	v_add_f32_e32 v167, 1.0, v167
	v_rcp_f32_e32 v158, v158
	v_rcp_f32_e32 v159, v159
	v_rcp_f32_e32 v168, v167
	v_add_f32_e32 v167, 1.0, v169
	v_add_f32_e32 v169, 1.0, v170
	v_add_f32_e32 v166, 1.0, v166
	v_rcp_f32_e32 v169, v169
	v_rcp_f32_e32 v166, v166
	v_rcp_f32_e32 v167, v167
	v_pk_mul_f32 v[160:161], v[16:17], v[160:161]
	v_pk_mul_f32 v[162:163], v[20:21], v[158:159]
	v_pk_fma_f32 v[158:159], v[20:21], v[158:159], v[160:161]
	v_pk_mul_f32 v[168:169], v[18:19], v[168:169]
	v_add_f32_e32 v158, 0, v158
	v_add_f32_e32 v172, v159, v158
	v_pk_fma_f32 v[158:159], v[22:23], v[166:167], v[168:169]
	v_pk_mul_f32 v[164:165], v[160:161], v[160:161]
	v_add_f32_e32 v158, v158, v172
	v_pk_fma_f32 v[164:165], v[162:163], v[162:163], v[164:165]
	v_pk_mul_f32 v[170:171], v[22:23], v[166:167]
	v_pk_mul_f32 v[166:167], v[168:169], v[168:169]
	v_add_f32_e32 v174, v159, v158
	v_cvt_pk_bf16_f32 v158, v162, v163
	v_mul_f32_e32 v162, 0x3d372713, v4
	v_pk_fma_f32 v[166:167], v[170:171], v[170:171], v[166:167]
	v_cvt_pk_bf16_f32 v159, v170, v171
	v_mul_f32_e32 v162, v4, v162
	v_mul_f32_e32 v170, 0x3d372713, v5
	v_fma_f32 v162, v4, v162, v4
	v_mul_f32_e32 v170, v5, v170
	v_mul_f32_e32 v162, 0x3f4c422a, v162
	v_fma_f32 v170, v5, v170, v5
	v_mul_f32_e32 v162, -2.0, v162
	v_mul_f32_e32 v170, 0x3f4c422a, v170
	v_mul_f32_e32 v162, 0x3fb8aa3b, v162
	v_mul_f32_e32 v170, -2.0, v170
	v_cvt_pk_bf16_f32 v160, v160, v161
	v_cvt_pk_bf16_f32 v161, v168, v169
	v_exp_f32_e32 v168, v162
	v_mul_f32_e32 v162, 0x3d372713, v0
	v_mul_f32_e32 v170, 0x3fb8aa3b, v170
	v_mul_f32_e32 v162, v0, v162
	v_exp_f32_e32 v171, v170
	v_mul_f32_e32 v170, 0x3d372713, v1
	v_fma_f32 v162, v0, v162, v0
	v_mul_f32_e32 v170, v1, v170
	v_mul_f32_e32 v162, 0x3f4c422a, v162
	v_fma_f32 v170, v1, v170, v1
	v_mul_f32_e32 v162, -2.0, v162
	v_mul_f32_e32 v170, 0x3f4c422a, v170
	v_mul_f32_e32 v162, 0x3fb8aa3b, v162
	v_mul_f32_e32 v170, -2.0, v170
	v_exp_f32_e32 v169, v162
	v_mul_f32_e32 v170, 0x3fb8aa3b, v170
	v_exp_f32_e32 v172, v170
	v_add_f32_e32 v168, 1.0, v168
	v_add_f32_e32 v169, 1.0, v169
	v_rcp_f32_e32 v170, v169
	v_add_f32_e32 v169, 1.0, v171
	v_add_f32_e32 v171, 1.0, v172
	v_rcp_f32_e32 v171, v171
	v_rcp_f32_e32 v168, v168
	v_rcp_f32_e32 v169, v169
	v_mul_f32_e32 v178, 0x3d372713, v7
	v_pk_mul_f32 v[170:171], v[0:1], v[170:171]
	v_mul_f32_e32 v178, v7, v178
	v_pk_mul_f32 v[172:173], v[4:5], v[168:169]
	v_pk_fma_f32 v[168:169], v[4:5], v[168:169], v[170:171]
	v_fma_f32 v178, v7, v178, v7
	v_add_f32_e32 v168, v174, v168
	v_mul_f32_e32 v174, 0x3d372713, v6
	v_mul_f32_e32 v174, v6, v174
	v_fma_f32 v174, v6, v174, v6
	v_mul_f32_e32 v174, 0x3f4c422a, v174
	v_mul_f32_e32 v174, -2.0, v174
	v_mul_f32_e32 v178, 0x3f4c422a, v178
	v_mul_f32_e32 v174, 0x3fb8aa3b, v174
	v_mul_f32_e32 v178, -2.0, v178
	v_exp_f32_e32 v176, v174
	v_mul_f32_e32 v174, 0x3d372713, v2
	v_mul_f32_e32 v178, 0x3fb8aa3b, v178
	v_mul_f32_e32 v174, v2, v174
	v_exp_f32_e32 v179, v178
	v_mul_f32_e32 v178, 0x3d372713, v3
	v_fma_f32 v174, v2, v174, v2
	v_mul_f32_e32 v178, v3, v178
	v_mul_f32_e32 v174, 0x3f4c422a, v174
	v_fma_f32 v178, v3, v178, v3
	v_mul_f32_e32 v174, -2.0, v174
	v_mul_f32_e32 v178, 0x3f4c422a, v178
	v_mul_f32_e32 v174, 0x3fb8aa3b, v174
	v_mul_f32_e32 v178, -2.0, v178
	v_exp_f32_e32 v177, v174
	v_mul_f32_e32 v178, 0x3fb8aa3b, v178
	v_exp_f32_e32 v180, v178
	v_add_f32_e32 v176, 1.0, v176
	v_add_f32_e32 v177, 1.0, v177
	v_rcp_f32_e32 v178, v177
	v_add_f32_e32 v177, 1.0, v179
	v_add_f32_e32 v179, 1.0, v180
	v_rcp_f32_e32 v179, v179
	v_rcp_f32_e32 v176, v176
	v_rcp_f32_e32 v177, v177
	v_add_f32_e32 v164, v164, v165
	v_pk_mul_f32 v[174:175], v[170:171], v[170:171]
	v_pk_mul_f32 v[178:179], v[2:3], v[178:179]
	v_add_f32_e32 v164, v166, v164
	v_pk_fma_f32 v[174:175], v[172:173], v[172:173], v[174:175]
	v_add_f32_e32 v180, v169, v168
	v_pk_mul_f32 v[168:169], v[6:7], v[176:177]
	v_pk_fma_f32 v[176:177], v[6:7], v[176:177], v[178:179]
	v_add_f32_e32 v164, v167, v164
	v_add_f32_e32 v176, v176, v180
	v_pk_mul_f32 v[180:181], v[178:179], v[178:179]
	v_add_f32_e32 v164, v164, v174
	v_pk_fma_f32 v[180:181], v[168:169], v[168:169], v[180:181]
	v_add_f32_e32 v164, v175, v164
	v_add_f32_e32 v164, v180, v164
	v_add_f32_e32 v176, v177, v176
	v_add_f32_e32 v164, v181, v164
	ds_bpermute_b32 v165, v147, v176
	ds_bpermute_b32 v147, v147, v164
	v_add_u32_e32 v157, 0xb0, v157
	v_mov_b64_e32 v[162:163], s[14:15]
	v_mad_i64_i32 v[162:163], s[28:29], v157, s52, v[162:163]
	v_lshl_add_u64 v[162:163], v[162:163], 0, s[4:5]
	v_lshl_add_u64 v[162:163], v[144:145], 1, v[162:163]
	s_waitcnt lgkmcnt(0)
	v_add_f32_e32 v144, v176, v165
	v_add_f32_e32 v145, v164, v147
	ds_bpermute_b32 v147, v146, v144
	ds_bpermute_b32 v146, v146, v145
	global_store_dwordx4 v[162:163], v[158:161], off nt
	s_nop 1
	v_cvt_pk_bf16_f32 v158, v172, v173
	v_cvt_pk_bf16_f32 v159, v168, v169
	v_cvt_pk_bf16_f32 v160, v170, v171
	v_cvt_pk_bf16_f32 v161, v178, v179
	global_store_dwordx4 v[162:163], v[158:161], off offset:256 nt
	s_and_saveexec_b64 s[28:29], vcc
	s_cbranch_execz .LBB0_1229
	s_waitcnt lgkmcnt(0)
	v_add_f32_e32 v147, v144, v147
	v_lshlrev_b32_e32 v144, 1, v157
	v_add_f32_e32 v146, v145, v146
	v_ashrrev_i32_e32 v145, 31, v144
	v_lshl_add_u64 v[144:145], v[144:145], 2, s[48:49]
	global_atomic_add_f32 v[144:145], v147, off
	global_atomic_add_f32 v[144:145], v146, off offset:4

.LBB0_1231:
	s_andn2_b64 vcc, exec, s[28:29]
	s_cbranch_vccnz .LBB0_1192
	s_lshl_b32 s4, s16, 8
	s_add_i32 s4, s4, s41
	s_waitcnt lgkmcnt(0)
	v_add_u32_e32 v146, s4, v155
	s_lshl_b32 s6, s6, 8
	v_lshl_add_u32 v144, v156, 3, s42
	v_cvt_pk_bf16_f32 v124, v124, v125
	v_cvt_pk_bf16_f32 v125, v126, v127
	v_cvt_pk_bf16_f32 v126, v120, v121
	v_mov_b64_e32 v[120:121], s[14:15]
	s_ashr_i32 s7, s6, 31
	v_cvt_pk_bf16_f32 v68, v68, v69
	v_cvt_pk_bf16_f32 v69, v70, v71
	v_cvt_pk_bf16_f32 v70, v64, v65
	v_add_u32_e32 v64, 0x80, v146
	v_ashrrev_i32_e32 v145, 31, v144
	v_cvt_pk_bf16_f32 v127, v122, v123
	v_mad_i64_i32 v[122:123], s[28:29], v146, s52, v[120:121]
	s_lshl_b64 s[6:7], s[6:7], 1
	v_cvt_pk_bf16_f32 v60, v60, v61
	v_cvt_pk_bf16_f32 v61, v62, v63
	v_cvt_pk_bf16_f32 v62, v56, v57
	v_mad_i64_i32 v[56:57], s[28:29], v64, s52, v[120:121]
	v_lshl_add_u64 v[122:123], v[122:123], 0, s[6:7]
	v_lshlrev_b64 v[144:145], 1, v[144:145]
	v_lshl_add_u64 v[56:57], v[56:57], 0, s[6:7]
	v_lshl_add_u64 v[122:123], v[122:123], 0, v[144:145]
	v_cvt_pk_bf16_f32 v108, v108, v109
	v_cvt_pk_bf16_f32 v109, v110, v111
	v_cvt_pk_bf16_f32 v110, v104, v105
	v_cvt_pk_bf16_f32 v111, v106, v107
	v_lshl_add_u64 v[56:57], v[56:57], 0, v[144:145]
	v_cvt_pk_bf16_f32 v44, v44, v45
	v_cvt_pk_bf16_f32 v45, v46, v47
	v_cvt_pk_bf16_f32 v46, v40, v41
	v_cvt_pk_bf16_f32 v47, v42, v43
	global_store_dwordx4 v[122:123], v[108:111], off offset:256 nt
	global_store_dwordx4 v[56:57], v[44:47], off offset:256 nt
	v_cvt_pk_bf16_f32 v92, v92, v93
	v_add_u32_e32 v108, 16, v146
	v_add_u32_e32 v44, 0x90, v146
	v_mad_i64_i32 v[108:109], s[28:29], v108, s52, v[120:121]
	v_mad_i64_i32 v[44:45], s[28:29], v44, s52, v[120:121]
	v_lshl_add_u64 v[108:109], v[108:109], 0, s[6:7]
	v_lshl_add_u64 v[44:45], v[44:45], 0, s[6:7]
	v_lshl_add_u64 v[108:109], v[108:109], 0, v[144:145]
	v_cvt_pk_bf16_f32 v93, v94, v95
	v_cvt_pk_bf16_f32 v94, v88, v89
	v_cvt_pk_bf16_f32 v95, v90, v91
	v_lshl_add_u64 v[44:45], v[44:45], 0, v[144:145]
	v_cvt_pk_bf16_f32 v28, v28, v29
	v_cvt_pk_bf16_f32 v29, v30, v31
	v_cvt_pk_bf16_f32 v30, v24, v25
	v_cvt_pk_bf16_f32 v31, v26, v27
	global_store_dwordx4 v[108:109], v[92:95], off offset:256 nt
	global_store_dwordx4 v[44:45], v[28:31], off offset:256 nt
	v_cvt_pk_bf16_f32 v76, v76, v77
	v_add_u32_e32 v92, 32, v146
	v_add_u32_e32 v28, 0xa0, v146
	v_mad_i64_i32 v[92:93], s[28:29], v92, s52, v[120:121]
	v_mad_i64_i32 v[28:29], s[28:29], v28, s52, v[120:121]
	v_lshl_add_u64 v[92:93], v[92:93], 0, s[6:7]
	v_lshl_add_u64 v[28:29], v[28:29], 0, s[6:7]
	v_lshl_add_u64 v[92:93], v[92:93], 0, v[144:145]
	v_cvt_pk_bf16_f32 v77, v78, v79
	v_cvt_pk_bf16_f32 v78, v72, v73
	v_cvt_pk_bf16_f32 v79, v74, v75
	v_lshl_add_u64 v[28:29], v[28:29], 0, v[144:145]
	v_cvt_pk_bf16_f32 v12, v12, v13
	v_cvt_pk_bf16_f32 v13, v14, v15
	v_cvt_pk_bf16_f32 v14, v8, v9
	v_cvt_pk_bf16_f32 v15, v10, v11
	global_store_dwordx4 v[92:93], v[76:79], off offset:256 nt
	global_store_dwordx4 v[28:29], v[12:15], off offset:256 nt
	v_cvt_pk_bf16_f32 v104, v116, v117
	v_add_u32_e32 v76, 48, v146
	v_add_u32_e32 v12, 0xb0, v146
	v_mad_i64_i32 v[76:77], s[28:29], v76, s52, v[120:121]
	v_mad_i64_i32 v[12:13], s[28:29], v12, s52, v[120:121]
	v_lshl_add_u64 v[76:77], v[76:77], 0, s[6:7]
	v_lshl_add_u64 v[12:13], v[12:13], 0, s[6:7]
	v_cvt_pk_bf16_f32 v105, v118, v119
	v_cvt_pk_bf16_f32 v106, v112, v113
	v_cvt_pk_bf16_f32 v107, v114, v115
	v_cvt_pk_bf16_f32 v88, v100, v101
	v_cvt_pk_bf16_f32 v89, v102, v103
	v_cvt_pk_bf16_f32 v90, v96, v97
	v_cvt_pk_bf16_f32 v91, v98, v99
	v_cvt_pk_bf16_f32 v72, v84, v85
	v_cvt_pk_bf16_f32 v73, v86, v87
	v_cvt_pk_bf16_f32 v74, v80, v81
	v_cvt_pk_bf16_f32 v75, v82, v83
	v_lshl_add_u64 v[76:77], v[76:77], 0, v[144:145]
	v_cvt_pk_bf16_f32 v71, v66, v67
	v_cvt_pk_bf16_f32 v63, v58, v59
	v_cvt_pk_bf16_f32 v40, v52, v53
	v_cvt_pk_bf16_f32 v41, v54, v55
	v_cvt_pk_bf16_f32 v42, v48, v49
	v_cvt_pk_bf16_f32 v43, v50, v51
	v_cvt_pk_bf16_f32 v24, v36, v37
	v_cvt_pk_bf16_f32 v25, v38, v39
	v_cvt_pk_bf16_f32 v26, v32, v33
	v_cvt_pk_bf16_f32 v27, v34, v35
	v_cvt_pk_bf16_f32 v8, v20, v21
	v_cvt_pk_bf16_f32 v9, v22, v23
	v_cvt_pk_bf16_f32 v10, v16, v17
	v_cvt_pk_bf16_f32 v11, v18, v19
	v_lshl_add_u64 v[12:13], v[12:13], 0, v[144:145]
	v_cvt_pk_bf16_f32 v4, v4, v5
	v_cvt_pk_bf16_f32 v5, v6, v7
	v_cvt_pk_bf16_f32 v6, v0, v1
	v_cvt_pk_bf16_f32 v7, v2, v3
	global_store_dwordx4 v[122:123], v[124:127], off nt
	global_store_dwordx4 v[108:109], v[104:107], off nt
	global_store_dwordx4 v[92:93], v[88:91], off nt
	global_store_dwordx4 v[76:77], v[72:75], off nt
	global_store_dwordx4 v[76:77], v[68:71], off offset:256 nt
	global_store_dwordx4 v[56:57], v[60:63], off nt
	global_store_dwordx4 v[44:45], v[40:43], off nt
	global_store_dwordx4 v[28:29], v[24:27], off nt
	global_store_dwordx4 v[12:13], v[8:11], off nt
	global_store_dwordx4 v[12:13], v[4:7], off offset:256 nt
	s_branch .LBB0_1192

.LBB0_1402:
	ds_read_b128 v[150:153], v147
	ds_read_b128 v[154:157], v147 offset:1024
	ds_read_b128 v[158:161], v147 offset:2048
	ds_read_b128 v[162:165], v147 offset:3072
	s_add_u32 s34, s30, 0x100
	s_addc_u32 s35, s31, 0
	s_cmp_eq_u32 s69, 36
	s_cselect_b32 s39, s5, s35
	s_cselect_b32 s38, s4, s34
	s_cselect_b32 s37, s7, s68
	s_cselect_b32 s36, s6, s67
	v_lshl_add_u64 v[198:199], s[30:31], 0, v[136:137]
	s_add_i32 m0, s41, 0xc000
	ds_read_b128 v[166:169], v148
	ds_read_b128 v[170:173], v148 offset:1024
	ds_read_b128 v[174:177], v148 offset:2048
	ds_read_b128 v[178:181], v148 offset:3072
	ds_read_b128 v[182:185], v148 offset:4096
	ds_read_b128 v[186:189], v148 offset:5120
	ds_read_b128 v[190:193], v148 offset:6144
	ds_read_b128 v[194:197], v148 offset:7168
	global_load_lds_dwordx4 v[198:199], off
	v_lshl_add_u64 v[198:199], s[30:31], 0, v[138:139]
	s_add_i32 m0, s41, 0xe000
	s_nop 0
	global_load_lds_dwordx4 v[198:199], off
	s_waitcnt lgkmcnt(8)
	s_barrier
	s_waitcnt lgkmcnt(0)
	s_setprio 1
	s_waitcnt lgkmcnt(0)
	v_mfma_f32_16x16x32_bf16 v[124:127], v[150:153], v[166:169], v[124:127]
	v_mfma_f32_16x16x32_bf16 v[120:123], v[158:161], v[166:169], v[120:123]
	v_mfma_f32_16x16x32_bf16 v[116:119], v[150:153], v[174:177], v[116:119]
	v_mfma_f32_16x16x32_bf16 v[112:115], v[158:161], v[174:177], v[112:115]
	v_mfma_f32_16x16x32_bf16 v[100:103], v[150:153], v[182:185], v[100:103]
	v_mfma_f32_16x16x32_bf16 v[96:99], v[158:161], v[182:185], v[96:99]
	v_mfma_f32_16x16x32_bf16 v[84:87], v[150:153], v[190:193], v[84:87]
	v_mfma_f32_16x16x32_bf16 v[80:83], v[158:161], v[190:193], v[80:83]
	v_mfma_f32_16x16x32_bf16 v[124:127], v[154:157], v[170:173], v[124:127]
	v_mfma_f32_16x16x32_bf16 v[120:123], v[162:165], v[170:173], v[120:123]
	v_mfma_f32_16x16x32_bf16 v[116:119], v[154:157], v[178:181], v[116:119]
	v_mfma_f32_16x16x32_bf16 v[112:115], v[162:165], v[178:181], v[112:115]
	v_mfma_f32_16x16x32_bf16 v[100:103], v[154:157], v[186:189], v[100:103]
	v_mfma_f32_16x16x32_bf16 v[96:99], v[162:165], v[186:189], v[96:99]
	v_mfma_f32_16x16x32_bf16 v[84:87], v[154:157], v[194:197], v[84:87]
	v_mfma_f32_16x16x32_bf16 v[80:83], v[162:165], v[194:197], v[80:83]
	s_setprio 0
	s_barrier
	s_add_i32 s30, s54, s40
	v_lshl_add_u64 v[206:207], s[36:37], 0, v[130:131]
	s_mov_b32 m0, s30
	ds_read_b128 v[198:201], v149
	ds_read_b128 v[202:205], v149 offset:1024
	ds_read_b128 v[210:213], v149 offset:2048
	ds_read_b128 v[214:217], v149 offset:3072
	global_load_lds_dwordx4 v[206:207], off
	v_lshl_add_u64 v[218:219], s[36:37], 0, v[134:135]
	s_add_i32 m0, s30, 0x2000
	s_nop 0
	global_load_lds_dwordx4 v[218:219], off
	s_barrier
	s_waitcnt lgkmcnt(0)
	s_setprio 1
	s_waitcnt lgkmcnt(0)
	v_mfma_f32_16x16x32_bf16 v[108:111], v[198:201], v[166:169], v[108:111]
	v_mfma_f32_16x16x32_bf16 v[104:107], v[210:213], v[166:169], v[104:107]
	v_mfma_f32_16x16x32_bf16 v[92:95], v[198:201], v[174:177], v[92:95]
	v_mfma_f32_16x16x32_bf16 v[88:91], v[210:213], v[174:177], v[88:91]
	v_mfma_f32_16x16x32_bf16 v[76:79], v[198:201], v[182:185], v[76:79]
	v_mfma_f32_16x16x32_bf16 v[72:75], v[210:213], v[182:185], v[72:75]
	v_mfma_f32_16x16x32_bf16 v[68:71], v[198:201], v[190:193], v[68:71]
	v_mfma_f32_16x16x32_bf16 v[64:67], v[210:213], v[190:193], v[64:67]
	v_mfma_f32_16x16x32_bf16 v[108:111], v[202:205], v[170:173], v[108:111]
	v_mfma_f32_16x16x32_bf16 v[104:107], v[214:217], v[170:173], v[104:107]
	v_mfma_f32_16x16x32_bf16 v[92:95], v[202:205], v[178:181], v[92:95]
	v_mfma_f32_16x16x32_bf16 v[88:91], v[214:217], v[178:181], v[88:91]
	v_mfma_f32_16x16x32_bf16 v[76:79], v[202:205], v[186:189], v[76:79]
	v_mfma_f32_16x16x32_bf16 v[72:75], v[214:217], v[186:189], v[72:75]
	v_mfma_f32_16x16x32_bf16 v[68:71], v[202:205], v[194:197], v[68:71]
	v_mfma_f32_16x16x32_bf16 v[64:67], v[214:217], v[194:197], v[64:67]
	s_setprio 0
	s_mov_b32 m0, s41
	v_lshl_add_u64 v[220:221], s[38:39], 0, v[128:129]
	s_barrier
	ds_read_b128 v[166:169], v148 offset:16384
	ds_read_b128 v[170:173], v148 offset:17408
	ds_read_b128 v[174:177], v148 offset:18432
	ds_read_b128 v[178:181], v148 offset:19456
	ds_read_b128 v[182:185], v148 offset:20480
	ds_read_b128 v[186:189], v148 offset:21504
	ds_read_b128 v[190:193], v148 offset:22528
	ds_read_b128 v[194:197], v148 offset:23552
	global_load_lds_dwordx4 v[220:221], off
	v_lshl_add_u64 v[222:223], s[38:39], 0, v[132:133]
	s_mov_b32 m0, s42
	s_nop 0
	global_load_lds_dwordx4 v[222:223], off
	s_barrier
	s_waitcnt lgkmcnt(0)
	s_setprio 1
	s_waitcnt lgkmcnt(0)
	v_mfma_f32_16x16x32_bf16 v[60:63], v[150:153], v[166:169], v[60:63]
	v_mfma_f32_16x16x32_bf16 v[56:59], v[158:161], v[166:169], v[56:59]
	v_mfma_f32_16x16x32_bf16 v[52:55], v[150:153], v[174:177], v[52:55]
	v_mfma_f32_16x16x32_bf16 v[48:51], v[158:161], v[174:177], v[48:51]
	v_mfma_f32_16x16x32_bf16 v[36:39], v[150:153], v[182:185], v[36:39]
	v_mfma_f32_16x16x32_bf16 v[32:35], v[158:161], v[182:185], v[32:35]
	v_mfma_f32_16x16x32_bf16 v[20:23], v[150:153], v[190:193], v[20:23]
	v_mfma_f32_16x16x32_bf16 v[16:19], v[158:161], v[190:193], v[16:19]
	v_mfma_f32_16x16x32_bf16 v[60:63], v[154:157], v[170:173], v[60:63]
	v_mfma_f32_16x16x32_bf16 v[56:59], v[162:165], v[170:173], v[56:59]
	v_mfma_f32_16x16x32_bf16 v[52:55], v[154:157], v[178:181], v[52:55]
	v_mfma_f32_16x16x32_bf16 v[48:51], v[162:165], v[178:181], v[48:51]
	v_mfma_f32_16x16x32_bf16 v[36:39], v[154:157], v[186:189], v[36:39]
	v_mfma_f32_16x16x32_bf16 v[32:35], v[162:165], v[186:189], v[32:35]
	v_mfma_f32_16x16x32_bf16 v[20:23], v[154:157], v[194:197], v[20:23]
	v_mfma_f32_16x16x32_bf16 v[16:19], v[162:165], v[194:197], v[16:19]
	s_setprio 0
	s_barrier
	s_add_u32 s30, s36, 0xa0000
	s_addc_u32 s31, s37, 0
	s_add_i32 s70, s55, s40
	v_lshl_add_u64 v[150:151], s[30:31], 0, v[130:131]
	s_mov_b32 m0, s70
	s_nop 0
	global_load_lds_dwordx4 v[150:151], off
	v_lshl_add_u64 v[150:151], s[30:31], 0, v[134:135]
	s_add_i32 m0, s70, 0x2000
	s_nop 0
	global_load_lds_dwordx4 v[150:151], off
	s_waitcnt vmcnt(6)
	s_barrier
	s_setprio 1
	v_mfma_f32_16x16x32_bf16 v[44:47], v[198:201], v[166:169], v[44:47]
	v_mfma_f32_16x16x32_bf16 v[40:43], v[210:213], v[166:169], v[40:43]
	v_mfma_f32_16x16x32_bf16 v[28:31], v[198:201], v[174:177], v[28:31]
	v_mfma_f32_16x16x32_bf16 v[24:27], v[210:213], v[174:177], v[24:27]
	v_mfma_f32_16x16x32_bf16 v[12:15], v[198:201], v[182:185], v[12:15]
	v_mfma_f32_16x16x32_bf16 v[8:11], v[210:213], v[182:185], v[8:11]
	v_mfma_f32_16x16x32_bf16 v[4:7], v[198:201], v[190:193], v[4:7]
	v_mfma_f32_16x16x32_bf16 v[0:3], v[210:213], v[190:193], v[0:3]
	v_mfma_f32_16x16x32_bf16 v[44:47], v[202:205], v[170:173], v[44:47]
	v_mfma_f32_16x16x32_bf16 v[40:43], v[214:217], v[170:173], v[40:43]
	v_mfma_f32_16x16x32_bf16 v[28:31], v[202:205], v[178:181], v[28:31]
	v_mfma_f32_16x16x32_bf16 v[24:27], v[214:217], v[178:181], v[24:27]
	v_mfma_f32_16x16x32_bf16 v[12:15], v[202:205], v[186:189], v[12:15]
	v_mfma_f32_16x16x32_bf16 v[8:11], v[214:217], v[186:189], v[8:11]
	v_mfma_f32_16x16x32_bf16 v[4:7], v[202:205], v[194:197], v[4:7]
	v_mfma_f32_16x16x32_bf16 v[0:3], v[214:217], v[194:197], v[0:3]
	s_setprio 0
	s_add_i32 s70, 0, 0x18000
	v_add_u32_e32 v162, s70, v146
	s_barrier
	ds_read_b128 v[150:153], v162
	ds_read_b128 v[154:157], v162 offset:1024
	ds_read_b128 v[158:161], v162 offset:2048
	ds_read_b128 v[162:165], v162 offset:3072
	s_add_u32 s30, s38, 0xa0000
	s_addc_u32 s31, s39, 0
	s_mov_b32 m0, s43
	v_lshl_add_u64 v[198:199], s[30:31], 0, v[128:129]
	ds_read_b128 v[166:169], v148 offset:32768
	ds_read_b128 v[170:173], v148 offset:33792
	ds_read_b128 v[174:177], v148 offset:34816
	ds_read_b128 v[178:181], v148 offset:35840
	ds_read_b128 v[182:185], v148 offset:36864
	ds_read_b128 v[186:189], v148 offset:37888
	ds_read_b128 v[190:193], v148 offset:38912
	ds_read_b128 v[194:197], v148 offset:39936
	global_load_lds_dwordx4 v[198:199], off
	v_lshl_add_u64 v[198:199], s[30:31], 0, v[132:133]
	s_mov_b32 m0, s44
	s_nop 0
	global_load_lds_dwordx4 v[198:199], off
	s_waitcnt lgkmcnt(8)
	s_barrier
	s_waitcnt lgkmcnt(0)
	s_setprio 1
	s_waitcnt lgkmcnt(0)
	v_mfma_f32_16x16x32_bf16 v[124:127], v[150:153], v[166:169], v[124:127]
	v_mfma_f32_16x16x32_bf16 v[120:123], v[158:161], v[166:169], v[120:123]
	v_mfma_f32_16x16x32_bf16 v[116:119], v[150:153], v[174:177], v[116:119]
	v_mfma_f32_16x16x32_bf16 v[112:115], v[158:161], v[174:177], v[112:115]
	v_mfma_f32_16x16x32_bf16 v[100:103], v[150:153], v[182:185], v[100:103]
	v_mfma_f32_16x16x32_bf16 v[96:99], v[158:161], v[182:185], v[96:99]
	v_mfma_f32_16x16x32_bf16 v[84:87], v[150:153], v[190:193], v[84:87]
	v_mfma_f32_16x16x32_bf16 v[80:83], v[158:161], v[190:193], v[80:83]
	v_mfma_f32_16x16x32_bf16 v[124:127], v[154:157], v[170:173], v[124:127]
	v_mfma_f32_16x16x32_bf16 v[120:123], v[162:165], v[170:173], v[120:123]
	v_mfma_f32_16x16x32_bf16 v[116:119], v[154:157], v[178:181], v[116:119]
	v_mfma_f32_16x16x32_bf16 v[112:115], v[162:165], v[178:181], v[112:115]
	v_mfma_f32_16x16x32_bf16 v[100:103], v[154:157], v[186:189], v[100:103]
	v_mfma_f32_16x16x32_bf16 v[96:99], v[162:165], v[186:189], v[96:99]
	v_mfma_f32_16x16x32_bf16 v[84:87], v[154:157], v[194:197], v[84:87]
	v_mfma_f32_16x16x32_bf16 v[80:83], v[162:165], v[194:197], v[80:83]
	s_setprio 0
	s_barrier
	s_add_i32 s38, 0, 0x1c000
	s_add_i32 s30, s70, s40
	v_add_u32_e32 v214, s38, v146
	v_lshl_add_u64 v[206:207], v[206:207], 0, s[14:15]
	s_mov_b32 m0, s30
	ds_read_b128 v[198:201], v214
	ds_read_b128 v[202:205], v214 offset:1024
	ds_read_b128 v[210:213], v214 offset:2048
	ds_read_b128 v[214:217], v214 offset:3072
	global_load_lds_dwordx4 v[206:207], off
	v_lshl_add_u64 v[206:207], v[218:219], 0, s[14:15]
	s_add_i32 m0, s30, 0x2000
	s_nop 0
	global_load_lds_dwordx4 v[206:207], off
	s_barrier
	s_waitcnt lgkmcnt(0)
	s_setprio 1
	s_waitcnt lgkmcnt(0)
	v_mfma_f32_16x16x32_bf16 v[108:111], v[198:201], v[166:169], v[108:111]
	v_mfma_f32_16x16x32_bf16 v[104:107], v[210:213], v[166:169], v[104:107]
	v_mfma_f32_16x16x32_bf16 v[92:95], v[198:201], v[174:177], v[92:95]
	v_mfma_f32_16x16x32_bf16 v[88:91], v[210:213], v[174:177], v[88:91]
	v_mfma_f32_16x16x32_bf16 v[76:79], v[198:201], v[182:185], v[76:79]
	v_mfma_f32_16x16x32_bf16 v[72:75], v[210:213], v[182:185], v[72:75]
	v_mfma_f32_16x16x32_bf16 v[68:71], v[198:201], v[190:193], v[68:71]
	v_mfma_f32_16x16x32_bf16 v[64:67], v[210:213], v[190:193], v[64:67]
	v_mfma_f32_16x16x32_bf16 v[108:111], v[202:205], v[170:173], v[108:111]
	v_mfma_f32_16x16x32_bf16 v[104:107], v[214:217], v[170:173], v[104:107]
	v_mfma_f32_16x16x32_bf16 v[92:95], v[202:205], v[178:181], v[92:95]
	v_mfma_f32_16x16x32_bf16 v[88:91], v[214:217], v[178:181], v[88:91]
	v_mfma_f32_16x16x32_bf16 v[76:79], v[202:205], v[186:189], v[76:79]
	v_mfma_f32_16x16x32_bf16 v[72:75], v[214:217], v[186:189], v[72:75]
	v_mfma_f32_16x16x32_bf16 v[68:71], v[202:205], v[194:197], v[68:71]
	v_mfma_f32_16x16x32_bf16 v[64:67], v[214:217], v[194:197], v[64:67]
	s_setprio 0
	s_mov_b32 m0, s52
	v_lshl_add_u64 v[206:207], v[220:221], 0, s[14:15]
	s_barrier
	ds_read_b128 v[166:169], v148 offset:49152
	ds_read_b128 v[170:173], v148 offset:50176
	ds_read_b128 v[174:177], v148 offset:51200
	ds_read_b128 v[178:181], v148 offset:52224
	ds_read_b128 v[182:185], v148 offset:53248
	ds_read_b128 v[186:189], v148 offset:54272
	ds_read_b128 v[190:193], v148 offset:55296
	ds_read_b128 v[194:197], v148 offset:56320
	global_load_lds_dwordx4 v[206:207], off
	v_lshl_add_u64 v[206:207], v[222:223], 0, s[14:15]
	s_mov_b32 m0, s53
	s_nop 0
	global_load_lds_dwordx4 v[206:207], off
	s_barrier
	s_waitcnt lgkmcnt(0)
	s_setprio 1
	s_waitcnt lgkmcnt(0)
	v_mfma_f32_16x16x32_bf16 v[60:63], v[150:153], v[166:169], v[60:63]
	v_mfma_f32_16x16x32_bf16 v[56:59], v[158:161], v[166:169], v[56:59]
	v_mfma_f32_16x16x32_bf16 v[52:55], v[150:153], v[174:177], v[52:55]
	v_mfma_f32_16x16x32_bf16 v[48:51], v[158:161], v[174:177], v[48:51]
	v_mfma_f32_16x16x32_bf16 v[36:39], v[150:153], v[182:185], v[36:39]
	v_mfma_f32_16x16x32_bf16 v[32:35], v[158:161], v[182:185], v[32:35]
	v_mfma_f32_16x16x32_bf16 v[20:23], v[150:153], v[190:193], v[20:23]
	v_mfma_f32_16x16x32_bf16 v[16:19], v[158:161], v[190:193], v[16:19]
	v_mfma_f32_16x16x32_bf16 v[60:63], v[154:157], v[170:173], v[60:63]
	v_mfma_f32_16x16x32_bf16 v[56:59], v[162:165], v[170:173], v[56:59]
	v_mfma_f32_16x16x32_bf16 v[52:55], v[154:157], v[178:181], v[52:55]
	v_mfma_f32_16x16x32_bf16 v[48:51], v[162:165], v[178:181], v[48:51]
	v_mfma_f32_16x16x32_bf16 v[36:39], v[154:157], v[186:189], v[36:39]
	v_mfma_f32_16x16x32_bf16 v[32:35], v[162:165], v[186:189], v[32:35]
	v_mfma_f32_16x16x32_bf16 v[20:23], v[154:157], v[194:197], v[20:23]
	v_mfma_f32_16x16x32_bf16 v[16:19], v[162:165], v[194:197], v[16:19]
	s_setprio 0
	s_barrier
	s_add_u32 s30, s36, 0xa0080
	s_addc_u32 s31, s37, 0
	s_add_i32 s36, s38, s40
	v_lshl_add_u64 v[150:151], s[30:31], 0, v[130:131]
	s_mov_b32 m0, s36
	s_nop 0
	global_load_lds_dwordx4 v[150:151], off
	v_lshl_add_u64 v[150:151], s[30:31], 0, v[134:135]
	s_add_i32 m0, s36, 0x2000
	s_nop 0
	global_load_lds_dwordx4 v[150:151], off
	s_waitcnt vmcnt(6)
	s_barrier
	s_setprio 1
	v_mfma_f32_16x16x32_bf16 v[44:47], v[198:201], v[166:169], v[44:47]
	v_mfma_f32_16x16x32_bf16 v[40:43], v[210:213], v[166:169], v[40:43]
	v_mfma_f32_16x16x32_bf16 v[28:31], v[198:201], v[174:177], v[28:31]
	v_mfma_f32_16x16x32_bf16 v[24:27], v[210:213], v[174:177], v[24:27]
	v_mfma_f32_16x16x32_bf16 v[12:15], v[198:201], v[182:185], v[12:15]
	v_mfma_f32_16x16x32_bf16 v[8:11], v[210:213], v[182:185], v[8:11]
	v_mfma_f32_16x16x32_bf16 v[4:7], v[198:201], v[190:193], v[4:7]
	v_mfma_f32_16x16x32_bf16 v[0:3], v[210:213], v[190:193], v[0:3]
	v_mfma_f32_16x16x32_bf16 v[44:47], v[202:205], v[170:173], v[44:47]
	v_mfma_f32_16x16x32_bf16 v[40:43], v[214:217], v[170:173], v[40:43]
	v_mfma_f32_16x16x32_bf16 v[28:31], v[202:205], v[178:181], v[28:31]
	v_mfma_f32_16x16x32_bf16 v[24:27], v[214:217], v[178:181], v[24:27]
	v_mfma_f32_16x16x32_bf16 v[12:15], v[202:205], v[186:189], v[12:15]
	v_mfma_f32_16x16x32_bf16 v[8:11], v[214:217], v[186:189], v[8:11]
	v_mfma_f32_16x16x32_bf16 v[4:7], v[202:205], v[194:197], v[4:7]
	v_mfma_f32_16x16x32_bf16 v[0:3], v[214:217], v[194:197], v[0:3]
	s_setprio 0
	s_add_i32 s69, s69, 2
	s_add_u32 s67, s67, 0x100
	s_addc_u32 s68, s68, 0
	s_cmp_gt_u32 s69, 37
	s_mov_b64 s[30:31], s[34:35]
	s_barrier
	s_cbranch_scc0 .LBB0_1402
	v_mov_b32_e32 v150, v145
	v_mov_b32_e32 v151, v144
	s_lshl_b32 s30, s63, 8
	s_add_i32 s30, s30, s49
	v_add_u32_e32 v150, s30, v150
	s_lshl_b32 s30, s66, 8
	s_or_b32 s30, s30, s51
	v_lshl_add_u32 v152, v151, 3, s30
	v_ashrrev_i32_e32 v151, 31, v150
	v_lshlrev_b64 v[150:151], 12, v[150:151]
	v_ashrrev_i32_e32 v153, 31, v152
	v_lshl_add_u64 v[150:151], s[10:11], 0, v[150:151]
	v_lshl_add_u64 v[150:151], v[152:153], 1, v[150:151]
	v_cvt_pk_bf16_f32 v108, v108, v109
	v_cvt_pk_bf16_f32 v109, v110, v111
	v_cvt_pk_bf16_f32 v110, v104, v105
	v_cvt_pk_bf16_f32 v111, v106, v107
	global_store_dwordx4 v[150:151], v[108:111], off offset:256 nt
	v_cvt_pk_bf16_f32 v92, v92, v93
	v_cvt_pk_bf16_f32 v93, v94, v95
	v_add_co_u32_e32 v110, vcc, s48, v150
	v_lshl_add_u64 v[108:109], v[150:151], 0, s[18:19]
	s_nop 0
	v_addc_co_u32_e32 v111, vcc, 0, v151, vcc
	v_cvt_pk_bf16_f32 v94, v88, v89
	v_cvt_pk_bf16_f32 v95, v90, v91
	global_store_dwordx4 v[108:109], v[92:95], off offset:256 nt
	v_cvt_pk_bf16_f32 v76, v76, v77
	v_cvt_pk_bf16_f32 v77, v78, v79
	v_add_co_u32_e32 v94, vcc, s56, v150
	v_lshl_add_u64 v[92:93], v[150:151], 0, s[20:21]
	s_nop 0
	v_addc_co_u32_e32 v95, vcc, 0, v151, vcc
	v_cvt_pk_bf16_f32 v78, v72, v73
	v_cvt_pk_bf16_f32 v79, v74, v75
	global_store_dwordx4 v[92:93], v[76:79], off offset:256 nt
	v_cvt_pk_bf16_f32 v60, v60, v61
	v_cvt_pk_bf16_f32 v61, v62, v63
	v_add_co_u32_e32 v78, vcc, s57, v150
	v_cvt_pk_bf16_f32 v62, v56, v57
	s_nop 0
	v_addc_co_u32_e32 v79, vcc, 0, v151, vcc
	v_add_co_u32_e32 v56, vcc, s59, v150
	v_cvt_pk_bf16_f32 v68, v68, v69
	v_cvt_pk_bf16_f32 v69, v70, v71
	v_cvt_pk_bf16_f32 v70, v64, v65
	v_lshl_add_u64 v[64:65], v[150:151], 0, s[24:25]
	v_addc_co_u32_e32 v57, vcc, 0, v151, vcc
	v_cvt_pk_bf16_f32 v44, v44, v45
	v_cvt_pk_bf16_f32 v45, v46, v47
	v_cvt_pk_bf16_f32 v46, v40, v41
	v_cvt_pk_bf16_f32 v47, v42, v43
	global_store_dwordx4 v[64:65], v[44:47], off offset:256 nt
	v_cvt_pk_bf16_f32 v28, v28, v29
	v_cvt_pk_bf16_f32 v29, v30, v31
	v_add_co_u32_e32 v46, vcc, s60, v150
	v_lshl_add_u64 v[44:45], v[150:151], 0, s[26:27]
	s_nop 0
	v_addc_co_u32_e32 v47, vcc, 0, v151, vcc
	v_cvt_pk_bf16_f32 v30, v24, v25
	v_cvt_pk_bf16_f32 v31, v26, v27
	global_store_dwordx4 v[44:45], v[28:31], off offset:256 nt
	v_cvt_pk_bf16_f32 v12, v12, v13
	v_cvt_pk_bf16_f32 v13, v14, v15
	v_add_co_u32_e32 v30, vcc, s61, v150
	v_lshl_add_u64 v[28:29], v[150:151], 0, s[8:9]
	s_nop 0
	v_addc_co_u32_e32 v31, vcc, 0, v151, vcc
	v_cvt_pk_bf16_f32 v14, v8, v9
	v_cvt_pk_bf16_f32 v15, v10, v11
	global_store_dwordx4 v[28:29], v[12:15], off offset:256 nt
	v_cvt_pk_bf16_f32 v124, v124, v125
	v_cvt_pk_bf16_f32 v125, v126, v127
	v_add_co_u32_e32 v14, vcc, s62, v150
	v_cvt_pk_bf16_f32 v126, v120, v121
	s_nop 0
	v_addc_co_u32_e32 v15, vcc, 0, v151, vcc
	v_cvt_pk_bf16_f32 v127, v122, v123
	v_cvt_pk_bf16_f32 v104, v116, v117
	v_cvt_pk_bf16_f32 v105, v118, v119
	v_cvt_pk_bf16_f32 v106, v112, v113
	v_cvt_pk_bf16_f32 v107, v114, v115
	v_cvt_pk_bf16_f32 v88, v100, v101
	v_cvt_pk_bf16_f32 v89, v102, v103
	v_cvt_pk_bf16_f32 v90, v96, v97
	v_cvt_pk_bf16_f32 v91, v98, v99
	v_lshl_add_u64 v[76:77], v[150:151], 0, s[22:23]
	v_cvt_pk_bf16_f32 v72, v84, v85
	v_cvt_pk_bf16_f32 v73, v86, v87
	v_cvt_pk_bf16_f32 v74, v80, v81
	v_cvt_pk_bf16_f32 v75, v82, v83
	v_cvt_pk_bf16_f32 v71, v66, v67
	v_cvt_pk_bf16_f32 v63, v58, v59
	v_cvt_pk_bf16_f32 v40, v52, v53
	v_cvt_pk_bf16_f32 v41, v54, v55
	v_cvt_pk_bf16_f32 v42, v48, v49
	v_cvt_pk_bf16_f32 v43, v50, v51
	v_cvt_pk_bf16_f32 v24, v36, v37
	v_cvt_pk_bf16_f32 v25, v38, v39
	v_cvt_pk_bf16_f32 v26, v32, v33
	v_cvt_pk_bf16_f32 v27, v34, v35
	v_lshl_add_u64 v[12:13], v[150:151], 0, s[28:29]
	v_cvt_pk_bf16_f32 v8, v20, v21
	v_cvt_pk_bf16_f32 v9, v22, v23
	v_cvt_pk_bf16_f32 v10, v16, v17
	v_cvt_pk_bf16_f32 v11, v18, v19
	v_cvt_pk_bf16_f32 v4, v4, v5
	v_cvt_pk_bf16_f32 v5, v6, v7
	v_cvt_pk_bf16_f32 v6, v0, v1
	v_cvt_pk_bf16_f32 v7, v2, v3
	s_and_b64 vcc, exec, s[2:3]
	s_mov_b32 s66, s64
	s_mov_b32 s63, s65
	s_mov_b64 s[34:35], s[6:7]
	s_mov_b64 s[30:31], s[4:5]
	global_store_dwordx4 v[150:151], v[124:127], off nt
	global_store_dwordx4 v[110:111], v[104:107], off nt
	global_store_dwordx4 v[94:95], v[88:91], off nt
	global_store_dwordx4 v[78:79], v[72:75], off nt
	global_store_dwordx4 v[76:77], v[68:71], off offset:256 nt
	global_store_dwordx4 v[56:57], v[60:63], off nt
	global_store_dwordx4 v[46:47], v[40:43], off nt
	global_store_dwordx4 v[30:31], v[24:27], off nt
	global_store_dwordx4 v[14:15], v[8:11], off nt
	global_store_dwordx4 v[12:13], v[4:7], off offset:256 nt
	s_cbranch_vccz .LBB0_1391
	s_waitcnt vmcnt(0)
	s_cmpk_gt_u32 s33, 0xff
	s_cbranch_scc1 .LBB0_1406
	s_barrier
